# speedup vs baseline: 1.0098x; 1.0098x over previous
; __device__ __forceinline__ void run_phase(const Params& p, const PD& d, const int type, char* shm, const int wave_s) {
;   GemmCfg g{};
;   const float* xin = (d.l == 0 && d.sub == 0) ? p.x : p.out;
;   g.xin = xin; g.xout = p.out; g.modl = p.mod + (size_t)d.l * 16 * 9216; g.sub = d.sub;
;   const int ff = d.l * 2 + (d.sub == 2 ? 1 : 0);
;   const int mj = d.l >> 1;
;   {
;     const int nl = (d.sub == 2) ? d.l + 1 : d.l, ns = (d.sub == 2) ? 0 : d.sub + 1;
;     g.has_next = (nl < 4) ? 1 : 0;
;     const int nlc = (nl < 4) ? nl : 3;
;     g.gnext = p.norm_g + (nlc * 3 + ns) * 1024;
;     g.scnext = p.mod + (size_t)nlc * 16 * 9216 + ns * 3072 + 1024;
;   }
;   switch (type) {
;     case PH_INIT: init_phase(p, shm, fresh_tid(wave_s)); break;
;     case PH_NORM: prep_phase(p, shm, fresh_tid(wave_s)); break;
.LBB0_74:
	s_or_b32 s0, s41, s3
	v_readlane_b32 s52, v253, 25
	s_cmp_eq_u32 s0, 0
	v_readlane_b32 s65, v253, 38
	v_readlane_b32 s53, v253, 26
	v_readlane_b32 s54, v253, 27
	v_readlane_b32 s55, v253, 28
	v_readlane_b32 s56, v253, 29
	v_readlane_b32 s57, v253, 30
	v_readlane_b32 s58, v253, 31
	v_readlane_b32 s59, v253, 32
	v_readlane_b32 s60, v253, 33
	v_readlane_b32 s61, v253, 34
	v_readlane_b32 s62, v253, 35
	v_readlane_b32 s63, v253, 36
	v_readlane_b32 s64, v253, 37
	v_readlane_b32 s66, v253, 39
	v_readlane_b32 s67, v253, 40
	s_cselect_b32 s0, s5, s65
	v_writelane_b32 v254, s0, 55
	s_cselect_b32 s0, s4, s64
	v_readlane_b32 s52, v252, 26
	s_mul_i32 s1, s41, 0x90000
	v_readlane_b32 s62, v252, 36
	v_writelane_b32 v254, s0, 56
	s_mul_hi_i32 s0, s41, 0x90000
	v_readlane_b32 s63, v252, 37
	s_add_u32 s1, s62, s1
	s_addc_u32 s0, s63, s0
	s_ashr_i32 s50, s41, 1
	s_add_i32 s2, s3, 1
	v_readlane_b32 s53, v252, 27
	s_cmp_eq_u32 s3, 2
	v_writelane_b32 v254, s1, 57
	s_cselect_b64 s[52:53], -1, 0
	v_writelane_b32 v254, s0, 58
	s_and_b64 s[0:1], s[52:53], exec
	s_cselect_b32 s2, 0, s2
	s_cmp_lg_u64 s[52:53], 0
	s_addc_u32 s0, s41, 0
	s_cmp_lt_i32 s0, 4
	v_writelane_b32 v254, s3, 59
	s_cselect_b64 s[4:5], -1, 0
	s_min_i32 s3, s0, 3
	s_mul_i32 s0, s3, 3
	s_add_i32 s0, s0, s2
	s_lshl_b32 s0, s0, 10
	s_ashr_i32 s1, s0, 31
	s_lshl_b64 s[0:1], s[0:1], 2
	v_writelane_b32 v254, s4, 60
	s_add_u32 s0, s12, s0
	s_addc_u32 s1, s13, s1
	v_writelane_b32 v254, s5, 61
	v_writelane_b32 v254, s0, 62
	v_readfirstlane_b32 s43, v0
	s_mov_b64 s[38:39], 0
	v_writelane_b32 v254, s1, 63
	s_mul_hi_i32 s0, s3, 0x90000
	s_mul_i32 s3, s3, 0x90000
	s_add_u32 s3, s62, s3
	s_addc_u32 s4, s63, s0
	s_mul_i32 s0, s2, 0xc00
	s_ashr_i32 s1, s0, 31
	s_lshl_b64 s[0:1], s[0:1], 2
	s_add_u32 s0, s3, s0
	s_addc_u32 s1, s4, s1
	s_add_u32 s0, s0, 0x1000
	v_writelane_b32 v255, s0, 0
	s_addc_u32 s0, s1, 0
	v_readlane_b32 s2, v254, 54
	v_writelane_b32 v255, s0, 1
	s_cmp_lt_i32 s2, 5
	s_mov_b64 s[2:3], 0
	v_writelane_b32 v255, s2, 2
	s_mov_b64 s[0:1], -1
	v_readlane_b32 s54, v252, 28
	v_writelane_b32 v255, s3, 3
	v_readlane_b32 s55, v252, 29
	v_readlane_b32 s56, v252, 30
	v_readlane_b32 s57, v252, 31
	v_readlane_b32 s58, v252, 32
	v_readlane_b32 s59, v252, 33
	v_readlane_b32 s60, v252, 34
	v_readlane_b32 s61, v252, 35
	v_readlane_b32 s64, v252, 38
	v_readlane_b32 s65, v252, 39
	v_readlane_b32 s66, v252, 40
	v_readlane_b32 s67, v252, 41
	s_cbranch_scc1 .LBB0_571
	v_readlane_b32 s0, v254, 54
	s_cmp_gt_i32 s0, 7
	s_cbranch_scc0 .LBB0_81
	s_cmp_gt_i32 s0, 8
	s_cbranch_scc0 .LBB0_297
	s_cmp_gt_i32 s0, 9
	s_cbranch_scc0 .LBB0_298
	s_cmp_eq_u32 s0, 10
	s_mov_b64 s[0:1], -1
	s_cbranch_scc0 .LBB0_300
	v_readlane_b32 s0, v252, 42
	v_readlane_b32 s1, v252, 43
	s_mov_b64 s[92:93], s[52:53]
	s_andn2_b64 vcc, exec, s[0:1]
	s_cbranch_vccnz .LBB0_299
; #define STG_A(b, h, kt) stage_half_s(lds0 + ((b) * 2 + (h)) * HT_B, ((h) ? A1 : Ap) + (kt) * BK, off0, off1)
; #define STG_B(b, h, kt) stage_half_s(lds0 + (4 + (b) * 2 + (h)) * HT_B, ((h) ? B1p : Bp) + (kt) * BK, off0, off1)
; #define STG_A(b, h, kt) stage_half_s(lds0 + ((b) * 2 + (h)) * HT_B, ((h) ? A1 : Ap) + (kt) * BK, off0, off1)
; #define STG_B(b, h, kt) stage_half_s(lds0 + (4 + (b) * 2 + (h)) * HT_B, ((h) ? B1p : Bp) + (kt) * BK, off0, off1)
; __device__ __forceinline__ void gemm8_prefetch(const u16* __restrict__ Ap, const u16* __restrict__ Bp, int K, char* shm, const int tid) {
;   int r0, c0, r1, c1;
;   stage_rc(tid * 16, r0, c0);
;   stage_rc(tid * 16 + 8192, r1, c1);
;   const unsigned off0 = (unsigned)(r0 * K + c0) * 2u, off1 = (unsigned)(r1 * K + c1) * 2u;
;   const int wvoff = __builtin_amdgcn_readfirstlane(tid >> 6) * 1024;
;   const u16* A1 = Ap + (size_t)128 * K;
;   const u16* B1p = Bp + (size_t)128 * K;
;   const unsigned lds0 = (unsigned)(size_t)(__attribute__((address_space(3))) char*)shm + (unsigned)wvoff;
;     ...
;   STG_B(0, 0, 0); STG_A(0, 0, 0); STG_B(0, 1, 0); STG_A(0, 1, 0);
;   STG_B(1, 0, 1); STG_A(1, 0, 1); STG_B(1, 1, 1);
;     ...
; }
; template <int EPI, bool HS = false>
; __device__ __forceinline__ void gemm_phase(const Params& p, const GemmCfg& g, char* shm, const int wave_s) {
;     ...
;   if ((int)blockIdx.x < nwg) {
;     int mt, pn, arow0, orow0;
;     tile_coords(blockIdx.x, mt, pn, arow0, orow0);
;     gemm8_prefetch(g.A + (size_t)arow0 * g.K, g.Bt + (size_t)pn * 256 * g.K, g.K, shm, fresh_tid(wave_s));
;   }
	v_readlane_b32 s4, v252, 26
	v_readlane_b32 s5, v252, 27
	s_mov_b32 s4, s82
	s_mov_b32 s5, -1
	s_mov_b32 s0, s50
	v_mbcnt_lo_u32_b32 v0, s5, 0
	v_mbcnt_hi_u32_b32 v0, s5, v0
	v_lshl_add_u32 v0, s4, 6, v0
	s_ashr_i32 s1, s50, 31
	v_bfe_i32 v4, v0, 27, 1
	v_lshlrev_b32_e32 v2, 4, v0
	v_lshrrev_b32_e32 v4, 22, v4
	v_add_u32_e32 v4, v2, v4
	v_and_b32_e32 v4, 0xfffffc00, v4
	v_ashrrev_i32_e32 v3, 31, v0
	v_sub_u32_e32 v4, v2, v4
	v_lshrrev_b32_e32 v3, 26, v3
	v_lshrrev_b32_e32 v5, 4, v4
	v_add_u32_e32 v3, v0, v3
	v_bitop3_b32 v5, v5, v4, 32 bitop3:0x6c
	v_ashrrev_i32_e32 v4, 31, v4
	v_ashrrev_i32_e32 v3, 6, v3
	v_lshrrev_b32_e32 v4, 26, v4
	v_lshlrev_b32_e32 v6, 3, v3
	v_add_u32_e32 v4, v5, v4
	v_and_b32_e32 v6, 0x1ffff0, v6
	v_ashrrev_i32_e32 v4, 6, v4
	v_add_u32_e32 v6, v4, v6
	v_mul_i32_i24_e32 v4, 64, v4
	v_add_u32_e32 v2, 0x2000, v2
	v_sub_u32_e32 v4, v5, v4
	v_ashrrev_i32_e32 v5, 31, v2
	v_lshrrev_b32_e32 v5, 22, v5
	v_add_u32_e32 v5, v2, v5
	v_ashrrev_i32_e32 v5, 10, v5
	v_mul_i32_i24_e32 v7, 0x400, v5
	s_lshl_b64 s[0:1], s[0:1], 21
	v_readlane_b32 s12, v252, 34
	v_sub_u32_e32 v2, v2, v7
	v_readlane_b32 s13, v252, 35
	s_add_u32 s0, s12, s0
	v_lshrrev_b32_e32 v7, 4, v2
	s_addc_u32 s1, s13, s1
	v_readlane_b32 s2, v254, 1
	v_bitop3_b32 v2, v7, v2, 32 bitop3:0x6c
	v_readlane_b32 s3, v254, 2
	s_add_u32 s2, s0, s2
	v_ashrrev_i32_e32 v8, 31, v2
	v_readlane_b32 s6, v252, 28
	s_addc_u32 s3, s1, s3
	v_lshrrev_b32_e32 v8, 26, v8
	v_add_u32_e32 v8, v2, v8
	v_readfirstlane_b32 s6, v0
	s_add_u32 s4, s2, 0x40000
	v_lshlrev_b32_e32 v3, 5, v3
	v_lshlrev_b32_e32 v7, 3, v5
	v_lshrrev_b32_e32 v9, 6, v8
	v_and_b32_e32 v8, 0xc0, v8
	s_addc_u32 s5, s3, 0
	s_lshl_b32 s6, s6, 4
	v_and_b32_e32 v3, 32, v3
	v_ashrrev_i16_sdwa v4, v178, sext(v4) dst_sel:DWORD dst_unused:UNUSED_PAD src0_sel:DWORD src1_sel:BYTE_0
	v_and_b32_e32 v7, 0x1ffff0, v7
	v_lshlrev_b32_e32 v5, 5, v5
	v_sub_u32_e32 v2, v2, v8
	s_and_b32 s6, s6, 0xfffffc00
	v_readlane_b32 s7, v252, 29
	v_readlane_b32 s8, v252, 30
	v_bfe_i32 v4, v4, 0, 16
	v_add_u32_e32 v7, v9, v7
	v_and_b32_e32 v5, 32, v5
	v_ashrrev_i16_sdwa v2, v178, sext(v2) dst_sel:DWORD dst_unused:UNUSED_PAD src0_sel:DWORD src1_sel:BYTE_0
	v_lshl_or_b32 v3, v6, 10, v3
	s_add_i32 s6, s6, 0
	v_readlane_b32 s10, v252, 32
	v_readlane_b32 s11, v252, 33
	v_bfe_i32 v2, v2, 0, 16
	v_add_lshl_u32 v3, v3, v4, 1
	v_lshl_or_b32 v4, v7, 10, v5
	s_add_i32 s7, s6, 0x10000
	s_mov_b32 m0, s7
	s_nop 0
	global_load_lds_dwordx4 v3, s[2:3]
	v_add_lshl_u32 v2, v4, v2, 1
	s_add_i32 s7, s6, 0x12000
	s_mov_b32 m0, s7
	s_nop 0
	global_load_lds_dwordx4 v2, s[2:3]
	v_readlane_b32 s10, v254, 5
	v_readlane_b32 s11, v254, 6
	s_mov_b32 m0, s6
	s_nop 3
	global_load_lds_dwordx4 v3, s[10:11]
	s_add_i32 s7, s6, 0x2000
	s_mov_b32 m0, s7
	s_nop 0
	global_load_lds_dwordx4 v2, s[10:11]
	s_add_i32 s7, s6, 0x14000
	s_mov_b32 m0, s7
	s_nop 0
	global_load_lds_dwordx4 v3, s[4:5]
	v_readlane_b32 s9, v252, 31
	s_add_i32 s7, s6, 0x16000
	s_mov_b32 m0, s7
	s_nop 0
	global_load_lds_dwordx4 v2, s[4:5]
	s_add_i32 s4, s6, 0x4000
	v_readlane_b32 s8, v254, 3
	v_readlane_b32 s9, v254, 4
	s_mov_b32 m0, s4
	s_nop 3
	global_load_lds_dwordx4 v3, s[8:9]
	s_add_i32 s4, s6, 0x6000
	s_mov_b32 m0, s4
	s_nop 0
	global_load_lds_dwordx4 v2, s[8:9]
	s_add_u32 s4, s2, 0x80
	s_addc_u32 s5, s3, 0
	s_add_i32 s7, s6, 0x18000
	s_mov_b32 m0, s7
	s_nop 0
	global_load_lds_dwordx4 v3, s[4:5]
	s_add_i32 s7, s6, 0x1a000
	s_mov_b32 m0, s7
	s_nop 0
	global_load_lds_dwordx4 v2, s[4:5]
	s_add_i32 s4, s6, 0x8000
	v_readlane_b32 s8, v254, 7
	v_readlane_b32 s9, v254, 8
	s_mov_b32 m0, s4
	s_nop 3
	global_load_lds_dwordx4 v3, s[8:9]
	s_add_i32 s4, s6, 0xa000
	s_mov_b32 m0, s4
	s_nop 0
	global_load_lds_dwordx4 v2, s[8:9]
	s_add_u32 s2, s2, 0x40080
	s_addc_u32 s3, s3, 0
	s_add_i32 s4, s6, 0x1c000
	s_mov_b32 m0, s4
	s_nop 0
	global_load_lds_dwordx4 v3, s[2:3]
	s_add_i32 s6, s6, 0x1e000
	s_mov_b32 m0, s6
	s_nop 0
	global_load_lds_dwordx4 v2, s[2:3]
	v_readlane_b32 s2, v254, 59
	s_mulk_i32 s2, 0xc00
	s_ashr_i32 s3, s2, 31
	s_lshl_b64 s[2:3], s[2:3], 2
	v_readlane_b32 s4, v254, 57
	s_add_u32 s72, s4, s2
	v_readlane_b32 s2, v254, 58
	s_addc_u32 s73, s2, s3
	s_mov_b32 s74, s45
	v_readlane_b32 s14, v252, 36
	v_readlane_b32 s15, v252, 37
	v_readlane_b32 s16, v252, 38
	v_readlane_b32 s17, v252, 39
	v_readlane_b32 s18, v252, 40
	v_readlane_b32 s19, v252, 41
	s_branch .LBB0_84

; #define STG_A(b, h, kt) stage_half_s(lds0 + ((b) * 2 + (h)) * HT_B, ((h) ? A1 : Ap) + (kt) * BK, off0, off1)
; #define STG_B(b, h, kt) stage_half_s(lds0 + (4 + (b) * 2 + (h)) * HT_B, ((h) ? B1p : Bp) + (kt) * BK, off0, off1)
; #define STG_A(b, h, kt) stage_half_s(lds0 + ((b) * 2 + (h)) * HT_B, ((h) ? A1 : Ap) + (kt) * BK, off0, off1)
; #define STG_B(b, h, kt) stage_half_s(lds0 + (4 + (b) * 2 + (h)) * HT_B, ((h) ? B1p : Bp) + (kt) * BK, off0, off1)
; __device__ __forceinline__ void gemm8_prefetch(const u16* __restrict__ Ap, const u16* __restrict__ Bp, int K, char* shm, const int tid) {
;   int r0, c0, r1, c1;
;   stage_rc(tid * 16, r0, c0);
;   stage_rc(tid * 16 + 8192, r1, c1);
;   const unsigned off0 = (unsigned)(r0 * K + c0) * 2u, off1 = (unsigned)(r1 * K + c1) * 2u;
;   const int wvoff = __builtin_amdgcn_readfirstlane(tid >> 6) * 1024;
;   const u16* A1 = Ap + (size_t)128 * K;
;   const u16* B1p = Bp + (size_t)128 * K;
;   const unsigned lds0 = (unsigned)(size_t)(__attribute__((address_space(3))) char*)shm + (unsigned)wvoff;
;     ...
;   STG_B(0, 0, 0); STG_A(0, 0, 0); STG_B(0, 1, 0); STG_A(0, 1, 0);
;   STG_B(1, 0, 1); STG_A(1, 0, 1); STG_B(1, 1, 1);
;     ...
; }
; template <int EPI, bool HS = false>
; __device__ __forceinline__ void gemm_phase(const Params& p, const GemmCfg& g, char* shm, const int wave_s) {
;     ...
;   auto tile_coords = [&](int tile, int& mt, int& pn, int& arow0, int& orow0) {
;     int wgid = tile;
;     { int q = nwg / 8, r = nwg % 8, xcd = wgid % 8, off = wgid / 8;
;       wgid = (xcd < r ? xcd * (q + 1) : r * (q + 1) + (xcd - r) * q) + off; }
;     int nig = 8 * g.nN, gid = wgid / nig, fm = gid * 8, gsz = (g.nM - fm < 8) ? (g.nM - fm) : 8;
;     mt = fm + ((wgid % nig) % gsz); pn = (wgid % nig) / gsz;
;     if (g.rev) mt = g.nM - 1 - mt;
;     int hrow0 = (mt >> 3) * 4096 + g.hf * 2048 + (mt & 7) * 256;
;     arow0 = g.a_half ? hrow0 : mt * 256;
;     orow0 = g.o_half ? hrow0 : mt * 256;
;   };
;     ...
;       if (tile + (int)gridDim.x < nwg) {
;         int mt2, pn2, arow2, orow2;
;         tile_coords(tile + gridDim.x, mt2, pn2, arow2, orow2);
;         gemm8_prefetch(g.A + (size_t)arow2 * g.K, g.Bt + (size_t)pn2 * 256 * g.K, g.K, shm, fresh_tid(wave_s));
;       }
.LBB0_82:
	s_add_i32 s2, s5, s2
	s_ashr_i32 s3, s2, 31
	s_lshr_b32 s3, s3, 27
	s_add_i32 s3, s2, s3
	s_and_b32 s4, s3, 0xffe0
	s_sub_i32 s4, s2, s4
	s_bfe_i32 s2, s4, 0x80000
	s_bfe_u32 s2, s2, 0x3000c
	s_add_i32 s5, s4, s2
	s_bfe_i32 s2, s5, 0x80000
	s_and_b32 s5, s5, 0xf8
	s_sub_i32 s4, s4, s5
	s_sext_i32_i8 s4, s4
	s_lshl_b32 s3, s3, 6
	s_and_b32 s3, s3, 0xfffff800
	s_lshl_b32 s4, s4, 8
	s_add_i32 s4, s4, s3
	s_sext_i32_i16 s2, s2
	s_ashr_i32 s5, s4, 31
	s_lshr_b32 s2, s2, 3
	s_lshl_b64 s[4:5], s[4:5], 11
	v_readlane_b32 s6, v253, 63
	v_readlane_b32 s7, v254, 0
	s_add_u32 s4, s6, s4
	s_addc_u32 s5, s7, s5
	s_mov_b32 s6, s82
	s_mov_b32 s7, -1
	s_bfe_i64 s[2:3], s[2:3], 0x100000
	v_mbcnt_lo_u32_b32 v0, s7, 0
	v_mbcnt_hi_u32_b32 v0, s7, v0
	v_lshl_add_u32 v0, s6, 6, v0
	s_lshl_b64 s[2:3], s[2:3], 19
	v_bfe_i32 v4, v0, 27, 1
	v_lshlrev_b32_e32 v2, 4, v0
	v_lshrrev_b32_e32 v4, 22, v4
	v_add_u32_e32 v4, v2, v4
	v_and_b32_e32 v4, 0xfffffc00, v4
	v_ashrrev_i32_e32 v3, 31, v0
	v_sub_u32_e32 v4, v2, v4
	v_lshrrev_b32_e32 v3, 26, v3
	v_lshrrev_b32_e32 v5, 4, v4
	v_add_u32_e32 v3, v0, v3
	v_bitop3_b32 v5, v5, v4, 32 bitop3:0x6c
	v_ashrrev_i32_e32 v4, 31, v4
	v_ashrrev_i32_e32 v3, 6, v3
	v_lshrrev_b32_e32 v4, 26, v4
	v_lshlrev_b32_e32 v6, 3, v3
	v_add_u32_e32 v4, v5, v4
	v_and_b32_e32 v6, 0x1ffff0, v6
	v_ashrrev_i32_e32 v4, 6, v4
	v_add_u32_e32 v6, v4, v6
	v_mul_i32_i24_e32 v4, 64, v4
	v_add_u32_e32 v2, 0x2000, v2
	v_sub_u32_e32 v4, v5, v4
	v_ashrrev_i32_e32 v5, 31, v2
	v_lshrrev_b32_e32 v5, 22, v5
	v_add_u32_e32 v5, v2, v5
	v_ashrrev_i32_e32 v5, 10, v5
	v_mul_i32_i24_e32 v7, 0x400, v5
	v_sub_u32_e32 v2, v2, v7
	s_add_u32 s2, s0, s2
	v_lshrrev_b32_e32 v7, 4, v2
	s_addc_u32 s3, s1, s3
	v_bitop3_b32 v2, v7, v2, 32 bitop3:0x6c
	v_ashrrev_i32_e32 v8, 31, v2
	s_add_u32 s6, s4, 0x40000
	v_lshrrev_b32_e32 v8, 26, v8
	s_addc_u32 s7, s5, 0
	v_add_u32_e32 v8, v2, v8
	v_readfirstlane_b32 s10, v0
	s_add_u32 s8, s2, 0x40000
	v_lshlrev_b32_e32 v3, 5, v3
	v_lshlrev_b32_e32 v7, 3, v5
	v_lshrrev_b32_e32 v9, 6, v8
	v_and_b32_e32 v8, 0xc0, v8
	s_addc_u32 s9, s3, 0
	s_lshl_b32 s10, s10, 4
	v_and_b32_e32 v3, 32, v3
	v_ashrrev_i16_sdwa v4, v178, sext(v4) dst_sel:DWORD dst_unused:UNUSED_PAD src0_sel:DWORD src1_sel:BYTE_0
	v_and_b32_e32 v7, 0x1ffff0, v7
	v_lshlrev_b32_e32 v5, 5, v5
	v_sub_u32_e32 v2, v2, v8
	s_and_b32 s10, s10, 0xfffffc00
	v_bfe_i32 v4, v4, 0, 16
	v_add_u32_e32 v7, v9, v7
	v_and_b32_e32 v5, 32, v5
	v_ashrrev_i16_sdwa v2, v178, sext(v2) dst_sel:DWORD dst_unused:UNUSED_PAD src0_sel:DWORD src1_sel:BYTE_0
	v_lshl_or_b32 v3, v6, 10, v3
	s_add_i32 s10, s10, 0
	v_bfe_i32 v2, v2, 0, 16
	v_add_lshl_u32 v3, v3, v4, 1
	v_lshl_or_b32 v4, v7, 10, v5
	s_add_i32 s11, s10, 0x10000
	s_mov_b32 m0, s11
	s_nop 0
	global_load_lds_dwordx4 v3, s[2:3]
	v_add_lshl_u32 v2, v4, v2, 1
	s_add_i32 s11, s10, 0x12000
	s_mov_b32 m0, s11
	s_nop 0
	global_load_lds_dwordx4 v2, s[2:3]
	s_mov_b32 m0, s10
	s_nop 0
	global_load_lds_dwordx4 v3, s[4:5]
	s_add_i32 s11, s10, 0x2000
	s_mov_b32 m0, s11
	s_nop 0
	global_load_lds_dwordx4 v2, s[4:5]
	s_add_i32 s11, s10, 0x14000
	s_mov_b32 m0, s11
	s_nop 0
	global_load_lds_dwordx4 v3, s[8:9]
	s_add_i32 s11, s10, 0x16000
	s_mov_b32 m0, s11
	s_nop 0
	global_load_lds_dwordx4 v2, s[8:9]
	s_add_i32 s8, s10, 0x4000
	s_mov_b32 m0, s8
	s_nop 0
	global_load_lds_dwordx4 v3, s[6:7]
	s_add_i32 s8, s10, 0x6000
	s_mov_b32 m0, s8
	s_nop 0
	global_load_lds_dwordx4 v2, s[6:7]
	s_add_u32 s6, s2, 0x80
	s_addc_u32 s7, s3, 0
	s_add_i32 s8, s10, 0x18000
	s_mov_b32 m0, s8
	s_nop 0
	global_load_lds_dwordx4 v3, s[6:7]
	s_add_i32 s8, s10, 0x1a000
	s_add_u32 s4, s4, 0x80
	s_mov_b32 m0, s8
	s_nop 0
	global_load_lds_dwordx4 v2, s[6:7]
	s_addc_u32 s5, s5, 0
	s_add_i32 s6, s10, 0x8000
	s_mov_b32 m0, s6
	s_nop 0
	global_load_lds_dwordx4 v3, s[4:5]
	s_add_i32 s6, s10, 0xa000
	s_mov_b32 m0, s6
	s_nop 0
	global_load_lds_dwordx4 v2, s[4:5]
	s_add_u32 s2, s2, 0x40080
	s_addc_u32 s3, s3, 0
	s_add_i32 s4, s10, 0x1c000
	s_mov_b32 m0, s4
	s_nop 0
	global_load_lds_dwordx4 v3, s[2:3]
	s_add_i32 s10, s10, 0x1e000
	s_mov_b32 m0, s10
	s_nop 0
	global_load_lds_dwordx4 v2, s[2:3]
	s_mov_b64 s[2:3], 0

; #define WAIT_L(n) asm volatile("s_waitcnt lgkmcnt(" #n ")" ::: "memory")
; #define BAR __builtin_amdgcn_s_barrier()
; #define SCHED __builtin_amdgcn_sched_barrier(0)
; #define STG_A(b, h, kt) stage_half_s(lds0 + ((b) * 2 + (h)) * HT_B, ((h) ? A1 : Ap) + (kt) * BK, off0, off1)
; #define STG_B(b, h, kt) stage_half_s(lds0 + (4 + (b) * 2 + (h)) * HT_B, ((h) ? B1p : Bp) + (kt) * BK, off0, off1)
; #define STG_A(b, h, kt) stage_half_s(lds0 + ((b) * 2 + (h)) * HT_B, ((h) ? A1 : Ap) + (kt) * BK, off0, off1)
; #define STG_B(b, h, kt) stage_half_s(lds0 + (4 + (b) * 2 + (h)) * HT_B, ((h) ? B1p : Bp) + (kt) * BK, off0, off1)
; #define LDA8(b, h) _Pragma("unroll") for (int m = 0; m < 4; ++m) _Pragma("unroll") for (int k = 0; k < 2; ++k) \
;     At[m][k] = *(const bf16x8*)(SA_(shm, b, h) + abase + (m * 2 + k) * 1024)
; #define LDB8(dst, b, h) _Pragma("unroll") for (int n = 0; n < 2; ++n) _Pragma("unroll") for (int k = 0; k < 2; ++k) \
;     dst[n][k] = *(const bf16x8*)(SB_(shm, b, h) + bbase + (n * 2 + k) * 1024)
; #define MMA8(ai, bj, Bx) do { __builtin_amdgcn_s_setprio(1); \
;     _Pragma("unroll") for (int m = 0; m < 4; ++m) _Pragma("unroll") for (int n = 0; n < 2; ++n) _Pragma("unroll") for (int k = 0; k < 2; ++k) \
;       acc[ai][bj][m][n] = __builtin_amdgcn_mfma_f32_16x16x32_bf16(At[m][k], Bx[n][k], acc[ai][bj][m][n], 0, 0, 0); \
;     __builtin_amdgcn_s_setprio(0); } while (0)
; template <bool HS>
; __device__ __forceinline__ void gemm_tile8(const u16* __restrict__ Ap, const u16* __restrict__ Bp, int K,
;                                            f32x4 (&acc)[2][2][4][2], char* shm, const int tid, const float* hsr = nullptr) {
;     ...
;     LDB8(B0, 0, 0); SCHED; LDA8(0, 0); STG_A(1, 1, t + 1);
;     WAIT_L(8); BAR; WAIT_L(0); MMA8(0, 0, B0); BAR; SCHED;
;     LDB8(B1, 0, 1); STG_B(0, 0, t + 2);
;     BAR; WAIT_L(0); MMA8(0, 1, B1); BAR;
;     LDA8(0, 1); STG_A(0, 0, t + 2);
;     BAR; WAIT_L(0); MMA8(1, 0, B0); BAR; SCHED;
.LBB0_99:
	s_add_i32 s24, 0, 0x10000
	v_add_u32_e32 v158, s24, v137
	ds_read_b128 v[138:141], v158
	ds_read_b128 v[142:145], v158 offset:1024
	ds_read_b128 v[154:157], v158 offset:2048
	ds_read_b128 v[158:161], v158 offset:3072
	ds_read_b128 v[162:165], v134
	ds_read_b128 v[166:169], v134 offset:1024
	ds_read_b128 v[170:173], v134 offset:2048
	ds_read_b128 v[174:177], v134 offset:3072
	ds_read_b128 v[180:183], v134 offset:4096
	ds_read_b128 v[184:187], v134 offset:5120
	ds_read_b128 v[188:191], v134 offset:6144
	ds_read_b128 v[192:195], v134 offset:7168
	s_add_u32 s20, s17, s2
	s_addc_u32 s21, s18, s3
	s_add_u32 s22, s20, 0x80
	s_addc_u32 s23, s21, 0
	s_add_i32 s20, s14, 0xc000
	s_mov_b32 m0, s20
	s_nop 0
	global_load_lds_dwordx4 v136, s[22:23]
	s_add_i32 s21, s14, 0xe000
	s_mov_b32 m0, s21
	s_nop 0
	global_load_lds_dwordx4 v135, s[22:23]
	s_waitcnt lgkmcnt(8)
	s_barrier
	s_waitcnt lgkmcnt(0)
	s_setprio 1
	s_waitcnt lgkmcnt(7)
	v_mfma_f32_16x16x32_bf16 v[126:129], v[162:165], v[138:141], v[126:129]
	v_mfma_f32_16x16x32_bf16 v[122:125], v[162:165], v[154:157], v[122:125]
	s_waitcnt lgkmcnt(5)
	v_mfma_f32_16x16x32_bf16 v[118:121], v[170:173], v[138:141], v[118:121]
	v_mfma_f32_16x16x32_bf16 v[114:117], v[170:173], v[154:157], v[114:117]
	s_waitcnt lgkmcnt(3)
	v_mfma_f32_16x16x32_bf16 v[110:113], v[180:183], v[138:141], v[110:113]
	v_mfma_f32_16x16x32_bf16 v[106:109], v[180:183], v[154:157], v[106:109]
	s_waitcnt lgkmcnt(1)
	v_mfma_f32_16x16x32_bf16 v[102:105], v[188:191], v[138:141], v[102:105]
	v_mfma_f32_16x16x32_bf16 v[98:101], v[188:191], v[154:157], v[98:101]
	v_mfma_f32_16x16x32_bf16 v[126:129], v[166:169], v[142:145], v[126:129]
	v_mfma_f32_16x16x32_bf16 v[122:125], v[166:169], v[158:161], v[122:125]
	v_mfma_f32_16x16x32_bf16 v[118:121], v[174:177], v[142:145], v[118:121]
	v_mfma_f32_16x16x32_bf16 v[114:117], v[174:177], v[158:161], v[114:117]
	v_mfma_f32_16x16x32_bf16 v[110:113], v[184:187], v[142:145], v[110:113]
	v_mfma_f32_16x16x32_bf16 v[106:109], v[184:187], v[158:161], v[106:109]
	s_waitcnt lgkmcnt(0)
	v_mfma_f32_16x16x32_bf16 v[102:105], v[192:195], v[142:145], v[102:105]
	v_mfma_f32_16x16x32_bf16 v[98:101], v[192:195], v[158:161], v[98:101]
	s_setprio 0
	s_barrier
	s_add_i32 s25, 0, 0x14000
	v_add_u32_e32 v208, s25, v137
	ds_read_b128 v[196:199], v208
	ds_read_b128 v[200:203], v208 offset:1024
	ds_read_b128 v[204:207], v208 offset:2048
	ds_read_b128 v[208:211], v208 offset:3072
	v_lshl_add_u64 v[212:213], v[130:131], 0, s[2:3]
	v_lshl_add_u64 v[214:215], v[212:213], 0, s[78:79]
	s_add_i32 s24, s13, s24
	v_readfirstlane_b32 s23, v215
	v_readfirstlane_b32 s22, v214
	s_mov_b32 m0, s24
	s_nop 3
	global_load_lds_dwordx4 v136, s[22:23]
	s_add_i32 s24, s14, 0x12000
	s_mov_b32 m0, s24
	s_nop 0
	global_load_lds_dwordx4 v135, s[22:23]
	s_barrier
	s_waitcnt lgkmcnt(0)
	s_setprio 1
	s_waitcnt lgkmcnt(3)
	v_mfma_f32_16x16x32_bf16 v[94:97], v[162:165], v[196:199], v[94:97]
	s_waitcnt lgkmcnt(1)
	v_mfma_f32_16x16x32_bf16 v[90:93], v[162:165], v[204:207], v[90:93]
	v_mfma_f32_16x16x32_bf16 v[86:89], v[170:173], v[196:199], v[86:89]
	v_mfma_f32_16x16x32_bf16 v[82:85], v[170:173], v[204:207], v[82:85]
	v_mfma_f32_16x16x32_bf16 v[78:81], v[180:183], v[196:199], v[78:81]
	v_mfma_f32_16x16x32_bf16 v[74:77], v[180:183], v[204:207], v[74:77]
	v_mfma_f32_16x16x32_bf16 v[70:73], v[188:191], v[196:199], v[70:73]
	v_mfma_f32_16x16x32_bf16 v[66:69], v[188:191], v[204:207], v[66:69]
	v_mfma_f32_16x16x32_bf16 v[94:97], v[166:169], v[200:203], v[94:97]
	s_waitcnt lgkmcnt(0)
	v_mfma_f32_16x16x32_bf16 v[90:93], v[166:169], v[208:211], v[90:93]
	v_mfma_f32_16x16x32_bf16 v[86:89], v[174:177], v[200:203], v[86:89]
	v_mfma_f32_16x16x32_bf16 v[82:85], v[174:177], v[208:211], v[82:85]
	v_mfma_f32_16x16x32_bf16 v[78:81], v[184:187], v[200:203], v[78:81]
	v_mfma_f32_16x16x32_bf16 v[74:77], v[184:187], v[208:211], v[74:77]
	v_mfma_f32_16x16x32_bf16 v[70:73], v[192:195], v[200:203], v[70:73]
	v_mfma_f32_16x16x32_bf16 v[66:69], v[192:195], v[208:211], v[66:69]
	s_setprio 0
	s_barrier
	ds_read_b128 v[162:165], v134 offset:16384
	ds_read_b128 v[166:169], v134 offset:17408
	ds_read_b128 v[170:173], v134 offset:18432
	ds_read_b128 v[174:177], v134 offset:19456
	ds_read_b128 v[180:183], v134 offset:20480
	ds_read_b128 v[184:187], v134 offset:21504
	ds_read_b128 v[188:191], v134 offset:22528
	ds_read_b128 v[192:195], v134 offset:23552
	s_add_u32 s24, s9, s2
	s_addc_u32 s26, s12, s3
	s_add_u32 s22, s24, 0x100
	s_addc_u32 s23, s26, 0
	s_mov_b32 m0, s14
	s_nop 0
	global_load_lds_dwordx4 v136, s[22:23]
	s_add_i32 s27, s14, 0x2000
	s_mov_b32 m0, s27
	s_nop 0
	global_load_lds_dwordx4 v135, s[22:23]
	s_barrier
	s_waitcnt lgkmcnt(0)
	s_setprio 1
	s_waitcnt lgkmcnt(7)
	v_mfma_f32_16x16x32_bf16 v[62:65], v[162:165], v[138:141], v[62:65]
	v_mfma_f32_16x16x32_bf16 v[58:61], v[162:165], v[154:157], v[58:61]
	s_waitcnt lgkmcnt(5)
	v_mfma_f32_16x16x32_bf16 v[54:57], v[170:173], v[138:141], v[54:57]
	v_mfma_f32_16x16x32_bf16 v[50:53], v[170:173], v[154:157], v[50:53]
	s_waitcnt lgkmcnt(3)
	v_mfma_f32_16x16x32_bf16 v[46:49], v[180:183], v[138:141], v[46:49]
	v_mfma_f32_16x16x32_bf16 v[42:45], v[180:183], v[154:157], v[42:45]
	s_waitcnt lgkmcnt(1)
	v_mfma_f32_16x16x32_bf16 v[38:41], v[188:191], v[138:141], v[38:41]
	v_mfma_f32_16x16x32_bf16 v[34:37], v[188:191], v[154:157], v[34:37]
	v_mfma_f32_16x16x32_bf16 v[62:65], v[166:169], v[142:145], v[62:65]
	v_mfma_f32_16x16x32_bf16 v[58:61], v[166:169], v[158:161], v[58:61]
	v_mfma_f32_16x16x32_bf16 v[54:57], v[174:177], v[142:145], v[54:57]
	v_mfma_f32_16x16x32_bf16 v[50:53], v[174:177], v[158:161], v[50:53]
	v_mfma_f32_16x16x32_bf16 v[46:49], v[184:187], v[142:145], v[46:49]
	v_mfma_f32_16x16x32_bf16 v[42:45], v[184:187], v[158:161], v[42:45]
	s_waitcnt lgkmcnt(0)
	v_mfma_f32_16x16x32_bf16 v[38:41], v[192:195], v[142:145], v[38:41]
	v_mfma_f32_16x16x32_bf16 v[34:37], v[192:195], v[158:161], v[34:37]
	s_setprio 0
	s_barrier
; #define WAIT_V(n) asm volatile("s_waitcnt vmcnt(" #n ")" ::: "memory")
; #define WAIT_L(n) asm volatile("s_waitcnt lgkmcnt(" #n ")" ::: "memory")
; #define BAR __builtin_amdgcn_s_barrier()
; #define SCHED __builtin_amdgcn_sched_barrier(0)
; #define STG_A(b, h, kt) stage_half_s(lds0 + ((b) * 2 + (h)) * HT_B, ((h) ? A1 : Ap) + (kt) * BK, off0, off1)
; #define STG_B(b, h, kt) stage_half_s(lds0 + (4 + (b) * 2 + (h)) * HT_B, ((h) ? B1p : Bp) + (kt) * BK, off0, off1)
; #define STG_A(b, h, kt) stage_half_s(lds0 + ((b) * 2 + (h)) * HT_B, ((h) ? A1 : Ap) + (kt) * BK, off0, off1)
; #define STG_B(b, h, kt) stage_half_s(lds0 + (4 + (b) * 2 + (h)) * HT_B, ((h) ? B1p : Bp) + (kt) * BK, off0, off1)
; #define LDA8(b, h) _Pragma("unroll") for (int m = 0; m < 4; ++m) _Pragma("unroll") for (int k = 0; k < 2; ++k) \
;     At[m][k] = *(const bf16x8*)(SA_(shm, b, h) + abase + (m * 2 + k) * 1024)
; #define LDB8(dst, b, h) _Pragma("unroll") for (int n = 0; n < 2; ++n) _Pragma("unroll") for (int k = 0; k < 2; ++k) \
;     dst[n][k] = *(const bf16x8*)(SB_(shm, b, h) + bbase + (n * 2 + k) * 1024)
; #define MMA8(ai, bj, Bx) do { __builtin_amdgcn_s_setprio(1); \
;     _Pragma("unroll") for (int m = 0; m < 4; ++m) _Pragma("unroll") for (int n = 0; n < 2; ++n) _Pragma("unroll") for (int k = 0; k < 2; ++k) \
;       acc[ai][bj][m][n] = __builtin_amdgcn_mfma_f32_16x16x32_bf16(At[m][k], Bx[n][k], acc[ai][bj][m][n], 0, 0, 0); \
;     __builtin_amdgcn_s_setprio(0); } while (0)
; template <bool HS>
; __device__ __forceinline__ void gemm_tile8(const u16* __restrict__ Ap, const u16* __restrict__ Bp, int K,
;                                            f32x4 (&acc)[2][2][4][2], char* shm, const int tid, const float* hsr = nullptr) {
;     ...
;     STG_B(0, 1, t + 2);
;     WAIT_V(6); BAR; MMA8(1, 1, B1); BAR;
;     LDB8(B0, 1, 0); SCHED; LDA8(1, 0); STG_A(0, 1, t + 2);
;     WAIT_L(8); BAR; WAIT_L(0); MMA8(0, 0, B0); BAR; SCHED;
;     LDB8(B1, 1, 1); STG_B(1, 0, t + 3);
;     BAR; WAIT_L(0); MMA8(0, 1, B1); BAR;
	v_lshl_add_u64 v[214:215], v[132:133], 0, s[2:3]
	v_lshl_add_u64 v[138:139], v[214:215], 0, s[78:79]
	s_add_i32 s25, s13, s25
	v_readfirstlane_b32 s23, v139
	v_readfirstlane_b32 s22, v138
	s_mov_b32 m0, s25
	s_nop 3
	global_load_lds_dwordx4 v136, s[22:23]
	s_add_i32 s25, s14, 0x16000
	s_mov_b32 m0, s25
	s_nop 0
	global_load_lds_dwordx4 v135, s[22:23]
	s_waitcnt vmcnt(6)
	s_barrier
	s_setprio 1
	v_mfma_f32_16x16x32_bf16 v[30:33], v[162:165], v[196:199], v[30:33]
	v_mfma_f32_16x16x32_bf16 v[26:29], v[162:165], v[204:207], v[26:29]
	v_mfma_f32_16x16x32_bf16 v[22:25], v[170:173], v[196:199], v[22:25]
	v_mfma_f32_16x16x32_bf16 v[18:21], v[170:173], v[204:207], v[18:21]
	v_mfma_f32_16x16x32_bf16 v[14:17], v[180:183], v[196:199], v[14:17]
	v_mfma_f32_16x16x32_bf16 v[10:13], v[180:183], v[204:207], v[10:13]
	v_mfma_f32_16x16x32_bf16 v[6:9], v[188:191], v[196:199], v[6:9]
	v_mfma_f32_16x16x32_bf16 v[2:5], v[188:191], v[204:207], v[2:5]
	v_mfma_f32_16x16x32_bf16 v[30:33], v[166:169], v[200:203], v[30:33]
	v_mfma_f32_16x16x32_bf16 v[26:29], v[166:169], v[208:211], v[26:29]
	v_mfma_f32_16x16x32_bf16 v[22:25], v[174:177], v[200:203], v[22:25]
	v_mfma_f32_16x16x32_bf16 v[18:21], v[174:177], v[208:211], v[18:21]
	v_mfma_f32_16x16x32_bf16 v[14:17], v[184:187], v[200:203], v[14:17]
	v_mfma_f32_16x16x32_bf16 v[10:13], v[184:187], v[208:211], v[10:13]
	v_mfma_f32_16x16x32_bf16 v[6:9], v[192:195], v[200:203], v[6:9]
	v_mfma_f32_16x16x32_bf16 v[2:5], v[192:195], v[208:211], v[2:5]
	s_setprio 0
	s_add_i32 s25, 0, 0x18000
	v_add_u32_e32 v158, s25, v137
	s_barrier
	ds_read_b128 v[138:141], v158
	ds_read_b128 v[142:145], v158 offset:1024
	ds_read_b128 v[154:157], v158 offset:2048
	ds_read_b128 v[158:161], v158 offset:3072
	ds_read_b128 v[162:165], v134 offset:32768
	ds_read_b128 v[166:169], v134 offset:33792
	ds_read_b128 v[170:173], v134 offset:34816
	ds_read_b128 v[174:177], v134 offset:35840
	ds_read_b128 v[180:183], v134 offset:36864
	ds_read_b128 v[184:187], v134 offset:37888
	ds_read_b128 v[188:191], v134 offset:38912
	ds_read_b128 v[192:195], v134 offset:39936
	s_add_u32 s22, s15, s2
	s_addc_u32 s23, s16, s3
	s_add_i32 s27, s14, 0x4000
	s_mov_b32 m0, s27
	s_nop 0
	global_load_lds_dwordx4 v136, s[22:23]
	s_add_i32 s27, s14, 0x6000
	s_mov_b32 m0, s27
	s_nop 0
	global_load_lds_dwordx4 v135, s[22:23]
	s_waitcnt lgkmcnt(8)
	s_barrier
	s_waitcnt lgkmcnt(0)
	s_setprio 1
	s_waitcnt lgkmcnt(7)
	v_mfma_f32_16x16x32_bf16 v[126:129], v[162:165], v[138:141], v[126:129]
	v_mfma_f32_16x16x32_bf16 v[122:125], v[162:165], v[154:157], v[122:125]
	s_waitcnt lgkmcnt(5)
	v_mfma_f32_16x16x32_bf16 v[118:121], v[170:173], v[138:141], v[118:121]
	v_mfma_f32_16x16x32_bf16 v[114:117], v[170:173], v[154:157], v[114:117]
	s_waitcnt lgkmcnt(3)
	v_mfma_f32_16x16x32_bf16 v[110:113], v[180:183], v[138:141], v[110:113]
	v_mfma_f32_16x16x32_bf16 v[106:109], v[180:183], v[154:157], v[106:109]
	s_waitcnt lgkmcnt(1)
	v_mfma_f32_16x16x32_bf16 v[102:105], v[188:191], v[138:141], v[102:105]
	v_mfma_f32_16x16x32_bf16 v[98:101], v[188:191], v[154:157], v[98:101]
	v_mfma_f32_16x16x32_bf16 v[126:129], v[166:169], v[142:145], v[126:129]
	v_mfma_f32_16x16x32_bf16 v[122:125], v[166:169], v[158:161], v[122:125]
	v_mfma_f32_16x16x32_bf16 v[118:121], v[174:177], v[142:145], v[118:121]
	v_mfma_f32_16x16x32_bf16 v[114:117], v[174:177], v[158:161], v[114:117]
	v_mfma_f32_16x16x32_bf16 v[110:113], v[184:187], v[142:145], v[110:113]
	v_mfma_f32_16x16x32_bf16 v[106:109], v[184:187], v[158:161], v[106:109]
	s_waitcnt lgkmcnt(0)
	v_mfma_f32_16x16x32_bf16 v[102:105], v[192:195], v[142:145], v[102:105]
	v_mfma_f32_16x16x32_bf16 v[98:101], v[192:195], v[158:161], v[98:101]
	s_setprio 0
	s_barrier
	s_add_i32 s27, 0, 0x1c000
	v_add_u32_e32 v208, s27, v137
	ds_read_b128 v[196:199], v208
	ds_read_b128 v[200:203], v208 offset:1024
	ds_read_b128 v[204:207], v208 offset:2048
	ds_read_b128 v[208:211], v208 offset:3072
	v_lshl_add_u64 v[212:213], v[212:213], 0, s[86:87]
	s_add_i32 s25, s13, s25
	v_readfirstlane_b32 s23, v213
	v_readfirstlane_b32 s22, v212
	s_mov_b32 m0, s25
	s_nop 3
	global_load_lds_dwordx4 v136, s[22:23]
	s_add_i32 s25, s14, 0x1a000
	s_mov_b32 m0, s25
	s_nop 0
	global_load_lds_dwordx4 v135, s[22:23]
	s_barrier
	s_waitcnt lgkmcnt(0)
	s_setprio 1
	s_waitcnt lgkmcnt(3)
	v_mfma_f32_16x16x32_bf16 v[94:97], v[162:165], v[196:199], v[94:97]
	s_waitcnt lgkmcnt(1)
	v_mfma_f32_16x16x32_bf16 v[90:93], v[162:165], v[204:207], v[90:93]
	v_mfma_f32_16x16x32_bf16 v[86:89], v[170:173], v[196:199], v[86:89]
	v_mfma_f32_16x16x32_bf16 v[82:85], v[170:173], v[204:207], v[82:85]
	v_mfma_f32_16x16x32_bf16 v[78:81], v[180:183], v[196:199], v[78:81]
	v_mfma_f32_16x16x32_bf16 v[74:77], v[180:183], v[204:207], v[74:77]
	v_mfma_f32_16x16x32_bf16 v[70:73], v[188:191], v[196:199], v[70:73]
	v_mfma_f32_16x16x32_bf16 v[66:69], v[188:191], v[204:207], v[66:69]
	v_mfma_f32_16x16x32_bf16 v[94:97], v[166:169], v[200:203], v[94:97]
	s_waitcnt lgkmcnt(0)
	v_mfma_f32_16x16x32_bf16 v[90:93], v[166:169], v[208:211], v[90:93]
	v_mfma_f32_16x16x32_bf16 v[86:89], v[174:177], v[200:203], v[86:89]
	v_mfma_f32_16x16x32_bf16 v[82:85], v[174:177], v[208:211], v[82:85]
	v_mfma_f32_16x16x32_bf16 v[78:81], v[184:187], v[200:203], v[78:81]
	v_mfma_f32_16x16x32_bf16 v[74:77], v[184:187], v[208:211], v[74:77]
	v_mfma_f32_16x16x32_bf16 v[70:73], v[192:195], v[200:203], v[70:73]
	v_mfma_f32_16x16x32_bf16 v[66:69], v[192:195], v[208:211], v[66:69]
	s_setprio 0
	s_barrier
; #define WAIT_V(n) asm volatile("s_waitcnt vmcnt(" #n ")" ::: "memory")
; #define WAIT_L(n) asm volatile("s_waitcnt lgkmcnt(" #n ")" ::: "memory")
; #define BAR __builtin_amdgcn_s_barrier()
; #define SCHED __builtin_amdgcn_sched_barrier(0)
; #define STG_A(b, h, kt) stage_half_s(lds0 + ((b) * 2 + (h)) * HT_B, ((h) ? A1 : Ap) + (kt) * BK, off0, off1)
; #define STG_B(b, h, kt) stage_half_s(lds0 + (4 + (b) * 2 + (h)) * HT_B, ((h) ? B1p : Bp) + (kt) * BK, off0, off1)
; #define STG_A(b, h, kt) stage_half_s(lds0 + ((b) * 2 + (h)) * HT_B, ((h) ? A1 : Ap) + (kt) * BK, off0, off1)
; #define STG_B(b, h, kt) stage_half_s(lds0 + (4 + (b) * 2 + (h)) * HT_B, ((h) ? B1p : Bp) + (kt) * BK, off0, off1)
; #define LDA8(b, h) _Pragma("unroll") for (int m = 0; m < 4; ++m) _Pragma("unroll") for (int k = 0; k < 2; ++k) \
;     At[m][k] = *(const bf16x8*)(SA_(shm, b, h) + abase + (m * 2 + k) * 1024)
; #define LDB8(dst, b, h) _Pragma("unroll") for (int n = 0; n < 2; ++n) _Pragma("unroll") for (int k = 0; k < 2; ++k) \
;     dst[n][k] = *(const bf16x8*)(SB_(shm, b, h) + bbase + (n * 2 + k) * 1024)
; #define MMA8(ai, bj, Bx) do { __builtin_amdgcn_s_setprio(1); \
;     _Pragma("unroll") for (int m = 0; m < 4; ++m) _Pragma("unroll") for (int n = 0; n < 2; ++n) _Pragma("unroll") for (int k = 0; k < 2; ++k) \
;       acc[ai][bj][m][n] = __builtin_amdgcn_mfma_f32_16x16x32_bf16(At[m][k], Bx[n][k], acc[ai][bj][m][n], 0, 0, 0); \
;     __builtin_amdgcn_s_setprio(0); } while (0)
; template <bool HS>
; __device__ __forceinline__ void gemm_tile8(const u16* __restrict__ Ap, const u16* __restrict__ Bp, int K,
;                                            f32x4 (&acc)[2][2][4][2], char* shm, const int tid, const float* hsr = nullptr) {
;     ...
;     LDA8(1, 1); STG_A(1, 0, t + 3);
;     BAR; WAIT_L(0); MMA8(1, 0, B0); BAR; SCHED;
;     STG_B(1, 1, t + 3);
;     WAIT_V(6); BAR; MMA8(1, 1, B1); BAR;
;   }
;   { LDB8(B0, 0, 0); LDA8(0, 0); STG_A(1, 1, nt - 1);
;     BAR; WAIT_L(0); MMA8(0, 0, B0); BAR;
	ds_read_b128 v[162:165], v134 offset:49152
	ds_read_b128 v[166:169], v134 offset:50176
	ds_read_b128 v[170:173], v134 offset:51200
	ds_read_b128 v[174:177], v134 offset:52224
	ds_read_b128 v[180:183], v134 offset:53248
	ds_read_b128 v[184:187], v134 offset:54272
	ds_read_b128 v[188:191], v134 offset:55296
	ds_read_b128 v[192:195], v134 offset:56320
	s_add_u32 s22, s24, 0x180
	s_addc_u32 s23, s26, 0
	s_add_i32 s24, s14, 0x8000
	s_mov_b32 m0, s24
	s_nop 0
	global_load_lds_dwordx4 v136, s[22:23]
	s_add_i32 s24, s14, 0xa000
	s_mov_b32 m0, s24
	s_nop 0
	global_load_lds_dwordx4 v135, s[22:23]
	s_barrier
	s_waitcnt lgkmcnt(0)
	s_setprio 1
	s_waitcnt lgkmcnt(7)
	v_mfma_f32_16x16x32_bf16 v[62:65], v[162:165], v[138:141], v[62:65]
	v_mfma_f32_16x16x32_bf16 v[58:61], v[162:165], v[154:157], v[58:61]
	s_waitcnt lgkmcnt(5)
	v_mfma_f32_16x16x32_bf16 v[54:57], v[170:173], v[138:141], v[54:57]
	v_mfma_f32_16x16x32_bf16 v[50:53], v[170:173], v[154:157], v[50:53]
	s_waitcnt lgkmcnt(3)
	v_mfma_f32_16x16x32_bf16 v[46:49], v[180:183], v[138:141], v[46:49]
	v_mfma_f32_16x16x32_bf16 v[42:45], v[180:183], v[154:157], v[42:45]
	s_waitcnt lgkmcnt(1)
	v_mfma_f32_16x16x32_bf16 v[38:41], v[188:191], v[138:141], v[38:41]
	v_mfma_f32_16x16x32_bf16 v[34:37], v[188:191], v[154:157], v[34:37]
	v_mfma_f32_16x16x32_bf16 v[62:65], v[166:169], v[142:145], v[62:65]
	v_mfma_f32_16x16x32_bf16 v[58:61], v[166:169], v[158:161], v[58:61]
	v_mfma_f32_16x16x32_bf16 v[54:57], v[174:177], v[142:145], v[54:57]
	v_mfma_f32_16x16x32_bf16 v[50:53], v[174:177], v[158:161], v[50:53]
	v_mfma_f32_16x16x32_bf16 v[46:49], v[184:187], v[142:145], v[46:49]
	v_mfma_f32_16x16x32_bf16 v[42:45], v[184:187], v[158:161], v[42:45]
	s_waitcnt lgkmcnt(0)
	v_mfma_f32_16x16x32_bf16 v[38:41], v[192:195], v[142:145], v[38:41]
	v_mfma_f32_16x16x32_bf16 v[34:37], v[192:195], v[158:161], v[34:37]
	s_setprio 0
	s_barrier
	v_lshl_add_u64 v[138:139], v[214:215], 0, s[86:87]
	s_add_i32 s24, s13, s27
	v_readfirstlane_b32 s23, v139
	v_readfirstlane_b32 s22, v138
	s_mov_b32 m0, s24
	s_nop 3
	global_load_lds_dwordx4 v136, s[22:23]
	s_add_i32 s24, s14, 0x1e000
	s_mov_b32 m0, s24
	s_nop 0
	global_load_lds_dwordx4 v135, s[22:23]
	s_waitcnt vmcnt(6)
	s_barrier
	s_setprio 1
	v_mfma_f32_16x16x32_bf16 v[30:33], v[162:165], v[196:199], v[30:33]
	v_mfma_f32_16x16x32_bf16 v[26:29], v[162:165], v[204:207], v[26:29]
	v_mfma_f32_16x16x32_bf16 v[22:25], v[170:173], v[196:199], v[22:25]
	v_mfma_f32_16x16x32_bf16 v[18:21], v[170:173], v[204:207], v[18:21]
	v_mfma_f32_16x16x32_bf16 v[14:17], v[180:183], v[196:199], v[14:17]
	v_mfma_f32_16x16x32_bf16 v[10:13], v[180:183], v[204:207], v[10:13]
	v_mfma_f32_16x16x32_bf16 v[6:9], v[188:191], v[196:199], v[6:9]
	v_mfma_f32_16x16x32_bf16 v[2:5], v[188:191], v[204:207], v[2:5]
	v_mfma_f32_16x16x32_bf16 v[30:33], v[166:169], v[200:203], v[30:33]
	v_mfma_f32_16x16x32_bf16 v[26:29], v[166:169], v[208:211], v[26:29]
	v_mfma_f32_16x16x32_bf16 v[22:25], v[174:177], v[200:203], v[22:25]
	v_mfma_f32_16x16x32_bf16 v[18:21], v[174:177], v[208:211], v[18:21]
	v_mfma_f32_16x16x32_bf16 v[14:17], v[184:187], v[200:203], v[14:17]
	v_mfma_f32_16x16x32_bf16 v[10:13], v[184:187], v[208:211], v[10:13]
	v_mfma_f32_16x16x32_bf16 v[6:9], v[192:195], v[200:203], v[6:9]
	v_mfma_f32_16x16x32_bf16 v[2:5], v[192:195], v[208:211], v[2:5]
	s_setprio 0
	s_add_i32 s19, s19, 2
	s_add_u32 s2, s2, 0x100
	s_addc_u32 s3, s3, 0
	s_cmp_lt_u32 s19, 12
	s_barrier
	s_cbranch_scc1 .LBB0_99
	v_add_u32_e32 v220, 0, v137
	v_add_u32_e32 v137, 0x10000, v220
	ds_read_b128 v[130:133], v137
	ds_read_b128 v[138:141], v137 offset:1024
	ds_read_b128 v[142:145], v137 offset:2048
	ds_read_b128 v[154:157], v137 offset:3072
	ds_read_b128 v[158:161], v134
	ds_read_b128 v[162:165], v134 offset:1024
	ds_read_b128 v[166:169], v134 offset:2048
	ds_read_b128 v[170:173], v134 offset:3072
	ds_read_b128 v[174:177], v134 offset:4096
	ds_read_b128 v[180:183], v134 offset:5120
	ds_read_b128 v[184:187], v134 offset:6144
	ds_read_b128 v[188:191], v134 offset:7168
	s_add_u32 s2, s9, 0x40780
	s_addc_u32 s3, s12, 0
	s_mov_b32 m0, s20
	s_nop 0
	global_load_lds_dwordx4 v136, s[2:3]
	s_nop 0
	s_mov_b32 m0, s21
	s_nop 0
	global_load_lds_dwordx4 v135, s[2:3]
	s_barrier
	s_waitcnt lgkmcnt(0)
	s_setprio 1
	s_waitcnt lgkmcnt(7)
	v_mfma_f32_16x16x32_bf16 v[126:129], v[158:161], v[130:133], v[126:129]
	s_waitcnt lgkmcnt(5)
	v_mfma_f32_16x16x32_bf16 v[118:121], v[166:169], v[130:133], v[118:121]
	v_mfma_f32_16x16x32_bf16 v[114:117], v[166:169], v[142:145], v[114:117]
	s_waitcnt lgkmcnt(1)
	v_mfma_f32_16x16x32_bf16 v[102:105], v[184:187], v[130:133], v[102:105]
	v_mfma_f32_16x16x32_bf16 v[98:101], v[184:187], v[142:145], v[98:101]
	v_mfma_f32_16x16x32_bf16 v[126:129], v[162:165], v[138:141], v[126:129]
	v_mfma_f32_16x16x32_bf16 v[122:125], v[158:161], v[142:145], v[122:125]
	v_mfma_f32_16x16x32_bf16 v[118:121], v[170:173], v[138:141], v[118:121]
	v_mfma_f32_16x16x32_bf16 v[114:117], v[170:173], v[154:157], v[114:117]
	v_mfma_f32_16x16x32_bf16 v[110:113], v[174:177], v[130:133], v[110:113]
	v_mfma_f32_16x16x32_bf16 v[106:109], v[174:177], v[142:145], v[106:109]
	s_waitcnt lgkmcnt(0)
	v_mfma_f32_16x16x32_bf16 v[102:105], v[188:191], v[138:141], v[102:105]
	v_mfma_f32_16x16x32_bf16 v[98:101], v[188:191], v[154:157], v[98:101]
	v_mfma_f32_16x16x32_bf16 v[192:195], v[162:165], v[154:157], v[122:125]
	v_mfma_f32_16x16x32_bf16 v[196:199], v[180:183], v[138:141], v[110:113]
	v_mfma_f32_16x16x32_bf16 v[200:203], v[180:183], v[154:157], v[106:109]
	s_setprio 0
	v_add_u32_e32 v135, 0x14000, v220
	s_barrier
; #define WAIT_V(n) asm volatile("s_waitcnt vmcnt(" #n ")" ::: "memory")
; #define WAIT_L(n) asm volatile("s_waitcnt lgkmcnt(" #n ")" ::: "memory")
; #define BAR __builtin_amdgcn_s_barrier()
; #define LDA8(b, h) _Pragma("unroll") for (int m = 0; m < 4; ++m) _Pragma("unroll") for (int k = 0; k < 2; ++k) \
;     At[m][k] = *(const bf16x8*)(SA_(shm, b, h) + abase + (m * 2 + k) * 1024)
; #define LDB8(dst, b, h) _Pragma("unroll") for (int n = 0; n < 2; ++n) _Pragma("unroll") for (int k = 0; k < 2; ++k) \
;     dst[n][k] = *(const bf16x8*)(SB_(shm, b, h) + bbase + (n * 2 + k) * 1024)
; #define MMA8(ai, bj, Bx) do { __builtin_amdgcn_s_setprio(1); \
;     _Pragma("unroll") for (int m = 0; m < 4; ++m) _Pragma("unroll") for (int n = 0; n < 2; ++n) _Pragma("unroll") for (int k = 0; k < 2; ++k) \
;       acc[ai][bj][m][n] = __builtin_amdgcn_mfma_f32_16x16x32_bf16(At[m][k], Bx[n][k], acc[ai][bj][m][n], 0, 0, 0); \
;     __builtin_amdgcn_s_setprio(0); } while (0)
; template <bool HS>
; __device__ __forceinline__ void gemm_tile8(const u16* __restrict__ Ap, const u16* __restrict__ Bp, int K,
;                                            f32x4 (&acc)[2][2][4][2], char* shm, const int tid, const float* hsr = nullptr) {
;     ...
;     LDB8(B1, 0, 1); BAR; WAIT_L(0); MMA8(0, 1, B1); BAR;
;     LDA8(0, 1); WAIT_V(4); BAR; WAIT_L(0); MMA8(1, 0, B0); MMA8(1, 1, B1); BAR; }
;   { LDB8(B0, 1, 0); LDA8(1, 0); WAIT_V(2); BAR; WAIT_L(0); MMA8(0, 0, B0); BAR;
	ds_read_b128 v[106:109], v135
	ds_read_b128 v[110:113], v135 offset:1024
	ds_read_b128 v[122:125], v135 offset:2048
	ds_read_b128 v[204:207], v135 offset:3072
	s_barrier
	s_waitcnt lgkmcnt(0)
	s_setprio 1
	s_waitcnt lgkmcnt(3)
	v_mfma_f32_16x16x32_bf16 v[86:89], v[166:169], v[106:109], v[86:89]
	s_waitcnt lgkmcnt(1)
	v_mfma_f32_16x16x32_bf16 v[82:85], v[166:169], v[122:125], v[82:85]
	v_mfma_f32_16x16x32_bf16 v[70:73], v[184:187], v[106:109], v[70:73]
	v_mfma_f32_16x16x32_bf16 v[94:97], v[158:161], v[106:109], v[94:97]
	v_mfma_f32_16x16x32_bf16 v[90:93], v[158:161], v[122:125], v[90:93]
	v_mfma_f32_16x16x32_bf16 v[86:89], v[170:173], v[110:113], v[86:89]
	s_waitcnt lgkmcnt(0)
	v_mfma_f32_16x16x32_bf16 v[82:85], v[170:173], v[204:207], v[82:85]
	v_mfma_f32_16x16x32_bf16 v[78:81], v[174:177], v[106:109], v[78:81]
	v_mfma_f32_16x16x32_bf16 v[74:77], v[174:177], v[122:125], v[74:77]
	v_mfma_f32_16x16x32_bf16 v[70:73], v[188:191], v[110:113], v[70:73]
	v_mfma_f32_16x16x32_bf16 v[66:69], v[184:187], v[122:125], v[66:69]
	v_mfma_f32_16x16x32_bf16 v[208:211], v[162:165], v[110:113], v[94:97]
	v_mfma_f32_16x16x32_bf16 v[158:161], v[162:165], v[204:207], v[90:93]
	v_mfma_f32_16x16x32_bf16 v[162:165], v[180:183], v[110:113], v[78:81]
	v_mfma_f32_16x16x32_bf16 v[166:169], v[180:183], v[204:207], v[74:77]
	v_mfma_f32_16x16x32_bf16 v[170:173], v[188:191], v[204:207], v[66:69]
	s_setprio 0
	s_barrier
	s_nop 0
	ds_read_b128 v[66:69], v134 offset:16384
	ds_read_b128 v[74:77], v134 offset:17408
	ds_read_b128 v[78:81], v134 offset:18432
	ds_read_b128 v[90:93], v134 offset:19456
	ds_read_b128 v[94:97], v134 offset:20480
	ds_read_b128 v[174:177], v134 offset:21504
	ds_read_b128 v[180:183], v134 offset:22528
	ds_read_b128 v[184:187], v134 offset:23552
	s_waitcnt vmcnt(4)
	s_barrier
	s_waitcnt lgkmcnt(0)
	s_setprio 1
	s_waitcnt lgkmcnt(7)
	v_mfma_f32_16x16x32_bf16 v[62:65], v[66:69], v[130:133], v[62:65]
	s_waitcnt lgkmcnt(5)
	v_mfma_f32_16x16x32_bf16 v[54:57], v[78:81], v[130:133], v[54:57]
	v_mfma_f32_16x16x32_bf16 v[50:53], v[78:81], v[142:145], v[50:53]
	s_waitcnt lgkmcnt(1)
	v_mfma_f32_16x16x32_bf16 v[38:41], v[180:183], v[130:133], v[38:41]
	v_mfma_f32_16x16x32_bf16 v[34:37], v[180:183], v[142:145], v[34:37]
	v_mfma_f32_16x16x32_bf16 v[62:65], v[74:77], v[138:141], v[62:65]
	v_mfma_f32_16x16x32_bf16 v[58:61], v[66:69], v[142:145], v[58:61]
	v_mfma_f32_16x16x32_bf16 v[54:57], v[90:93], v[138:141], v[54:57]
	v_mfma_f32_16x16x32_bf16 v[50:53], v[90:93], v[154:157], v[50:53]
	v_mfma_f32_16x16x32_bf16 v[46:49], v[94:97], v[130:133], v[46:49]
	v_mfma_f32_16x16x32_bf16 v[42:45], v[94:97], v[142:145], v[42:45]
	s_waitcnt lgkmcnt(0)
	v_mfma_f32_16x16x32_bf16 v[38:41], v[184:187], v[138:141], v[38:41]
	v_mfma_f32_16x16x32_bf16 v[34:37], v[184:187], v[154:157], v[34:37]
	v_mfma_f32_16x16x32_bf16 v[188:191], v[74:77], v[154:157], v[58:61]
	v_mfma_f32_16x16x32_bf16 v[212:215], v[174:177], v[138:141], v[46:49]
	v_mfma_f32_16x16x32_bf16 v[216:219], v[174:177], v[154:157], v[42:45]
	s_setprio 0
	s_setprio 1
	v_mfma_f32_16x16x32_bf16 v[22:25], v[78:81], v[106:109], v[22:25]
	v_mfma_f32_16x16x32_bf16 v[18:21], v[78:81], v[122:125], v[18:21]
	v_mfma_f32_16x16x32_bf16 v[6:9], v[180:183], v[106:109], v[6:9]
	v_mfma_f32_16x16x32_bf16 v[30:33], v[66:69], v[106:109], v[30:33]
	v_mfma_f32_16x16x32_bf16 v[26:29], v[66:69], v[122:125], v[26:29]
	v_mfma_f32_16x16x32_bf16 v[22:25], v[90:93], v[110:113], v[22:25]
	v_mfma_f32_16x16x32_bf16 v[18:21], v[90:93], v[204:207], v[18:21]
	v_mfma_f32_16x16x32_bf16 v[14:17], v[94:97], v[106:109], v[14:17]
	v_mfma_f32_16x16x32_bf16 v[10:13], v[94:97], v[122:125], v[10:13]
	v_mfma_f32_16x16x32_bf16 v[6:9], v[184:187], v[110:113], v[6:9]
	v_mfma_f32_16x16x32_bf16 v[2:5], v[180:183], v[122:125], v[2:5]
	v_mfma_f32_16x16x32_bf16 v[130:133], v[74:77], v[110:113], v[30:33]
	v_mfma_f32_16x16x32_bf16 v[136:139], v[74:77], v[204:207], v[26:29]
	v_mfma_f32_16x16x32_bf16 v[140:143], v[174:177], v[110:113], v[14:17]
	v_mfma_f32_16x16x32_bf16 v[154:157], v[174:177], v[204:207], v[10:13]
	v_mfma_f32_16x16x32_bf16 v[174:177], v[184:187], v[204:207], v[2:5]
	s_setprio 0
	v_add_u32_e32 v26, 0x18000, v220
	s_barrier
	ds_read_b128 v[2:5], v26
	ds_read_b128 v[10:13], v26 offset:1024
	ds_read_b128 v[14:17], v26 offset:2048
	ds_read_b128 v[180:183], v26 offset:3072
	ds_read_b128 v[26:29], v134 offset:32768
	ds_read_b128 v[30:33], v134 offset:33792
	ds_read_b128 v[42:45], v134 offset:34816
	ds_read_b128 v[46:49], v134 offset:35840
	ds_read_b128 v[58:61], v134 offset:36864
	ds_read_b128 v[66:69], v134 offset:37888
	ds_read_b128 v[184:187], v134 offset:38912
	ds_read_b128 v[204:207], v134 offset:39936
	s_waitcnt vmcnt(2)
	s_barrier
	s_waitcnt lgkmcnt(0)
	s_setprio 1
	s_waitcnt lgkmcnt(7)
	v_mfma_f32_16x16x32_bf16 v[74:77], v[26:29], v[2:5], v[126:129]
	s_waitcnt lgkmcnt(6)
	v_mfma_f32_16x16x32_bf16 v[122:125], v[30:33], v[10:13], v[74:77]
	v_mfma_f32_16x16x32_bf16 v[74:77], v[26:29], v[14:17], v[192:195]
	v_mfma_f32_16x16x32_bf16 v[126:129], v[30:33], v[180:183], v[74:77]
	s_waitcnt lgkmcnt(5)
	v_mfma_f32_16x16x32_bf16 v[74:77], v[42:45], v[2:5], v[118:121]
	s_waitcnt lgkmcnt(4)
	v_mfma_f32_16x16x32_bf16 v[106:109], v[46:49], v[10:13], v[74:77]
	v_mfma_f32_16x16x32_bf16 v[74:77], v[42:45], v[14:17], v[114:117]
	v_mfma_f32_16x16x32_bf16 v[110:113], v[46:49], v[180:183], v[74:77]
	s_waitcnt lgkmcnt(3)
	v_mfma_f32_16x16x32_bf16 v[74:77], v[58:61], v[2:5], v[196:199]
	s_waitcnt lgkmcnt(2)
	v_mfma_f32_16x16x32_bf16 v[90:93], v[66:69], v[10:13], v[74:77]
	v_mfma_f32_16x16x32_bf16 v[74:77], v[58:61], v[14:17], v[200:203]
	v_mfma_f32_16x16x32_bf16 v[94:97], v[66:69], v[180:183], v[74:77]
	s_waitcnt lgkmcnt(1)
	v_mfma_f32_16x16x32_bf16 v[74:77], v[184:187], v[2:5], v[102:105]
	v_mfma_f32_16x16x32_bf16 v[78:81], v[184:187], v[14:17], v[98:101]
	s_waitcnt lgkmcnt(0)
	v_mfma_f32_16x16x32_bf16 v[74:77], v[204:207], v[10:13], v[74:77]
	v_mfma_f32_16x16x32_bf16 v[78:81], v[204:207], v[180:183], v[78:81]
	s_setprio 0
	v_add_u32_e32 v98, 0x1c000, v220
	s_barrier
; #define WAIT_V(n) asm volatile("s_waitcnt vmcnt(" #n ")" ::: "memory")
; #define WAIT_L(n) asm volatile("s_waitcnt lgkmcnt(" #n ")" ::: "memory")
; #define BAR __builtin_amdgcn_s_barrier()
; #define LDA8(b, h) _Pragma("unroll") for (int m = 0; m < 4; ++m) _Pragma("unroll") for (int k = 0; k < 2; ++k) \
;     At[m][k] = *(const bf16x8*)(SA_(shm, b, h) + abase + (m * 2 + k) * 1024)
; #define LDB8(dst, b, h) _Pragma("unroll") for (int n = 0; n < 2; ++n) _Pragma("unroll") for (int k = 0; k < 2; ++k) \
;     dst[n][k] = *(const bf16x8*)(SB_(shm, b, h) + bbase + (n * 2 + k) * 1024)
; #define MMA8(ai, bj, Bx) do { __builtin_amdgcn_s_setprio(1); \
;     _Pragma("unroll") for (int m = 0; m < 4; ++m) _Pragma("unroll") for (int n = 0; n < 2; ++n) _Pragma("unroll") for (int k = 0; k < 2; ++k) \
;       acc[ai][bj][m][n] = __builtin_amdgcn_mfma_f32_16x16x32_bf16(At[m][k], Bx[n][k], acc[ai][bj][m][n], 0, 0, 0); \
;     __builtin_amdgcn_s_setprio(0); } while (0)
; template <bool HS>
; __device__ __forceinline__ void gemm_tile8(const u16* __restrict__ Ap, const u16* __restrict__ Bp, int K,
;                                            f32x4 (&acc)[2][2][4][2], char* shm, const int tid, const float* hsr = nullptr) {
;     ...
;     LDB8(B1, 1, 1); WAIT_V(0); BAR; WAIT_L(0); MMA8(0, 1, B1); BAR;
;     LDA8(1, 1); BAR; WAIT_L(0); MMA8(1, 0, B0); MMA8(1, 1, B1); BAR; }
;   if (wr == 0) BAR;
	ds_read_b128 v[192:195], v98
	ds_read_b128 v[196:199], v98 offset:1024
	ds_read_b128 v[200:203], v98 offset:2048
	ds_read_b128 v[220:223], v98 offset:3072
	s_waitcnt vmcnt(0)
	s_barrier
	s_waitcnt lgkmcnt(0)
	s_setprio 1
	s_waitcnt lgkmcnt(3)
	v_mfma_f32_16x16x32_bf16 v[98:101], v[26:29], v[192:195], v[208:211]
	s_waitcnt lgkmcnt(1)
	v_mfma_f32_16x16x32_bf16 v[26:29], v[26:29], v[200:203], v[158:161]
	s_waitcnt lgkmcnt(0)
	v_mfma_f32_16x16x32_bf16 v[118:121], v[30:33], v[220:223], v[26:29]
	v_mfma_f32_16x16x32_bf16 v[26:29], v[42:45], v[192:195], v[86:89]
	v_mfma_f32_16x16x32_bf16 v[114:117], v[30:33], v[196:199], v[98:101]
	v_mfma_f32_16x16x32_bf16 v[98:101], v[46:49], v[196:199], v[26:29]
	v_mfma_f32_16x16x32_bf16 v[26:29], v[42:45], v[200:203], v[82:85]
	v_mfma_f32_16x16x32_bf16 v[102:105], v[46:49], v[220:223], v[26:29]
	v_mfma_f32_16x16x32_bf16 v[26:29], v[58:61], v[192:195], v[162:165]
	v_mfma_f32_16x16x32_bf16 v[82:85], v[66:69], v[196:199], v[26:29]
	v_mfma_f32_16x16x32_bf16 v[26:29], v[58:61], v[200:203], v[166:169]
	v_mfma_f32_16x16x32_bf16 v[86:89], v[66:69], v[220:223], v[26:29]
	v_mfma_f32_16x16x32_bf16 v[26:29], v[184:187], v[192:195], v[70:73]
	v_mfma_f32_16x16x32_bf16 v[66:69], v[204:207], v[196:199], v[26:29]
	v_mfma_f32_16x16x32_bf16 v[26:29], v[184:187], v[200:203], v[170:173]
	v_mfma_f32_16x16x32_bf16 v[70:73], v[204:207], v[220:223], v[26:29]
	s_setprio 0
	s_barrier
	ds_read_b128 v[158:161], v134 offset:49152
	ds_read_b128 v[162:165], v134 offset:50176
	ds_read_b128 v[166:169], v134 offset:51200
	ds_read_b128 v[170:173], v134 offset:52224
	ds_read_b128 v[184:187], v134 offset:53248
	ds_read_b128 v[204:207], v134 offset:54272
	ds_read_b128 v[208:211], v134 offset:55296
	ds_read_b128 v[224:227], v134 offset:56320
	s_barrier
	s_waitcnt lgkmcnt(0)
	s_setprio 1
	s_waitcnt lgkmcnt(7)
	v_mfma_f32_16x16x32_bf16 v[26:29], v[158:161], v[2:5], v[62:65]
	s_waitcnt lgkmcnt(6)
	v_mfma_f32_16x16x32_bf16 v[58:61], v[162:165], v[10:13], v[26:29]
	v_mfma_f32_16x16x32_bf16 v[26:29], v[158:161], v[14:17], v[188:191]
	v_mfma_f32_16x16x32_bf16 v[62:65], v[162:165], v[180:183], v[26:29]
	s_waitcnt lgkmcnt(5)
	v_mfma_f32_16x16x32_bf16 v[26:29], v[166:169], v[2:5], v[54:57]
	s_waitcnt lgkmcnt(4)
	v_mfma_f32_16x16x32_bf16 v[42:45], v[170:173], v[10:13], v[26:29]
	v_mfma_f32_16x16x32_bf16 v[26:29], v[166:169], v[14:17], v[50:53]
	v_mfma_f32_16x16x32_bf16 v[46:49], v[170:173], v[180:183], v[26:29]
	s_waitcnt lgkmcnt(3)
	v_mfma_f32_16x16x32_bf16 v[26:29], v[184:187], v[2:5], v[212:215]
	s_waitcnt lgkmcnt(1)
	v_mfma_f32_16x16x32_bf16 v[2:5], v[208:211], v[2:5], v[38:41]
	v_mfma_f32_16x16x32_bf16 v[26:29], v[204:207], v[10:13], v[26:29]
	v_mfma_f32_16x16x32_bf16 v[30:33], v[184:187], v[14:17], v[216:219]
	s_waitcnt lgkmcnt(0)
	v_mfma_f32_16x16x32_bf16 v[10:13], v[224:227], v[10:13], v[2:5]
	v_mfma_f32_16x16x32_bf16 v[2:5], v[208:211], v[14:17], v[34:37]
	v_mfma_f32_16x16x32_bf16 v[30:33], v[204:207], v[180:183], v[30:33]
	v_mfma_f32_16x16x32_bf16 v[14:17], v[224:227], v[180:183], v[2:5]
	s_setprio 0
	s_setprio 1
	v_mfma_f32_16x16x32_bf16 v[2:5], v[158:161], v[192:195], v[130:133]
	v_mfma_f32_16x16x32_bf16 v[50:53], v[162:165], v[196:199], v[2:5]
	v_mfma_f32_16x16x32_bf16 v[2:5], v[158:161], v[200:203], v[136:139]
	v_mfma_f32_16x16x32_bf16 v[54:57], v[162:165], v[220:223], v[2:5]
	v_mfma_f32_16x16x32_bf16 v[2:5], v[166:169], v[192:195], v[22:25]
	v_mfma_f32_16x16x32_bf16 v[34:37], v[170:173], v[196:199], v[2:5]
	v_mfma_f32_16x16x32_bf16 v[2:5], v[166:169], v[200:203], v[18:21]
	v_mfma_f32_16x16x32_bf16 v[38:41], v[170:173], v[220:223], v[2:5]
	v_mfma_f32_16x16x32_bf16 v[2:5], v[184:187], v[192:195], v[140:143]
	v_mfma_f32_16x16x32_bf16 v[18:21], v[204:207], v[196:199], v[2:5]
	v_mfma_f32_16x16x32_bf16 v[2:5], v[184:187], v[200:203], v[154:157]
	v_mfma_f32_16x16x32_bf16 v[22:25], v[204:207], v[220:223], v[2:5]
	v_mfma_f32_16x16x32_bf16 v[2:5], v[208:211], v[192:195], v[6:9]
	v_mfma_f32_16x16x32_bf16 v[6:9], v[208:211], v[200:203], v[174:177]
	v_mfma_f32_16x16x32_bf16 v[2:5], v[224:227], v[196:199], v[2:5]
	v_mfma_f32_16x16x32_bf16 v[6:9], v[224:227], v[220:223], v[6:9]
	s_setprio 0
	s_movk_i32 s2, 0x100
	v_cmp_gt_u32_e32 vcc, s2, v0
	s_barrier
	s_and_saveexec_b64 s[2:3], vcc
	s_cbranch_execz .LBB0_102
	s_barrier
; __device__ __forceinline__ unsigned pack2(float a, float b) { return (unsigned)f2bf(a) | ((unsigned)f2bf(b) << 16); }
; #define WAIT_V(n) asm volatile("s_waitcnt vmcnt(" #n ")" ::: "memory")
; template <int EPI, bool HS = false>
; __device__ __forceinline__ void gemm_phase(const Params& p, const GemmCfg& g, char* shm, const int wave_s) {
;     ...
;       const float* xin_t = g.xin + (size_t)orow0 * 1024 + pn * 256;
;       float* xout_t = g.xout + (size_t)orow0 * 1024 + pn * 256;
;       u16* xg_t = p.h + (size_t)orow0 * 1024 + pn * 256;
;       float* rss_t = p.rowss + (size_t)orow0 * 16 + pn * 4 + wc;
;       const unsigned tb = (unsigned)((wr * 64 + fq * 4) * 1024 + wc * 32 + 2 * fr);
;       const unsigned ldsb = (unsigned)(size_t)(__attribute__((address_space(3))) char*)shm;
;       const int wv_s = __builtin_amdgcn_readfirstlane(wid);
;       constexpr int XROW = 1040;
;       const char* xl = shm + (wr * 64 + fq * 4) * XROW + (wc * 32 + 2 * fr) * 4;
; #pragma unroll
;       for (int ai = 0; ai < 2; ++ai) {
; #pragma unroll
;         for (int i = 0; i < 16; ++i) {
;           const int r = wv_s * 16 + i;
;           glds_row(xin_t + (size_t)(ai * 128 + r) * 1024, (unsigned)lane * 16u, ldsb + (unsigned)(r * XROW));
;         }
;         WAIT_V(0);
;         __syncthreads();
; #pragma unroll
;         for (int m = 0; m < 4; ++m) {
;           float2 xv[4][2];
; #pragma unroll
;           for (int j = 0; j < 4; ++j)
; #pragma unroll
;             for (int bj = 0; bj < 2; ++bj) xv[j][bj] = *(const float2*)(xl + (m * 16 + j) * XROW + bj * 512);
; #pragma unroll
;           for (int j = 0; j < 4; ++j) {
;             float ss = 0.f;
; #pragma unroll
;             for (int bj = 0; bj < 2; ++bj) {
;               float2 xn;
;               xn.x = xv[j][bj].x + gt[bj][0] * acc[ai][bj][m][0][j];
;               xn.y = xv[j][bj].y + gt[bj][1] * acc[ai][bj][m][1][j];
;               const unsigned o = tb + (unsigned)((ai * 128 + m * 16 + j) * 1024 + bj * 128);
;               *(float2*)(xout_t + o) = xn;
;               if (g.has_next) *(unsigned*)(xg_t + o) = pack2(xn.x * gn[bj][0], xn.y * gn[bj][1]);
.LBB0_102:
	s_mov_b32 s85, s43
	s_mov_b32 s77, s41
	s_or_b64 exec, exec, s[2:3]
	s_mov_b32 s2, s82
	s_mov_b32 s3, -1
	v_readlane_b32 s9, v254, 56
	v_mbcnt_lo_u32_b32 v0, s3, 0
	v_mbcnt_hi_u32_b32 v0, s3, v0
	v_lshl_add_u32 v0, s2, 6, v0
	s_lshl_b64 s[2:3], s[4:5], 12
	s_add_u32 s14, s9, s2
	v_readlane_b32 s9, v254, 55
	s_addc_u32 s15, s9, s3
	s_ashr_i32 s9, s8, 31
	s_lshl_b64 s[12:13], s[8:9], 2
	s_add_u32 s71, s14, s12
	v_readlane_b32 s52, v253, 25
	s_addc_u32 s75, s15, s13
	v_readlane_b32 s64, v253, 37
	v_readlane_b32 s65, v253, 38
	s_add_u32 s2, s64, s2
	s_addc_u32 s3, s65, s3
	s_add_u32 s2, s2, s12
	s_addc_u32 s3, s3, s13
	s_add_u32 s10, s88, s10
	s_addc_u32 s11, s89, s11
	v_lshrrev_b32_e32 v132, 2, v0
	s_lshl_b64 s[8:9], s[8:9], 1
	v_ashrrev_i32_e32 v130, 6, v0
	v_ashrrev_i32_e32 v131, 2, v0
	v_and_b32_e32 v132, 12, v132
	s_add_u32 s8, s10, s8
	s_movk_i32 s10, 0xffc0
	v_and_or_b32 v160, v131, s10, v132
	v_readfirstlane_b32 s10, v130
	s_addc_u32 s9, s11, s9
	s_movk_i32 s11, 0x410
	s_lshl_b32 s10, s10, 4
	v_and_b32_e32 v166, 3, v130
	v_mul_lo_u32 v130, v160, s11
	s_ashr_i32 s11, s10, 31
	s_lshl_b64 s[12:13], s[10:11], 12
	v_and_b32_e32 v165, 15, v0
	v_lshlrev_b32_e32 v0, 4, v0
	s_add_u32 s12, s71, s12
	s_mul_i32 s70, s10, 0x410
	v_and_b32_e32 v164, 0x3f0, v0
	s_addc_u32 s13, s75, s13
	s_add_i32 s70, s70, 0
	s_mov_b32 m0, s70
	s_nop 0
	global_load_lds_dwordx4 v164, s[12:13]
	s_or_b32 s12, s10, 1
	s_ashr_i32 s13, s12, 31
	s_lshl_b64 s[14:15], s[12:13], 12
	s_add_u32 s14, s71, s14
	s_mul_i32 s76, s12, 0x410
	s_addc_u32 s15, s75, s15
	s_add_i32 s76, s76, 0
	s_mov_b32 m0, s76
	s_nop 0
	global_load_lds_dwordx4 v164, s[14:15]
	s_or_b32 s12, s10, 2
	s_ashr_i32 s13, s12, 31
	s_lshl_b64 s[14:15], s[12:13], 12
	s_add_u32 s14, s71, s14
	s_mulk_i32 s12, 0x410
	s_addc_u32 s15, s75, s15
	s_add_i32 s12, s12, 0
	s_mov_b32 m0, s12
	s_nop 0
	global_load_lds_dwordx4 v164, s[14:15]
	s_or_b32 s14, s10, 3
	s_ashr_i32 s15, s14, 31
	s_lshl_b64 s[16:17], s[14:15], 12
	s_add_u32 s16, s71, s16
	s_mul_i32 s13, s14, 0x410
	s_addc_u32 s17, s75, s17
	s_add_i32 s13, s13, 0
	s_mov_b32 m0, s13
	s_nop 0
	global_load_lds_dwordx4 v164, s[16:17]
	s_or_b32 s14, s10, 4
	s_ashr_i32 s15, s14, 31
	s_lshl_b64 s[16:17], s[14:15], 12
	s_add_u32 s16, s71, s16
	s_mulk_i32 s14, 0x410
	s_addc_u32 s17, s75, s17
	s_add_i32 s14, s14, 0
	s_mov_b32 m0, s14
	s_nop 0
	global_load_lds_dwordx4 v164, s[16:17]
	s_or_b32 s16, s10, 5
	s_ashr_i32 s17, s16, 31
	s_lshl_b64 s[18:19], s[16:17], 12
	s_add_u32 s18, s71, s18
	s_mul_i32 s15, s16, 0x410
	s_addc_u32 s19, s75, s19
	s_add_i32 s15, s15, 0
	s_mov_b32 m0, s15
	s_nop 0
	global_load_lds_dwordx4 v164, s[18:19]
	s_or_b32 s16, s10, 6
	s_ashr_i32 s17, s16, 31
	s_lshl_b64 s[18:19], s[16:17], 12
	s_add_u32 s18, s71, s18
	s_mulk_i32 s16, 0x410
	s_addc_u32 s19, s75, s19
	s_add_i32 s16, s16, 0
	s_mov_b32 m0, s16
	s_nop 0
	global_load_lds_dwordx4 v164, s[18:19]
	s_or_b32 s18, s10, 7
	s_ashr_i32 s19, s18, 31
	s_lshl_b64 s[20:21], s[18:19], 12
	s_add_u32 s20, s71, s20
	s_mul_i32 s17, s18, 0x410
	s_addc_u32 s21, s75, s21
	s_add_i32 s17, s17, 0
	s_mov_b32 m0, s17
	s_nop 0
	global_load_lds_dwordx4 v164, s[20:21]
	s_or_b32 s18, s10, 8
	s_ashr_i32 s19, s18, 31
	s_lshl_b64 s[20:21], s[18:19], 12
	s_add_u32 s20, s71, s20
	s_mulk_i32 s18, 0x410
	s_addc_u32 s21, s75, s21
	s_add_i32 s18, s18, 0
	s_mov_b32 m0, s18
	s_nop 0
	global_load_lds_dwordx4 v164, s[20:21]
	s_or_b32 s20, s10, 9
	s_ashr_i32 s21, s20, 31
	s_lshl_b64 s[22:23], s[20:21], 12
	s_add_u32 s22, s71, s22
	s_mul_i32 s19, s20, 0x410
	s_addc_u32 s23, s75, s23
	s_add_i32 s19, s19, 0
	s_mov_b32 m0, s19
	s_nop 0
	global_load_lds_dwordx4 v164, s[22:23]
	s_or_b32 s20, s10, 10
	s_ashr_i32 s21, s20, 31
	s_lshl_b64 s[22:23], s[20:21], 12
	s_add_u32 s22, s71, s22
	s_mulk_i32 s20, 0x410
	s_addc_u32 s23, s75, s23
	s_add_i32 s20, s20, 0
	s_mov_b32 m0, s20
	s_nop 0
	global_load_lds_dwordx4 v164, s[22:23]
	s_or_b32 s22, s10, 11
	s_ashr_i32 s23, s22, 31
	s_lshl_b64 s[24:25], s[22:23], 12
	s_add_u32 s24, s71, s24
	s_mul_i32 s21, s22, 0x410
	s_addc_u32 s25, s75, s25
	s_add_i32 s21, s21, 0
	s_mov_b32 m0, s21
	s_nop 0
	global_load_lds_dwordx4 v164, s[24:25]
	s_or_b32 s22, s10, 12
	s_ashr_i32 s23, s22, 31
	s_lshl_b64 s[24:25], s[22:23], 12
	s_add_u32 s24, s71, s24
	s_mulk_i32 s22, 0x410
	s_addc_u32 s25, s75, s25
	s_add_i32 s22, s22, 0
	s_mov_b32 m0, s22
	s_nop 0
	global_load_lds_dwordx4 v164, s[24:25]
	s_or_b32 s24, s10, 13
	s_ashr_i32 s25, s24, 31
	s_lshl_b64 s[26:27], s[24:25], 12
	s_add_u32 s26, s71, s26
	s_mul_i32 s23, s24, 0x410
	s_addc_u32 s27, s75, s27
	s_add_i32 s23, s23, 0
	s_mov_b32 m0, s23
	s_nop 0
	global_load_lds_dwordx4 v164, s[26:27]
	s_or_b32 s24, s10, 14
	s_ashr_i32 s25, s24, 31
	s_lshl_b64 s[26:27], s[24:25], 12
	s_add_u32 s26, s71, s26
	s_mulk_i32 s24, 0x410
	v_lshlrev_b32_e32 v132, 5, v166
	v_lshlrev_b32_e32 v133, 1, v165
	s_addc_u32 s27, s75, s27
	s_add_i32 s24, s24, 0
	s_mov_b32 m0, s24
	s_nop 0
	global_load_lds_dwordx4 v164, s[26:27]
	s_or_b32 s26, s10, 15
	v_or_b32_e32 v134, v132, v133
	s_ashr_i32 s27, s26, 31
	v_add_u32_e32 v130, 0, v130
	v_lshlrev_b32_e32 v134, 2, v134
	s_lshl_b64 s[36:37], s[26:27], 12
	v_add_u32_e32 v161, v130, v134
	s_add_u32 s36, s71, s36
	s_mul_i32 s25, s26, 0x410
	v_lshlrev_b32_e32 v131, 10, v160
	s_addc_u32 s37, s75, s37
	s_add_i32 s25, s25, 0
	s_mov_b32 m0, s25
	s_nop 0
	global_load_lds_dwordx4 v164, s[36:37]
	v_add_u32_e32 v162, 32, v161
	v_add_u32_e32 v163, 48, v161
	v_or3_b32 v0, v131, v133, v132
	s_waitcnt vmcnt(0)
	s_barrier
	ds_read2st64_b64 v[142:145], v161 offset1:1
	ds_read2_b64 v[138:141], v161 offset0:130 offset1:194
	ds_read2st64_b64 v[134:137], v162 offset0:4 offset1:5
	ds_read2st64_b64 v[130:133], v163 offset0:6 offset1:7
	v_readlane_b32 s26, v254, 60
	v_mov_b32_e32 v154, v122
	v_mov_b32_e32 v155, v126
	v_readlane_b32 s27, v254, 61
	s_waitcnt lgkmcnt(3)
	v_pk_fma_f32 v[156:157], v[150:151], v[154:155], v[142:143]
	v_lshl_add_u64 v[158:159], v[0:1], 2, s[2:3]
	s_and_b64 vcc, exec, s[26:27]
	v_lshl_add_u64 v[154:155], v[0:1], 1, s[8:9]
	v_readlane_b32 s53, v253, 26
	v_readlane_b32 s54, v253, 27
	v_readlane_b32 s55, v253, 28
	v_readlane_b32 s56, v253, 29
	v_readlane_b32 s57, v253, 30
	v_readlane_b32 s58, v253, 31
	v_readlane_b32 s59, v253, 32
	v_readlane_b32 s60, v253, 33
	v_readlane_b32 s61, v253, 34
	v_readlane_b32 s62, v253, 35
	v_readlane_b32 s63, v253, 36
	v_readlane_b32 s66, v253, 39
	v_readlane_b32 s67, v253, 40
	global_store_dwordx2 v[158:159], v[156:157], off
	s_cbranch_vccz .LBB0_104
	v_pk_mul_f32 v[142:143], v[148:149], v[156:157]
	s_nop 0
	v_and_b32_sdwa v126, v142, v178 dst_sel:DWORD dst_unused:UNUSED_PAD src0_sel:WORD_1 src1_sel:DWORD
	v_and_b32_sdwa v122, v143, v178 dst_sel:DWORD dst_unused:UNUSED_PAD src0_sel:WORD_1 src1_sel:DWORD
	v_add3_u32 v126, v142, v126, s81
	v_add3_u32 v122, v143, v122, s81
	v_lshrrev_b32_e32 v126, 16, v126
	v_and_or_b32 v122, v122, s28, v126
	global_store_dword v[154:155], v122, off

; __device__ __forceinline__ unsigned pack2(float a, float b) { return (unsigned)f2bf(a) | ((unsigned)f2bf(b) << 16); }
; #define WAIT_V(n) asm volatile("s_waitcnt vmcnt(" #n ")" ::: "memory")
; template <int EPI, bool HS = false>
; __device__ __forceinline__ void gemm_phase(const Params& p, const GemmCfg& g, char* shm, const int wave_s) {
;     ...
;       for (int ai = 0; ai < 2; ++ai) {
; #pragma unroll
;         for (int i = 0; i < 16; ++i) {
;           const int r = wv_s * 16 + i;
;           glds_row(xin_t + (size_t)(ai * 128 + r) * 1024, (unsigned)lane * 16u, ldsb + (unsigned)(r * XROW));
;         }
;         WAIT_V(0);
;         __syncthreads();
; #pragma unroll
;         for (int m = 0; m < 4; ++m) {
;           float2 xv[4][2];
; #pragma unroll
;           for (int j = 0; j < 4; ++j)
; #pragma unroll
;             for (int bj = 0; bj < 2; ++bj) xv[j][bj] = *(const float2*)(xl + (m * 16 + j) * XROW + bj * 512);
; #pragma unroll
;           for (int j = 0; j < 4; ++j) {
;             float ss = 0.f;
; #pragma unroll
;             for (int bj = 0; bj < 2; ++bj) {
;               float2 xn;
;               xn.x = xv[j][bj].x + gt[bj][0] * acc[ai][bj][m][0][j];
;               xn.y = xv[j][bj].y + gt[bj][1] * acc[ai][bj][m][1][j];
;               const unsigned o = tb + (unsigned)((ai * 128 + m * 16 + j) * 1024 + bj * 128);
;               *(float2*)(xout_t + o) = xn;
;               if (g.has_next) *(unsigned*)(xg_t + o) = pack2(xn.x * gn[bj][0], xn.y * gn[bj][1]);
;               ss += xn.x * xn.x + xn.y * xn.y;
;             }
;             if (g.has_next) {
;               ss = dpp_row_sum16(ss);
;               if (fr == 0) rss_t[(wr * 64 + fq * 4 + ai * 128 + m * 16 + j) * 16] = ss;
.LBB0_196:
	s_lshl_b64 s[10:11], s[10:11], 12
	s_add_u32 s26, s71, s10
	s_addc_u32 s27, s75, s11
	s_add_u32 s10, s26, 0x80000
	s_addc_u32 s11, s27, 0
	s_waitcnt vmcnt(63) expcnt(7) lgkmcnt(15)
	s_barrier
	s_mov_b32 m0, s70
	s_nop 0
	global_load_lds_dwordx4 v164, s[10:11]
	s_add_u32 s10, s26, 0x81000
	s_addc_u32 s11, s27, 0
	s_mov_b32 m0, s76
	s_nop 0
	global_load_lds_dwordx4 v164, s[10:11]
	s_add_u32 s10, s26, 0x82000
	s_addc_u32 s11, s27, 0
	s_mov_b32 m0, s12
	s_nop 0
	global_load_lds_dwordx4 v164, s[10:11]
	s_add_u32 s10, s26, 0x83000
	s_addc_u32 s11, s27, 0
	s_mov_b32 m0, s13
	s_nop 0
	global_load_lds_dwordx4 v164, s[10:11]
	s_add_u32 s10, s26, 0x84000
	s_addc_u32 s11, s27, 0
	s_mov_b32 m0, s14
	s_nop 0
	global_load_lds_dwordx4 v164, s[10:11]
	s_add_u32 s10, s26, 0x85000
	s_addc_u32 s11, s27, 0
	s_mov_b32 m0, s15
	s_nop 0
	global_load_lds_dwordx4 v164, s[10:11]
	s_add_u32 s10, s26, 0x86000
	s_addc_u32 s11, s27, 0
	s_mov_b32 m0, s16
	s_nop 0
	global_load_lds_dwordx4 v164, s[10:11]
	s_add_u32 s10, s26, 0x87000
	s_addc_u32 s11, s27, 0
	s_mov_b32 m0, s17
	s_nop 0
	global_load_lds_dwordx4 v164, s[10:11]
	s_add_u32 s10, s26, 0x88000
	s_addc_u32 s11, s27, 0
	s_mov_b32 m0, s18
	s_nop 0
	global_load_lds_dwordx4 v164, s[10:11]
	s_add_u32 s10, s26, 0x89000
	s_addc_u32 s11, s27, 0
	s_mov_b32 m0, s19
	s_nop 0
	global_load_lds_dwordx4 v164, s[10:11]
	s_add_u32 s10, s26, 0x8a000
	s_addc_u32 s11, s27, 0
	s_mov_b32 m0, s20
	s_nop 0
	global_load_lds_dwordx4 v164, s[10:11]
	s_add_u32 s10, s26, 0x8b000
	s_addc_u32 s11, s27, 0
	s_mov_b32 m0, s21
	s_nop 0
	global_load_lds_dwordx4 v164, s[10:11]
	s_add_u32 s10, s26, 0x8c000
	s_addc_u32 s11, s27, 0
	s_mov_b32 m0, s22
	s_nop 0
	global_load_lds_dwordx4 v164, s[10:11]
	s_add_u32 s10, s26, 0x8d000
	s_addc_u32 s11, s27, 0
	s_mov_b32 m0, s23
	s_nop 0
	global_load_lds_dwordx4 v164, s[10:11]
	s_add_u32 s10, s26, 0x8e000
	s_addc_u32 s11, s27, 0
	s_mov_b32 m0, s24
	s_nop 0
	global_load_lds_dwordx4 v164, s[10:11]
	s_add_u32 s10, s26, 0x8f000
	s_addc_u32 s11, s27, 0
	s_mov_b32 m0, s25
	s_nop 0
	global_load_lds_dwordx4 v164, s[10:11]
	s_waitcnt vmcnt(0)
	s_barrier
	ds_read2st64_b64 v[78:81], v161 offset1:1
	ds_read2_b64 v[74:77], v161 offset0:130 offset1:194
	ds_read2st64_b64 v[70:73], v162 offset0:4 offset1:5
	ds_read2st64_b64 v[66:69], v163 offset0:6 offset1:7
	v_add_u32_e32 v84, 0x20000, v0
	v_mov_b32_e32 v82, v58
	v_mov_b32_e32 v83, v62
	v_mov_b32_e32 v85, v1
	s_waitcnt lgkmcnt(3)
	v_pk_fma_f32 v[82:83], v[150:151], v[82:83], v[78:79]
	v_lshl_add_u64 v[78:79], v[84:85], 2, s[2:3]
	global_store_dwordx2 v[78:79], v[82:83], off
	s_mov_b64 s[10:11], -1
	s_and_b64 vcc, exec, s[6:7]
	v_add_u32_e32 v78, 0x20080, v0
	s_cbranch_vccnz .LBB0_200
	v_pk_mul_f32 v[86:87], v[148:149], v[82:83]
	v_lshl_add_u64 v[84:85], v[84:85], 1, s[8:9]
	v_and_b32_sdwa v62, v86, v178 dst_sel:DWORD dst_unused:UNUSED_PAD src0_sel:WORD_1 src1_sel:DWORD
	v_and_b32_sdwa v58, v87, v178 dst_sel:DWORD dst_unused:UNUSED_PAD src0_sel:WORD_1 src1_sel:DWORD
	v_add3_u32 v62, v86, v62, s81
	v_add3_u32 v58, v87, v58, s81
	v_lshrrev_b32_e32 v62, 16, v62
	v_and_or_b32 v58, v58, s28, v62
	global_store_dword v[84:85], v58, off
	v_mov_b32_e32 v84, v50
	v_mov_b32_e32 v85, v54
	v_mov_b32_e32 v79, v1
	v_pk_fma_f32 v[84:85], v[146:147], v[84:85], v[80:81]
	v_lshl_add_u64 v[86:87], v[78:79], 2, s[2:3]
	global_store_dwordx2 v[86:87], v[84:85], off
	v_pk_mul_f32 v[86:87], v[152:153], v[84:85]
	v_pk_mul_f32 v[82:83], v[82:83], v[82:83]
	v_and_b32_sdwa v62, v86, v178 dst_sel:DWORD dst_unused:UNUSED_PAD src0_sel:WORD_1 src1_sel:DWORD
	v_and_b32_sdwa v58, v87, v178 dst_sel:DWORD dst_unused:UNUSED_PAD src0_sel:WORD_1 src1_sel:DWORD
	v_add3_u32 v62, v86, v62, s81
	v_add3_u32 v58, v87, v58, s81
	v_lshrrev_b32_e32 v62, 16, v62
	v_and_or_b32 v58, v58, s28, v62
	v_lshl_add_u64 v[86:87], v[78:79], 1, s[8:9]
	v_pk_mul_f32 v[84:85], v[84:85], v[84:85]
	global_store_dword v[86:87], v58, off
	v_add_f32_e32 v58, v84, v85
	v_add_f32_e32 v62, v82, v83
	v_add_f32_e32 v58, v62, v58
	s_nop 1
	v_add_f32_dpp v58, v58, v58 quad_perm:[1,0,3,2] row_mask:0xf bank_mask:0xf bound_ctrl:1
	s_nop 1
	v_add_f32_dpp v58, v58, v58 quad_perm:[2,3,0,1] row_mask:0xf bank_mask:0xf bound_ctrl:1
	s_nop 1
	v_add_f32_dpp v58, v58, v58 row_half_mirror row_mask:0xf bank_mask:0xf bound_ctrl:1
	s_nop 1
	v_mov_b32_dpp v62, v58 row_mirror row_mask:0xf bank_mask:0xf bound_ctrl:1
	s_and_saveexec_b64 s[10:11], s[4:5]
	s_cbranch_execz .LBB0_199
	v_add_f32_e32 v58, v58, v62
	v_mov_b32_e32 v62, 0x800
	v_lshl_add_u32 v82, v160, 4, v62
	v_ashrrev_i32_e32 v83, 31, v82
	v_lshl_add_u64 v[82:83], v[82:83], 2, v[142:143]
	global_store_dword v[82:83], v58, off

; #define STG_A(b, h, kt) stage_half_s(lds0 + ((b) * 2 + (h)) * HT_B, ((h) ? A1 : Ap) + (kt) * BK, off0, off1)
; #define STG_B(b, h, kt) stage_half_s(lds0 + (4 + (b) * 2 + (h)) * HT_B, ((h) ? B1p : Bp) + (kt) * BK, off0, off1)
; #define STG_A(b, h, kt) stage_half_s(lds0 + ((b) * 2 + (h)) * HT_B, ((h) ? A1 : Ap) + (kt) * BK, off0, off1)
; #define STG_B(b, h, kt) stage_half_s(lds0 + (4 + (b) * 2 + (h)) * HT_B, ((h) ? B1p : Bp) + (kt) * BK, off0, off1)
; __device__ __forceinline__ void gemm8_prefetch(const u16* __restrict__ Ap, const u16* __restrict__ Bp, int K, char* shm, const int tid) {
;   int r0, c0, r1, c1;
;   stage_rc(tid * 16, r0, c0);
;   stage_rc(tid * 16 + 8192, r1, c1);
;   const unsigned off0 = (unsigned)(r0 * K + c0) * 2u, off1 = (unsigned)(r1 * K + c1) * 2u;
;   const int wvoff = __builtin_amdgcn_readfirstlane(tid >> 6) * 1024;
;   const u16* A1 = Ap + (size_t)128 * K;
;   const u16* B1p = Bp + (size_t)128 * K;
;   const unsigned lds0 = (unsigned)(size_t)(__attribute__((address_space(3))) char*)shm + (unsigned)wvoff;
;     ...
;   STG_B(0, 0, 0); STG_A(0, 0, 0); STG_B(0, 1, 0); STG_A(0, 1, 0);
;   STG_B(1, 0, 1); STG_A(1, 0, 1); STG_B(1, 1, 1);
;     ...
; }
; template <int EPI, bool HS = false>
; __device__ __forceinline__ void gemm_phase(const Params& p, const GemmCfg& g, char* shm, const int wave_s) {
;     ...
;   if ((int)blockIdx.x < nwg) {
;     int mt, pn, arow0, orow0;
;     tile_coords(blockIdx.x, mt, pn, arow0, orow0);
;     gemm8_prefetch(g.A + (size_t)arow0 * g.K, g.Bt + (size_t)pn * 256 * g.K, g.K, shm, fresh_tid(wave_s));
;   }
.LBB0_310:
	v_readlane_b32 s0, v252, 47
	v_readlane_b32 s1, v252, 48
	s_andn2_b64 vcc, exec, s[0:1]
	s_cbranch_vccnz .LBB0_327
	v_readlane_b32 s4, v252, 26
	s_mul_i32 s0, s50, 0x600000
	v_readlane_b32 s10, v252, 32
	s_mul_hi_i32 s1, s50, 0x600000
	v_readlane_b32 s11, v252, 33
	s_add_u32 s0, s10, s0
	s_mul_i32 s2, s50, 0xc000
	s_addc_u32 s1, s11, s1
	s_ashr_i32 s3, s2, 31
	v_readlane_b32 s5, v252, 27
	s_lshl_b64 s[2:3], s[2:3], 2
	v_readlane_b32 s4, v252, 46
	s_add_u32 s68, s4, s2
	s_mov_b32 s4, s82
	s_mov_b32 s5, -1
	s_addc_u32 s69, s49, s3
	v_mbcnt_lo_u32_b32 v0, s5, 0
	v_mbcnt_hi_u32_b32 v0, s5, v0
	v_lshl_add_u32 v0, s4, 6, v0
	v_readlane_b32 s2, v252, 49
	v_bfe_i32 v4, v0, 27, 1
	v_lshlrev_b32_e32 v2, 4, v0
	v_lshrrev_b32_e32 v4, 22, v4
	v_add_u32_e32 v4, v2, v4
	v_and_b32_e32 v4, 0xfffffc00, v4
	v_ashrrev_i32_e32 v3, 31, v0
	v_sub_u32_e32 v4, v2, v4
	v_lshrrev_b32_e32 v3, 26, v3
	v_lshrrev_b32_e32 v5, 4, v4
	v_add_u32_e32 v3, v0, v3
	v_bitop3_b32 v5, v5, v4, 32 bitop3:0x6c
	v_ashrrev_i32_e32 v4, 31, v4
	v_ashrrev_i32_e32 v3, 6, v3
	v_lshrrev_b32_e32 v4, 26, v4
	v_lshlrev_b32_e32 v6, 3, v3
	v_add_u32_e32 v4, v5, v4
	v_and_b32_e32 v6, 0x1ffff0, v6
	v_ashrrev_i32_e32 v4, 6, v4
	v_add_u32_e32 v6, v4, v6
	v_mul_i32_i24_e32 v4, 64, v4
	v_add_u32_e32 v2, 0x2000, v2
	v_sub_u32_e32 v4, v5, v4
	v_ashrrev_i32_e32 v5, 31, v2
	v_lshrrev_b32_e32 v5, 22, v5
	v_add_u32_e32 v5, v2, v5
	v_ashrrev_i32_e32 v5, 10, v5
	v_mul_i32_i24_e32 v7, 0x400, v5
	v_sub_u32_e32 v2, v2, v7
	v_lshrrev_b32_e32 v7, 4, v2
	v_bitop3_b32 v2, v7, v2, 32 bitop3:0x6c
	v_readlane_b32 s3, v252, 50
	s_add_u32 s2, s0, s2
	v_ashrrev_i32_e32 v8, 31, v2
	v_readlane_b32 s6, v252, 28
	s_addc_u32 s3, s1, s3
	v_lshrrev_b32_e32 v8, 26, v8
	v_add_u32_e32 v8, v2, v8
	v_readfirstlane_b32 s6, v0
	s_add_u32 s4, s2, 0x40000
	v_lshlrev_b32_e32 v3, 5, v3
	v_lshlrev_b32_e32 v7, 3, v5
	v_lshrrev_b32_e32 v9, 6, v8
	v_and_b32_e32 v8, 0xc0, v8
	s_addc_u32 s5, s3, 0
	s_lshl_b32 s6, s6, 4
	v_and_b32_e32 v3, 32, v3
	v_ashrrev_i16_sdwa v4, v178, sext(v4) dst_sel:DWORD dst_unused:UNUSED_PAD src0_sel:DWORD src1_sel:BYTE_0
	v_and_b32_e32 v7, 0x1ffff0, v7
	v_lshlrev_b32_e32 v5, 5, v5
	v_sub_u32_e32 v2, v2, v8
	s_and_b32 s6, s6, 0xfffffc00
	v_readlane_b32 s7, v252, 29
	v_readlane_b32 s8, v252, 30
	v_bfe_i32 v4, v4, 0, 16
	v_add_u32_e32 v7, v9, v7
	v_and_b32_e32 v5, 32, v5
	v_ashrrev_i16_sdwa v2, v178, sext(v2) dst_sel:DWORD dst_unused:UNUSED_PAD src0_sel:DWORD src1_sel:BYTE_0
	v_lshl_or_b32 v3, v6, 10, v3
	s_add_i32 s6, s6, 0
	v_bfe_i32 v2, v2, 0, 16
	v_add_lshl_u32 v3, v3, v4, 1
	v_lshl_or_b32 v4, v7, 10, v5
	s_add_i32 s7, s6, 0x10000
	s_mov_b32 m0, s7
	s_nop 0
	global_load_lds_dwordx4 v3, s[2:3]
	v_add_lshl_u32 v2, v4, v2, 1
	s_add_i32 s7, s6, 0x12000
	s_mov_b32 m0, s7
	s_nop 0
	global_load_lds_dwordx4 v2, s[2:3]
	v_readlane_b32 s10, v252, 53
	v_readlane_b32 s11, v252, 54
	s_mov_b32 m0, s6
	s_nop 3
	global_load_lds_dwordx4 v3, s[10:11]
	s_add_i32 s7, s6, 0x2000
	s_mov_b32 m0, s7
	s_nop 0
	global_load_lds_dwordx4 v2, s[10:11]
	s_add_i32 s7, s6, 0x14000
	s_mov_b32 m0, s7
	s_nop 0
	global_load_lds_dwordx4 v3, s[4:5]
	v_readlane_b32 s9, v252, 31
	s_add_i32 s7, s6, 0x16000
	s_mov_b32 m0, s7
	s_nop 0
	global_load_lds_dwordx4 v2, s[4:5]
	s_add_i32 s4, s6, 0x4000
	v_readlane_b32 s8, v252, 51
	v_readlane_b32 s9, v252, 52
	s_mov_b32 m0, s4
	s_nop 3
	global_load_lds_dwordx4 v3, s[8:9]
	s_add_i32 s4, s6, 0x6000
	s_mov_b32 m0, s4
	s_nop 0
	global_load_lds_dwordx4 v2, s[8:9]
	s_add_u32 s4, s2, 0x80
	s_addc_u32 s5, s3, 0
	s_add_i32 s7, s6, 0x18000
	s_mov_b32 m0, s7
	s_nop 0
	global_load_lds_dwordx4 v3, s[4:5]
	s_add_i32 s7, s6, 0x1a000
	s_mov_b32 m0, s7
	s_nop 0
	global_load_lds_dwordx4 v2, s[4:5]
	s_add_i32 s4, s6, 0x8000
	v_readlane_b32 s8, v252, 55
	v_readlane_b32 s9, v252, 56
	s_mov_b32 m0, s4
	s_nop 3
	global_load_lds_dwordx4 v3, s[8:9]
	s_add_i32 s4, s6, 0xa000
	s_mov_b32 m0, s4
	s_nop 0
	global_load_lds_dwordx4 v2, s[8:9]
	s_add_u32 s2, s2, 0x40080
	s_addc_u32 s3, s3, 0
	s_add_i32 s4, s6, 0x1c000
	s_mov_b32 m0, s4
	s_nop 0
	global_load_lds_dwordx4 v3, s[2:3]
	s_add_i32 s6, s6, 0x1e000
	s_mov_b32 m0, s6
	s_nop 0
	global_load_lds_dwordx4 v2, s[2:3]
	s_mov_b32 s72, s45
	v_readlane_b32 s12, v252, 34
	v_readlane_b32 s13, v252, 35
	v_readlane_b32 s14, v252, 36
	v_readlane_b32 s15, v252, 37
	v_readlane_b32 s16, v252, 38
	v_readlane_b32 s17, v252, 39
	v_readlane_b32 s18, v252, 40
	v_readlane_b32 s19, v252, 41
	s_branch .LBB0_313

; #define WAIT_L(n) asm volatile("s_waitcnt lgkmcnt(" #n ")" ::: "memory")
; #define BAR __builtin_amdgcn_s_barrier()
; #define SCHED __builtin_amdgcn_sched_barrier(0)
; #define STG_A(b, h, kt) stage_half_s(lds0 + ((b) * 2 + (h)) * HT_B, ((h) ? A1 : Ap) + (kt) * BK, off0, off1)
; #define STG_B(b, h, kt) stage_half_s(lds0 + (4 + (b) * 2 + (h)) * HT_B, ((h) ? B1p : Bp) + (kt) * BK, off0, off1)
; #define STG_A(b, h, kt) stage_half_s(lds0 + ((b) * 2 + (h)) * HT_B, ((h) ? A1 : Ap) + (kt) * BK, off0, off1)
; #define STG_B(b, h, kt) stage_half_s(lds0 + (4 + (b) * 2 + (h)) * HT_B, ((h) ? B1p : Bp) + (kt) * BK, off0, off1)
; #define LDA8(b, h) _Pragma("unroll") for (int m = 0; m < 4; ++m) _Pragma("unroll") for (int k = 0; k < 2; ++k) \
;     At[m][k] = *(const bf16x8*)(SA_(shm, b, h) + abase + (m * 2 + k) * 1024)
; #define LDB8(dst, b, h) _Pragma("unroll") for (int n = 0; n < 2; ++n) _Pragma("unroll") for (int k = 0; k < 2; ++k) \
;     dst[n][k] = *(const bf16x8*)(SB_(shm, b, h) + bbase + (n * 2 + k) * 1024)
; #define MMA8(ai, bj, Bx) do { __builtin_amdgcn_s_setprio(1); \
;     _Pragma("unroll") for (int m = 0; m < 4; ++m) _Pragma("unroll") for (int n = 0; n < 2; ++n) _Pragma("unroll") for (int k = 0; k < 2; ++k) \
;       acc[ai][bj][m][n] = __builtin_amdgcn_mfma_f32_16x16x32_bf16(At[m][k], Bx[n][k], acc[ai][bj][m][n], 0, 0, 0); \
;     __builtin_amdgcn_s_setprio(0); } while (0)
; template <bool HS>
; __device__ __forceinline__ void gemm_tile8(const u16* __restrict__ Ap, const u16* __restrict__ Bp, int K,
;                                            f32x4 (&acc)[2][2][4][2], char* shm, const int tid, const float* hsr = nullptr) {
;     ...
;     LDB8(B0, 0, 0); SCHED; LDA8(0, 0); STG_A(1, 1, t + 1);
;     WAIT_L(8); BAR; WAIT_L(0); MMA8(0, 0, B0); BAR; SCHED;
;     LDB8(B1, 0, 1); STG_B(0, 0, t + 2);
;     BAR; WAIT_L(0); MMA8(0, 1, B1); BAR;
;     LDA8(0, 1); STG_A(0, 0, t + 2);
;     BAR; WAIT_L(0); MMA8(1, 0, B0); BAR; SCHED;
.LBB0_318:
	s_add_i32 s22, 0, 0x10000
	v_add_u32_e32 v154, s22, v141
	ds_read_b128 v[142:145], v154
	ds_read_b128 v[146:149], v154 offset:1024
	ds_read_b128 v[150:153], v154 offset:2048
	ds_read_b128 v[154:157], v154 offset:3072
	ds_read_b128 v[158:161], v138
	ds_read_b128 v[162:165], v138 offset:1024
	ds_read_b128 v[166:169], v138 offset:2048
	ds_read_b128 v[170:173], v138 offset:3072
	ds_read_b128 v[174:177], v138 offset:4096
	ds_read_b128 v[180:183], v138 offset:5120
	ds_read_b128 v[184:187], v138 offset:6144
	ds_read_b128 v[188:191], v138 offset:7168
	s_add_u32 s18, s15, s4
	s_addc_u32 s19, s16, s5
	s_add_u32 s20, s18, 0x80
	s_addc_u32 s21, s19, 0
	s_add_i32 s18, s11, 0xc000
	s_mov_b32 m0, s18
	s_nop 0
	global_load_lds_dwordx4 v140, s[20:21]
	s_add_i32 s19, s11, 0xe000
	s_mov_b32 m0, s19
	s_nop 0
	global_load_lds_dwordx4 v139, s[20:21]
	s_waitcnt lgkmcnt(8)
	s_barrier
	s_waitcnt lgkmcnt(0)
	s_setprio 1
	s_waitcnt lgkmcnt(7)
	v_mfma_f32_16x16x32_bf16 v[126:129], v[158:161], v[142:145], v[126:129]
	v_mfma_f32_16x16x32_bf16 v[122:125], v[158:161], v[150:153], v[122:125]
	s_waitcnt lgkmcnt(5)
	v_mfma_f32_16x16x32_bf16 v[118:121], v[166:169], v[142:145], v[118:121]
	v_mfma_f32_16x16x32_bf16 v[114:117], v[166:169], v[150:153], v[114:117]
	s_waitcnt lgkmcnt(3)
	v_mfma_f32_16x16x32_bf16 v[110:113], v[174:177], v[142:145], v[110:113]
	v_mfma_f32_16x16x32_bf16 v[106:109], v[174:177], v[150:153], v[106:109]
	s_waitcnt lgkmcnt(1)
	v_mfma_f32_16x16x32_bf16 v[102:105], v[184:187], v[142:145], v[102:105]
	v_mfma_f32_16x16x32_bf16 v[98:101], v[184:187], v[150:153], v[98:101]
	v_mfma_f32_16x16x32_bf16 v[126:129], v[162:165], v[146:149], v[126:129]
	v_mfma_f32_16x16x32_bf16 v[122:125], v[162:165], v[154:157], v[122:125]
	v_mfma_f32_16x16x32_bf16 v[118:121], v[170:173], v[146:149], v[118:121]
	v_mfma_f32_16x16x32_bf16 v[114:117], v[170:173], v[154:157], v[114:117]
	v_mfma_f32_16x16x32_bf16 v[110:113], v[180:183], v[146:149], v[110:113]
	v_mfma_f32_16x16x32_bf16 v[106:109], v[180:183], v[154:157], v[106:109]
	s_waitcnt lgkmcnt(0)
	v_mfma_f32_16x16x32_bf16 v[102:105], v[188:191], v[146:149], v[102:105]
	v_mfma_f32_16x16x32_bf16 v[98:101], v[188:191], v[154:157], v[98:101]
	s_setprio 0
	s_barrier
	s_add_i32 s23, 0, 0x14000
	v_add_u32_e32 v204, s23, v141
	ds_read_b128 v[192:195], v204
	ds_read_b128 v[196:199], v204 offset:1024
	ds_read_b128 v[200:203], v204 offset:2048
	ds_read_b128 v[204:207], v204 offset:3072
	v_lshl_add_u64 v[208:209], v[130:131], 0, s[4:5]
	v_lshl_add_u64 v[210:211], v[208:209], 0, s[78:79]
	s_add_i32 s22, s10, s22
	v_readfirstlane_b32 s21, v211
	v_readfirstlane_b32 s20, v210
	s_mov_b32 m0, s22
	s_nop 3
	global_load_lds_dwordx4 v140, s[20:21]
	s_add_i32 s22, s11, 0x12000
	s_mov_b32 m0, s22
	s_nop 0
	global_load_lds_dwordx4 v139, s[20:21]
	s_barrier
	s_waitcnt lgkmcnt(0)
	s_setprio 1
	s_waitcnt lgkmcnt(3)
	v_mfma_f32_16x16x32_bf16 v[94:97], v[158:161], v[192:195], v[94:97]
	s_waitcnt lgkmcnt(1)
	v_mfma_f32_16x16x32_bf16 v[90:93], v[158:161], v[200:203], v[90:93]
	v_mfma_f32_16x16x32_bf16 v[86:89], v[166:169], v[192:195], v[86:89]
	v_mfma_f32_16x16x32_bf16 v[82:85], v[166:169], v[200:203], v[82:85]
	v_mfma_f32_16x16x32_bf16 v[78:81], v[174:177], v[192:195], v[78:81]
	v_mfma_f32_16x16x32_bf16 v[74:77], v[174:177], v[200:203], v[74:77]
	v_mfma_f32_16x16x32_bf16 v[70:73], v[184:187], v[192:195], v[70:73]
	v_mfma_f32_16x16x32_bf16 v[66:69], v[184:187], v[200:203], v[66:69]
	v_mfma_f32_16x16x32_bf16 v[94:97], v[162:165], v[196:199], v[94:97]
	s_waitcnt lgkmcnt(0)
	v_mfma_f32_16x16x32_bf16 v[90:93], v[162:165], v[204:207], v[90:93]
	v_mfma_f32_16x16x32_bf16 v[86:89], v[170:173], v[196:199], v[86:89]
	v_mfma_f32_16x16x32_bf16 v[82:85], v[170:173], v[204:207], v[82:85]
	v_mfma_f32_16x16x32_bf16 v[78:81], v[180:183], v[196:199], v[78:81]
	v_mfma_f32_16x16x32_bf16 v[74:77], v[180:183], v[204:207], v[74:77]
	v_mfma_f32_16x16x32_bf16 v[70:73], v[188:191], v[196:199], v[70:73]
	v_mfma_f32_16x16x32_bf16 v[66:69], v[188:191], v[204:207], v[66:69]
	s_setprio 0
	s_barrier
	ds_read_b128 v[158:161], v138 offset:16384
	ds_read_b128 v[162:165], v138 offset:17408
	ds_read_b128 v[166:169], v138 offset:18432
	ds_read_b128 v[170:173], v138 offset:19456
	ds_read_b128 v[174:177], v138 offset:20480
	ds_read_b128 v[180:183], v138 offset:21504
	ds_read_b128 v[184:187], v138 offset:22528
	ds_read_b128 v[188:191], v138 offset:23552
	s_add_u32 s22, s8, s4
	s_addc_u32 s24, s9, s5
	s_add_u32 s20, s22, 0x100
	s_addc_u32 s21, s24, 0
	s_mov_b32 m0, s11
	s_nop 0
	global_load_lds_dwordx4 v140, s[20:21]
	s_add_i32 s25, s11, 0x2000
	s_mov_b32 m0, s25
	s_nop 0
	global_load_lds_dwordx4 v139, s[20:21]
	s_barrier
	s_waitcnt lgkmcnt(0)
	s_setprio 1
	s_waitcnt lgkmcnt(7)
	v_mfma_f32_16x16x32_bf16 v[62:65], v[158:161], v[142:145], v[62:65]
	v_mfma_f32_16x16x32_bf16 v[58:61], v[158:161], v[150:153], v[58:61]
	s_waitcnt lgkmcnt(5)
	v_mfma_f32_16x16x32_bf16 v[54:57], v[166:169], v[142:145], v[54:57]
	v_mfma_f32_16x16x32_bf16 v[50:53], v[166:169], v[150:153], v[50:53]
	s_waitcnt lgkmcnt(3)
	v_mfma_f32_16x16x32_bf16 v[46:49], v[174:177], v[142:145], v[46:49]
	v_mfma_f32_16x16x32_bf16 v[42:45], v[174:177], v[150:153], v[42:45]
	s_waitcnt lgkmcnt(1)
	v_mfma_f32_16x16x32_bf16 v[38:41], v[184:187], v[142:145], v[38:41]
	v_mfma_f32_16x16x32_bf16 v[34:37], v[184:187], v[150:153], v[34:37]
	v_mfma_f32_16x16x32_bf16 v[62:65], v[162:165], v[146:149], v[62:65]
	v_mfma_f32_16x16x32_bf16 v[58:61], v[162:165], v[154:157], v[58:61]
	v_mfma_f32_16x16x32_bf16 v[54:57], v[170:173], v[146:149], v[54:57]
	v_mfma_f32_16x16x32_bf16 v[50:53], v[170:173], v[154:157], v[50:53]
	v_mfma_f32_16x16x32_bf16 v[46:49], v[180:183], v[146:149], v[46:49]
	v_mfma_f32_16x16x32_bf16 v[42:45], v[180:183], v[154:157], v[42:45]
	s_waitcnt lgkmcnt(0)
	v_mfma_f32_16x16x32_bf16 v[38:41], v[188:191], v[146:149], v[38:41]
	v_mfma_f32_16x16x32_bf16 v[34:37], v[188:191], v[154:157], v[34:37]
	s_setprio 0
	s_barrier
; #define WAIT_V(n) asm volatile("s_waitcnt vmcnt(" #n ")" ::: "memory")
; #define WAIT_L(n) asm volatile("s_waitcnt lgkmcnt(" #n ")" ::: "memory")
; #define BAR __builtin_amdgcn_s_barrier()
; #define SCHED __builtin_amdgcn_sched_barrier(0)
; #define STG_A(b, h, kt) stage_half_s(lds0 + ((b) * 2 + (h)) * HT_B, ((h) ? A1 : Ap) + (kt) * BK, off0, off1)
; #define STG_B(b, h, kt) stage_half_s(lds0 + (4 + (b) * 2 + (h)) * HT_B, ((h) ? B1p : Bp) + (kt) * BK, off0, off1)
; #define STG_A(b, h, kt) stage_half_s(lds0 + ((b) * 2 + (h)) * HT_B, ((h) ? A1 : Ap) + (kt) * BK, off0, off1)
; #define STG_B(b, h, kt) stage_half_s(lds0 + (4 + (b) * 2 + (h)) * HT_B, ((h) ? B1p : Bp) + (kt) * BK, off0, off1)
; #define LDA8(b, h) _Pragma("unroll") for (int m = 0; m < 4; ++m) _Pragma("unroll") for (int k = 0; k < 2; ++k) \
;     At[m][k] = *(const bf16x8*)(SA_(shm, b, h) + abase + (m * 2 + k) * 1024)
; #define LDB8(dst, b, h) _Pragma("unroll") for (int n = 0; n < 2; ++n) _Pragma("unroll") for (int k = 0; k < 2; ++k) \
;     dst[n][k] = *(const bf16x8*)(SB_(shm, b, h) + bbase + (n * 2 + k) * 1024)
; #define MMA8(ai, bj, Bx) do { __builtin_amdgcn_s_setprio(1); \
;     _Pragma("unroll") for (int m = 0; m < 4; ++m) _Pragma("unroll") for (int n = 0; n < 2; ++n) _Pragma("unroll") for (int k = 0; k < 2; ++k) \
;       acc[ai][bj][m][n] = __builtin_amdgcn_mfma_f32_16x16x32_bf16(At[m][k], Bx[n][k], acc[ai][bj][m][n], 0, 0, 0); \
;     __builtin_amdgcn_s_setprio(0); } while (0)
; template <bool HS>
; __device__ __forceinline__ void gemm_tile8(const u16* __restrict__ Ap, const u16* __restrict__ Bp, int K,
;                                            f32x4 (&acc)[2][2][4][2], char* shm, const int tid, const float* hsr = nullptr) {
;     ...
;     STG_B(0, 1, t + 2);
;     WAIT_V(6); BAR; MMA8(1, 1, B1); BAR;
;     LDB8(B0, 1, 0); SCHED; LDA8(1, 0); STG_A(0, 1, t + 2);
;     WAIT_L(8); BAR; WAIT_L(0); MMA8(0, 0, B0); BAR; SCHED;
;     LDB8(B1, 1, 1); STG_B(1, 0, t + 3);
;     BAR; WAIT_L(0); MMA8(0, 1, B1); BAR;
	v_lshl_add_u64 v[210:211], v[132:133], 0, s[4:5]
	v_lshl_add_u64 v[142:143], v[210:211], 0, s[78:79]
	s_add_i32 s23, s10, s23
	v_readfirstlane_b32 s21, v143
	v_readfirstlane_b32 s20, v142
	s_mov_b32 m0, s23
	s_nop 3
	global_load_lds_dwordx4 v140, s[20:21]
	s_add_i32 s23, s11, 0x16000
	s_mov_b32 m0, s23
	s_nop 0
	global_load_lds_dwordx4 v139, s[20:21]
	s_waitcnt vmcnt(6)
	s_barrier
	s_setprio 1
	v_mfma_f32_16x16x32_bf16 v[30:33], v[158:161], v[192:195], v[30:33]
	v_mfma_f32_16x16x32_bf16 v[26:29], v[158:161], v[200:203], v[26:29]
	v_mfma_f32_16x16x32_bf16 v[22:25], v[166:169], v[192:195], v[22:25]
	v_mfma_f32_16x16x32_bf16 v[18:21], v[166:169], v[200:203], v[18:21]
	v_mfma_f32_16x16x32_bf16 v[14:17], v[174:177], v[192:195], v[14:17]
	v_mfma_f32_16x16x32_bf16 v[10:13], v[174:177], v[200:203], v[10:13]
	v_mfma_f32_16x16x32_bf16 v[6:9], v[184:187], v[192:195], v[6:9]
	v_mfma_f32_16x16x32_bf16 v[2:5], v[184:187], v[200:203], v[2:5]
	v_mfma_f32_16x16x32_bf16 v[30:33], v[162:165], v[196:199], v[30:33]
	v_mfma_f32_16x16x32_bf16 v[26:29], v[162:165], v[204:207], v[26:29]
	v_mfma_f32_16x16x32_bf16 v[22:25], v[170:173], v[196:199], v[22:25]
	v_mfma_f32_16x16x32_bf16 v[18:21], v[170:173], v[204:207], v[18:21]
	v_mfma_f32_16x16x32_bf16 v[14:17], v[180:183], v[196:199], v[14:17]
	v_mfma_f32_16x16x32_bf16 v[10:13], v[180:183], v[204:207], v[10:13]
	v_mfma_f32_16x16x32_bf16 v[6:9], v[188:191], v[196:199], v[6:9]
	v_mfma_f32_16x16x32_bf16 v[2:5], v[188:191], v[204:207], v[2:5]
	s_setprio 0
	s_add_i32 s23, 0, 0x18000
	v_add_u32_e32 v154, s23, v141
	s_barrier
	ds_read_b128 v[142:145], v154
	ds_read_b128 v[146:149], v154 offset:1024
	ds_read_b128 v[150:153], v154 offset:2048
	ds_read_b128 v[154:157], v154 offset:3072
	ds_read_b128 v[158:161], v138 offset:32768
	ds_read_b128 v[162:165], v138 offset:33792
	ds_read_b128 v[166:169], v138 offset:34816
	ds_read_b128 v[170:173], v138 offset:35840
	ds_read_b128 v[174:177], v138 offset:36864
	ds_read_b128 v[180:183], v138 offset:37888
	ds_read_b128 v[184:187], v138 offset:38912
	ds_read_b128 v[188:191], v138 offset:39936
	s_add_u32 s20, s13, s4
	s_addc_u32 s21, s14, s5
	s_add_i32 s25, s11, 0x4000
	s_mov_b32 m0, s25
	s_nop 0
	global_load_lds_dwordx4 v140, s[20:21]
	s_add_i32 s25, s11, 0x6000
	s_mov_b32 m0, s25
	s_nop 0
	global_load_lds_dwordx4 v139, s[20:21]
	s_waitcnt lgkmcnt(8)
	s_barrier
	s_waitcnt lgkmcnt(0)
	s_setprio 1
	s_waitcnt lgkmcnt(7)
	v_mfma_f32_16x16x32_bf16 v[126:129], v[158:161], v[142:145], v[126:129]
	v_mfma_f32_16x16x32_bf16 v[122:125], v[158:161], v[150:153], v[122:125]
	s_waitcnt lgkmcnt(5)
	v_mfma_f32_16x16x32_bf16 v[118:121], v[166:169], v[142:145], v[118:121]
	v_mfma_f32_16x16x32_bf16 v[114:117], v[166:169], v[150:153], v[114:117]
	s_waitcnt lgkmcnt(3)
	v_mfma_f32_16x16x32_bf16 v[110:113], v[174:177], v[142:145], v[110:113]
	v_mfma_f32_16x16x32_bf16 v[106:109], v[174:177], v[150:153], v[106:109]
	s_waitcnt lgkmcnt(1)
	v_mfma_f32_16x16x32_bf16 v[102:105], v[184:187], v[142:145], v[102:105]
	v_mfma_f32_16x16x32_bf16 v[98:101], v[184:187], v[150:153], v[98:101]
	v_mfma_f32_16x16x32_bf16 v[126:129], v[162:165], v[146:149], v[126:129]
	v_mfma_f32_16x16x32_bf16 v[122:125], v[162:165], v[154:157], v[122:125]
	v_mfma_f32_16x16x32_bf16 v[118:121], v[170:173], v[146:149], v[118:121]
	v_mfma_f32_16x16x32_bf16 v[114:117], v[170:173], v[154:157], v[114:117]
	v_mfma_f32_16x16x32_bf16 v[110:113], v[180:183], v[146:149], v[110:113]
	v_mfma_f32_16x16x32_bf16 v[106:109], v[180:183], v[154:157], v[106:109]
	s_waitcnt lgkmcnt(0)
	v_mfma_f32_16x16x32_bf16 v[102:105], v[188:191], v[146:149], v[102:105]
	v_mfma_f32_16x16x32_bf16 v[98:101], v[188:191], v[154:157], v[98:101]
	s_setprio 0
	s_barrier
	s_add_i32 s25, 0, 0x1c000
	v_add_u32_e32 v204, s25, v141
	ds_read_b128 v[192:195], v204
	ds_read_b128 v[196:199], v204 offset:1024
	ds_read_b128 v[200:203], v204 offset:2048
	ds_read_b128 v[204:207], v204 offset:3072
	v_lshl_add_u64 v[208:209], v[208:209], 0, s[86:87]
	s_add_i32 s23, s10, s23
	v_readfirstlane_b32 s21, v209
	v_readfirstlane_b32 s20, v208
	s_mov_b32 m0, s23
	s_nop 3
	global_load_lds_dwordx4 v140, s[20:21]
	s_add_i32 s23, s11, 0x1a000
	s_mov_b32 m0, s23
	s_nop 0
	global_load_lds_dwordx4 v139, s[20:21]
	s_barrier
	s_waitcnt lgkmcnt(0)
	s_setprio 1
	s_waitcnt lgkmcnt(3)
	v_mfma_f32_16x16x32_bf16 v[94:97], v[158:161], v[192:195], v[94:97]
	s_waitcnt lgkmcnt(1)
	v_mfma_f32_16x16x32_bf16 v[90:93], v[158:161], v[200:203], v[90:93]
	v_mfma_f32_16x16x32_bf16 v[86:89], v[166:169], v[192:195], v[86:89]
	v_mfma_f32_16x16x32_bf16 v[82:85], v[166:169], v[200:203], v[82:85]
	v_mfma_f32_16x16x32_bf16 v[78:81], v[174:177], v[192:195], v[78:81]
	v_mfma_f32_16x16x32_bf16 v[74:77], v[174:177], v[200:203], v[74:77]
	v_mfma_f32_16x16x32_bf16 v[70:73], v[184:187], v[192:195], v[70:73]
	v_mfma_f32_16x16x32_bf16 v[66:69], v[184:187], v[200:203], v[66:69]
	v_mfma_f32_16x16x32_bf16 v[94:97], v[162:165], v[196:199], v[94:97]
	s_waitcnt lgkmcnt(0)
	v_mfma_f32_16x16x32_bf16 v[90:93], v[162:165], v[204:207], v[90:93]
	v_mfma_f32_16x16x32_bf16 v[86:89], v[170:173], v[196:199], v[86:89]
	v_mfma_f32_16x16x32_bf16 v[82:85], v[170:173], v[204:207], v[82:85]
	v_mfma_f32_16x16x32_bf16 v[78:81], v[180:183], v[196:199], v[78:81]
	v_mfma_f32_16x16x32_bf16 v[74:77], v[180:183], v[204:207], v[74:77]
	v_mfma_f32_16x16x32_bf16 v[70:73], v[188:191], v[196:199], v[70:73]
	v_mfma_f32_16x16x32_bf16 v[66:69], v[188:191], v[204:207], v[66:69]
	s_setprio 0
	s_barrier
; #define WAIT_V(n) asm volatile("s_waitcnt vmcnt(" #n ")" ::: "memory")
; #define WAIT_L(n) asm volatile("s_waitcnt lgkmcnt(" #n ")" ::: "memory")
; #define BAR __builtin_amdgcn_s_barrier()
; #define SCHED __builtin_amdgcn_sched_barrier(0)
; #define STG_A(b, h, kt) stage_half_s(lds0 + ((b) * 2 + (h)) * HT_B, ((h) ? A1 : Ap) + (kt) * BK, off0, off1)
; #define STG_B(b, h, kt) stage_half_s(lds0 + (4 + (b) * 2 + (h)) * HT_B, ((h) ? B1p : Bp) + (kt) * BK, off0, off1)
; #define STG_A(b, h, kt) stage_half_s(lds0 + ((b) * 2 + (h)) * HT_B, ((h) ? A1 : Ap) + (kt) * BK, off0, off1)
; #define STG_B(b, h, kt) stage_half_s(lds0 + (4 + (b) * 2 + (h)) * HT_B, ((h) ? B1p : Bp) + (kt) * BK, off0, off1)
; #define LDA8(b, h) _Pragma("unroll") for (int m = 0; m < 4; ++m) _Pragma("unroll") for (int k = 0; k < 2; ++k) \
;     At[m][k] = *(const bf16x8*)(SA_(shm, b, h) + abase + (m * 2 + k) * 1024)
; #define LDB8(dst, b, h) _Pragma("unroll") for (int n = 0; n < 2; ++n) _Pragma("unroll") for (int k = 0; k < 2; ++k) \
;     dst[n][k] = *(const bf16x8*)(SB_(shm, b, h) + bbase + (n * 2 + k) * 1024)
; #define MMA8(ai, bj, Bx) do { __builtin_amdgcn_s_setprio(1); \
;     _Pragma("unroll") for (int m = 0; m < 4; ++m) _Pragma("unroll") for (int n = 0; n < 2; ++n) _Pragma("unroll") for (int k = 0; k < 2; ++k) \
;       acc[ai][bj][m][n] = __builtin_amdgcn_mfma_f32_16x16x32_bf16(At[m][k], Bx[n][k], acc[ai][bj][m][n], 0, 0, 0); \
;     __builtin_amdgcn_s_setprio(0); } while (0)
; template <bool HS>
; __device__ __forceinline__ void gemm_tile8(const u16* __restrict__ Ap, const u16* __restrict__ Bp, int K,
;                                            f32x4 (&acc)[2][2][4][2], char* shm, const int tid, const float* hsr = nullptr) {
;     ...
;     LDA8(1, 1); STG_A(1, 0, t + 3);
;     BAR; WAIT_L(0); MMA8(1, 0, B0); BAR; SCHED;
;     STG_B(1, 1, t + 3);
;     WAIT_V(6); BAR; MMA8(1, 1, B1); BAR;
;   }
;   { LDB8(B0, 0, 0); LDA8(0, 0); STG_A(1, 1, nt - 1);
;     BAR; WAIT_L(0); MMA8(0, 0, B0); BAR;
	ds_read_b128 v[158:161], v138 offset:49152
	ds_read_b128 v[162:165], v138 offset:50176
	ds_read_b128 v[166:169], v138 offset:51200
	ds_read_b128 v[170:173], v138 offset:52224
	ds_read_b128 v[174:177], v138 offset:53248
	ds_read_b128 v[180:183], v138 offset:54272
	ds_read_b128 v[184:187], v138 offset:55296
	ds_read_b128 v[188:191], v138 offset:56320
	s_add_u32 s20, s22, 0x180
	s_addc_u32 s21, s24, 0
	s_add_i32 s22, s11, 0x8000
	s_mov_b32 m0, s22
	s_nop 0
	global_load_lds_dwordx4 v140, s[20:21]
	s_add_i32 s22, s11, 0xa000
	s_mov_b32 m0, s22
	s_nop 0
	global_load_lds_dwordx4 v139, s[20:21]
	s_barrier
	s_waitcnt lgkmcnt(0)
	s_setprio 1
	s_waitcnt lgkmcnt(7)
	v_mfma_f32_16x16x32_bf16 v[62:65], v[158:161], v[142:145], v[62:65]
	v_mfma_f32_16x16x32_bf16 v[58:61], v[158:161], v[150:153], v[58:61]
	s_waitcnt lgkmcnt(5)
	v_mfma_f32_16x16x32_bf16 v[54:57], v[166:169], v[142:145], v[54:57]
	v_mfma_f32_16x16x32_bf16 v[50:53], v[166:169], v[150:153], v[50:53]
	s_waitcnt lgkmcnt(3)
	v_mfma_f32_16x16x32_bf16 v[46:49], v[174:177], v[142:145], v[46:49]
	v_mfma_f32_16x16x32_bf16 v[42:45], v[174:177], v[150:153], v[42:45]
	s_waitcnt lgkmcnt(1)
	v_mfma_f32_16x16x32_bf16 v[38:41], v[184:187], v[142:145], v[38:41]
	v_mfma_f32_16x16x32_bf16 v[34:37], v[184:187], v[150:153], v[34:37]
	v_mfma_f32_16x16x32_bf16 v[62:65], v[162:165], v[146:149], v[62:65]
	v_mfma_f32_16x16x32_bf16 v[58:61], v[162:165], v[154:157], v[58:61]
	v_mfma_f32_16x16x32_bf16 v[54:57], v[170:173], v[146:149], v[54:57]
	v_mfma_f32_16x16x32_bf16 v[50:53], v[170:173], v[154:157], v[50:53]
	v_mfma_f32_16x16x32_bf16 v[46:49], v[180:183], v[146:149], v[46:49]
	v_mfma_f32_16x16x32_bf16 v[42:45], v[180:183], v[154:157], v[42:45]
	s_waitcnt lgkmcnt(0)
	v_mfma_f32_16x16x32_bf16 v[38:41], v[188:191], v[146:149], v[38:41]
	v_mfma_f32_16x16x32_bf16 v[34:37], v[188:191], v[154:157], v[34:37]
	s_setprio 0
	s_barrier
	v_lshl_add_u64 v[142:143], v[210:211], 0, s[86:87]
	s_add_i32 s22, s10, s25
	v_readfirstlane_b32 s21, v143
	v_readfirstlane_b32 s20, v142
	s_mov_b32 m0, s22
	s_nop 3
	global_load_lds_dwordx4 v140, s[20:21]
	s_add_i32 s22, s11, 0x1e000
	s_mov_b32 m0, s22
	s_nop 0
	global_load_lds_dwordx4 v139, s[20:21]
	s_waitcnt vmcnt(6)
	s_barrier
	s_setprio 1
	v_mfma_f32_16x16x32_bf16 v[30:33], v[158:161], v[192:195], v[30:33]
	v_mfma_f32_16x16x32_bf16 v[26:29], v[158:161], v[200:203], v[26:29]
	v_mfma_f32_16x16x32_bf16 v[22:25], v[166:169], v[192:195], v[22:25]
	v_mfma_f32_16x16x32_bf16 v[18:21], v[166:169], v[200:203], v[18:21]
	v_mfma_f32_16x16x32_bf16 v[14:17], v[174:177], v[192:195], v[14:17]
	v_mfma_f32_16x16x32_bf16 v[10:13], v[174:177], v[200:203], v[10:13]
	v_mfma_f32_16x16x32_bf16 v[6:9], v[184:187], v[192:195], v[6:9]
	v_mfma_f32_16x16x32_bf16 v[2:5], v[184:187], v[200:203], v[2:5]
	v_mfma_f32_16x16x32_bf16 v[30:33], v[162:165], v[196:199], v[30:33]
	v_mfma_f32_16x16x32_bf16 v[26:29], v[162:165], v[204:207], v[26:29]
	v_mfma_f32_16x16x32_bf16 v[22:25], v[170:173], v[196:199], v[22:25]
	v_mfma_f32_16x16x32_bf16 v[18:21], v[170:173], v[204:207], v[18:21]
	v_mfma_f32_16x16x32_bf16 v[14:17], v[180:183], v[196:199], v[14:17]
	v_mfma_f32_16x16x32_bf16 v[10:13], v[180:183], v[204:207], v[10:13]
	v_mfma_f32_16x16x32_bf16 v[6:9], v[188:191], v[196:199], v[6:9]
	v_mfma_f32_16x16x32_bf16 v[2:5], v[188:191], v[204:207], v[2:5]
	s_setprio 0
	s_add_i32 s17, s17, 2
	s_add_u32 s4, s4, 0x100
	s_addc_u32 s5, s5, 0
	s_cmp_lt_u32 s17, 12
	s_barrier
	s_cbranch_scc1 .LBB0_318
	v_add_u32_e32 v220, 0, v141
	v_add_u32_e32 v141, 0x10000, v220
	ds_read_b128 v[130:133], v141
	ds_read_b128 v[142:145], v141 offset:1024
	ds_read_b128 v[146:149], v141 offset:2048
	ds_read_b128 v[150:153], v141 offset:3072
	ds_read_b128 v[154:157], v138
	ds_read_b128 v[158:161], v138 offset:1024
	ds_read_b128 v[162:165], v138 offset:2048
	ds_read_b128 v[166:169], v138 offset:3072
	ds_read_b128 v[170:173], v138 offset:4096
	ds_read_b128 v[174:177], v138 offset:5120
	ds_read_b128 v[180:183], v138 offset:6144
	ds_read_b128 v[184:187], v138 offset:7168
	s_add_u32 s4, s8, 0x40780
	s_addc_u32 s5, s9, 0
	s_mov_b32 m0, s18
	s_nop 0
	global_load_lds_dwordx4 v140, s[4:5]
	s_nop 0
	s_mov_b32 m0, s19
	s_nop 0
	global_load_lds_dwordx4 v139, s[4:5]
	s_barrier
	s_waitcnt lgkmcnt(0)
	s_setprio 1
	s_waitcnt lgkmcnt(7)
	v_mfma_f32_16x16x32_bf16 v[126:129], v[154:157], v[130:133], v[126:129]
	v_mfma_f32_16x16x32_bf16 v[122:125], v[154:157], v[146:149], v[122:125]
	s_waitcnt lgkmcnt(3)
	v_mfma_f32_16x16x32_bf16 v[110:113], v[170:173], v[130:133], v[110:113]
	v_mfma_f32_16x16x32_bf16 v[106:109], v[170:173], v[146:149], v[106:109]
	v_mfma_f32_16x16x32_bf16 v[126:129], v[158:161], v[142:145], v[126:129]
	v_mfma_f32_16x16x32_bf16 v[122:125], v[158:161], v[150:153], v[122:125]
	v_mfma_f32_16x16x32_bf16 v[118:121], v[162:165], v[130:133], v[118:121]
	v_mfma_f32_16x16x32_bf16 v[114:117], v[162:165], v[146:149], v[114:117]
	s_waitcnt lgkmcnt(2)
	v_mfma_f32_16x16x32_bf16 v[110:113], v[174:177], v[142:145], v[110:113]
	v_mfma_f32_16x16x32_bf16 v[106:109], v[174:177], v[150:153], v[106:109]
	s_waitcnt lgkmcnt(1)
	v_mfma_f32_16x16x32_bf16 v[102:105], v[180:183], v[130:133], v[102:105]
	v_mfma_f32_16x16x32_bf16 v[98:101], v[180:183], v[146:149], v[98:101]
	v_mfma_f32_16x16x32_bf16 v[188:191], v[166:169], v[142:145], v[118:121]
	v_mfma_f32_16x16x32_bf16 v[192:195], v[166:169], v[150:153], v[114:117]
	s_waitcnt lgkmcnt(0)
	v_mfma_f32_16x16x32_bf16 v[196:199], v[184:187], v[142:145], v[102:105]
	v_mfma_f32_16x16x32_bf16 v[200:203], v[184:187], v[150:153], v[98:101]
	s_setprio 0
	v_add_u32_e32 v118, 0x14000, v220
	s_barrier
; #define WAIT_V(n) asm volatile("s_waitcnt vmcnt(" #n ")" ::: "memory")
; #define WAIT_L(n) asm volatile("s_waitcnt lgkmcnt(" #n ")" ::: "memory")
; #define BAR __builtin_amdgcn_s_barrier()
; #define LDA8(b, h) _Pragma("unroll") for (int m = 0; m < 4; ++m) _Pragma("unroll") for (int k = 0; k < 2; ++k) \
;     At[m][k] = *(const bf16x8*)(SA_(shm, b, h) + abase + (m * 2 + k) * 1024)
; #define LDB8(dst, b, h) _Pragma("unroll") for (int n = 0; n < 2; ++n) _Pragma("unroll") for (int k = 0; k < 2; ++k) \
;     dst[n][k] = *(const bf16x8*)(SB_(shm, b, h) + bbase + (n * 2 + k) * 1024)
; #define MMA8(ai, bj, Bx) do { __builtin_amdgcn_s_setprio(1); \
;     _Pragma("unroll") for (int m = 0; m < 4; ++m) _Pragma("unroll") for (int n = 0; n < 2; ++n) _Pragma("unroll") for (int k = 0; k < 2; ++k) \
;       acc[ai][bj][m][n] = __builtin_amdgcn_mfma_f32_16x16x32_bf16(At[m][k], Bx[n][k], acc[ai][bj][m][n], 0, 0, 0); \
;     __builtin_amdgcn_s_setprio(0); } while (0)
; template <bool HS>
; __device__ __forceinline__ void gemm_tile8(const u16* __restrict__ Ap, const u16* __restrict__ Bp, int K,
;                                            f32x4 (&acc)[2][2][4][2], char* shm, const int tid, const float* hsr = nullptr) {
;     ...
;     LDB8(B1, 0, 1); BAR; WAIT_L(0); MMA8(0, 1, B1); BAR;
;     LDA8(0, 1); WAIT_V(4); BAR; WAIT_L(0); MMA8(1, 0, B0); MMA8(1, 1, B1); BAR; }
;   { LDB8(B0, 1, 0); LDA8(1, 0); WAIT_V(2); BAR; WAIT_L(0); MMA8(0, 0, B0); BAR;
	ds_read_b128 v[98:101], v118
	ds_read_b128 v[102:105], v118 offset:1024
	ds_read_b128 v[114:117], v118 offset:2048
	ds_read_b128 v[118:121], v118 offset:3072
	s_barrier
	s_waitcnt lgkmcnt(0)
	s_setprio 1
	s_waitcnt lgkmcnt(3)
	v_mfma_f32_16x16x32_bf16 v[94:97], v[154:157], v[98:101], v[94:97]
	s_waitcnt lgkmcnt(1)
	v_mfma_f32_16x16x32_bf16 v[90:93], v[154:157], v[114:117], v[90:93]
	v_mfma_f32_16x16x32_bf16 v[78:81], v[170:173], v[98:101], v[78:81]
	v_mfma_f32_16x16x32_bf16 v[74:77], v[170:173], v[114:117], v[74:77]
	v_mfma_f32_16x16x32_bf16 v[94:97], v[158:161], v[102:105], v[94:97]
	s_waitcnt lgkmcnt(0)
	v_mfma_f32_16x16x32_bf16 v[90:93], v[158:161], v[118:121], v[90:93]
	v_mfma_f32_16x16x32_bf16 v[86:89], v[162:165], v[98:101], v[86:89]
	v_mfma_f32_16x16x32_bf16 v[82:85], v[162:165], v[114:117], v[82:85]
	v_mfma_f32_16x16x32_bf16 v[78:81], v[174:177], v[102:105], v[78:81]
	v_mfma_f32_16x16x32_bf16 v[74:77], v[174:177], v[118:121], v[74:77]
	v_mfma_f32_16x16x32_bf16 v[70:73], v[180:183], v[98:101], v[70:73]
	v_mfma_f32_16x16x32_bf16 v[66:69], v[180:183], v[114:117], v[66:69]
	v_mfma_f32_16x16x32_bf16 v[154:157], v[166:169], v[102:105], v[86:89]
	v_mfma_f32_16x16x32_bf16 v[158:161], v[166:169], v[118:121], v[82:85]
	v_mfma_f32_16x16x32_bf16 v[162:165], v[184:187], v[102:105], v[70:73]
	v_mfma_f32_16x16x32_bf16 v[166:169], v[184:187], v[118:121], v[66:69]
	s_setprio 0
	s_barrier
	s_nop 1
	ds_read_b128 v[66:69], v138 offset:16384
	ds_read_b128 v[70:73], v138 offset:17408
	ds_read_b128 v[82:85], v138 offset:18432
	ds_read_b128 v[86:89], v138 offset:19456
	ds_read_b128 v[170:173], v138 offset:20480
	ds_read_b128 v[174:177], v138 offset:21504
	ds_read_b128 v[180:183], v138 offset:22528
	ds_read_b128 v[184:187], v138 offset:23552
	s_waitcnt vmcnt(4)
	s_barrier
	s_waitcnt lgkmcnt(0)
	s_setprio 1
	s_waitcnt lgkmcnt(7)
	v_mfma_f32_16x16x32_bf16 v[62:65], v[66:69], v[130:133], v[62:65]
	s_waitcnt lgkmcnt(5)
	v_mfma_f32_16x16x32_bf16 v[54:57], v[82:85], v[130:133], v[54:57]
	s_waitcnt lgkmcnt(3)
	v_mfma_f32_16x16x32_bf16 v[46:49], v[170:173], v[130:133], v[46:49]
	s_waitcnt lgkmcnt(1)
	v_mfma_f32_16x16x32_bf16 v[38:41], v[180:183], v[130:133], v[38:41]
	v_mfma_f32_16x16x32_bf16 v[62:65], v[70:73], v[142:145], v[62:65]
	v_mfma_f32_16x16x32_bf16 v[58:61], v[66:69], v[146:149], v[58:61]
	v_mfma_f32_16x16x32_bf16 v[54:57], v[86:89], v[142:145], v[54:57]
	v_mfma_f32_16x16x32_bf16 v[50:53], v[82:85], v[146:149], v[50:53]
	v_mfma_f32_16x16x32_bf16 v[46:49], v[174:177], v[142:145], v[46:49]
	v_mfma_f32_16x16x32_bf16 v[42:45], v[170:173], v[146:149], v[42:45]
	s_waitcnt lgkmcnt(0)
	v_mfma_f32_16x16x32_bf16 v[38:41], v[184:187], v[142:145], v[38:41]
	v_mfma_f32_16x16x32_bf16 v[34:37], v[180:183], v[146:149], v[34:37]
	v_mfma_f32_16x16x32_bf16 v[204:207], v[70:73], v[150:153], v[58:61]
	v_mfma_f32_16x16x32_bf16 v[208:211], v[86:89], v[150:153], v[50:53]
	v_mfma_f32_16x16x32_bf16 v[212:215], v[174:177], v[150:153], v[42:45]
	v_mfma_f32_16x16x32_bf16 v[130:133], v[184:187], v[150:153], v[34:37]
	s_setprio 0
	s_setprio 1
	v_mfma_f32_16x16x32_bf16 v[30:33], v[66:69], v[98:101], v[30:33]
	v_mfma_f32_16x16x32_bf16 v[22:25], v[82:85], v[98:101], v[22:25]
	v_mfma_f32_16x16x32_bf16 v[14:17], v[170:173], v[98:101], v[14:17]
	v_mfma_f32_16x16x32_bf16 v[6:9], v[180:183], v[98:101], v[6:9]
	v_mfma_f32_16x16x32_bf16 v[30:33], v[70:73], v[102:105], v[30:33]
	v_mfma_f32_16x16x32_bf16 v[26:29], v[66:69], v[114:117], v[26:29]
	v_mfma_f32_16x16x32_bf16 v[22:25], v[86:89], v[102:105], v[22:25]
	v_mfma_f32_16x16x32_bf16 v[18:21], v[82:85], v[114:117], v[18:21]
	v_mfma_f32_16x16x32_bf16 v[14:17], v[174:177], v[102:105], v[14:17]
	v_mfma_f32_16x16x32_bf16 v[10:13], v[170:173], v[114:117], v[10:13]
	v_mfma_f32_16x16x32_bf16 v[6:9], v[184:187], v[102:105], v[6:9]
	v_mfma_f32_16x16x32_bf16 v[2:5], v[180:183], v[114:117], v[2:5]
	v_mfma_f32_16x16x32_bf16 v[140:143], v[70:73], v[118:121], v[26:29]
	v_mfma_f32_16x16x32_bf16 v[144:147], v[86:89], v[118:121], v[18:21]
	v_mfma_f32_16x16x32_bf16 v[148:151], v[174:177], v[118:121], v[10:13]
	v_mfma_f32_16x16x32_bf16 v[170:173], v[184:187], v[118:121], v[2:5]
	s_setprio 0
	v_add_u32_e32 v18, 0x18000, v220
	s_barrier
	s_nop 0
	ds_read_b128 v[2:5], v18
	ds_read_b128 v[10:13], v18 offset:1024
	ds_read_b128 v[174:177], v18 offset:2048
	ds_read_b128 v[180:183], v18 offset:3072
	ds_read_b128 v[18:21], v138 offset:32768
	ds_read_b128 v[26:29], v138 offset:33792
	ds_read_b128 v[34:37], v138 offset:34816
	ds_read_b128 v[42:45], v138 offset:35840
	ds_read_b128 v[50:53], v138 offset:36864
	ds_read_b128 v[58:61], v138 offset:37888
	ds_read_b128 v[184:187], v138 offset:38912
	ds_read_b128 v[216:219], v138 offset:39936
	s_waitcnt vmcnt(2)
	s_barrier
	s_waitcnt lgkmcnt(0)
	s_setprio 1
	s_waitcnt lgkmcnt(7)
	v_mfma_f32_16x16x32_bf16 v[66:69], v[18:21], v[2:5], v[126:129]
	s_waitcnt lgkmcnt(6)
	v_mfma_f32_16x16x32_bf16 v[118:121], v[26:29], v[10:13], v[66:69]
	v_mfma_f32_16x16x32_bf16 v[66:69], v[18:21], v[174:177], v[122:125]
	v_mfma_f32_16x16x32_bf16 v[114:117], v[26:29], v[180:183], v[66:69]
	s_waitcnt lgkmcnt(5)
	v_mfma_f32_16x16x32_bf16 v[66:69], v[34:37], v[2:5], v[188:191]
	s_waitcnt lgkmcnt(4)
	v_mfma_f32_16x16x32_bf16 v[102:105], v[42:45], v[10:13], v[66:69]
	v_mfma_f32_16x16x32_bf16 v[66:69], v[34:37], v[174:177], v[192:195]
	v_mfma_f32_16x16x32_bf16 v[98:101], v[42:45], v[180:183], v[66:69]
	s_waitcnt lgkmcnt(3)
	v_mfma_f32_16x16x32_bf16 v[66:69], v[50:53], v[2:5], v[110:113]
	s_waitcnt lgkmcnt(2)
	v_mfma_f32_16x16x32_bf16 v[86:89], v[58:61], v[10:13], v[66:69]
	v_mfma_f32_16x16x32_bf16 v[66:69], v[50:53], v[174:177], v[106:109]
	v_mfma_f32_16x16x32_bf16 v[82:85], v[58:61], v[180:183], v[66:69]
	s_waitcnt lgkmcnt(1)
	v_mfma_f32_16x16x32_bf16 v[66:69], v[184:187], v[2:5], v[196:199]
	s_waitcnt lgkmcnt(0)
	v_mfma_f32_16x16x32_bf16 v[70:73], v[216:219], v[10:13], v[66:69]
	v_mfma_f32_16x16x32_bf16 v[66:69], v[184:187], v[174:177], v[200:203]
	v_mfma_f32_16x16x32_bf16 v[66:69], v[216:219], v[180:183], v[66:69]
	s_setprio 0
	v_add_u32_e32 v106, 0x1c000, v220
	s_barrier
; #define WAIT_V(n) asm volatile("s_waitcnt vmcnt(" #n ")" ::: "memory")
; #define WAIT_L(n) asm volatile("s_waitcnt lgkmcnt(" #n ")" ::: "memory")
; #define BAR __builtin_amdgcn_s_barrier()
; #define LDA8(b, h) _Pragma("unroll") for (int m = 0; m < 4; ++m) _Pragma("unroll") for (int k = 0; k < 2; ++k) \
;     At[m][k] = *(const bf16x8*)(SA_(shm, b, h) + abase + (m * 2 + k) * 1024)
; #define LDB8(dst, b, h) _Pragma("unroll") for (int n = 0; n < 2; ++n) _Pragma("unroll") for (int k = 0; k < 2; ++k) \
;     dst[n][k] = *(const bf16x8*)(SB_(shm, b, h) + bbase + (n * 2 + k) * 1024)
; #define MMA8(ai, bj, Bx) do { __builtin_amdgcn_s_setprio(1); \
;     _Pragma("unroll") for (int m = 0; m < 4; ++m) _Pragma("unroll") for (int n = 0; n < 2; ++n) _Pragma("unroll") for (int k = 0; k < 2; ++k) \
;       acc[ai][bj][m][n] = __builtin_amdgcn_mfma_f32_16x16x32_bf16(At[m][k], Bx[n][k], acc[ai][bj][m][n], 0, 0, 0); \
;     __builtin_amdgcn_s_setprio(0); } while (0)
; template <bool HS>
; __device__ __forceinline__ void gemm_tile8(const u16* __restrict__ Ap, const u16* __restrict__ Bp, int K,
;                                            f32x4 (&acc)[2][2][4][2], char* shm, const int tid, const float* hsr = nullptr) {
;     ...
;     LDB8(B1, 1, 1); WAIT_V(0); BAR; WAIT_L(0); MMA8(0, 1, B1); BAR;
;     LDA8(1, 1); BAR; WAIT_L(0); MMA8(1, 0, B0); MMA8(1, 1, B1); BAR; }
;   if (wr == 0) BAR;
	ds_read_b128 v[188:191], v106
	ds_read_b128 v[192:195], v106 offset:1024
	ds_read_b128 v[196:199], v106 offset:2048
	ds_read_b128 v[200:203], v106 offset:3072
	s_waitcnt vmcnt(0)
	s_barrier
	s_waitcnt lgkmcnt(0)
	s_setprio 1
	s_waitcnt lgkmcnt(3)
	v_mfma_f32_16x16x32_bf16 v[94:97], v[18:21], v[188:191], v[94:97]
	s_waitcnt lgkmcnt(1)
	v_mfma_f32_16x16x32_bf16 v[18:21], v[18:21], v[196:199], v[90:93]
	s_waitcnt lgkmcnt(0)
	v_mfma_f32_16x16x32_bf16 v[122:125], v[26:29], v[200:203], v[18:21]
	v_mfma_f32_16x16x32_bf16 v[18:21], v[34:37], v[188:191], v[154:157]
	v_mfma_f32_16x16x32_bf16 v[110:113], v[42:45], v[192:195], v[18:21]
	v_mfma_f32_16x16x32_bf16 v[18:21], v[34:37], v[196:199], v[158:161]
	v_mfma_f32_16x16x32_bf16 v[106:109], v[42:45], v[200:203], v[18:21]
	v_mfma_f32_16x16x32_bf16 v[18:21], v[50:53], v[188:191], v[78:81]
	v_mfma_f32_16x16x32_bf16 v[126:129], v[26:29], v[192:195], v[94:97]
	v_mfma_f32_16x16x32_bf16 v[94:97], v[58:61], v[192:195], v[18:21]
	v_mfma_f32_16x16x32_bf16 v[18:21], v[50:53], v[196:199], v[74:77]
	v_mfma_f32_16x16x32_bf16 v[90:93], v[58:61], v[200:203], v[18:21]
	v_mfma_f32_16x16x32_bf16 v[18:21], v[184:187], v[188:191], v[162:165]
	v_mfma_f32_16x16x32_bf16 v[78:81], v[216:219], v[192:195], v[18:21]
	v_mfma_f32_16x16x32_bf16 v[18:21], v[184:187], v[196:199], v[166:169]
	v_mfma_f32_16x16x32_bf16 v[74:77], v[216:219], v[200:203], v[18:21]
	s_setprio 0
	s_barrier
	ds_read_b128 v[152:155], v138 offset:49152
	ds_read_b128 v[156:159], v138 offset:50176
	ds_read_b128 v[160:163], v138 offset:51200
	ds_read_b128 v[164:167], v138 offset:52224
	ds_read_b128 v[184:187], v138 offset:53248
	ds_read_b128 v[216:219], v138 offset:54272
	ds_read_b128 v[220:223], v138 offset:55296
	ds_read_b128 v[224:227], v138 offset:56320
	s_barrier
	s_waitcnt lgkmcnt(0)
	s_setprio 1
	s_waitcnt lgkmcnt(7)
	v_mfma_f32_16x16x32_bf16 v[18:21], v[152:155], v[2:5], v[62:65]
	s_waitcnt lgkmcnt(6)
	v_mfma_f32_16x16x32_bf16 v[58:61], v[156:159], v[10:13], v[18:21]
	v_mfma_f32_16x16x32_bf16 v[18:21], v[152:155], v[174:177], v[204:207]
	v_mfma_f32_16x16x32_bf16 v[50:53], v[156:159], v[180:183], v[18:21]
	s_waitcnt lgkmcnt(5)
	v_mfma_f32_16x16x32_bf16 v[18:21], v[160:163], v[2:5], v[54:57]
	s_waitcnt lgkmcnt(4)
	v_mfma_f32_16x16x32_bf16 v[42:45], v[164:167], v[10:13], v[18:21]
	v_mfma_f32_16x16x32_bf16 v[18:21], v[160:163], v[174:177], v[208:211]
	v_mfma_f32_16x16x32_bf16 v[34:37], v[164:167], v[180:183], v[18:21]
	s_waitcnt lgkmcnt(3)
	v_mfma_f32_16x16x32_bf16 v[18:21], v[184:187], v[2:5], v[46:49]
	s_waitcnt lgkmcnt(1)
	v_mfma_f32_16x16x32_bf16 v[2:5], v[220:223], v[2:5], v[38:41]
	v_mfma_f32_16x16x32_bf16 v[26:29], v[216:219], v[10:13], v[18:21]
	v_mfma_f32_16x16x32_bf16 v[18:21], v[184:187], v[174:177], v[212:215]
	s_waitcnt lgkmcnt(0)
	v_mfma_f32_16x16x32_bf16 v[10:13], v[224:227], v[10:13], v[2:5]
	v_mfma_f32_16x16x32_bf16 v[2:5], v[220:223], v[174:177], v[130:133]
	v_mfma_f32_16x16x32_bf16 v[18:21], v[216:219], v[180:183], v[18:21]
	v_mfma_f32_16x16x32_bf16 v[2:5], v[224:227], v[180:183], v[2:5]
	s_setprio 0
	s_setprio 1
	v_mfma_f32_16x16x32_bf16 v[30:33], v[152:155], v[188:191], v[30:33]
	v_mfma_f32_16x16x32_bf16 v[62:65], v[156:159], v[192:195], v[30:33]
	v_mfma_f32_16x16x32_bf16 v[30:33], v[152:155], v[196:199], v[140:143]
	v_mfma_f32_16x16x32_bf16 v[22:25], v[160:163], v[188:191], v[22:25]
	v_mfma_f32_16x16x32_bf16 v[14:17], v[184:187], v[188:191], v[14:17]
	v_mfma_f32_16x16x32_bf16 v[54:57], v[156:159], v[200:203], v[30:33]
	v_mfma_f32_16x16x32_bf16 v[46:49], v[164:167], v[192:195], v[22:25]
	v_mfma_f32_16x16x32_bf16 v[22:25], v[160:163], v[196:199], v[144:147]
	v_mfma_f32_16x16x32_bf16 v[30:33], v[216:219], v[192:195], v[14:17]
	v_mfma_f32_16x16x32_bf16 v[14:17], v[184:187], v[196:199], v[148:151]
	v_mfma_f32_16x16x32_bf16 v[6:9], v[220:223], v[188:191], v[6:9]
	v_mfma_f32_16x16x32_bf16 v[38:41], v[164:167], v[200:203], v[22:25]
	v_mfma_f32_16x16x32_bf16 v[22:25], v[216:219], v[200:203], v[14:17]
	v_mfma_f32_16x16x32_bf16 v[14:17], v[224:227], v[192:195], v[6:9]
	v_mfma_f32_16x16x32_bf16 v[6:9], v[220:223], v[196:199], v[170:173]
	v_mfma_f32_16x16x32_bf16 v[6:9], v[224:227], v[200:203], v[6:9]
	s_setprio 0
	s_movk_i32 s4, 0x100
	v_cmp_gt_u32_e32 vcc, s4, v0
	s_barrier
	s_and_saveexec_b64 s[4:5], vcc
	s_cbranch_execz .LBB0_321
	s_barrier
; #define STG_A(b, h, kt) stage_half_s(lds0 + ((b) * 2 + (h)) * HT_B, ((h) ? A1 : Ap) + (kt) * BK, off0, off1)
; #define STG_B(b, h, kt) stage_half_s(lds0 + (4 + (b) * 2 + (h)) * HT_B, ((h) ? B1p : Bp) + (kt) * BK, off0, off1)
; #define STG_A(b, h, kt) stage_half_s(lds0 + ((b) * 2 + (h)) * HT_B, ((h) ? A1 : Ap) + (kt) * BK, off0, off1)
; #define STG_B(b, h, kt) stage_half_s(lds0 + (4 + (b) * 2 + (h)) * HT_B, ((h) ? B1p : Bp) + (kt) * BK, off0, off1)
; __device__ __forceinline__ void gemm8_prefetch(const u16* __restrict__ Ap, const u16* __restrict__ Bp, int K, char* shm, const int tid) {
;   int r0, c0, r1, c1;
;   stage_rc(tid * 16, r0, c0);
;   stage_rc(tid * 16 + 8192, r1, c1);
;   const unsigned off0 = (unsigned)(r0 * K + c0) * 2u, off1 = (unsigned)(r1 * K + c1) * 2u;
;   const int wvoff = __builtin_amdgcn_readfirstlane(tid >> 6) * 1024;
;   const u16* A1 = Ap + (size_t)128 * K;
;   const u16* B1p = Bp + (size_t)128 * K;
;   const unsigned lds0 = (unsigned)(size_t)(__attribute__((address_space(3))) char*)shm + (unsigned)wvoff;
;     ...
;   STG_B(0, 0, 0); STG_A(0, 0, 0); STG_B(0, 1, 0); STG_A(0, 1, 0);
;   STG_B(1, 0, 1); STG_A(1, 0, 1); STG_B(1, 1, 1);
;     ...
; }
; template <int EPI, bool HS = false>
; __device__ __forceinline__ void gemm_phase(const Params& p, const GemmCfg& g, char* shm, const int wave_s) {
;     ...
;   auto tile_coords = [&](int tile, int& mt, int& pn, int& arow0, int& orow0) {
;     int wgid = tile;
;     { int q = nwg / 8, r = nwg % 8, xcd = wgid % 8, off = wgid / 8;
;       wgid = (xcd < r ? xcd * (q + 1) : r * (q + 1) + (xcd - r) * q) + off; }
;     int nig = 8 * g.nN, gid = wgid / nig, fm = gid * 8, gsz = (g.nM - fm < 8) ? (g.nM - fm) : 8;
;     mt = fm + ((wgid % nig) % gsz); pn = (wgid % nig) / gsz;
;     if (g.rev) mt = g.nM - 1 - mt;
;     int hrow0 = (mt >> 3) * 4096 + g.hf * 2048 + (mt & 7) * 256;
;     arow0 = g.a_half ? hrow0 : mt * 256;
;     orow0 = g.o_half ? hrow0 : mt * 256;
;   };
;     ...
;     const bool defer_pf = (EPI == EPI_RESID) || (EPI == EPI_RETIN && pn < 8);
;     if (!defer_pf && tile + (int)gridDim.x < nwg) {
;       int mt2, pn2, arow2, orow2;
;       tile_coords(tile + gridDim.x, mt2, pn2, arow2, orow2);
;       gemm8_prefetch(g.A + (size_t)arow2 * g.K, g.Bt + (size_t)pn2 * 256 * g.K, g.K, shm, fresh_tid(wave_s));
;     }
.LBB0_321:
	s_or_b64 exec, exec, s[4:5]
	s_add_i32 s72, s72, s44
	s_cmpk_gt_i32 s72, 0xbff
	s_cselect_b64 s[4:5], -1, 0
	s_and_b64 vcc, exec, s[4:5]
	s_cbranch_vccnz .LBB0_323
	s_ashr_i32 s8, s72, 31
	s_lshr_b32 s8, s8, 29
	s_add_i32 s8, s72, s8
	s_ashr_i32 s9, s8, 3
	s_and_b32 s8, s8, -8
	s_sub_i32 s8, s72, s8
	s_cmp_lt_i32 s8, 0
	s_movk_i32 s10, 0x181
	s_cselect_b32 s10, s10, 0x180
	s_mov_b32 s13, s82
	s_mov_b32 s14, -1
	s_mul_i32 s8, s10, s8
	s_add_i32 s8, s8, s9
	v_mbcnt_lo_u32_b32 v0, s14, 0
	v_mbcnt_hi_u32_b32 v0, s14, v0
	s_mul_hi_i32 s9, s8, 0x2aaaaaab
	v_lshl_add_u32 v0, s13, 6, v0
	s_lshr_b32 s10, s9, 31
	s_ashr_i32 s9, s9, 4
	s_add_i32 s9, s9, s10
	v_bfe_i32 v132, v0, 27, 1
	v_lshlrev_b32_e32 v130, 4, v0
	v_lshrrev_b32_e32 v132, 22, v132
	s_mul_i32 s10, s9, 0x60
	v_add_u32_e32 v132, v130, v132
	s_sub_i32 s10, s8, s10
	v_and_b32_e32 v132, 0xfffffc00, v132
	s_bfe_i32 s8, s10, 0x80000
	v_ashrrev_i32_e32 v131, 31, v0
	v_sub_u32_e32 v132, v130, v132
	s_bfe_u32 s8, s8, 0x3000c
	v_lshrrev_b32_e32 v131, 26, v131
	v_lshrrev_b32_e32 v133, 4, v132
	s_add_i32 s11, s10, s8
	v_add_u32_e32 v131, v0, v131
	v_bitop3_b32 v133, v133, v132, 32 bitop3:0x6c
	v_ashrrev_i32_e32 v132, 31, v132
	s_bfe_i32 s8, s11, 0x80000
	s_and_b32 s11, s11, 0xf8
	v_ashrrev_i32_e32 v131, 6, v131
	v_lshrrev_b32_e32 v132, 26, v132
	s_sub_i32 s10, s10, s11
	v_lshlrev_b32_e32 v138, 3, v131
	v_add_u32_e32 v132, v133, v132
	s_sext_i32_i8 s10, s10
	v_and_b32_e32 v138, 0x1ffff0, v138
	v_ashrrev_i32_e32 v132, 6, v132
	s_lshl_b32 s9, s9, 11
	s_lshl_b32 s10, s10, 8
	v_add_u32_e32 v138, v132, v138
	v_mul_i32_i24_e32 v132, 64, v132
	v_add_u32_e32 v130, 0x2000, v130
	s_add_i32 s10, s10, s9
	v_sub_u32_e32 v132, v133, v132
	v_ashrrev_i32_e32 v133, 31, v130
	s_sext_i32_i16 s8, s8
	s_ashr_i32 s11, s10, 31
	v_lshrrev_b32_e32 v133, 22, v133
	s_lshr_b32 s8, s8, 3
	s_lshl_b64 s[10:11], s[10:11], 11
	v_add_u32_e32 v133, v130, v133
	s_add_u32 s10, s88, s10
	v_ashrrev_i32_e32 v133, 10, v133
	s_addc_u32 s11, s89, s11
	s_bfe_i64 s[8:9], s[8:9], 0x100000
	v_mul_i32_i24_e32 v139, 0x400, v133
	s_lshl_b64 s[8:9], s[8:9], 19
	v_sub_u32_e32 v130, v130, v139
	s_add_u32 s8, s0, s8
	v_lshrrev_b32_e32 v139, 4, v130
	s_addc_u32 s9, s1, s9
	v_bitop3_b32 v130, v139, v130, 32 bitop3:0x6c
	v_ashrrev_i32_e32 v140, 31, v130
	s_add_u32 s14, s10, 0x40000
	v_lshrrev_b32_e32 v140, 26, v140
	s_addc_u32 s15, s11, 0
	v_add_u32_e32 v140, v130, v140
	v_readfirstlane_b32 s13, v0
	s_add_u32 s16, s8, 0x40000
	v_lshlrev_b32_e32 v131, 5, v131
	v_lshlrev_b32_e32 v139, 3, v133
	v_lshrrev_b32_e32 v141, 6, v140
	v_and_b32_e32 v140, 0xc0, v140
	s_addc_u32 s17, s9, 0
	s_lshl_b32 s13, s13, 4
	v_and_b32_e32 v131, 32, v131
	v_ashrrev_i16_sdwa v132, v178, sext(v132) dst_sel:DWORD dst_unused:UNUSED_PAD src0_sel:DWORD src1_sel:BYTE_0
	v_and_b32_e32 v139, 0x1ffff0, v139
	v_lshlrev_b32_e32 v133, 5, v133
	v_sub_u32_e32 v130, v130, v140
	s_and_b32 s13, s13, 0xfffffc00
	v_bfe_i32 v132, v132, 0, 16
	v_add_u32_e32 v139, v141, v139
	v_and_b32_e32 v133, 32, v133
	v_ashrrev_i16_sdwa v130, v178, sext(v130) dst_sel:DWORD dst_unused:UNUSED_PAD src0_sel:DWORD src1_sel:BYTE_0
	v_lshl_or_b32 v131, v138, 10, v131
	s_add_i32 s13, s13, 0
	v_bfe_i32 v130, v130, 0, 16
	v_add_lshl_u32 v131, v131, v132, 1
	v_lshl_or_b32 v132, v139, 10, v133
	s_add_i32 s18, s13, 0x10000
	s_mov_b32 m0, s18
	s_nop 0
	global_load_lds_dwordx4 v131, s[8:9]
	v_add_lshl_u32 v130, v132, v130, 1
	s_add_i32 s18, s13, 0x12000
	s_mov_b32 m0, s18
	s_nop 0
	global_load_lds_dwordx4 v130, s[8:9]
	s_mov_b32 m0, s13
	s_nop 0
	global_load_lds_dwordx4 v131, s[10:11]
	s_add_i32 s18, s13, 0x2000
	s_mov_b32 m0, s18
	s_nop 0
	global_load_lds_dwordx4 v130, s[10:11]
	s_add_i32 s18, s13, 0x14000
	s_mov_b32 m0, s18
	s_nop 0
	global_load_lds_dwordx4 v131, s[16:17]
	s_add_i32 s18, s13, 0x16000
	s_mov_b32 m0, s18
	s_nop 0
	global_load_lds_dwordx4 v130, s[16:17]
	s_add_i32 s16, s13, 0x4000
	s_mov_b32 m0, s16
	s_nop 0
	global_load_lds_dwordx4 v131, s[14:15]
	s_add_i32 s16, s13, 0x6000
	s_mov_b32 m0, s16
	s_nop 0
	global_load_lds_dwordx4 v130, s[14:15]
	s_add_u32 s14, s8, 0x80
	s_addc_u32 s15, s9, 0
	s_add_i32 s16, s13, 0x18000
	s_mov_b32 m0, s16
	s_nop 0
	global_load_lds_dwordx4 v131, s[14:15]
	s_add_i32 s16, s13, 0x1a000
	s_add_u32 s10, s10, 0x80
	s_mov_b32 m0, s16
	s_nop 0
	global_load_lds_dwordx4 v130, s[14:15]
	s_addc_u32 s11, s11, 0
	s_add_i32 s14, s13, 0x8000
	s_mov_b32 m0, s14
	s_nop 0
	global_load_lds_dwordx4 v131, s[10:11]
	s_add_i32 s14, s13, 0xa000
	s_mov_b32 m0, s14
	s_nop 0
	global_load_lds_dwordx4 v130, s[10:11]
	s_add_u32 s8, s8, 0x40080
	s_addc_u32 s9, s9, 0
	s_add_i32 s10, s13, 0x1c000
	s_mov_b32 m0, s10
	s_nop 0
	global_load_lds_dwordx4 v131, s[8:9]
	s_add_i32 s13, s13, 0x1e000
	s_mov_b32 m0, s13
	s_nop 0
	global_load_lds_dwordx4 v130, s[8:9]

; #define STG_A(b, h, kt) stage_half_s(lds0 + ((b) * 2 + (h)) * HT_B, ((h) ? A1 : Ap) + (kt) * BK, off0, off1)
; #define STG_B(b, h, kt) stage_half_s(lds0 + (4 + (b) * 2 + (h)) * HT_B, ((h) ? B1p : Bp) + (kt) * BK, off0, off1)
; #define STG_A(b, h, kt) stage_half_s(lds0 + ((b) * 2 + (h)) * HT_B, ((h) ? A1 : Ap) + (kt) * BK, off0, off1)
; #define STG_B(b, h, kt) stage_half_s(lds0 + (4 + (b) * 2 + (h)) * HT_B, ((h) ? B1p : Bp) + (kt) * BK, off0, off1)
; __device__ __forceinline__ void gemm8_prefetch(const u16* __restrict__ Ap, const u16* __restrict__ Bp, int K, char* shm, const int tid) {
;   int r0, c0, r1, c1;
;   stage_rc(tid * 16, r0, c0);
;   stage_rc(tid * 16 + 8192, r1, c1);
;   const unsigned off0 = (unsigned)(r0 * K + c0) * 2u, off1 = (unsigned)(r1 * K + c1) * 2u;
;   const int wvoff = __builtin_amdgcn_readfirstlane(tid >> 6) * 1024;
;   const u16* A1 = Ap + (size_t)128 * K;
;   const u16* B1p = Bp + (size_t)128 * K;
;   const unsigned lds0 = (unsigned)(size_t)(__attribute__((address_space(3))) char*)shm + (unsigned)wvoff;
;     ...
;   STG_B(0, 0, 0); STG_A(0, 0, 0); STG_B(0, 1, 0); STG_A(0, 1, 0);
;   STG_B(1, 0, 1); STG_A(1, 0, 1); STG_B(1, 1, 1);
;     ...
; }
; template <int EPI, bool HS = false>
; __device__ __forceinline__ void gemm_phase(const Params& p, const GemmCfg& g, char* shm, const int wave_s) {
;     ...
;   if ((int)blockIdx.x < nwg) {
;     int mt, pn, arow0, orow0;
;     tile_coords(blockIdx.x, mt, pn, arow0, orow0);
;     gemm8_prefetch(g.A + (size_t)arow0 * g.K, g.Bt + (size_t)pn * 256 * g.K, g.K, shm, fresh_tid(wave_s));
;   }
.LBB0_328:
	v_readlane_b32 s0, v254, 54
	s_cmp_gt_i32 s0, 6
	s_mov_b64 s[0:1], -1
	s_cbranch_scc0 .LBB0_551
	v_readlane_b32 s0, v252, 57
	v_writelane_b32 v255, s52, 5
	v_readlane_b32 s1, v252, 58
	s_andn2_b64 vcc, exec, s[0:1]
	v_writelane_b32 v255, s53, 6
	s_cbranch_vccnz .LBB0_550
	s_mov_b32 s0, s50
	s_ashr_i32 s1, s50, 31
	v_readlane_b32 s4, v252, 26
	s_lshl_b64 s[0:1], s[0:1], 22
	v_readlane_b32 s8, v252, 30
	v_readlane_b32 s5, v252, 27
	v_readlane_b32 s9, v252, 31
	s_add_u32 s4, s8, s0
	s_addc_u32 s5, s9, s1
	s_lshl_b32 s0, s43, 11
	v_writelane_b32 v255, s0, 7
	v_readlane_b32 s0, v254, 11
	v_readlane_b32 s1, v254, 12
	s_add_u32 s2, s4, s0
	s_addc_u32 s3, s5, s1
	s_mov_b32 s0, s82
	s_mov_b32 s1, -1
	s_mov_b64 s[48:49], s[4:5]
	v_mbcnt_lo_u32_b32 v0, s1, 0
	v_mbcnt_hi_u32_b32 v0, s1, v0
	v_lshl_add_u32 v0, s0, 6, v0
	s_add_u32 s0, s2, 0x80000
	v_bfe_i32 v4, v0, 27, 1
	v_lshlrev_b32_e32 v2, 4, v0
	v_lshrrev_b32_e32 v4, 22, v4
	v_add_u32_e32 v4, v2, v4
	v_and_b32_e32 v4, 0xfffffc00, v4
	v_ashrrev_i32_e32 v3, 31, v0
	v_sub_u32_e32 v4, v2, v4
	v_lshrrev_b32_e32 v3, 26, v3
	v_lshrrev_b32_e32 v5, 4, v4
	v_add_u32_e32 v3, v0, v3
	v_bitop3_b32 v5, v5, v4, 32 bitop3:0x6c
	v_ashrrev_i32_e32 v4, 31, v4
	v_ashrrev_i32_e32 v3, 6, v3
	v_lshrrev_b32_e32 v4, 26, v4
	v_lshlrev_b32_e32 v6, 3, v3
	v_add_u32_e32 v4, v5, v4
	v_and_b32_e32 v6, 0xffff0, v6
	v_ashrrev_i32_e32 v4, 6, v4
	v_add_u32_e32 v6, v4, v6
	v_mul_i32_i24_e32 v4, 64, v4
	v_add_u32_e32 v2, 0x2000, v2
	v_sub_u32_e32 v4, v5, v4
	v_ashrrev_i32_e32 v5, 31, v2
	v_lshrrev_b32_e32 v5, 22, v5
	v_add_u32_e32 v5, v2, v5
	v_ashrrev_i32_e32 v5, 10, v5
	v_mul_i32_i24_e32 v7, 0x400, v5
	v_sub_u32_e32 v2, v2, v7
	v_lshrrev_b32_e32 v7, 4, v2
	v_bitop3_b32 v2, v7, v2, 32 bitop3:0x6c
	v_ashrrev_i32_e32 v8, 31, v2
	v_lshrrev_b32_e32 v8, 26, v8
	v_add_u32_e32 v8, v2, v8
	v_readfirstlane_b32 s4, v0
	v_lshlrev_b32_e32 v3, 5, v3
	v_lshlrev_b32_e32 v7, 3, v5
	v_lshrrev_b32_e32 v9, 6, v8
	v_and_b32_e32 v8, 0xc0, v8
	s_addc_u32 s1, s3, 0
	s_lshl_b32 s4, s4, 4
	v_and_b32_e32 v3, 32, v3
	v_ashrrev_i16_sdwa v4, v178, sext(v4) dst_sel:DWORD dst_unused:UNUSED_PAD src0_sel:DWORD src1_sel:BYTE_0
	v_and_b32_e32 v7, 0xffff0, v7
	v_lshlrev_b32_e32 v5, 5, v5
	v_sub_u32_e32 v2, v2, v8
	s_and_b32 s4, s4, 0xfffffc00
	v_readlane_b32 s6, v252, 28
	v_bfe_i32 v4, v4, 0, 16
	v_add_u32_e32 v7, v9, v7
	v_and_b32_e32 v5, 32, v5
	v_ashrrev_i16_sdwa v2, v178, sext(v2) dst_sel:DWORD dst_unused:UNUSED_PAD src0_sel:DWORD src1_sel:BYTE_0
	v_lshl_or_b32 v3, v6, 11, v3
	s_add_i32 s4, s4, 0
	v_bfe_i32 v2, v2, 0, 16
	v_add_lshl_u32 v3, v3, v4, 1
	v_lshl_or_b32 v4, v7, 11, v5
	s_add_i32 s5, s4, 0x10000
	s_mov_b32 m0, s5
	s_nop 0
	global_load_lds_dwordx4 v3, s[2:3]
	v_add_lshl_u32 v2, v4, v2, 1
	s_add_i32 s5, s4, 0x12000
	s_mov_b32 m0, s5
	s_nop 0
	global_load_lds_dwordx4 v2, s[2:3]
	v_readlane_b32 s8, v254, 15
	v_readlane_b32 s9, v254, 16
	s_mov_b32 m0, s4
	s_nop 3
	global_load_lds_dwordx4 v3, s[8:9]
	s_add_i32 s5, s4, 0x2000
	s_mov_b32 m0, s5
	s_nop 0
	global_load_lds_dwordx4 v2, s[8:9]
	s_add_i32 s5, s4, 0x14000
	s_mov_b32 m0, s5
	s_nop 0
	global_load_lds_dwordx4 v3, s[0:1]
	v_readlane_b32 s7, v252, 29
	s_add_i32 s5, s4, 0x16000
	s_mov_b32 m0, s5
	s_nop 0
	global_load_lds_dwordx4 v2, s[0:1]
	s_add_i32 s0, s4, 0x4000
	v_readlane_b32 s6, v254, 13
	v_readlane_b32 s7, v254, 14
	s_mov_b32 m0, s0
	s_nop 3
	global_load_lds_dwordx4 v3, s[6:7]
	s_add_i32 s0, s4, 0x6000
	s_mov_b32 m0, s0
	s_nop 0
	global_load_lds_dwordx4 v2, s[6:7]
	s_add_u32 s0, s2, 0x80
	s_addc_u32 s1, s3, 0
	s_add_i32 s5, s4, 0x18000
	s_mov_b32 m0, s5
	s_nop 0
	global_load_lds_dwordx4 v3, s[0:1]
	s_add_i32 s5, s4, 0x1a000
	s_mov_b32 m0, s5
	s_nop 0
	global_load_lds_dwordx4 v2, s[0:1]
	s_add_i32 s0, s4, 0x8000
	v_readlane_b32 s6, v254, 17
	v_readlane_b32 s7, v254, 18
	s_mov_b32 m0, s0
	s_nop 3
	global_load_lds_dwordx4 v3, s[6:7]
	s_add_i32 s0, s4, 0xa000
	s_mov_b32 m0, s0
	s_nop 0
	global_load_lds_dwordx4 v2, s[6:7]
	s_add_u32 s0, s2, 0x80080
	s_addc_u32 s1, s3, 0
	s_add_i32 s2, s4, 0x1c000
	s_mov_b32 m0, s2
	s_nop 0
	global_load_lds_dwordx4 v3, s[0:1]
	s_add_i32 s4, s4, 0x1e000
	s_mov_b32 m0, s4
	s_nop 0
	global_load_lds_dwordx4 v2, s[0:1]
	v_readlane_b32 s0, v254, 59
	s_mulk_i32 s0, 0xc00
	s_ashr_i32 s1, s0, 31
	s_lshl_b64 s[0:1], s[0:1], 2
	v_readlane_b32 s2, v254, 57
	s_add_u32 s0, s2, s0
	v_writelane_b32 v255, s0, 8
	v_readlane_b32 s0, v254, 58
	s_addc_u32 s0, s0, s1
	s_mov_b32 s75, s45
	v_writelane_b32 v255, s0, 4
	v_readlane_b32 s10, v252, 32
	v_readlane_b32 s11, v252, 33
	v_readlane_b32 s12, v252, 34
	v_readlane_b32 s13, v252, 35
	v_readlane_b32 s14, v252, 36
	v_readlane_b32 s15, v252, 37
	v_readlane_b32 s16, v252, 38
	v_readlane_b32 s17, v252, 39
	v_readlane_b32 s18, v252, 40
	v_readlane_b32 s19, v252, 41
	s_branch .LBB0_333
; #define STG_A(b, h, kt) stage_half_s(lds0 + ((b) * 2 + (h)) * HT_B, ((h) ? A1 : Ap) + (kt) * BK, off0, off1)
; #define STG_B(b, h, kt) stage_half_s(lds0 + (4 + (b) * 2 + (h)) * HT_B, ((h) ? B1p : Bp) + (kt) * BK, off0, off1)
; #define STG_A(b, h, kt) stage_half_s(lds0 + ((b) * 2 + (h)) * HT_B, ((h) ? A1 : Ap) + (kt) * BK, off0, off1)
; #define STG_B(b, h, kt) stage_half_s(lds0 + (4 + (b) * 2 + (h)) * HT_B, ((h) ? B1p : Bp) + (kt) * BK, off0, off1)
; __device__ __forceinline__ void gemm8_prefetch(const u16* __restrict__ Ap, const u16* __restrict__ Bp, int K, char* shm, const int tid) {
;   int r0, c0, r1, c1;
;   stage_rc(tid * 16, r0, c0);
;   stage_rc(tid * 16 + 8192, r1, c1);
;   const unsigned off0 = (unsigned)(r0 * K + c0) * 2u, off1 = (unsigned)(r1 * K + c1) * 2u;
;   const int wvoff = __builtin_amdgcn_readfirstlane(tid >> 6) * 1024;
;   const u16* A1 = Ap + (size_t)128 * K;
;   const u16* B1p = Bp + (size_t)128 * K;
;   const unsigned lds0 = (unsigned)(size_t)(__attribute__((address_space(3))) char*)shm + (unsigned)wvoff;
;     ...
;   STG_B(0, 0, 0); STG_A(0, 0, 0); STG_B(0, 1, 0); STG_A(0, 1, 0);
;   STG_B(1, 0, 1); STG_A(1, 0, 1); STG_B(1, 1, 1);
;     ...
; }
; template <int EPI, bool HS = false>
; __device__ __forceinline__ void gemm_phase(const Params& p, const GemmCfg& g, char* shm, const int wave_s) {
;     ...
;   auto tile_coords = [&](int tile, int& mt, int& pn, int& arow0, int& orow0) {
;     int wgid = tile;
;     { int q = nwg / 8, r = nwg % 8, xcd = wgid % 8, off = wgid / 8;
;       wgid = (xcd < r ? xcd * (q + 1) : r * (q + 1) + (xcd - r) * q) + off; }
;     int nig = 8 * g.nN, gid = wgid / nig, fm = gid * 8, gsz = (g.nM - fm < 8) ? (g.nM - fm) : 8;
;     mt = fm + ((wgid % nig) % gsz); pn = (wgid % nig) / gsz;
;     if (g.rev) mt = g.nM - 1 - mt;
;     int hrow0 = (mt >> 3) * 4096 + g.hf * 2048 + (mt & 7) * 256;
;     arow0 = g.a_half ? hrow0 : mt * 256;
;     orow0 = g.o_half ? hrow0 : mt * 256;
;   };
;     ...
;       if (tile + (int)gridDim.x < nwg) {
;         int mt2, pn2, arow2, orow2;
;         tile_coords(tile + gridDim.x, mt2, pn2, arow2, orow2);
;         gemm8_prefetch(g.A + (size_t)arow2 * g.K, g.Bt + (size_t)pn2 * 256 * g.K, g.K, shm, fresh_tid(wave_s));
;       }
.LBB0_331:
	s_add_i32 s0, s1, s2
	s_ashr_i32 s1, s0, 31
	s_lshr_b32 s1, s1, 27
	s_add_i32 s1, s0, s1
	s_and_b32 s2, s1, 0xffe0
	s_sub_i32 s2, s0, s2
	s_bfe_i32 s0, s2, 0x80000
	s_bfe_u32 s0, s0, 0x3000c
	s_add_i32 s3, s2, s0
	s_bfe_i32 s0, s3, 0x80000
	s_and_b32 s3, s3, 0xf8
	s_sub_i32 s2, s2, s3
	s_sext_i32_i8 s2, s2
	s_lshl_b32 s1, s1, 6
	s_and_b32 s1, s1, 0xfffff800
	s_lshl_b32 s2, s2, 8
	s_add_i32 s2, s2, s1
	s_sext_i32_i16 s0, s0
	s_ashr_i32 s3, s2, 31
	s_lshr_b32 s0, s0, 3
	s_lshl_b64 s[2:3], s[2:3], 12
	v_readlane_b32 s1, v254, 9
	s_add_u32 s4, s1, s2
	v_readlane_b32 s1, v254, 10
	s_addc_u32 s5, s1, s3
	s_bfe_i64 s[0:1], s[0:1], 0x100000
	s_lshl_b64 s[0:1], s[0:1], 20
	s_mov_b64 s[2:3], s[48:49]
	s_add_u32 s2, s2, s0
	s_addc_u32 s3, s3, s1
	s_mov_b32 s0, s82
	s_mov_b32 s1, -1
	s_nop 0
	v_mbcnt_lo_u32_b32 v0, s1, 0
	v_mbcnt_hi_u32_b32 v0, s1, v0
	v_lshl_add_u32 v0, s0, 6, v0
	s_add_u32 s0, s4, 0x80000
	v_bfe_i32 v4, v0, 27, 1
	v_lshlrev_b32_e32 v2, 4, v0
	v_lshrrev_b32_e32 v4, 22, v4
	v_add_u32_e32 v4, v2, v4
	v_and_b32_e32 v4, 0xfffffc00, v4
	v_ashrrev_i32_e32 v3, 31, v0
	v_sub_u32_e32 v4, v2, v4
	v_lshrrev_b32_e32 v3, 26, v3
	v_lshrrev_b32_e32 v5, 4, v4
	v_add_u32_e32 v3, v0, v3
	v_bitop3_b32 v5, v5, v4, 32 bitop3:0x6c
	v_ashrrev_i32_e32 v4, 31, v4
	v_ashrrev_i32_e32 v3, 6, v3
	v_lshrrev_b32_e32 v4, 26, v4
	v_lshlrev_b32_e32 v6, 3, v3
	v_add_u32_e32 v4, v5, v4
	v_and_b32_e32 v6, 0xffff0, v6
	v_ashrrev_i32_e32 v4, 6, v4
	v_add_u32_e32 v6, v4, v6
	v_mul_i32_i24_e32 v4, 64, v4
	v_add_u32_e32 v2, 0x2000, v2
	v_sub_u32_e32 v4, v5, v4
	v_ashrrev_i32_e32 v5, 31, v2
	v_lshrrev_b32_e32 v5, 22, v5
	v_add_u32_e32 v5, v2, v5
	v_ashrrev_i32_e32 v5, 10, v5
	v_mul_i32_i24_e32 v7, 0x400, v5
	v_sub_u32_e32 v2, v2, v7
	v_lshrrev_b32_e32 v7, 4, v2
	v_bitop3_b32 v2, v7, v2, 32 bitop3:0x6c
	v_ashrrev_i32_e32 v8, 31, v2
	v_lshrrev_b32_e32 v8, 26, v8
	s_addc_u32 s1, s5, 0
	v_add_u32_e32 v8, v2, v8
	v_readfirstlane_b32 s8, v0
	s_add_u32 s6, s2, 0x80000
	v_lshlrev_b32_e32 v3, 5, v3
	v_lshlrev_b32_e32 v7, 3, v5
	v_lshrrev_b32_e32 v9, 6, v8
	v_and_b32_e32 v8, 0xc0, v8
	s_addc_u32 s7, s3, 0
	s_lshl_b32 s8, s8, 4
	v_and_b32_e32 v3, 32, v3
	v_ashrrev_i16_sdwa v4, v178, sext(v4) dst_sel:DWORD dst_unused:UNUSED_PAD src0_sel:DWORD src1_sel:BYTE_0
	v_and_b32_e32 v7, 0xffff0, v7
	v_lshlrev_b32_e32 v5, 5, v5
	v_sub_u32_e32 v2, v2, v8
	s_and_b32 s8, s8, 0xfffffc00
	v_bfe_i32 v4, v4, 0, 16
	v_add_u32_e32 v7, v9, v7
	v_and_b32_e32 v5, 32, v5
	v_ashrrev_i16_sdwa v2, v178, sext(v2) dst_sel:DWORD dst_unused:UNUSED_PAD src0_sel:DWORD src1_sel:BYTE_0
	v_lshl_or_b32 v3, v6, 11, v3
	s_add_i32 s8, s8, 0
	v_bfe_i32 v2, v2, 0, 16
	v_add_lshl_u32 v3, v3, v4, 1
	v_lshl_or_b32 v4, v7, 11, v5
	s_add_i32 s9, s8, 0x10000
	s_mov_b32 m0, s9
	s_nop 0
	global_load_lds_dwordx4 v3, s[2:3]
	v_add_lshl_u32 v2, v4, v2, 1
	s_add_i32 s9, s8, 0x12000
	s_mov_b32 m0, s9
	s_nop 0
	global_load_lds_dwordx4 v2, s[2:3]
	s_mov_b32 m0, s8
	s_nop 0
	global_load_lds_dwordx4 v3, s[4:5]
	s_add_i32 s9, s8, 0x2000
	s_mov_b32 m0, s9
	s_nop 0
	global_load_lds_dwordx4 v2, s[4:5]
	s_add_i32 s9, s8, 0x14000
	s_mov_b32 m0, s9
	s_nop 0
	global_load_lds_dwordx4 v3, s[6:7]
	s_add_i32 s9, s8, 0x16000
	s_mov_b32 m0, s9
	s_nop 0
	global_load_lds_dwordx4 v2, s[6:7]
	s_add_i32 s6, s8, 0x4000
	s_mov_b32 m0, s6
	s_nop 0
	global_load_lds_dwordx4 v3, s[0:1]
	s_add_i32 s6, s8, 0x6000
	s_mov_b32 m0, s6
	s_nop 0
	global_load_lds_dwordx4 v2, s[0:1]
	s_add_u32 s0, s2, 0x80
	s_addc_u32 s1, s3, 0
	s_add_i32 s6, s8, 0x18000
	s_mov_b32 m0, s6
	s_nop 0
	global_load_lds_dwordx4 v3, s[0:1]
	s_add_i32 s6, s8, 0x1a000
	s_mov_b32 m0, s6
	s_nop 0
	global_load_lds_dwordx4 v2, s[0:1]
	s_add_u32 s0, s4, 0x80
	s_addc_u32 s1, s5, 0
	s_add_i32 s4, s8, 0x8000
	s_mov_b32 m0, s4
	s_nop 0
	global_load_lds_dwordx4 v3, s[0:1]
	s_add_i32 s4, s8, 0xa000
	s_mov_b32 m0, s4
	s_nop 0
	global_load_lds_dwordx4 v2, s[0:1]
	s_add_u32 s0, s2, 0x80080
	s_addc_u32 s1, s3, 0
	s_add_i32 s2, s8, 0x1c000
	s_mov_b32 m0, s2
	s_nop 0
	global_load_lds_dwordx4 v3, s[0:1]
	s_add_i32 s8, s8, 0x1e000
	s_mov_b32 m0, s8
	s_nop 0
	global_load_lds_dwordx4 v2, s[0:1]
	s_mov_b64 s[2:3], 0

; #define WAIT_V(n) asm volatile("s_waitcnt vmcnt(" #n ")" ::: "memory")
; #define WAIT_L(n) asm volatile("s_waitcnt lgkmcnt(" #n ")" ::: "memory")
; #define BAR __builtin_amdgcn_s_barrier()
; #define SCHED __builtin_amdgcn_sched_barrier(0)
; template <bool HS>
; __device__ __forceinline__ void gemm_tile8(const u16* __restrict__ Ap, const u16* __restrict__ Bp, int K,
;                                            f32x4 (&acc)[2][2][4][2], char* shm, const int tid, const float* hsr = nullptr) {
;   const int wid = tid >> 6, lane = tid & 63, wr = wid >> 2, wc = wid & 3, fr = lane & 15, fq = lane >> 4;
;   int r0, c0, r1, c1;
;   stage_rc(tid * 16, r0, c0);
;   stage_rc(tid * 16 + 8192, r1, c1);
;   const unsigned off0 = (unsigned)(r0 * K + c0) * 2u, off1 = (unsigned)(r1 * K + c1) * 2u;
;   const int wvoff = __builtin_amdgcn_readfirstlane(tid >> 6) * 1024;
;   const u16* A1 = Ap + (size_t)128 * K;
;   const u16* B1p = Bp + (size_t)128 * K;
; #pragma unroll
;   for (int a = 0; a < 2; ++a)
; #pragma unroll
;     for (int b = 0; b < 2; ++b)
; #pragma unroll
;       for (int m = 0; m < 4; ++m)
; #pragma unroll
;         for (int n = 0; n < 2; ++n) acc[a][b][m][n] = f32x4{0.f, 0.f, 0.f, 0.f};
;   const int abase = lds_byte(wr * 64 + fr, fq * 8), bbase = lds_byte(wc * 32 + fr, fq * 8);
;   bf16x8 At[4][2], B0[2][2], B1[2][2];
;   const unsigned lds0 = (unsigned)(size_t)(__attribute__((address_space(3))) char*)shm + (unsigned)wvoff;
;     ...
;   const int nt = K / BK;
;   WAIT_V(0);
;   if (wr == 1) BAR;
;   BAR;
;   BAR;
;   for (int t = 0; t < nt - 2; t += 2) {
;     if constexpr (HS) {
;       if (t > 0 && (t & 7) == 0) {
;         const float* rt = hsr + ((t >> 3) - 1) * 256 + wr * 64 + fq * 4;
; #pragma unroll
;         for (int ai = 0; ai < 2; ++ai)
; #pragma unroll
;           for (int m = 0; m < 4; ++m) {
;             const f32x4 q4 = *(const f32x4*)(rt + ai * 128 + m * 16);
; #pragma unroll
;             for (int bj = 0; bj < 2; ++bj)
; #pragma unroll
;               for (int n = 0; n < 2; ++n) acc[ai][bj][m][n] *= q4;
;             SCHED;
;           }
;       }
;     }
;     LDB8(B0, 0, 0); SCHED; LDA8(0, 0); STG_A(1, 1, t + 1);
;     WAIT_L(8); BAR; WAIT_L(0); MMA8(0, 0, B0); BAR; SCHED;
;     LDB8(B1, 0, 1); STG_B(0, 0, t + 2);
;     BAR; WAIT_L(0); MMA8(0, 1, B1); BAR;
.LBB0_341:
	s_or_b64 exec, exec, s[4:5]
	v_mov_b32_e32 v4, s0
	v_bfe_i32 v4, v4, 0, 8
	v_ashrrev_i32_e32 v5, 31, v4
	v_lshlrev_b64 v[4:5], 20, v[4:5]
	v_lshl_add_u64 v[250:251], s[48:49], 0, v[4:5]
	v_bfe_i32 v5, v0, 27, 1
	v_lshlrev_b32_e32 v3, 4, v0
	v_lshrrev_b32_e32 v5, 22, v5
	v_add_u32_e32 v5, v3, v5
	v_and_b32_e32 v5, 0xfffffc00, v5
	v_ashrrev_i32_e32 v4, 31, v0
	v_sub_u32_e32 v5, v3, v5
	v_lshrrev_b32_e32 v4, 26, v4
	v_lshrrev_b32_e32 v6, 4, v5
	v_add_u32_e32 v4, v0, v4
	v_bitop3_b32 v6, v6, v5, 32 bitop3:0x6c
	v_ashrrev_i32_e32 v5, 31, v5
	v_ashrrev_i32_e32 v4, 6, v4
	v_lshrrev_b32_e32 v5, 26, v5
	v_lshlrev_b32_e32 v7, 3, v4
	v_add_u32_e32 v5, v6, v5
	v_and_b32_e32 v7, 0xffff0, v7
	v_ashrrev_i32_e32 v5, 6, v5
	v_add_u32_e32 v7, v5, v7
	v_mul_i32_i24_e32 v5, 64, v5
	v_add_u32_e32 v3, 0x2000, v3
	v_sub_u32_e32 v5, v6, v5
	v_ashrrev_i32_e32 v6, 31, v3
	v_lshrrev_b32_e32 v6, 22, v6
	v_add_u32_e32 v6, v3, v6
	v_ashrrev_i32_e32 v6, 10, v6
	v_mul_i32_i24_e32 v8, 0x400, v6
	v_sub_u32_e32 v3, v3, v8
	v_lshrrev_b32_e32 v8, 4, v3
	v_bitop3_b32 v3, v8, v3, 32 bitop3:0x6c
	v_ashrrev_i32_e32 v9, 31, v3
	v_lshrrev_b32_e32 v9, 26, v9
	v_add_u32_e32 v9, v3, v9
	v_lshlrev_b32_e32 v8, 3, v6
	v_lshrrev_b32_e32 v10, 6, v9
	v_and_b32_e32 v9, 0xc0, v9
	v_lshlrev_b32_e32 v4, 5, v4
	v_and_b32_e32 v8, 0xffff0, v8
	v_lshlrev_b32_e32 v6, 5, v6
	v_sub_u32_e32 v3, v3, v9
	s_ashr_i32 s3, s2, 31
	v_and_b32_e32 v4, 32, v4
	v_ashrrev_i16_sdwa v5, v178, sext(v5) dst_sel:DWORD dst_unused:UNUSED_PAD src0_sel:DWORD src1_sel:BYTE_0
	v_add_u32_e32 v8, v10, v8
	v_and_b32_e32 v6, 32, v6
	v_ashrrev_i16_sdwa v3, v178, sext(v3) dst_sel:DWORD dst_unused:UNUSED_PAD src0_sel:DWORD src1_sel:BYTE_0
	s_lshl_b64 s[4:5], s[2:3], 12
	v_readlane_b32 s1, v254, 9
	v_bfe_i32 v5, v5, 0, 16
	v_bfe_i32 v3, v3, 0, 16
	v_lshl_or_b32 v4, v7, 11, v4
	v_lshl_or_b32 v6, v8, 11, v6
	s_add_u32 s1, s1, s4
	v_readlane_b32 s3, v254, 10
	v_add_lshl_u32 v134, v4, v5, 1
	v_add_lshl_u32 v135, v6, v3, 1
	v_lshlrev_b32_e32 v4, 6, v0
	v_lshlrev_b32_e32 v6, 2, v0
	s_addc_u32 s3, s3, s5
	v_and_b32_e32 v158, 48, v0
	s_lshl_b32 s23, s6, 10
	s_mov_b64 s[6:7], 0x80000
	v_and_b32_e32 v4, 0x3c0, v4
	v_and_b32_e32 v6, 32, v6
	v_lshl_add_u64 v[236:237], v[250:251], 0, s[6:7]
	v_or_b32_e32 v5, v4, v158
	v_lshlrev_b32_e32 v2, 12, v2
	v_bitop3_b32 v4, v4, v6, v158 bitop3:0x36
	s_movk_i32 s6, 0x3000
	v_lshlrev_b32_e32 v3, 13, v141
	v_and_or_b32 v136, v2, s6, v4
	s_add_i32 s16, 0, 0x10000
	v_bitop3_b32 v3, v5, v3, v6 bitop3:0xde
	v_add_u32_e32 v137, s16, v136
	s_barrier
	s_barrier
	s_waitcnt vmcnt(7)
	v_add_u32_e32 v160, 0, v3
	ds_read_b128 v[2:5], v137 offset:3072
	ds_read_b128 v[6:9], v137 offset:2048
	ds_read_b128 v[10:13], v137 offset:1024
	ds_read_b128 v[14:17], v137
	s_add_i32 s18, 0, 0x14000
	s_add_i32 s19, 0, 0x18000
	s_add_i32 s24, 0, 0x1c000
	v_lshlrev_b32_e32 v159, 6, v141
	s_mov_b32 s11, 2
	s_add_i32 s6, s23, 0
	v_add_u32_e32 v138, s18, v136
	v_add_u32_e32 v139, s19, v136
	v_add_u32_e32 v140, s24, v136
	ds_read_b128 v[18:21], v160
	ds_read_b128 v[22:25], v160 offset:1024
	s_waitcnt lgkmcnt(6)
	ds_read_b128 v[26:29], v160 offset:2048
	ds_read_b128 v[30:33], v160 offset:3072
	ds_read_b128 v[34:37], v160 offset:4096
	ds_read_b128 v[38:41], v160 offset:5120
	ds_read_b128 v[42:45], v160 offset:6144
	ds_read_b128 v[46:49], v160 offset:7168
	s_add_u32 s12, s1, 0x80080
	s_addc_u32 s13, s3, 0
	s_add_i32 s7, s6, 0xc000
	s_mov_b32 m0, s7
	s_nop 0
	global_load_lds_dwordx4 v134, s[12:13]
	s_add_i32 s10, s6, 0xe000
	s_mov_b32 m0, s10
	s_nop 0
	global_load_lds_dwordx4 v135, s[12:13]
	s_waitcnt lgkmcnt(8)
	s_barrier
	s_waitcnt lgkmcnt(0)
	s_setprio 1
	s_waitcnt lgkmcnt(7)
	v_mfma_f32_16x16x32_bf16 v[50:53], v[18:21], v[14:17], 0
	v_mfma_f32_16x16x32_bf16 v[54:57], v[18:21], v[6:9], 0
	s_waitcnt lgkmcnt(5)
	v_mfma_f32_16x16x32_bf16 v[58:61], v[26:29], v[14:17], 0
	v_mfma_f32_16x16x32_bf16 v[62:65], v[26:29], v[6:9], 0
	s_waitcnt lgkmcnt(3)
	v_mfma_f32_16x16x32_bf16 v[66:69], v[34:37], v[14:17], 0
	s_waitcnt vmcnt(0)
	v_mfma_f32_16x16x32_bf16 v[70:73], v[34:37], v[6:9], 0
	s_waitcnt lgkmcnt(1)
	v_mfma_f32_16x16x32_bf16 v[74:77], v[42:45], v[14:17], 0
	v_mfma_f32_16x16x32_bf16 v[78:81], v[42:45], v[6:9], 0
	v_mfma_f32_16x16x32_bf16 v[50:53], v[22:25], v[10:13], v[50:53]
	v_mfma_f32_16x16x32_bf16 v[54:57], v[22:25], v[2:5], v[54:57]
	v_mfma_f32_16x16x32_bf16 v[58:61], v[30:33], v[10:13], v[58:61]
	v_mfma_f32_16x16x32_bf16 v[62:65], v[30:33], v[2:5], v[62:65]
	v_mfma_f32_16x16x32_bf16 v[66:69], v[38:41], v[10:13], v[66:69]
	v_mfma_f32_16x16x32_bf16 v[70:73], v[38:41], v[2:5], v[70:73]
	s_waitcnt lgkmcnt(0)
	v_mfma_f32_16x16x32_bf16 v[74:77], v[46:49], v[10:13], v[74:77]
	v_mfma_f32_16x16x32_bf16 v[78:81], v[46:49], v[2:5], v[78:81]
	s_setprio 0
	s_barrier
	ds_read_b128 v[82:85], v138
	ds_read_b128 v[86:89], v138 offset:1024
	ds_read_b128 v[90:93], v138 offset:2048
	ds_read_b128 v[94:97], v138 offset:3072
	v_lshl_add_u64 v[98:99], v[250:251], 0, s[78:79]
	s_add_i32 s12, s23, s16
	v_readfirstlane_b32 s15, v99
	v_readfirstlane_b32 s14, v98
	s_mov_b32 m0, s12
	s_nop 3
	global_load_lds_dwordx4 v134, s[14:15]
	s_add_i32 s13, s6, 0x12000
	s_mov_b32 m0, s13
	s_nop 0
	global_load_lds_dwordx4 v135, s[14:15]
	s_barrier
; #define WAIT_V(n) asm volatile("s_waitcnt vmcnt(" #n ")" ::: "memory")
; #define WAIT_L(n) asm volatile("s_waitcnt lgkmcnt(" #n ")" ::: "memory")
; #define BAR __builtin_amdgcn_s_barrier()
; #define SCHED __builtin_amdgcn_sched_barrier(0)
; #define STG_A(b, h, kt) stage_half_s(lds0 + ((b) * 2 + (h)) * HT_B, ((h) ? A1 : Ap) + (kt) * BK, off0, off1)
; #define STG_B(b, h, kt) stage_half_s(lds0 + (4 + (b) * 2 + (h)) * HT_B, ((h) ? B1p : Bp) + (kt) * BK, off0, off1)
; #define STG_A(b, h, kt) stage_half_s(lds0 + ((b) * 2 + (h)) * HT_B, ((h) ? A1 : Ap) + (kt) * BK, off0, off1)
; #define STG_B(b, h, kt) stage_half_s(lds0 + (4 + (b) * 2 + (h)) * HT_B, ((h) ? B1p : Bp) + (kt) * BK, off0, off1)
; #define LDA8(b, h) _Pragma("unroll") for (int m = 0; m < 4; ++m) _Pragma("unroll") for (int k = 0; k < 2; ++k) \
;     At[m][k] = *(const bf16x8*)(SA_(shm, b, h) + abase + (m * 2 + k) * 1024)
; #define LDB8(dst, b, h) _Pragma("unroll") for (int n = 0; n < 2; ++n) _Pragma("unroll") for (int k = 0; k < 2; ++k) \
;     dst[n][k] = *(const bf16x8*)(SB_(shm, b, h) + bbase + (n * 2 + k) * 1024)
; #define MMA8(ai, bj, Bx) do { __builtin_amdgcn_s_setprio(1); \
;     _Pragma("unroll") for (int m = 0; m < 4; ++m) _Pragma("unroll") for (int n = 0; n < 2; ++n) _Pragma("unroll") for (int k = 0; k < 2; ++k) \
;       acc[ai][bj][m][n] = __builtin_amdgcn_mfma_f32_16x16x32_bf16(At[m][k], Bx[n][k], acc[ai][bj][m][n], 0, 0, 0); \
;     __builtin_amdgcn_s_setprio(0); } while (0)
; template <bool HS>
; __device__ __forceinline__ void gemm_tile8(const u16* __restrict__ Ap, const u16* __restrict__ Bp, int K,
;                                            f32x4 (&acc)[2][2][4][2], char* shm, const int tid, const float* hsr = nullptr) {
;     ...
;     BAR; WAIT_L(0); MMA8(0, 1, B1); BAR;
;     LDA8(0, 1); STG_A(0, 0, t + 2);
;     BAR; WAIT_L(0); MMA8(1, 0, B0); BAR; SCHED;
;     STG_B(0, 1, t + 2);
;     WAIT_V(6); BAR; MMA8(1, 1, B1); BAR;
;     LDB8(B0, 1, 0); SCHED; LDA8(1, 0); STG_A(0, 1, t + 2);
	s_waitcnt lgkmcnt(0)
	s_setprio 1
	s_waitcnt lgkmcnt(3)
	v_mfma_f32_16x16x32_bf16 v[98:101], v[18:21], v[82:85], 0
	s_waitcnt lgkmcnt(1)
	v_mfma_f32_16x16x32_bf16 v[18:21], v[18:21], v[90:93], 0
	s_waitcnt lgkmcnt(0)
	v_mfma_f32_16x16x32_bf16 v[102:105], v[22:25], v[94:97], v[18:21]
	v_mfma_f32_16x16x32_bf16 v[18:21], v[26:29], v[82:85], 0
	v_mfma_f32_16x16x32_bf16 v[106:109], v[30:33], v[86:89], v[18:21]
	v_mfma_f32_16x16x32_bf16 v[18:21], v[26:29], v[90:93], 0
	v_mfma_f32_16x16x32_bf16 v[110:113], v[30:33], v[94:97], v[18:21]
	v_mfma_f32_16x16x32_bf16 v[18:21], v[34:37], v[82:85], 0
	v_mfma_f32_16x16x32_bf16 v[114:117], v[38:41], v[86:89], v[18:21]
	v_mfma_f32_16x16x32_bf16 v[18:21], v[34:37], v[90:93], 0
	v_mfma_f32_16x16x32_bf16 v[34:37], v[38:41], v[94:97], v[18:21]
	v_mfma_f32_16x16x32_bf16 v[18:21], v[42:45], v[82:85], 0
	v_mfma_f32_16x16x32_bf16 v[38:41], v[46:49], v[86:89], v[18:21]
	v_mfma_f32_16x16x32_bf16 v[18:21], v[42:45], v[90:93], 0
	v_mfma_f32_16x16x32_bf16 v[98:101], v[22:25], v[86:89], v[98:101]
	v_mfma_f32_16x16x32_bf16 v[118:121], v[46:49], v[94:97], v[18:21]
	s_setprio 0
	s_barrier
	s_nop 3
	ds_read_b128 v[18:21], v160 offset:16384
	ds_read_b128 v[22:25], v160 offset:17408
	ds_read_b128 v[26:29], v160 offset:18432
	ds_read_b128 v[30:33], v160 offset:19456
	ds_read_b128 v[42:45], v160 offset:20480
	ds_read_b128 v[46:49], v160 offset:21504
	ds_read_b128 v[122:125], v160 offset:22528
	ds_read_b128 v[126:129], v160 offset:23552
	s_add_u32 s16, s1, 0x100
	s_addc_u32 s17, s3, 0
	s_mov_b32 m0, s6
	s_nop 0
	global_load_lds_dwordx4 v134, s[16:17]
	s_add_i32 s14, s6, 0x2000
	s_mov_b32 m0, s14
	s_nop 0
	global_load_lds_dwordx4 v135, s[16:17]
	s_barrier
	s_waitcnt lgkmcnt(0)
	s_setprio 1
	s_waitcnt lgkmcnt(7)
	v_mfma_f32_16x16x32_bf16 v[142:145], v[18:21], v[14:17], 0
	v_mfma_f32_16x16x32_bf16 v[146:149], v[18:21], v[6:9], 0
	s_waitcnt lgkmcnt(5)
	v_mfma_f32_16x16x32_bf16 v[150:153], v[26:29], v[14:17], 0
	v_mfma_f32_16x16x32_bf16 v[154:157], v[26:29], v[6:9], 0
	s_waitcnt lgkmcnt(3)
	v_mfma_f32_16x16x32_bf16 v[162:165], v[42:45], v[14:17], 0
	v_mfma_f32_16x16x32_bf16 v[166:169], v[42:45], v[6:9], 0
	s_waitcnt lgkmcnt(1)
	v_mfma_f32_16x16x32_bf16 v[14:17], v[122:125], v[14:17], 0
	v_mfma_f32_16x16x32_bf16 v[6:9], v[122:125], v[6:9], 0
	v_mfma_f32_16x16x32_bf16 v[142:145], v[22:25], v[10:13], v[142:145]
	v_mfma_f32_16x16x32_bf16 v[146:149], v[22:25], v[2:5], v[146:149]
	v_mfma_f32_16x16x32_bf16 v[150:153], v[30:33], v[10:13], v[150:153]
	v_mfma_f32_16x16x32_bf16 v[154:157], v[30:33], v[2:5], v[154:157]
	v_mfma_f32_16x16x32_bf16 v[162:165], v[46:49], v[10:13], v[162:165]
	v_mfma_f32_16x16x32_bf16 v[166:169], v[46:49], v[2:5], v[166:169]
	s_waitcnt lgkmcnt(0)
	v_mfma_f32_16x16x32_bf16 v[170:173], v[126:129], v[10:13], v[14:17]
	v_mfma_f32_16x16x32_bf16 v[174:177], v[126:129], v[2:5], v[6:9]
	s_setprio 0
	s_barrier
	s_mov_b64 s[16:17], 0x80100
	v_lshl_add_u64 v[2:3], v[250:251], 0, s[16:17]
	s_add_i32 s15, s23, s18
	v_readfirstlane_b32 s21, v3
	v_readfirstlane_b32 s20, v2
	s_mov_b32 m0, s15
	s_nop 3
	global_load_lds_dwordx4 v134, s[20:21]
	s_add_i32 s16, s6, 0x16000
	s_mov_b32 m0, s16
	s_nop 0
	global_load_lds_dwordx4 v135, s[20:21]
	s_waitcnt vmcnt(6)
	s_barrier
	s_setprio 1
	v_mfma_f32_16x16x32_bf16 v[2:5], v[18:21], v[82:85], 0
	v_mfma_f32_16x16x32_bf16 v[180:183], v[22:25], v[86:89], v[2:5]
	v_mfma_f32_16x16x32_bf16 v[2:5], v[18:21], v[90:93], 0
	v_mfma_f32_16x16x32_bf16 v[184:187], v[22:25], v[94:97], v[2:5]
	v_mfma_f32_16x16x32_bf16 v[2:5], v[26:29], v[82:85], 0
	v_mfma_f32_16x16x32_bf16 v[188:191], v[30:33], v[86:89], v[2:5]
	v_mfma_f32_16x16x32_bf16 v[2:5], v[26:29], v[90:93], 0
	v_mfma_f32_16x16x32_bf16 v[192:195], v[30:33], v[94:97], v[2:5]
	v_mfma_f32_16x16x32_bf16 v[2:5], v[42:45], v[82:85], 0
	v_mfma_f32_16x16x32_bf16 v[196:199], v[46:49], v[86:89], v[2:5]
	v_mfma_f32_16x16x32_bf16 v[2:5], v[42:45], v[90:93], 0
	v_mfma_f32_16x16x32_bf16 v[200:203], v[46:49], v[94:97], v[2:5]
	v_mfma_f32_16x16x32_bf16 v[2:5], v[122:125], v[82:85], 0
	v_mfma_f32_16x16x32_bf16 v[204:207], v[126:129], v[86:89], v[2:5]
	v_mfma_f32_16x16x32_bf16 v[2:5], v[122:125], v[90:93], 0
	v_mfma_f32_16x16x32_bf16 v[208:211], v[126:129], v[94:97], v[2:5]
	s_setprio 0
	s_barrier
	ds_read_b128 v[122:125], v139
	ds_read_b128 v[126:129], v139 offset:1024
	ds_read_b128 v[212:215], v139 offset:2048
	ds_read_b128 v[220:223], v139 offset:3072
	ds_read_b128 v[42:45], v160 offset:32768
	ds_read_b128 v[46:49], v160 offset:33792
	ds_read_b128 v[82:85], v160 offset:34816
	ds_read_b128 v[86:89], v160 offset:35840
	ds_read_b128 v[90:93], v160 offset:36864
	ds_read_b128 v[94:97], v160 offset:37888
	ds_read_b128 v[224:227], v160 offset:38912
	ds_read_b128 v[228:231], v160 offset:39936
	s_add_u32 s20, s1, 0x80100
	s_addc_u32 s21, s3, 0
	s_add_i32 s17, s6, 0x4000
	s_mov_b32 m0, s17
	s_nop 0
	global_load_lds_dwordx4 v134, s[20:21]
	s_add_i32 s18, s6, 0x6000
	s_mov_b32 m0, s18
	s_nop 0
	global_load_lds_dwordx4 v135, s[20:21]
	s_waitcnt lgkmcnt(8)
	s_barrier
; #define WAIT_V(n) asm volatile("s_waitcnt vmcnt(" #n ")" ::: "memory")
; #define WAIT_L(n) asm volatile("s_waitcnt lgkmcnt(" #n ")" ::: "memory")
; #define BAR __builtin_amdgcn_s_barrier()
; #define SCHED __builtin_amdgcn_sched_barrier(0)
; #define STG_A(b, h, kt) stage_half_s(lds0 + ((b) * 2 + (h)) * HT_B, ((h) ? A1 : Ap) + (kt) * BK, off0, off1)
; #define STG_B(b, h, kt) stage_half_s(lds0 + (4 + (b) * 2 + (h)) * HT_B, ((h) ? B1p : Bp) + (kt) * BK, off0, off1)
; #define STG_A(b, h, kt) stage_half_s(lds0 + ((b) * 2 + (h)) * HT_B, ((h) ? A1 : Ap) + (kt) * BK, off0, off1)
; #define STG_B(b, h, kt) stage_half_s(lds0 + (4 + (b) * 2 + (h)) * HT_B, ((h) ? B1p : Bp) + (kt) * BK, off0, off1)
; #define LDA8(b, h) _Pragma("unroll") for (int m = 0; m < 4; ++m) _Pragma("unroll") for (int k = 0; k < 2; ++k) \
;     At[m][k] = *(const bf16x8*)(SA_(shm, b, h) + abase + (m * 2 + k) * 1024)
; #define LDB8(dst, b, h) _Pragma("unroll") for (int n = 0; n < 2; ++n) _Pragma("unroll") for (int k = 0; k < 2; ++k) \
;     dst[n][k] = *(const bf16x8*)(SB_(shm, b, h) + bbase + (n * 2 + k) * 1024)
; #define MMA8(ai, bj, Bx) do { __builtin_amdgcn_s_setprio(1); \
;     _Pragma("unroll") for (int m = 0; m < 4; ++m) _Pragma("unroll") for (int n = 0; n < 2; ++n) _Pragma("unroll") for (int k = 0; k < 2; ++k) \
;       acc[ai][bj][m][n] = __builtin_amdgcn_mfma_f32_16x16x32_bf16(At[m][k], Bx[n][k], acc[ai][bj][m][n], 0, 0, 0); \
;     __builtin_amdgcn_s_setprio(0); } while (0)
; template <bool HS>
; __device__ __forceinline__ void gemm_tile8(const u16* __restrict__ Ap, const u16* __restrict__ Bp, int K,
;                                            f32x4 (&acc)[2][2][4][2], char* shm, const int tid, const float* hsr = nullptr) {
;     ...
;     if constexpr (HS) {
;       if (t > 0 && (t & 7) == 0) {
;         const float* rt = hsr + ((t >> 3) - 1) * 256 + wr * 64 + fq * 4;
;     ...
;     WAIT_L(8); BAR; WAIT_L(0); MMA8(0, 0, B0); BAR; SCHED;
;     LDB8(B1, 1, 1); STG_B(1, 0, t + 3);
;     BAR; WAIT_L(0); MMA8(0, 1, B1); BAR;
;     LDA8(1, 1); STG_A(1, 0, t + 3);
;     BAR; WAIT_L(0); MMA8(1, 0, B0); BAR; SCHED;
;     STG_B(1, 1, t + 3);
;     WAIT_V(6); BAR; MMA8(1, 1, B1); BAR;
;   }
	s_waitcnt lgkmcnt(0)
	s_setprio 1
	s_waitcnt lgkmcnt(7)
	v_mfma_f32_16x16x32_bf16 v[2:5], v[42:45], v[122:125], v[50:53]
	s_waitcnt lgkmcnt(6)
	v_mfma_f32_16x16x32_bf16 v[30:33], v[46:49], v[126:129], v[2:5]
	v_mfma_f32_16x16x32_bf16 v[2:5], v[42:45], v[212:215], v[54:57]
	v_mfma_f32_16x16x32_bf16 v[26:29], v[46:49], v[220:223], v[2:5]
	s_waitcnt lgkmcnt(5)
	v_mfma_f32_16x16x32_bf16 v[2:5], v[82:85], v[122:125], v[58:61]
	s_waitcnt lgkmcnt(4)
	v_mfma_f32_16x16x32_bf16 v[22:25], v[86:89], v[126:129], v[2:5]
	v_mfma_f32_16x16x32_bf16 v[2:5], v[82:85], v[212:215], v[62:65]
	v_mfma_f32_16x16x32_bf16 v[18:21], v[86:89], v[220:223], v[2:5]
	s_waitcnt lgkmcnt(3)
	v_mfma_f32_16x16x32_bf16 v[2:5], v[90:93], v[122:125], v[66:69]
	s_waitcnt lgkmcnt(2)
	v_mfma_f32_16x16x32_bf16 v[14:17], v[94:97], v[126:129], v[2:5]
	v_mfma_f32_16x16x32_bf16 v[2:5], v[90:93], v[212:215], v[70:73]
	v_mfma_f32_16x16x32_bf16 v[10:13], v[94:97], v[220:223], v[2:5]
	s_waitcnt lgkmcnt(1)
	v_mfma_f32_16x16x32_bf16 v[2:5], v[224:227], v[122:125], v[74:77]
	s_waitcnt lgkmcnt(0)
	v_mfma_f32_16x16x32_bf16 v[6:9], v[228:231], v[126:129], v[2:5]
	v_mfma_f32_16x16x32_bf16 v[2:5], v[224:227], v[212:215], v[78:81]
	v_mfma_f32_16x16x32_bf16 v[2:5], v[228:231], v[220:223], v[2:5]
	s_setprio 0
	s_barrier
	ds_read_b128 v[242:245], v140
	ds_read_b128 v[246:249], v140 offset:1024
	ds_read_b128 v[232:235], v140 offset:2048
	ds_read_b128 v[238:241], v140 offset:3072
	v_lshl_add_u64 v[50:51], v[250:251], 0, s[86:87]
	s_add_i32 s19, s23, s19
	v_readfirstlane_b32 s37, v51
	v_readfirstlane_b32 s36, v50
	s_mov_b32 m0, s19
	s_nop 3
	global_load_lds_dwordx4 v134, s[36:37]
	s_add_i32 s20, s6, 0x1a000
	s_mov_b32 m0, s20
	s_nop 0
	global_load_lds_dwordx4 v135, s[36:37]
	s_barrier
	s_waitcnt lgkmcnt(0)
	s_setprio 1
	s_waitcnt lgkmcnt(3)
	v_mfma_f32_16x16x32_bf16 v[50:53], v[42:45], v[242:245], v[98:101]
	s_waitcnt lgkmcnt(1)
	v_mfma_f32_16x16x32_bf16 v[42:45], v[42:45], v[232:235], v[102:105]
	s_waitcnt lgkmcnt(0)
	v_mfma_f32_16x16x32_bf16 v[58:61], v[46:49], v[238:241], v[42:45]
	v_mfma_f32_16x16x32_bf16 v[42:45], v[82:85], v[242:245], v[106:109]
	v_mfma_f32_16x16x32_bf16 v[54:57], v[86:89], v[246:249], v[42:45]
	v_mfma_f32_16x16x32_bf16 v[42:45], v[82:85], v[232:235], v[110:113]
	v_mfma_f32_16x16x32_bf16 v[62:65], v[46:49], v[246:249], v[50:53]
	v_mfma_f32_16x16x32_bf16 v[50:53], v[86:89], v[238:241], v[42:45]
	v_mfma_f32_16x16x32_bf16 v[42:45], v[90:93], v[242:245], v[114:117]
	v_mfma_f32_16x16x32_bf16 v[34:37], v[90:93], v[232:235], v[34:37]
	v_mfma_f32_16x16x32_bf16 v[46:49], v[94:97], v[246:249], v[42:45]
	v_mfma_f32_16x16x32_bf16 v[42:45], v[94:97], v[238:241], v[34:37]
	v_mfma_f32_16x16x32_bf16 v[34:37], v[224:227], v[242:245], v[38:41]
	v_mfma_f32_16x16x32_bf16 v[38:41], v[228:231], v[246:249], v[34:37]
	v_mfma_f32_16x16x32_bf16 v[34:37], v[224:227], v[232:235], v[118:121]
	v_mfma_f32_16x16x32_bf16 v[34:37], v[228:231], v[238:241], v[34:37]
	s_setprio 0
	s_barrier
	ds_read_b128 v[98:101], v160 offset:49152
	ds_read_b128 v[102:105], v160 offset:50176
	ds_read_b128 v[106:109], v160 offset:51200
	ds_read_b128 v[110:113], v160 offset:52224
	ds_read_b128 v[224:227], v160 offset:53248
	ds_read_b128 v[228:231], v160 offset:54272
	ds_read_b128 v[216:219], v160 offset:55296
	ds_read_b128 v[130:133], v160 offset:56320
	s_add_u32 s36, s1, 0x180
	s_addc_u32 s37, s3, 0
	s_add_i32 s21, s6, 0x8000
	s_mov_b32 m0, s21
	s_nop 0
	global_load_lds_dwordx4 v134, s[36:37]
	s_add_i32 s22, s6, 0xa000
	s_mov_b32 m0, s22
	s_nop 0
	global_load_lds_dwordx4 v135, s[36:37]
	s_barrier
	s_waitcnt lgkmcnt(0)
	s_setprio 1
	s_waitcnt lgkmcnt(7)
	v_mfma_f32_16x16x32_bf16 v[66:69], v[98:101], v[122:125], v[142:145]
	s_waitcnt lgkmcnt(6)
	v_mfma_f32_16x16x32_bf16 v[94:97], v[102:105], v[126:129], v[66:69]
	v_mfma_f32_16x16x32_bf16 v[66:69], v[98:101], v[212:215], v[146:149]
	v_mfma_f32_16x16x32_bf16 v[90:93], v[102:105], v[220:223], v[66:69]
	s_waitcnt lgkmcnt(5)
	v_mfma_f32_16x16x32_bf16 v[66:69], v[106:109], v[122:125], v[150:153]
	s_waitcnt lgkmcnt(4)
	v_mfma_f32_16x16x32_bf16 v[86:89], v[110:113], v[126:129], v[66:69]
	v_mfma_f32_16x16x32_bf16 v[66:69], v[106:109], v[212:215], v[154:157]
	v_mfma_f32_16x16x32_bf16 v[82:85], v[110:113], v[220:223], v[66:69]
	s_waitcnt lgkmcnt(3)
	v_mfma_f32_16x16x32_bf16 v[66:69], v[224:227], v[122:125], v[162:165]
	s_waitcnt lgkmcnt(2)
	v_mfma_f32_16x16x32_bf16 v[78:81], v[228:231], v[126:129], v[66:69]
	v_mfma_f32_16x16x32_bf16 v[66:69], v[224:227], v[212:215], v[166:169]
	v_mfma_f32_16x16x32_bf16 v[74:77], v[228:231], v[220:223], v[66:69]
	s_waitcnt lgkmcnt(1)
	v_mfma_f32_16x16x32_bf16 v[66:69], v[216:219], v[122:125], v[170:173]
	s_waitcnt lgkmcnt(0)
	v_mfma_f32_16x16x32_bf16 v[70:73], v[130:133], v[126:129], v[66:69]
	v_mfma_f32_16x16x32_bf16 v[66:69], v[216:219], v[212:215], v[174:177]
	v_mfma_f32_16x16x32_bf16 v[66:69], v[130:133], v[220:223], v[66:69]
	s_setprio 0
	s_barrier
	s_mov_b64 s[36:37], 0x80180
	v_lshl_add_u64 v[114:115], v[250:251], 0, s[36:37]
	s_add_i32 s23, s23, s24
	v_readfirstlane_b32 s37, v115
	v_readfirstlane_b32 s36, v114
	s_mov_b32 m0, s23
	s_nop 3
	global_load_lds_dwordx4 v134, s[36:37]
	s_add_i32 s24, s6, 0x1e000
	s_mov_b32 m0, s24
	s_nop 0
	global_load_lds_dwordx4 v135, s[36:37]
	s_waitcnt vmcnt(6)
	s_barrier
	s_setprio 1
	v_mfma_f32_16x16x32_bf16 v[114:117], v[98:101], v[242:245], v[180:183]
	v_mfma_f32_16x16x32_bf16 v[98:101], v[98:101], v[232:235], v[184:187]
	v_mfma_f32_16x16x32_bf16 v[122:125], v[102:105], v[238:241], v[98:101]
	v_mfma_f32_16x16x32_bf16 v[98:101], v[106:109], v[242:245], v[188:191]
	v_mfma_f32_16x16x32_bf16 v[118:121], v[110:113], v[246:249], v[98:101]
	v_mfma_f32_16x16x32_bf16 v[98:101], v[106:109], v[232:235], v[192:195]
	v_mfma_f32_16x16x32_bf16 v[126:129], v[102:105], v[246:249], v[114:117]
	v_mfma_f32_16x16x32_bf16 v[114:117], v[110:113], v[238:241], v[98:101]
	v_mfma_f32_16x16x32_bf16 v[98:101], v[224:227], v[242:245], v[196:199]
	v_mfma_f32_16x16x32_bf16 v[110:113], v[228:231], v[246:249], v[98:101]
	v_mfma_f32_16x16x32_bf16 v[98:101], v[224:227], v[232:235], v[200:203]
	v_mfma_f32_16x16x32_bf16 v[106:109], v[228:231], v[238:241], v[98:101]
	v_mfma_f32_16x16x32_bf16 v[98:101], v[216:219], v[242:245], v[204:207]
	v_mfma_f32_16x16x32_bf16 v[102:105], v[130:133], v[246:249], v[98:101]
	v_mfma_f32_16x16x32_bf16 v[98:101], v[216:219], v[232:235], v[208:211]
	v_mfma_f32_16x16x32_bf16 v[98:101], v[130:133], v[238:241], v[98:101]
	s_setprio 0
	v_readlane_b32 s25, v254, 36
	s_add_u32 s25, s25, s4
	v_readlane_b32 s4, v254, 37
	s_addc_u32 s26, s4, s5
	s_lshl_b32 s4, s27, 2
	s_and_b32 s4, s4, 0x1000
	v_lshl_add_u32 v130, v141, 8, s4
	v_or_b32_e32 v130, v130, v158
	v_readlane_b32 s4, v254, 40
	s_add_u32 s27, s1, 0x80200
	s_addc_u32 s68, s3, 0
	v_add_u32_e32 v141, s4, v130
	s_mov_b64 s[4:5], 0
	s_barrier
	s_and_b32 s36, s11, 6
	s_cmp_lg_u32 s36, 0
	s_cbranch_scc1 .LBB0_343

; #define WAIT_V(n) asm volatile("s_waitcnt vmcnt(" #n ")" ::: "memory")
; #define WAIT_L(n) asm volatile("s_waitcnt lgkmcnt(" #n ")" ::: "memory")
; #define BAR __builtin_amdgcn_s_barrier()
; #define SCHED __builtin_amdgcn_sched_barrier(0)
; #define STG_A(b, h, kt) stage_half_s(lds0 + ((b) * 2 + (h)) * HT_B, ((h) ? A1 : Ap) + (kt) * BK, off0, off1)
; #define STG_B(b, h, kt) stage_half_s(lds0 + (4 + (b) * 2 + (h)) * HT_B, ((h) ? B1p : Bp) + (kt) * BK, off0, off1)
; #define STG_A(b, h, kt) stage_half_s(lds0 + ((b) * 2 + (h)) * HT_B, ((h) ? A1 : Ap) + (kt) * BK, off0, off1)
; #define STG_B(b, h, kt) stage_half_s(lds0 + (4 + (b) * 2 + (h)) * HT_B, ((h) ? B1p : Bp) + (kt) * BK, off0, off1)
; #define LDA8(b, h) _Pragma("unroll") for (int m = 0; m < 4; ++m) _Pragma("unroll") for (int k = 0; k < 2; ++k) \
;     At[m][k] = *(const bf16x8*)(SA_(shm, b, h) + abase + (m * 2 + k) * 1024)
; #define LDB8(dst, b, h) _Pragma("unroll") for (int n = 0; n < 2; ++n) _Pragma("unroll") for (int k = 0; k < 2; ++k) \
;     dst[n][k] = *(const bf16x8*)(SB_(shm, b, h) + bbase + (n * 2 + k) * 1024)
; #define MMA8(ai, bj, Bx) do { __builtin_amdgcn_s_setprio(1); \
;     _Pragma("unroll") for (int m = 0; m < 4; ++m) _Pragma("unroll") for (int n = 0; n < 2; ++n) _Pragma("unroll") for (int k = 0; k < 2; ++k) \
;       acc[ai][bj][m][n] = __builtin_amdgcn_mfma_f32_16x16x32_bf16(At[m][k], Bx[n][k], acc[ai][bj][m][n], 0, 0, 0); \
;     __builtin_amdgcn_s_setprio(0); } while (0)
; template <bool HS>
; __device__ __forceinline__ void gemm_tile8(const u16* __restrict__ Ap, const u16* __restrict__ Bp, int K,
;                                            f32x4 (&acc)[2][2][4][2], char* shm, const int tid, const float* hsr = nullptr) {
;     ...
;     LDB8(B0, 0, 0); SCHED; LDA8(0, 0); STG_A(1, 1, t + 1);
;     WAIT_L(8); BAR; WAIT_L(0); MMA8(0, 0, B0); BAR; SCHED;
;     LDB8(B1, 0, 1); STG_B(0, 0, t + 2);
;     BAR; WAIT_L(0); MMA8(0, 1, B1); BAR;
;     LDA8(0, 1); STG_A(0, 0, t + 2);
;     BAR; WAIT_L(0); MMA8(1, 0, B0); BAR; SCHED;
;     STG_B(0, 1, t + 2);
;     WAIT_V(6); BAR; MMA8(1, 1, B1); BAR;
;     LDB8(B0, 1, 0); SCHED; LDA8(1, 0); STG_A(0, 1, t + 2);
;     WAIT_L(8); BAR; WAIT_L(0); MMA8(0, 0, B0); BAR; SCHED;
;     LDB8(B1, 1, 1); STG_B(1, 0, t + 3);
.LBB0_343:
	ds_read_b128 v[130:133], v137
	ds_read_b128 v[142:145], v137 offset:1024
	ds_read_b128 v[146:149], v137 offset:2048
	ds_read_b128 v[150:153], v137 offset:3072
	ds_read_b128 v[154:157], v160
	ds_read_b128 v[162:165], v160 offset:1024
	ds_read_b128 v[166:169], v160 offset:2048
	ds_read_b128 v[170:173], v160 offset:3072
	ds_read_b128 v[174:177], v160 offset:4096
	ds_read_b128 v[180:183], v160 offset:5120
	ds_read_b128 v[184:187], v160 offset:6144
	ds_read_b128 v[188:191], v160 offset:7168
	s_add_u32 s36, s25, s4
	s_addc_u32 s37, s26, s5
	s_add_u32 s36, s36, 0x80
	s_addc_u32 s37, s37, 0
	s_mov_b32 m0, s7
	s_nop 0
	global_load_lds_dwordx4 v134, s[36:37]
	s_nop 0
	s_mov_b32 m0, s10
	s_nop 0
	global_load_lds_dwordx4 v135, s[36:37]
	s_waitcnt lgkmcnt(8)
	s_barrier
	s_waitcnt lgkmcnt(0)
	s_setprio 1
	s_waitcnt lgkmcnt(7)
	v_mfma_f32_16x16x32_bf16 v[30:33], v[154:157], v[130:133], v[30:33]
	v_mfma_f32_16x16x32_bf16 v[26:29], v[154:157], v[146:149], v[26:29]
	s_waitcnt lgkmcnt(5)
	v_mfma_f32_16x16x32_bf16 v[22:25], v[166:169], v[130:133], v[22:25]
	v_mfma_f32_16x16x32_bf16 v[18:21], v[166:169], v[146:149], v[18:21]
	s_waitcnt lgkmcnt(3)
	v_mfma_f32_16x16x32_bf16 v[14:17], v[174:177], v[130:133], v[14:17]
	v_mfma_f32_16x16x32_bf16 v[10:13], v[174:177], v[146:149], v[10:13]
	s_waitcnt lgkmcnt(1)
	v_mfma_f32_16x16x32_bf16 v[6:9], v[184:187], v[130:133], v[6:9]
	v_mfma_f32_16x16x32_bf16 v[2:5], v[184:187], v[146:149], v[2:5]
	v_mfma_f32_16x16x32_bf16 v[30:33], v[162:165], v[142:145], v[30:33]
	v_mfma_f32_16x16x32_bf16 v[26:29], v[162:165], v[150:153], v[26:29]
	v_mfma_f32_16x16x32_bf16 v[22:25], v[170:173], v[142:145], v[22:25]
	v_mfma_f32_16x16x32_bf16 v[18:21], v[170:173], v[150:153], v[18:21]
	v_mfma_f32_16x16x32_bf16 v[14:17], v[180:183], v[142:145], v[14:17]
	v_mfma_f32_16x16x32_bf16 v[10:13], v[180:183], v[150:153], v[10:13]
	s_waitcnt lgkmcnt(0)
	v_mfma_f32_16x16x32_bf16 v[6:9], v[188:191], v[142:145], v[6:9]
	v_mfma_f32_16x16x32_bf16 v[2:5], v[188:191], v[150:153], v[2:5]
	s_setprio 0
	s_barrier
	ds_read_b128 v[192:195], v138
	ds_read_b128 v[196:199], v138 offset:1024
	ds_read_b128 v[200:203], v138 offset:2048
	ds_read_b128 v[204:207], v138 offset:3072
	v_lshl_add_u64 v[208:209], v[250:251], 0, s[4:5]
	s_mov_b64 s[52:53], 0x200
	v_lshl_add_u64 v[210:211], v[208:209], 0, s[52:53]
	s_add_i32 s69, s11, 2
	v_readfirstlane_b32 s37, v211
	v_readfirstlane_b32 s36, v210
	s_mov_b32 m0, s12
	s_nop 3
	global_load_lds_dwordx4 v134, s[36:37]
	s_nop 0
	s_mov_b32 m0, s13
	s_nop 0
	global_load_lds_dwordx4 v135, s[36:37]
	s_barrier
	s_waitcnt lgkmcnt(0)
	s_setprio 1
	s_waitcnt lgkmcnt(3)
	v_mfma_f32_16x16x32_bf16 v[62:65], v[154:157], v[192:195], v[62:65]
	s_waitcnt lgkmcnt(1)
	v_mfma_f32_16x16x32_bf16 v[58:61], v[154:157], v[200:203], v[58:61]
	v_mfma_f32_16x16x32_bf16 v[54:57], v[166:169], v[192:195], v[54:57]
	v_mfma_f32_16x16x32_bf16 v[50:53], v[166:169], v[200:203], v[50:53]
	v_mfma_f32_16x16x32_bf16 v[46:49], v[174:177], v[192:195], v[46:49]
	v_mfma_f32_16x16x32_bf16 v[42:45], v[174:177], v[200:203], v[42:45]
	v_mfma_f32_16x16x32_bf16 v[38:41], v[184:187], v[192:195], v[38:41]
	v_mfma_f32_16x16x32_bf16 v[34:37], v[184:187], v[200:203], v[34:37]
	v_mfma_f32_16x16x32_bf16 v[62:65], v[162:165], v[196:199], v[62:65]
	s_waitcnt lgkmcnt(0)
	v_mfma_f32_16x16x32_bf16 v[58:61], v[162:165], v[204:207], v[58:61]
	v_mfma_f32_16x16x32_bf16 v[54:57], v[170:173], v[196:199], v[54:57]
	v_mfma_f32_16x16x32_bf16 v[50:53], v[170:173], v[204:207], v[50:53]
	v_mfma_f32_16x16x32_bf16 v[46:49], v[180:183], v[196:199], v[46:49]
	v_mfma_f32_16x16x32_bf16 v[42:45], v[180:183], v[204:207], v[42:45]
	v_mfma_f32_16x16x32_bf16 v[38:41], v[188:191], v[196:199], v[38:41]
	v_mfma_f32_16x16x32_bf16 v[34:37], v[188:191], v[204:207], v[34:37]
	s_setprio 0
	s_barrier
	ds_read_b128 v[154:157], v160 offset:16384
	ds_read_b128 v[162:165], v160 offset:17408
	ds_read_b128 v[166:169], v160 offset:18432
	ds_read_b128 v[170:173], v160 offset:19456
	ds_read_b128 v[174:177], v160 offset:20480
	ds_read_b128 v[180:183], v160 offset:21504
	ds_read_b128 v[184:187], v160 offset:22528
	ds_read_b128 v[188:191], v160 offset:23552
	s_add_u32 s38, s1, s4
	s_addc_u32 s39, s3, s5
	s_add_u32 s36, s38, 0x200
	s_addc_u32 s37, s39, 0
	s_mov_b32 m0, s6
	s_nop 0
	global_load_lds_dwordx4 v134, s[36:37]
	s_nop 0
	s_mov_b32 m0, s14
	s_nop 0
	global_load_lds_dwordx4 v135, s[36:37]
	s_barrier
	s_waitcnt lgkmcnt(0)
	s_setprio 1
	s_waitcnt lgkmcnt(7)
	v_mfma_f32_16x16x32_bf16 v[94:97], v[154:157], v[130:133], v[94:97]
	v_mfma_f32_16x16x32_bf16 v[90:93], v[154:157], v[146:149], v[90:93]
	s_waitcnt lgkmcnt(5)
	v_mfma_f32_16x16x32_bf16 v[86:89], v[166:169], v[130:133], v[86:89]
	v_mfma_f32_16x16x32_bf16 v[82:85], v[166:169], v[146:149], v[82:85]
	s_waitcnt lgkmcnt(3)
	v_mfma_f32_16x16x32_bf16 v[78:81], v[174:177], v[130:133], v[78:81]
	v_mfma_f32_16x16x32_bf16 v[74:77], v[174:177], v[146:149], v[74:77]
	s_waitcnt lgkmcnt(1)
	v_mfma_f32_16x16x32_bf16 v[70:73], v[184:187], v[130:133], v[70:73]
	v_mfma_f32_16x16x32_bf16 v[66:69], v[184:187], v[146:149], v[66:69]
	v_mfma_f32_16x16x32_bf16 v[94:97], v[162:165], v[142:145], v[94:97]
	v_mfma_f32_16x16x32_bf16 v[90:93], v[162:165], v[150:153], v[90:93]
	v_mfma_f32_16x16x32_bf16 v[86:89], v[170:173], v[142:145], v[86:89]
	v_mfma_f32_16x16x32_bf16 v[82:85], v[170:173], v[150:153], v[82:85]
	v_mfma_f32_16x16x32_bf16 v[78:81], v[180:183], v[142:145], v[78:81]
	v_mfma_f32_16x16x32_bf16 v[74:77], v[180:183], v[150:153], v[74:77]
	s_waitcnt lgkmcnt(0)
	v_mfma_f32_16x16x32_bf16 v[70:73], v[188:191], v[142:145], v[70:73]
	v_mfma_f32_16x16x32_bf16 v[66:69], v[188:191], v[150:153], v[66:69]
	s_setprio 0
	s_barrier
; #define WAIT_V(n) asm volatile("s_waitcnt vmcnt(" #n ")" ::: "memory")
; #define WAIT_L(n) asm volatile("s_waitcnt lgkmcnt(" #n ")" ::: "memory")
; #define BAR __builtin_amdgcn_s_barrier()
; #define SCHED __builtin_amdgcn_sched_barrier(0)
; #define STG_A(b, h, kt) stage_half_s(lds0 + ((b) * 2 + (h)) * HT_B, ((h) ? A1 : Ap) + (kt) * BK, off0, off1)
; #define STG_B(b, h, kt) stage_half_s(lds0 + (4 + (b) * 2 + (h)) * HT_B, ((h) ? B1p : Bp) + (kt) * BK, off0, off1)
; #define STG_A(b, h, kt) stage_half_s(lds0 + ((b) * 2 + (h)) * HT_B, ((h) ? A1 : Ap) + (kt) * BK, off0, off1)
; #define STG_B(b, h, kt) stage_half_s(lds0 + (4 + (b) * 2 + (h)) * HT_B, ((h) ? B1p : Bp) + (kt) * BK, off0, off1)
; #define LDA8(b, h) _Pragma("unroll") for (int m = 0; m < 4; ++m) _Pragma("unroll") for (int k = 0; k < 2; ++k) \
;     At[m][k] = *(const bf16x8*)(SA_(shm, b, h) + abase + (m * 2 + k) * 1024)
; #define LDB8(dst, b, h) _Pragma("unroll") for (int n = 0; n < 2; ++n) _Pragma("unroll") for (int k = 0; k < 2; ++k) \
;     dst[n][k] = *(const bf16x8*)(SB_(shm, b, h) + bbase + (n * 2 + k) * 1024)
; #define MMA8(ai, bj, Bx) do { __builtin_amdgcn_s_setprio(1); \
;     _Pragma("unroll") for (int m = 0; m < 4; ++m) _Pragma("unroll") for (int n = 0; n < 2; ++n) _Pragma("unroll") for (int k = 0; k < 2; ++k) \
;       acc[ai][bj][m][n] = __builtin_amdgcn_mfma_f32_16x16x32_bf16(At[m][k], Bx[n][k], acc[ai][bj][m][n], 0, 0, 0); \
;     __builtin_amdgcn_s_setprio(0); } while (0)
; template <bool HS>
; __device__ __forceinline__ void gemm_tile8(const u16* __restrict__ Ap, const u16* __restrict__ Bp, int K,
;                                            f32x4 (&acc)[2][2][4][2], char* shm, const int tid, const float* hsr = nullptr) {
;     ...
;     STG_B(0, 1, t + 2);
;     WAIT_V(6); BAR; MMA8(1, 1, B1); BAR;
;     LDB8(B0, 1, 0); SCHED; LDA8(1, 0); STG_A(0, 1, t + 2);
;     WAIT_L(8); BAR; WAIT_L(0); MMA8(0, 0, B0); BAR; SCHED;
;     LDB8(B1, 1, 1); STG_B(1, 0, t + 3);
;     BAR; WAIT_L(0); MMA8(0, 1, B1); BAR;
;     LDA8(1, 1); STG_A(1, 0, t + 3);
;     BAR; WAIT_L(0); MMA8(1, 0, B0); BAR; SCHED;
	v_lshl_add_u64 v[210:211], v[236:237], 0, s[4:5]
	v_lshl_add_u64 v[130:131], v[210:211], 0, s[52:53]
	s_nop 0
	v_readfirstlane_b32 s37, v131
	v_readfirstlane_b32 s36, v130
	s_mov_b32 m0, s15
	s_nop 3
	global_load_lds_dwordx4 v134, s[36:37]
	s_nop 0
	s_mov_b32 m0, s16
	s_nop 0
	global_load_lds_dwordx4 v135, s[36:37]
	s_waitcnt vmcnt(6)
	s_barrier
	s_setprio 1
	v_mfma_f32_16x16x32_bf16 v[126:129], v[154:157], v[192:195], v[126:129]
	v_mfma_f32_16x16x32_bf16 v[122:125], v[154:157], v[200:203], v[122:125]
	v_mfma_f32_16x16x32_bf16 v[118:121], v[166:169], v[192:195], v[118:121]
	v_mfma_f32_16x16x32_bf16 v[114:117], v[166:169], v[200:203], v[114:117]
	v_mfma_f32_16x16x32_bf16 v[110:113], v[174:177], v[192:195], v[110:113]
	v_mfma_f32_16x16x32_bf16 v[106:109], v[174:177], v[200:203], v[106:109]
	v_mfma_f32_16x16x32_bf16 v[102:105], v[184:187], v[192:195], v[102:105]
	v_mfma_f32_16x16x32_bf16 v[98:101], v[184:187], v[200:203], v[98:101]
	v_mfma_f32_16x16x32_bf16 v[126:129], v[162:165], v[196:199], v[126:129]
	v_mfma_f32_16x16x32_bf16 v[122:125], v[162:165], v[204:207], v[122:125]
	v_mfma_f32_16x16x32_bf16 v[118:121], v[170:173], v[196:199], v[118:121]
	v_mfma_f32_16x16x32_bf16 v[114:117], v[170:173], v[204:207], v[114:117]
	v_mfma_f32_16x16x32_bf16 v[110:113], v[180:183], v[196:199], v[110:113]
	v_mfma_f32_16x16x32_bf16 v[106:109], v[180:183], v[204:207], v[106:109]
	v_mfma_f32_16x16x32_bf16 v[102:105], v[188:191], v[196:199], v[102:105]
	v_mfma_f32_16x16x32_bf16 v[98:101], v[188:191], v[204:207], v[98:101]
	s_setprio 0
	s_barrier
	ds_read_b128 v[130:133], v139
	ds_read_b128 v[142:145], v139 offset:1024
	ds_read_b128 v[146:149], v139 offset:2048
	ds_read_b128 v[150:153], v139 offset:3072
	ds_read_b128 v[154:157], v160 offset:32768
	ds_read_b128 v[162:165], v160 offset:33792
	ds_read_b128 v[166:169], v160 offset:34816
	ds_read_b128 v[170:173], v160 offset:35840
	ds_read_b128 v[174:177], v160 offset:36864
	ds_read_b128 v[180:183], v160 offset:37888
	ds_read_b128 v[184:187], v160 offset:38912
	ds_read_b128 v[188:191], v160 offset:39936
	s_add_u32 s36, s27, s4
	s_addc_u32 s37, s68, s5
	s_mov_b32 m0, s17
	s_nop 0
	global_load_lds_dwordx4 v134, s[36:37]
	s_nop 0
	s_mov_b32 m0, s18
	s_nop 0
	global_load_lds_dwordx4 v135, s[36:37]
	s_waitcnt lgkmcnt(8)
	s_barrier
	s_waitcnt lgkmcnt(0)
	s_setprio 1
	s_waitcnt lgkmcnt(7)
	v_mfma_f32_16x16x32_bf16 v[30:33], v[154:157], v[130:133], v[30:33]
	v_mfma_f32_16x16x32_bf16 v[26:29], v[154:157], v[146:149], v[26:29]
	s_waitcnt lgkmcnt(5)
	v_mfma_f32_16x16x32_bf16 v[22:25], v[166:169], v[130:133], v[22:25]
	v_mfma_f32_16x16x32_bf16 v[18:21], v[166:169], v[146:149], v[18:21]
	s_waitcnt lgkmcnt(3)
	v_mfma_f32_16x16x32_bf16 v[14:17], v[174:177], v[130:133], v[14:17]
	v_mfma_f32_16x16x32_bf16 v[10:13], v[174:177], v[146:149], v[10:13]
	s_waitcnt lgkmcnt(1)
	v_mfma_f32_16x16x32_bf16 v[6:9], v[184:187], v[130:133], v[6:9]
	v_mfma_f32_16x16x32_bf16 v[2:5], v[184:187], v[146:149], v[2:5]
	v_mfma_f32_16x16x32_bf16 v[30:33], v[162:165], v[142:145], v[30:33]
	v_mfma_f32_16x16x32_bf16 v[26:29], v[162:165], v[150:153], v[26:29]
	v_mfma_f32_16x16x32_bf16 v[22:25], v[170:173], v[142:145], v[22:25]
	v_mfma_f32_16x16x32_bf16 v[18:21], v[170:173], v[150:153], v[18:21]
	v_mfma_f32_16x16x32_bf16 v[14:17], v[180:183], v[142:145], v[14:17]
	v_mfma_f32_16x16x32_bf16 v[10:13], v[180:183], v[150:153], v[10:13]
	s_waitcnt lgkmcnt(0)
	v_mfma_f32_16x16x32_bf16 v[6:9], v[188:191], v[142:145], v[6:9]
	v_mfma_f32_16x16x32_bf16 v[2:5], v[188:191], v[150:153], v[2:5]
	s_setprio 0
	s_barrier
	ds_read_b128 v[192:195], v140
	ds_read_b128 v[196:199], v140 offset:1024
	ds_read_b128 v[200:203], v140 offset:2048
	ds_read_b128 v[204:207], v140 offset:3072
	s_mov_b64 s[52:53], 0x280
	v_lshl_add_u64 v[208:209], v[208:209], 0, s[52:53]
	s_nop 0
	v_readfirstlane_b32 s37, v209
	v_readfirstlane_b32 s36, v208
	s_mov_b32 m0, s19
	s_nop 3
	global_load_lds_dwordx4 v134, s[36:37]
	s_nop 0
	s_mov_b32 m0, s20
	s_nop 0
	global_load_lds_dwordx4 v135, s[36:37]
	s_barrier
	s_waitcnt lgkmcnt(0)
	s_setprio 1
	s_waitcnt lgkmcnt(3)
	v_mfma_f32_16x16x32_bf16 v[62:65], v[154:157], v[192:195], v[62:65]
	s_waitcnt lgkmcnt(1)
	v_mfma_f32_16x16x32_bf16 v[58:61], v[154:157], v[200:203], v[58:61]
	v_mfma_f32_16x16x32_bf16 v[54:57], v[166:169], v[192:195], v[54:57]
	v_mfma_f32_16x16x32_bf16 v[50:53], v[166:169], v[200:203], v[50:53]
	v_mfma_f32_16x16x32_bf16 v[46:49], v[174:177], v[192:195], v[46:49]
	v_mfma_f32_16x16x32_bf16 v[42:45], v[174:177], v[200:203], v[42:45]
	v_mfma_f32_16x16x32_bf16 v[38:41], v[184:187], v[192:195], v[38:41]
	v_mfma_f32_16x16x32_bf16 v[34:37], v[184:187], v[200:203], v[34:37]
	v_mfma_f32_16x16x32_bf16 v[62:65], v[162:165], v[196:199], v[62:65]
	s_waitcnt lgkmcnt(0)
	v_mfma_f32_16x16x32_bf16 v[58:61], v[162:165], v[204:207], v[58:61]
	v_mfma_f32_16x16x32_bf16 v[54:57], v[170:173], v[196:199], v[54:57]
	v_mfma_f32_16x16x32_bf16 v[50:53], v[170:173], v[204:207], v[50:53]
	v_mfma_f32_16x16x32_bf16 v[46:49], v[180:183], v[196:199], v[46:49]
	v_mfma_f32_16x16x32_bf16 v[42:45], v[180:183], v[204:207], v[42:45]
	v_mfma_f32_16x16x32_bf16 v[38:41], v[188:191], v[196:199], v[38:41]
	v_mfma_f32_16x16x32_bf16 v[34:37], v[188:191], v[204:207], v[34:37]
	s_setprio 0
	s_barrier
	ds_read_b128 v[154:157], v160 offset:49152
	ds_read_b128 v[162:165], v160 offset:50176
	ds_read_b128 v[166:169], v160 offset:51200
	ds_read_b128 v[170:173], v160 offset:52224
	ds_read_b128 v[174:177], v160 offset:53248
	ds_read_b128 v[180:183], v160 offset:54272
	ds_read_b128 v[184:187], v160 offset:55296
	ds_read_b128 v[188:191], v160 offset:56320
	s_add_u32 s36, s38, 0x280
	s_addc_u32 s37, s39, 0
	s_mov_b32 m0, s21
	s_nop 0
	global_load_lds_dwordx4 v134, s[36:37]
	s_nop 0
	s_mov_b32 m0, s22
	s_nop 0
	global_load_lds_dwordx4 v135, s[36:37]
	s_barrier
; #define WAIT_V(n) asm volatile("s_waitcnt vmcnt(" #n ")" ::: "memory")
; #define WAIT_L(n) asm volatile("s_waitcnt lgkmcnt(" #n ")" ::: "memory")
; #define BAR __builtin_amdgcn_s_barrier()
; #define SCHED __builtin_amdgcn_sched_barrier(0)
; #define STG_A(b, h, kt) stage_half_s(lds0 + ((b) * 2 + (h)) * HT_B, ((h) ? A1 : Ap) + (kt) * BK, off0, off1)
; #define STG_B(b, h, kt) stage_half_s(lds0 + (4 + (b) * 2 + (h)) * HT_B, ((h) ? B1p : Bp) + (kt) * BK, off0, off1)
; #define STG_A(b, h, kt) stage_half_s(lds0 + ((b) * 2 + (h)) * HT_B, ((h) ? A1 : Ap) + (kt) * BK, off0, off1)
; #define STG_B(b, h, kt) stage_half_s(lds0 + (4 + (b) * 2 + (h)) * HT_B, ((h) ? B1p : Bp) + (kt) * BK, off0, off1)
; #define LDA8(b, h) _Pragma("unroll") for (int m = 0; m < 4; ++m) _Pragma("unroll") for (int k = 0; k < 2; ++k) \
;     At[m][k] = *(const bf16x8*)(SA_(shm, b, h) + abase + (m * 2 + k) * 1024)
; #define LDB8(dst, b, h) _Pragma("unroll") for (int n = 0; n < 2; ++n) _Pragma("unroll") for (int k = 0; k < 2; ++k) \
;     dst[n][k] = *(const bf16x8*)(SB_(shm, b, h) + bbase + (n * 2 + k) * 1024)
; #define MMA8(ai, bj, Bx) do { __builtin_amdgcn_s_setprio(1); \
;     _Pragma("unroll") for (int m = 0; m < 4; ++m) _Pragma("unroll") for (int n = 0; n < 2; ++n) _Pragma("unroll") for (int k = 0; k < 2; ++k) \
;       acc[ai][bj][m][n] = __builtin_amdgcn_mfma_f32_16x16x32_bf16(At[m][k], Bx[n][k], acc[ai][bj][m][n], 0, 0, 0); \
;     __builtin_amdgcn_s_setprio(0); } while (0)
; template <bool HS>
; __device__ __forceinline__ void gemm_tile8(const u16* __restrict__ Ap, const u16* __restrict__ Bp, int K,
;                                            f32x4 (&acc)[2][2][4][2], char* shm, const int tid, const float* hsr = nullptr) {
;     ...
;     BAR; WAIT_L(0); MMA8(1, 0, B0); BAR; SCHED;
;     STG_B(1, 1, t + 3);
;     WAIT_V(6); BAR; MMA8(1, 1, B1); BAR;
;   }
;   { LDB8(B0, 0, 0); LDA8(0, 0); STG_A(1, 1, nt - 1);
;     BAR; WAIT_L(0); MMA8(0, 0, B0); BAR;
;     LDB8(B1, 0, 1); BAR; WAIT_L(0); MMA8(0, 1, B1); BAR;
;     LDA8(0, 1); WAIT_V(4); BAR; WAIT_L(0); MMA8(1, 0, B0); MMA8(1, 1, B1); BAR; }
	s_waitcnt lgkmcnt(0)
	s_setprio 1
	s_waitcnt lgkmcnt(7)
	v_mfma_f32_16x16x32_bf16 v[94:97], v[154:157], v[130:133], v[94:97]
	v_mfma_f32_16x16x32_bf16 v[90:93], v[154:157], v[146:149], v[90:93]
	s_waitcnt lgkmcnt(5)
	v_mfma_f32_16x16x32_bf16 v[86:89], v[166:169], v[130:133], v[86:89]
	v_mfma_f32_16x16x32_bf16 v[82:85], v[166:169], v[146:149], v[82:85]
	s_waitcnt lgkmcnt(3)
	v_mfma_f32_16x16x32_bf16 v[78:81], v[174:177], v[130:133], v[78:81]
	v_mfma_f32_16x16x32_bf16 v[74:77], v[174:177], v[146:149], v[74:77]
	s_waitcnt lgkmcnt(1)
	v_mfma_f32_16x16x32_bf16 v[70:73], v[184:187], v[130:133], v[70:73]
	v_mfma_f32_16x16x32_bf16 v[66:69], v[184:187], v[146:149], v[66:69]
	v_mfma_f32_16x16x32_bf16 v[94:97], v[162:165], v[142:145], v[94:97]
	v_mfma_f32_16x16x32_bf16 v[90:93], v[162:165], v[150:153], v[90:93]
	v_mfma_f32_16x16x32_bf16 v[86:89], v[170:173], v[142:145], v[86:89]
	v_mfma_f32_16x16x32_bf16 v[82:85], v[170:173], v[150:153], v[82:85]
	v_mfma_f32_16x16x32_bf16 v[78:81], v[180:183], v[142:145], v[78:81]
	v_mfma_f32_16x16x32_bf16 v[74:77], v[180:183], v[150:153], v[74:77]
	s_waitcnt lgkmcnt(0)
	v_mfma_f32_16x16x32_bf16 v[70:73], v[188:191], v[142:145], v[70:73]
	v_mfma_f32_16x16x32_bf16 v[66:69], v[188:191], v[150:153], v[66:69]
	s_setprio 0
	s_barrier
	v_lshl_add_u64 v[130:131], v[210:211], 0, s[52:53]
	s_nop 0
	v_readfirstlane_b32 s37, v131
	v_readfirstlane_b32 s36, v130
	s_mov_b32 m0, s23
	s_nop 3
	global_load_lds_dwordx4 v134, s[36:37]
	s_nop 0
	s_mov_b32 m0, s24
	s_nop 0
	global_load_lds_dwordx4 v135, s[36:37]
	s_waitcnt vmcnt(6)
	s_barrier
	s_setprio 1
	v_mfma_f32_16x16x32_bf16 v[126:129], v[154:157], v[192:195], v[126:129]
	v_mfma_f32_16x16x32_bf16 v[122:125], v[154:157], v[200:203], v[122:125]
	v_mfma_f32_16x16x32_bf16 v[118:121], v[166:169], v[192:195], v[118:121]
	v_mfma_f32_16x16x32_bf16 v[114:117], v[166:169], v[200:203], v[114:117]
	v_mfma_f32_16x16x32_bf16 v[110:113], v[174:177], v[192:195], v[110:113]
	v_mfma_f32_16x16x32_bf16 v[106:109], v[174:177], v[200:203], v[106:109]
	v_mfma_f32_16x16x32_bf16 v[102:105], v[184:187], v[192:195], v[102:105]
	v_mfma_f32_16x16x32_bf16 v[98:101], v[184:187], v[200:203], v[98:101]
	v_mfma_f32_16x16x32_bf16 v[126:129], v[162:165], v[196:199], v[126:129]
	v_mfma_f32_16x16x32_bf16 v[122:125], v[162:165], v[204:207], v[122:125]
	v_mfma_f32_16x16x32_bf16 v[118:121], v[170:173], v[196:199], v[118:121]
	v_mfma_f32_16x16x32_bf16 v[114:117], v[170:173], v[204:207], v[114:117]
	v_mfma_f32_16x16x32_bf16 v[110:113], v[180:183], v[196:199], v[110:113]
	v_mfma_f32_16x16x32_bf16 v[106:109], v[180:183], v[204:207], v[106:109]
	v_mfma_f32_16x16x32_bf16 v[102:105], v[188:191], v[196:199], v[102:105]
	v_mfma_f32_16x16x32_bf16 v[98:101], v[188:191], v[204:207], v[98:101]
	s_setprio 0
	s_add_u32 s4, s4, 0x100
	s_addc_u32 s5, s5, 0
	s_cmp_gt_u32 s11, 27
	v_add_u32_e32 v141, 0x100, v141
	s_barrier
	s_cbranch_scc1 .LBB0_345
	s_mov_b32 s11, s69
	s_and_b32 s36, s11, 6
	s_cmp_lg_u32 s36, 0
	s_cbranch_scc1 .LBB0_343
	s_branch .LBB0_342
.LBB0_345:
	v_add_u32_e32 v161, 0, v136
	v_add_u32_e32 v144, 0x10000, v161
	ds_read_b128 v[130:133], v144
	ds_read_b128 v[136:139], v144 offset:1024
	ds_read_b128 v[140:143], v144 offset:2048
	ds_read_b128 v[144:147], v144 offset:3072
	ds_read_b128 v[148:151], v160
	ds_read_b128 v[152:155], v160 offset:1024
	ds_read_b128 v[162:165], v160 offset:2048
	ds_read_b128 v[166:169], v160 offset:3072
	ds_read_b128 v[170:173], v160 offset:4096
	ds_read_b128 v[174:177], v160 offset:5120
	ds_read_b128 v[180:183], v160 offset:6144
	ds_read_b128 v[184:187], v160 offset:7168
	s_add_u32 s4, s1, 0x80f80
	s_addc_u32 s5, s3, 0
	s_mov_b32 m0, s7
	s_nop 0
	global_load_lds_dwordx4 v134, s[4:5]
	s_nop 0
	s_mov_b32 m0, s10
	s_nop 0
	global_load_lds_dwordx4 v135, s[4:5]
	s_barrier
	s_waitcnt lgkmcnt(0)
	s_setprio 1
	s_waitcnt lgkmcnt(7)
	v_mfma_f32_16x16x32_bf16 v[26:29], v[148:151], v[140:143], v[26:29]
	s_waitcnt lgkmcnt(5)
	v_mfma_f32_16x16x32_bf16 v[22:25], v[162:165], v[130:133], v[22:25]
	v_mfma_f32_16x16x32_bf16 v[18:21], v[162:165], v[140:143], v[18:21]
	s_waitcnt lgkmcnt(3)
	v_mfma_f32_16x16x32_bf16 v[14:17], v[170:173], v[130:133], v[14:17]
	s_waitcnt lgkmcnt(1)
	v_mfma_f32_16x16x32_bf16 v[6:9], v[180:183], v[130:133], v[6:9]
	v_mfma_f32_16x16x32_bf16 v[2:5], v[180:183], v[140:143], v[2:5]
	v_mfma_f32_16x16x32_bf16 v[30:33], v[148:151], v[130:133], v[30:33]
	v_mfma_f32_16x16x32_bf16 v[26:29], v[152:155], v[144:147], v[26:29]
	v_mfma_f32_16x16x32_bf16 v[22:25], v[166:169], v[136:139], v[22:25]
	v_mfma_f32_16x16x32_bf16 v[18:21], v[166:169], v[144:147], v[18:21]
	v_mfma_f32_16x16x32_bf16 v[14:17], v[174:177], v[136:139], v[14:17]
	v_mfma_f32_16x16x32_bf16 v[10:13], v[170:173], v[140:143], v[10:13]
	s_waitcnt lgkmcnt(0)
	v_mfma_f32_16x16x32_bf16 v[6:9], v[184:187], v[136:139], v[6:9]
	v_mfma_f32_16x16x32_bf16 v[2:5], v[184:187], v[144:147], v[2:5]
	v_mfma_f32_16x16x32_bf16 v[30:33], v[152:155], v[136:139], v[30:33]
	v_mfma_f32_16x16x32_bf16 v[10:13], v[174:177], v[144:147], v[10:13]
	s_setprio 0
	v_add_u32_e32 v134, 0x14000, v161
	s_barrier
	ds_read_b128 v[188:191], v134
	ds_read_b128 v[192:195], v134 offset:1024
	ds_read_b128 v[196:199], v134 offset:2048
	ds_read_b128 v[200:203], v134 offset:3072
	s_barrier
; #define WAIT_V(n) asm volatile("s_waitcnt vmcnt(" #n ")" ::: "memory")
; #define WAIT_L(n) asm volatile("s_waitcnt lgkmcnt(" #n ")" ::: "memory")
; #define BAR __builtin_amdgcn_s_barrier()
; #define LDA8(b, h) _Pragma("unroll") for (int m = 0; m < 4; ++m) _Pragma("unroll") for (int k = 0; k < 2; ++k) \
;     At[m][k] = *(const bf16x8*)(SA_(shm, b, h) + abase + (m * 2 + k) * 1024)
; #define LDB8(dst, b, h) _Pragma("unroll") for (int n = 0; n < 2; ++n) _Pragma("unroll") for (int k = 0; k < 2; ++k) \
;     dst[n][k] = *(const bf16x8*)(SB_(shm, b, h) + bbase + (n * 2 + k) * 1024)
; #define MMA8(ai, bj, Bx) do { __builtin_amdgcn_s_setprio(1); \
;     _Pragma("unroll") for (int m = 0; m < 4; ++m) _Pragma("unroll") for (int n = 0; n < 2; ++n) _Pragma("unroll") for (int k = 0; k < 2; ++k) \
;       acc[ai][bj][m][n] = __builtin_amdgcn_mfma_f32_16x16x32_bf16(At[m][k], Bx[n][k], acc[ai][bj][m][n], 0, 0, 0); \
;     __builtin_amdgcn_s_setprio(0); } while (0)
; template <bool HS>
; __device__ __forceinline__ void gemm_tile8(const u16* __restrict__ Ap, const u16* __restrict__ Bp, int K,
;                                            f32x4 (&acc)[2][2][4][2], char* shm, const int tid, const float* hsr = nullptr) {
;     ...
;     BAR; WAIT_L(0); MMA8(0, 0, B0); BAR;
;     LDB8(B1, 0, 1); BAR; WAIT_L(0); MMA8(0, 1, B1); BAR;
;     LDA8(0, 1); WAIT_V(4); BAR; WAIT_L(0); MMA8(1, 0, B0); MMA8(1, 1, B1); BAR; }
;   { LDB8(B0, 1, 0); LDA8(1, 0); WAIT_V(2); BAR; WAIT_L(0); MMA8(0, 0, B0); BAR;
	s_waitcnt lgkmcnt(0)
	s_setprio 1
	s_waitcnt lgkmcnt(3)
	v_mfma_f32_16x16x32_bf16 v[62:65], v[148:151], v[188:191], v[62:65]
	s_waitcnt lgkmcnt(1)
	v_mfma_f32_16x16x32_bf16 v[58:61], v[148:151], v[196:199], v[58:61]
	v_mfma_f32_16x16x32_bf16 v[54:57], v[162:165], v[188:191], v[54:57]
	v_mfma_f32_16x16x32_bf16 v[46:49], v[170:173], v[188:191], v[46:49]
	v_mfma_f32_16x16x32_bf16 v[42:45], v[170:173], v[196:199], v[42:45]
	v_mfma_f32_16x16x32_bf16 v[38:41], v[180:183], v[188:191], v[38:41]
	v_mfma_f32_16x16x32_bf16 v[34:37], v[180:183], v[196:199], v[34:37]
	v_mfma_f32_16x16x32_bf16 v[62:65], v[152:155], v[192:195], v[62:65]
	s_waitcnt lgkmcnt(0)
	v_mfma_f32_16x16x32_bf16 v[58:61], v[152:155], v[200:203], v[58:61]
	v_mfma_f32_16x16x32_bf16 v[54:57], v[166:169], v[192:195], v[54:57]
	v_mfma_f32_16x16x32_bf16 v[50:53], v[162:165], v[196:199], v[50:53]
	v_mfma_f32_16x16x32_bf16 v[46:49], v[174:177], v[192:195], v[46:49]
	v_mfma_f32_16x16x32_bf16 v[42:45], v[174:177], v[200:203], v[42:45]
	v_mfma_f32_16x16x32_bf16 v[38:41], v[184:187], v[192:195], v[38:41]
	v_mfma_f32_16x16x32_bf16 v[34:37], v[184:187], v[200:203], v[34:37]
	v_mfma_f32_16x16x32_bf16 v[50:53], v[166:169], v[200:203], v[50:53]
	s_setprio 0
	s_barrier
	ds_read_b128 v[148:151], v160 offset:16384
	ds_read_b128 v[152:155], v160 offset:17408
	ds_read_b128 v[162:165], v160 offset:18432
	ds_read_b128 v[166:169], v160 offset:19456
	ds_read_b128 v[170:173], v160 offset:20480
	ds_read_b128 v[174:177], v160 offset:21504
	ds_read_b128 v[180:183], v160 offset:22528
	ds_read_b128 v[184:187], v160 offset:23552
	s_waitcnt vmcnt(4)
	s_barrier
	s_waitcnt lgkmcnt(0)
	s_setprio 1
	s_waitcnt lgkmcnt(3)
	v_mfma_f32_16x16x32_bf16 v[78:81], v[170:173], v[130:133], v[78:81]
	v_mfma_f32_16x16x32_bf16 v[74:77], v[170:173], v[140:143], v[74:77]
	v_mfma_f32_16x16x32_bf16 v[94:97], v[148:151], v[130:133], v[94:97]
	v_mfma_f32_16x16x32_bf16 v[90:93], v[148:151], v[140:143], v[90:93]
	v_mfma_f32_16x16x32_bf16 v[86:89], v[162:165], v[130:133], v[86:89]
	v_mfma_f32_16x16x32_bf16 v[82:85], v[162:165], v[140:143], v[82:85]
	s_waitcnt lgkmcnt(2)
	v_mfma_f32_16x16x32_bf16 v[78:81], v[174:177], v[136:139], v[78:81]
	v_mfma_f32_16x16x32_bf16 v[74:77], v[174:177], v[144:147], v[74:77]
	s_waitcnt lgkmcnt(1)
	v_mfma_f32_16x16x32_bf16 v[70:73], v[180:183], v[130:133], v[70:73]
	v_mfma_f32_16x16x32_bf16 v[66:69], v[180:183], v[140:143], v[66:69]
	v_mfma_f32_16x16x32_bf16 v[204:207], v[152:155], v[136:139], v[94:97]
	v_mfma_f32_16x16x32_bf16 v[90:93], v[152:155], v[144:147], v[90:93]
	v_mfma_f32_16x16x32_bf16 v[208:211], v[166:169], v[136:139], v[86:89]
	v_mfma_f32_16x16x32_bf16 v[212:215], v[166:169], v[144:147], v[82:85]
	s_waitcnt lgkmcnt(0)
	v_mfma_f32_16x16x32_bf16 v[70:73], v[184:187], v[136:139], v[70:73]
	v_mfma_f32_16x16x32_bf16 v[130:133], v[184:187], v[144:147], v[66:69]
	s_setprio 0
	s_setprio 1
	v_mfma_f32_16x16x32_bf16 v[66:69], v[148:151], v[188:191], v[126:129]
	v_mfma_f32_16x16x32_bf16 v[216:219], v[152:155], v[192:195], v[66:69]
	v_mfma_f32_16x16x32_bf16 v[66:69], v[148:151], v[196:199], v[122:125]
	v_mfma_f32_16x16x32_bf16 v[220:223], v[152:155], v[200:203], v[66:69]
	v_mfma_f32_16x16x32_bf16 v[66:69], v[162:165], v[188:191], v[118:121]
	v_mfma_f32_16x16x32_bf16 v[224:227], v[166:169], v[192:195], v[66:69]
	v_mfma_f32_16x16x32_bf16 v[66:69], v[162:165], v[196:199], v[114:117]
	v_mfma_f32_16x16x32_bf16 v[162:165], v[166:169], v[200:203], v[66:69]
	v_mfma_f32_16x16x32_bf16 v[66:69], v[170:173], v[188:191], v[110:113]
	v_mfma_f32_16x16x32_bf16 v[110:113], v[174:177], v[192:195], v[66:69]
	v_mfma_f32_16x16x32_bf16 v[66:69], v[170:173], v[196:199], v[106:109]
	v_mfma_f32_16x16x32_bf16 v[166:169], v[174:177], v[200:203], v[66:69]
	v_mfma_f32_16x16x32_bf16 v[66:69], v[180:183], v[188:191], v[102:105]
	v_mfma_f32_16x16x32_bf16 v[170:173], v[184:187], v[192:195], v[66:69]
	v_mfma_f32_16x16x32_bf16 v[66:69], v[180:183], v[196:199], v[98:101]
	v_mfma_f32_16x16x32_bf16 v[174:177], v[184:187], v[200:203], v[66:69]
	s_setprio 0
	s_nop 5
	v_add_u32_e32 v66, 0x18000, v161
	s_barrier
	ds_read_b128 v[180:183], v66
	ds_read_b128 v[184:187], v66 offset:1024
	ds_read_b128 v[188:191], v66 offset:2048
	ds_read_b128 v[192:195], v66 offset:3072
	ds_read_b128 v[66:69], v160 offset:32768
	ds_read_b128 v[94:97], v160 offset:33792
	ds_read_b128 v[98:101], v160 offset:34816
	ds_read_b128 v[114:117], v160 offset:35840
	ds_read_b128 v[196:199], v160 offset:36864
	ds_read_b128 v[200:203], v160 offset:37888
	ds_read_b128 v[228:231], v160 offset:38912
	ds_read_b128 v[232:235], v160 offset:39936
	s_waitcnt vmcnt(2)
	s_barrier
; #define WAIT_V(n) asm volatile("s_waitcnt vmcnt(" #n ")" ::: "memory")
; #define WAIT_L(n) asm volatile("s_waitcnt lgkmcnt(" #n ")" ::: "memory")
; #define BAR __builtin_amdgcn_s_barrier()
; #define LDA8(b, h) _Pragma("unroll") for (int m = 0; m < 4; ++m) _Pragma("unroll") for (int k = 0; k < 2; ++k) \
;     At[m][k] = *(const bf16x8*)(SA_(shm, b, h) + abase + (m * 2 + k) * 1024)
; #define LDB8(dst, b, h) _Pragma("unroll") for (int n = 0; n < 2; ++n) _Pragma("unroll") for (int k = 0; k < 2; ++k) \
;     dst[n][k] = *(const bf16x8*)(SB_(shm, b, h) + bbase + (n * 2 + k) * 1024)
; #define MMA8(ai, bj, Bx) do { __builtin_amdgcn_s_setprio(1); \
;     _Pragma("unroll") for (int m = 0; m < 4; ++m) _Pragma("unroll") for (int n = 0; n < 2; ++n) _Pragma("unroll") for (int k = 0; k < 2; ++k) \
;       acc[ai][bj][m][n] = __builtin_amdgcn_mfma_f32_16x16x32_bf16(At[m][k], Bx[n][k], acc[ai][bj][m][n], 0, 0, 0); \
;     __builtin_amdgcn_s_setprio(0); } while (0)
; template <bool HS>
; __device__ __forceinline__ void gemm_tile8(const u16* __restrict__ Ap, const u16* __restrict__ Bp, int K,
;                                            f32x4 (&acc)[2][2][4][2], char* shm, const int tid, const float* hsr = nullptr) {
;     ...
;   { LDB8(B0, 1, 0); LDA8(1, 0); WAIT_V(2); BAR; WAIT_L(0); MMA8(0, 0, B0); BAR;
;     LDB8(B1, 1, 1); WAIT_V(0); BAR; WAIT_L(0); MMA8(0, 1, B1); BAR;
;     LDA8(1, 1); BAR; WAIT_L(0); MMA8(1, 0, B0); MMA8(1, 1, B1); BAR; }
;   if (wr == 0) BAR;
	s_waitcnt lgkmcnt(0)
	s_setprio 1
	s_waitcnt lgkmcnt(7)
	v_mfma_f32_16x16x32_bf16 v[30:33], v[66:69], v[180:183], v[30:33]
	v_mfma_f32_16x16x32_bf16 v[26:29], v[66:69], v[188:191], v[26:29]
	s_waitcnt lgkmcnt(5)
	v_mfma_f32_16x16x32_bf16 v[22:25], v[98:101], v[180:183], v[22:25]
	v_mfma_f32_16x16x32_bf16 v[18:21], v[98:101], v[188:191], v[18:21]
	s_waitcnt lgkmcnt(3)
	v_mfma_f32_16x16x32_bf16 v[14:17], v[196:199], v[180:183], v[14:17]
	v_mfma_f32_16x16x32_bf16 v[10:13], v[196:199], v[188:191], v[10:13]
	s_waitcnt lgkmcnt(1)
	v_mfma_f32_16x16x32_bf16 v[6:9], v[228:231], v[180:183], v[6:9]
	v_mfma_f32_16x16x32_bf16 v[2:5], v[228:231], v[188:191], v[2:5]
	v_mfma_f32_16x16x32_bf16 v[154:157], v[94:97], v[184:187], v[30:33]
	v_mfma_f32_16x16x32_bf16 v[150:153], v[94:97], v[192:195], v[26:29]
	v_mfma_f32_16x16x32_bf16 v[126:129], v[114:117], v[184:187], v[22:25]
	v_mfma_f32_16x16x32_bf16 v[122:125], v[114:117], v[192:195], v[18:21]
	v_mfma_f32_16x16x32_bf16 v[106:109], v[200:203], v[184:187], v[14:17]
	v_mfma_f32_16x16x32_bf16 v[102:105], v[200:203], v[192:195], v[10:13]
	s_waitcnt lgkmcnt(0)
	v_mfma_f32_16x16x32_bf16 v[86:89], v[232:235], v[184:187], v[6:9]
	v_mfma_f32_16x16x32_bf16 v[82:85], v[232:235], v[192:195], v[2:5]
	s_setprio 0
	s_nop 1
	v_add_u32_e32 v2, 0x1c000, v161
	s_barrier
	ds_read_b128 v[10:13], v2
	ds_read_b128 v[14:17], v2 offset:1024
	ds_read_b128 v[30:33], v2 offset:2048
	ds_read_b128 v[236:239], v2 offset:3072
	s_waitcnt vmcnt(0)
	s_barrier
	s_waitcnt lgkmcnt(0)
	s_setprio 1
	s_waitcnt lgkmcnt(3)
	v_mfma_f32_16x16x32_bf16 v[2:5], v[66:69], v[10:13], v[62:65]
	s_waitcnt lgkmcnt(2)
	v_mfma_f32_16x16x32_bf16 v[146:149], v[94:97], v[14:17], v[2:5]
	s_waitcnt lgkmcnt(1)
	v_mfma_f32_16x16x32_bf16 v[2:5], v[66:69], v[30:33], v[58:61]
	s_waitcnt lgkmcnt(0)
	v_mfma_f32_16x16x32_bf16 v[142:145], v[94:97], v[236:239], v[2:5]
	v_mfma_f32_16x16x32_bf16 v[2:5], v[98:101], v[10:13], v[54:57]
	v_mfma_f32_16x16x32_bf16 v[138:141], v[114:117], v[14:17], v[2:5]
	v_mfma_f32_16x16x32_bf16 v[2:5], v[98:101], v[30:33], v[50:53]
	v_mfma_f32_16x16x32_bf16 v[134:137], v[114:117], v[236:239], v[2:5]
	v_mfma_f32_16x16x32_bf16 v[2:5], v[196:199], v[10:13], v[46:49]
	v_mfma_f32_16x16x32_bf16 v[118:121], v[200:203], v[14:17], v[2:5]
	v_mfma_f32_16x16x32_bf16 v[2:5], v[196:199], v[30:33], v[42:45]
	v_mfma_f32_16x16x32_bf16 v[114:117], v[200:203], v[236:239], v[2:5]
	v_mfma_f32_16x16x32_bf16 v[2:5], v[228:231], v[10:13], v[38:41]
	v_mfma_f32_16x16x32_bf16 v[98:101], v[232:235], v[14:17], v[2:5]
	v_mfma_f32_16x16x32_bf16 v[2:5], v[228:231], v[30:33], v[34:37]
	v_mfma_f32_16x16x32_bf16 v[94:97], v[232:235], v[236:239], v[2:5]
	s_setprio 0
	s_barrier
	ds_read_b128 v[18:21], v160 offset:49152
	ds_read_b128 v[34:37], v160 offset:50176
	ds_read_b128 v[38:41], v160 offset:51200
	ds_read_b128 v[50:53], v160 offset:52224
	ds_read_b128 v[196:199], v160 offset:53248
	ds_read_b128 v[200:203], v160 offset:54272
	ds_read_b128 v[228:231], v160 offset:55296
	ds_read_b128 v[232:235], v160 offset:56320
	s_barrier
	s_waitcnt lgkmcnt(0)
	s_setprio 1
	s_waitcnt lgkmcnt(7)
	v_mfma_f32_16x16x32_bf16 v[2:5], v[18:21], v[180:183], v[204:207]
	s_waitcnt lgkmcnt(6)
	v_mfma_f32_16x16x32_bf16 v[66:69], v[34:37], v[184:187], v[2:5]
	v_mfma_f32_16x16x32_bf16 v[2:5], v[18:21], v[188:191], v[90:93]
	v_mfma_f32_16x16x32_bf16 v[62:65], v[34:37], v[192:195], v[2:5]
	s_waitcnt lgkmcnt(5)
	v_mfma_f32_16x16x32_bf16 v[2:5], v[38:41], v[180:183], v[208:211]
	s_waitcnt lgkmcnt(4)
	v_mfma_f32_16x16x32_bf16 v[46:49], v[50:53], v[184:187], v[2:5]
	v_mfma_f32_16x16x32_bf16 v[2:5], v[38:41], v[188:191], v[212:215]
	v_mfma_f32_16x16x32_bf16 v[42:45], v[50:53], v[192:195], v[2:5]
	s_waitcnt lgkmcnt(3)
	v_mfma_f32_16x16x32_bf16 v[2:5], v[196:199], v[180:183], v[78:81]
	s_waitcnt lgkmcnt(2)
	v_mfma_f32_16x16x32_bf16 v[26:29], v[200:203], v[184:187], v[2:5]
	v_mfma_f32_16x16x32_bf16 v[2:5], v[196:199], v[188:191], v[74:77]
	v_mfma_f32_16x16x32_bf16 v[22:25], v[200:203], v[192:195], v[2:5]
	s_waitcnt lgkmcnt(1)
	v_mfma_f32_16x16x32_bf16 v[2:5], v[228:231], v[180:183], v[70:73]
	s_waitcnt lgkmcnt(0)
	v_mfma_f32_16x16x32_bf16 v[6:9], v[232:235], v[184:187], v[2:5]
	v_mfma_f32_16x16x32_bf16 v[2:5], v[228:231], v[188:191], v[130:133]
	v_mfma_f32_16x16x32_bf16 v[2:5], v[232:235], v[192:195], v[2:5]
	s_setprio 0
	s_setprio 1
	v_mfma_f32_16x16x32_bf16 v[54:57], v[18:21], v[10:13], v[216:219]
	v_mfma_f32_16x16x32_bf16 v[18:21], v[18:21], v[30:33], v[220:223]
	v_mfma_f32_16x16x32_bf16 v[74:77], v[34:37], v[236:239], v[18:21]
	v_mfma_f32_16x16x32_bf16 v[18:21], v[38:41], v[10:13], v[224:227]
	v_mfma_f32_16x16x32_bf16 v[58:61], v[50:53], v[14:17], v[18:21]
	v_mfma_f32_16x16x32_bf16 v[18:21], v[38:41], v[30:33], v[162:165]
	v_mfma_f32_16x16x32_bf16 v[78:81], v[34:37], v[14:17], v[54:57]
	v_mfma_f32_16x16x32_bf16 v[54:57], v[50:53], v[236:239], v[18:21]
	v_mfma_f32_16x16x32_bf16 v[18:21], v[196:199], v[10:13], v[110:113]
	v_mfma_f32_16x16x32_bf16 v[38:41], v[200:203], v[14:17], v[18:21]
	v_mfma_f32_16x16x32_bf16 v[18:21], v[196:199], v[30:33], v[166:169]
	v_mfma_f32_16x16x32_bf16 v[10:13], v[228:231], v[10:13], v[170:173]
	v_mfma_f32_16x16x32_bf16 v[34:37], v[200:203], v[236:239], v[18:21]
	v_mfma_f32_16x16x32_bf16 v[18:21], v[232:235], v[14:17], v[10:13]
	v_mfma_f32_16x16x32_bf16 v[10:13], v[228:231], v[30:33], v[174:177]
	v_mfma_f32_16x16x32_bf16 v[14:17], v[232:235], v[236:239], v[10:13]
	s_setprio 0
	s_movk_i32 s1, 0x100
	v_cmp_gt_u32_e32 vcc, s1, v0
	s_barrier
	s_and_saveexec_b64 s[4:5], vcc
	s_cbranch_execz .LBB0_347
	s_barrier

; #define WAIT_V(n) asm volatile("s_waitcnt vmcnt(" #n ")" ::: "memory")
; #define SCHED __builtin_amdgcn_sched_barrier(0)
; template <bool HS>
; __device__ __forceinline__ void gemm_tile8(const u16* __restrict__ Ap, const u16* __restrict__ Bp, int K,
;                                            f32x4 (&acc)[2][2][4][2], char* shm, const int tid, const float* hsr = nullptr) {
;     ...
;   if constexpr (HS) {
;     const float* rt = hsr + 3 * 256 + wr * 64 + fq * 4;
; #pragma unroll
;     for (int ai = 0; ai < 2; ++ai)
; #pragma unroll
;       for (int m = 0; m < 4; ++m) {
;         const f32x4 q4 = *(const f32x4*)(rt + ai * 128 + m * 16);
; #pragma unroll
;         for (int bj = 0; bj < 2; ++bj)
; #pragma unroll
;           for (int n = 0; n < 2; ++n) acc[ai][bj][m][n] *= q4;
;         SCHED;
;       }
; template <int EPI, bool HS = false>
; __device__ __forceinline__ void gemm_phase(const Params& p, const GemmCfg& g, char* shm, const int wave_s) {
;     ...
;       const float* xin_t = g.xin + (size_t)orow0 * 1024 + pn * 256;
;       float* xout_t = g.xout + (size_t)orow0 * 1024 + pn * 256;
;       u16* xg_t = p.h + (size_t)orow0 * 1024 + pn * 256;
;       float* rss_t = p.rowss + (size_t)orow0 * 16 + pn * 4 + wc;
;       const unsigned tb = (unsigned)((wr * 64 + fq * 4) * 1024 + wc * 32 + 2 * fr);
;       const unsigned ldsb = (unsigned)(size_t)(__attribute__((address_space(3))) char*)shm;
;       const int wv_s = __builtin_amdgcn_readfirstlane(wid);
;       constexpr int XROW = 1040;
;       const char* xl = shm + (wr * 64 + fq * 4) * XROW + (wc * 32 + 2 * fr) * 4;
; #pragma unroll
;       for (int ai = 0; ai < 2; ++ai) {
; #pragma unroll
;         for (int i = 0; i < 16; ++i) {
;           const int r = wv_s * 16 + i;
;           glds_row(xin_t + (size_t)(ai * 128 + r) * 1024, (unsigned)lane * 16u, ldsb + (unsigned)(r * XROW));
;         }
;         WAIT_V(0);
.LBB0_355:
	s_and_b32 s1, s2, 0x700
	s_or_b32 s4, s0, s1
	s_ashr_i32 s5, s4, 31
	s_lshl_b64 s[0:1], s[4:5], 12
	v_readlane_b32 s2, v254, 56
	s_add_u32 s10, s2, s0
	v_readlane_b32 s2, v254, 55
	s_addc_u32 s11, s2, s1
	s_ashr_i32 s9, s8, 31
	s_lshl_b64 s[2:3], s[8:9], 2
	s_add_u32 s76, s10, s2
	v_readlane_b32 s52, v253, 25
	s_addc_u32 s77, s11, s3
	v_readlane_b32 s64, v253, 37
	v_readlane_b32 s65, v253, 38
	s_add_u32 s0, s64, s0
	s_addc_u32 s1, s65, s1
	s_add_u32 s2, s0, s2
	s_addc_u32 s3, s1, s3
	s_lshl_b64 s[0:1], s[4:5], 11
	s_add_u32 s10, s88, s0
	s_waitcnt lgkmcnt(7)
	v_pk_mul_f32 v[188:189], v[154:155], v[158:159]
	v_pk_mul_f32 v[154:155], v[150:151], v[158:159]
	v_lshrrev_b32_e32 v151, 2, v0
	s_addc_u32 s11, s89, s1
	s_lshl_b64 s[0:1], s[8:9], 1
	v_ashrrev_i32_e32 v150, 2, v0
	v_and_b32_e32 v151, 12, v151
	s_add_u32 s8, s10, s0
	s_movk_i32 s0, 0xffc0
	v_and_or_b32 v194, v150, s0, v151
	v_readfirstlane_b32 s0, v170
	s_addc_u32 s9, s11, s1
	s_lshl_b32 s10, s0, 4
	s_movk_i32 s1, 0x410
	s_ashr_i32 s11, s10, 31
	v_mul_lo_u32 v151, v194, s1
	s_lshl_b64 s[0:1], s[10:11], 12
	v_lshlrev_b32_e32 v0, 4, v0
	s_add_u32 s0, s76, s0
	s_mul_i32 s84, s10, 0x410
	v_and_b32_e32 v198, 0x3f0, v0
	s_addc_u32 s1, s77, s1
	s_add_i32 s84, s84, 0
	s_mov_b32 m0, s84
	s_nop 0
	global_load_lds_dwordx4 v198, s[0:1]
	s_or_b32 s0, s10, 1
	s_ashr_i32 s1, s0, 31
	s_lshl_b64 s[14:15], s[0:1], 12
	s_add_u32 s14, s76, s14
	s_mul_i32 s85, s0, 0x410
	s_addc_u32 s15, s77, s15
	s_add_i32 s85, s85, 0
	s_mov_b32 m0, s85
	s_nop 0
	global_load_lds_dwordx4 v198, s[14:15]
	s_or_b32 s0, s10, 2
	s_ashr_i32 s1, s0, 31
	s_lshl_b64 s[14:15], s[0:1], 12
	s_add_u32 s14, s76, s14
	s_mul_i32 s88, s0, 0x410
	s_addc_u32 s15, s77, s15
	s_add_i32 s88, s88, 0
	s_mov_b32 m0, s88
	s_nop 0
	global_load_lds_dwordx4 v198, s[14:15]
	s_or_b32 s0, s10, 3
	s_ashr_i32 s1, s0, 31
	s_lshl_b64 s[14:15], s[0:1], 12
	s_add_u32 s14, s76, s14
	s_mul_i32 s89, s0, 0x410
	s_addc_u32 s15, s77, s15
	s_add_i32 s89, s89, 0
	s_mov_b32 m0, s89
	s_nop 0
	global_load_lds_dwordx4 v198, s[14:15]
	s_or_b32 s0, s10, 4
	s_ashr_i32 s1, s0, 31
	s_lshl_b64 s[14:15], s[0:1], 12
	s_add_u32 s14, s76, s14
	s_mul_i32 s90, s0, 0x410
	s_addc_u32 s15, s77, s15
	s_add_i32 s90, s90, 0
	s_mov_b32 m0, s90
	s_nop 0
	global_load_lds_dwordx4 v198, s[14:15]
	s_or_b32 s0, s10, 5
	s_ashr_i32 s1, s0, 31
	s_lshl_b64 s[14:15], s[0:1], 12
	s_add_u32 s14, s76, s14
	s_mul_i32 s91, s0, 0x410
	s_addc_u32 s15, s77, s15
	s_add_i32 s91, s91, 0
	s_mov_b32 m0, s91
	s_nop 0
	global_load_lds_dwordx4 v198, s[14:15]
	s_or_b32 s0, s10, 6
	s_ashr_i32 s1, s0, 31
	s_lshl_b64 s[14:15], s[0:1], 12
	s_add_u32 s14, s76, s14
	s_mul_i32 s92, s0, 0x410
	s_addc_u32 s15, s77, s15
	s_add_i32 s92, s92, 0
	s_mov_b32 m0, s92
	s_nop 0
	global_load_lds_dwordx4 v198, s[14:15]
	s_or_b32 s0, s10, 7
	s_ashr_i32 s1, s0, 31
	s_lshl_b64 s[14:15], s[0:1], 12
	s_add_u32 s14, s76, s14
	s_mul_i32 s93, s0, 0x410
	s_addc_u32 s15, s77, s15
	s_add_i32 s93, s93, 0
	s_mov_b32 m0, s93
	s_nop 0
	global_load_lds_dwordx4 v198, s[14:15]
	s_or_b32 s0, s10, 8
	s_ashr_i32 s1, s0, 31
	s_lshl_b64 s[14:15], s[0:1], 12
	s_add_u32 s14, s76, s14
	s_mul_i32 s71, s0, 0x410
	s_addc_u32 s15, s77, s15
	s_add_i32 s71, s71, 0
	s_mov_b32 m0, s71
	s_nop 0
	global_load_lds_dwordx4 v198, s[14:15]
	s_or_b32 s0, s10, 9
	s_ashr_i32 s1, s0, 31
	s_lshl_b64 s[14:15], s[0:1], 12
	s_add_u32 s14, s76, s14
	s_mul_i32 s70, s0, 0x410
	s_addc_u32 s15, s77, s15
	s_add_i32 s70, s70, 0
	s_mov_b32 m0, s70
	s_nop 0
	global_load_lds_dwordx4 v198, s[14:15]
	s_or_b32 s0, s10, 10
	s_ashr_i32 s1, s0, 31
	s_lshl_b64 s[14:15], s[0:1], 12
	s_add_u32 s14, s76, s14
	s_mul_i32 s72, s0, 0x410
	s_addc_u32 s15, s77, s15
	s_add_i32 s72, s72, 0
	s_mov_b32 m0, s72
	s_nop 0
	global_load_lds_dwordx4 v198, s[14:15]
	s_or_b32 s0, s10, 11
	s_ashr_i32 s1, s0, 31
	s_lshl_b64 s[14:15], s[0:1], 12
	s_add_u32 s14, s76, s14
	s_mul_i32 s73, s0, 0x410
	s_addc_u32 s15, s77, s15
	s_add_i32 s73, s73, 0
	s_mov_b32 m0, s73
	s_nop 0
	global_load_lds_dwordx4 v198, s[14:15]
	s_or_b32 s0, s10, 12
	s_ashr_i32 s1, s0, 31
	s_lshl_b64 s[14:15], s[0:1], 12
	s_add_u32 s14, s76, s14
	s_mul_i32 s74, s0, 0x410
	s_addc_u32 s15, s77, s15
	s_add_i32 s74, s74, 0
	s_mov_b32 m0, s74
	s_nop 0
	global_load_lds_dwordx4 v198, s[14:15]
	s_or_b32 s0, s10, 13
	s_ashr_i32 s1, s0, 31
	s_lshl_b64 s[14:15], s[0:1], 12
	s_add_u32 s14, s76, s14
	s_mulk_i32 s0, 0x410
	s_addc_u32 s15, s77, s15
	s_add_i32 s0, s0, 0
	s_mov_b32 m0, s0
	s_nop 0
	global_load_lds_dwordx4 v198, s[14:15]
	s_or_b32 s14, s10, 14
	s_ashr_i32 s15, s14, 31
	s_lshl_b64 s[16:17], s[14:15], 12
	s_add_u32 s16, s76, s16
	s_addc_u32 s17, s77, s17
	s_mul_i32 s1, s14, 0x410
	s_or_b32 s14, s10, 15
	s_ashr_i32 s15, s14, 31
	v_add_u32_e32 v151, 0, v151
	v_lshlrev_b32_e32 v162, 2, v171
	s_add_i32 s1, s1, 0
	s_mov_b32 m0, s1
	s_nop 0
	global_load_lds_dwordx4 v198, s[16:17]
	s_lshl_b64 s[16:17], s[14:15], 12
	v_add_u32_e32 v195, v151, v162
	s_add_u32 s16, s76, s16
	s_mul_i32 s12, s14, 0x410
	v_lshlrev_b32_e32 v150, 10, v194
	s_addc_u32 s17, s77, s17
	s_add_i32 s12, s12, 0
	s_mov_b32 m0, s12
	s_nop 0
	global_load_lds_dwordx4 v198, s[16:17]
	v_add_u32_e32 v196, 32, v195
	v_add_u32_e32 v197, 48, v195
	v_or3_b32 v0, v150, v169, v168
	s_waitcnt vmcnt(0)
	s_waitcnt lgkmcnt(0)
	s_barrier
	ds_read2st64_b64 v[174:177], v195 offset1:1
	ds_read2_b64 v[170:173], v195 offset0:130 offset1:194
	ds_read2st64_b64 v[166:169], v196 offset0:4 offset1:5
	ds_read2st64_b64 v[162:165], v197 offset0:6 offset1:7
	v_mov_b32_e32 v150, v188
	v_mov_b32_e32 v151, v154
	s_waitcnt vmcnt(2) lgkmcnt(3)
	v_pk_fma_f32 v[190:191], v[150:151], v[184:185], v[174:175]
	v_lshl_add_u64 v[192:193], v[0:1], 2, s[2:3]
	s_and_b64 vcc, exec, s[6:7]
	v_lshl_add_u64 v[174:175], v[0:1], 1, s[8:9]
	v_readlane_b32 s53, v253, 26
	v_readlane_b32 s54, v253, 27
	v_readlane_b32 s55, v253, 28
	v_readlane_b32 s56, v253, 29
	v_readlane_b32 s57, v253, 30
	v_readlane_b32 s58, v253, 31
	v_readlane_b32 s59, v253, 32
	v_readlane_b32 s60, v253, 33
	v_readlane_b32 s61, v253, 34
	v_readlane_b32 s62, v253, 35
	v_readlane_b32 s63, v253, 36
	v_readlane_b32 s66, v253, 39
	v_readlane_b32 s67, v253, 40
	global_store_dwordx2 v[192:193], v[190:191], off
	s_cbranch_vccnz .LBB0_357
	v_pk_mul_f32 v[150:151], v[182:183], v[190:191]
	s_nop 0
	v_and_b32_sdwa v188, v150, v178 dst_sel:DWORD dst_unused:UNUSED_PAD src0_sel:WORD_1 src1_sel:DWORD
	v_and_b32_sdwa v154, v151, v178 dst_sel:DWORD dst_unused:UNUSED_PAD src0_sel:WORD_1 src1_sel:DWORD
	v_add3_u32 v150, v150, v188, s81
	v_add3_u32 v151, v151, v154, s81
	v_lshrrev_b32_e32 v150, 16, v150
	v_and_or_b32 v150, v151, s28, v150
	global_store_dword v[174:175], v150, off

; __device__ __forceinline__ unsigned pack2(float a, float b) { return (unsigned)f2bf(a) | ((unsigned)f2bf(b) << 16); }
; #define WAIT_V(n) asm volatile("s_waitcnt vmcnt(" #n ")" ::: "memory")
; template <int EPI, bool HS = false>
; __device__ __forceinline__ void gemm_phase(const Params& p, const GemmCfg& g, char* shm, const int wave_s) {
;     ...
; #pragma unroll
;       for (int ai = 0; ai < 2; ++ai) {
; #pragma unroll
;         for (int i = 0; i < 16; ++i) {
;           const int r = wv_s * 16 + i;
;           glds_row(xin_t + (size_t)(ai * 128 + r) * 1024, (unsigned)lane * 16u, ldsb + (unsigned)(r * XROW));
;         }
;         WAIT_V(0);
;         __syncthreads();
; #pragma unroll
;         for (int m = 0; m < 4; ++m) {
;           float2 xv[4][2];
; #pragma unroll
;           for (int j = 0; j < 4; ++j)
; #pragma unroll
;             for (int bj = 0; bj < 2; ++bj) xv[j][bj] = *(const float2*)(xl + (m * 16 + j) * XROW + bj * 512);
; #pragma unroll
;           for (int j = 0; j < 4; ++j) {
;             float ss = 0.f;
; #pragma unroll
;             for (int bj = 0; bj < 2; ++bj) {
;               float2 xn;
;               xn.x = xv[j][bj].x + gt[bj][0] * acc[ai][bj][m][0][j];
;               xn.y = xv[j][bj].y + gt[bj][1] * acc[ai][bj][m][1][j];
;               const unsigned o = tb + (unsigned)((ai * 128 + m * 16 + j) * 1024 + bj * 128);
;               *(float2*)(xout_t + o) = xn;
;               if (g.has_next) *(unsigned*)(xg_t + o) = pack2(xn.x * gn[bj][0], xn.y * gn[bj][1]);
;               ss += xn.x * xn.x + xn.y * xn.y;
;             }
;             if (g.has_next) {
;               ss = dpp_row_sum16(ss);
;               if (fr == 0) rss_t[(wr * 64 + fq * 4 + ai * 128 + m * 16 + j) * 16] = ss;
;             }
.LBB0_449:
	v_pk_mul_f32 v[94:95], v[66:67], v[70:71]
	v_pk_mul_f32 v[92:93], v[62:63], v[70:71]
	v_pk_mul_f32 v[62:63], v[80:81], v[72:73]
	v_pk_mul_f32 v[90:91], v[78:79], v[70:71]
	v_pk_mul_f32 v[66:67], v[76:77], v[72:73]
	v_pk_mul_f32 v[70:71], v[74:75], v[70:71]
	s_lshl_b64 s[10:11], s[10:11], 12
	s_add_u32 s13, s76, s10
	s_addc_u32 s14, s77, s11
	s_add_u32 s10, s13, 0x80000
	s_addc_u32 s11, s14, 0
	s_waitcnt vmcnt(63) expcnt(7) lgkmcnt(15)
	s_barrier
	s_mov_b32 m0, s84
	s_nop 0
	global_load_lds_dwordx4 v198, s[10:11]
	s_add_u32 s10, s13, 0x81000
	s_addc_u32 s11, s14, 0
	s_mov_b32 m0, s85
	s_nop 0
	global_load_lds_dwordx4 v198, s[10:11]
	s_add_u32 s10, s13, 0x82000
	s_addc_u32 s11, s14, 0
	s_mov_b32 m0, s88
	s_nop 0
	global_load_lds_dwordx4 v198, s[10:11]
	s_add_u32 s10, s13, 0x83000
	s_addc_u32 s11, s14, 0
	s_mov_b32 m0, s89
	s_nop 0
	global_load_lds_dwordx4 v198, s[10:11]
	s_add_u32 s10, s13, 0x84000
	s_addc_u32 s11, s14, 0
	s_mov_b32 m0, s90
	s_nop 0
	global_load_lds_dwordx4 v198, s[10:11]
	s_add_u32 s10, s13, 0x85000
	s_addc_u32 s11, s14, 0
	s_mov_b32 m0, s91
	s_nop 0
	global_load_lds_dwordx4 v198, s[10:11]
	s_add_u32 s10, s13, 0x86000
	s_addc_u32 s11, s14, 0
	s_mov_b32 m0, s92
	s_nop 0
	global_load_lds_dwordx4 v198, s[10:11]
	s_add_u32 s10, s13, 0x87000
	s_addc_u32 s11, s14, 0
	s_mov_b32 m0, s93
	s_nop 0
	global_load_lds_dwordx4 v198, s[10:11]
	s_add_u32 s10, s13, 0x88000
	s_addc_u32 s11, s14, 0
	s_mov_b32 m0, s71
	s_nop 0
	global_load_lds_dwordx4 v198, s[10:11]
	s_add_u32 s10, s13, 0x89000
	s_addc_u32 s11, s14, 0
	s_mov_b32 m0, s70
	s_nop 0
	global_load_lds_dwordx4 v198, s[10:11]
	s_add_u32 s10, s13, 0x8a000
	s_addc_u32 s11, s14, 0
	s_mov_b32 m0, s72
	s_nop 0
	global_load_lds_dwordx4 v198, s[10:11]
	s_add_u32 s10, s13, 0x8b000
	s_addc_u32 s11, s14, 0
	s_mov_b32 m0, s73
	s_nop 0
	global_load_lds_dwordx4 v198, s[10:11]
	s_add_u32 s10, s13, 0x8c000
	s_addc_u32 s11, s14, 0
	s_mov_b32 m0, s74
	s_nop 0
	global_load_lds_dwordx4 v198, s[10:11]
	s_add_u32 s10, s13, 0x8d000
	s_addc_u32 s11, s14, 0
	s_mov_b32 m0, s0
	s_nop 0
	global_load_lds_dwordx4 v198, s[10:11]
	s_add_u32 s10, s13, 0x8e000
	s_addc_u32 s11, s14, 0
	s_mov_b32 m0, s1
	s_nop 0
	global_load_lds_dwordx4 v198, s[10:11]
	s_add_u32 s0, s13, 0x8f000
	s_addc_u32 s1, s14, 0
	s_mov_b32 m0, s12
	s_nop 0
	global_load_lds_dwordx4 v198, s[0:1]
	s_waitcnt vmcnt(0)
	s_barrier
	ds_read2st64_b64 v[86:89], v195 offset1:1
	ds_read2_b64 v[82:85], v195 offset0:130 offset1:194
	ds_read2st64_b64 v[78:81], v196 offset0:4 offset1:5
	ds_read2st64_b64 v[74:77], v197 offset0:6 offset1:7
	v_add_u32_e32 v98, 0x20000, v0
	v_mov_b32_e32 v96, v94
	v_mov_b32_e32 v97, v92
	v_mov_b32_e32 v99, v1
	s_waitcnt lgkmcnt(3)
	v_pk_fma_f32 v[96:97], v[96:97], v[184:185], v[86:87]
	v_lshl_add_u64 v[86:87], v[98:99], 2, s[2:3]
	v_readlane_b32 s88, v254, 47
	global_store_dwordx2 v[86:87], v[96:97], off
	s_mov_b64 s[10:11], -1
	s_and_b64 vcc, exec, s[6:7]
	v_add_u32_e32 v86, 0x20080, v0
	s_mov_b32 s84, 0x8000
	v_readlane_b32 s89, v254, 48
	v_readlane_b32 s90, v254, 49
	v_readlane_b32 s91, v254, 50
	s_cbranch_vccnz .LBB0_453
	v_pk_mul_f32 v[100:101], v[182:183], v[96:97]
	v_lshl_add_u64 v[98:99], v[98:99], 1, s[8:9]
	v_and_b32_sdwa v92, v100, v178 dst_sel:DWORD dst_unused:UNUSED_PAD src0_sel:WORD_1 src1_sel:DWORD
	v_and_b32_sdwa v87, v101, v178 dst_sel:DWORD dst_unused:UNUSED_PAD src0_sel:WORD_1 src1_sel:DWORD
	v_add3_u32 v92, v100, v92, s81
	v_add3_u32 v87, v101, v87, s81
	v_lshrrev_b32_e32 v92, 16, v92
	v_and_or_b32 v87, v87, s28, v92
	global_store_dword v[98:99], v87, off
	v_mov_b32_e32 v98, v90
	v_mov_b32_e32 v99, v70
	v_mov_b32_e32 v87, v1
	v_pk_fma_f32 v[98:99], v[98:99], v[180:181], v[88:89]
	v_lshl_add_u64 v[100:101], v[86:87], 2, s[2:3]
	global_store_dwordx2 v[100:101], v[98:99], off
	v_pk_mul_f32 v[100:101], v[186:187], v[98:99]
	v_pk_mul_f32 v[96:97], v[96:97], v[96:97]
	v_and_b32_sdwa v94, v100, v178 dst_sel:DWORD dst_unused:UNUSED_PAD src0_sel:WORD_1 src1_sel:DWORD
	v_and_b32_sdwa v92, v101, v178 dst_sel:DWORD dst_unused:UNUSED_PAD src0_sel:WORD_1 src1_sel:DWORD
	v_add3_u32 v94, v100, v94, s81
	v_add3_u32 v92, v101, v92, s81
	v_lshrrev_b32_e32 v94, 16, v94
	v_and_or_b32 v92, v92, s28, v94
	v_lshl_add_u64 v[100:101], v[86:87], 1, s[8:9]
	v_pk_mul_f32 v[98:99], v[98:99], v[98:99]
	global_store_dword v[100:101], v92, off
	v_add_f32_e32 v87, v98, v99
	v_add_f32_e32 v92, v96, v97
	v_add_f32_e32 v87, v92, v87
	s_nop 1
	v_add_f32_dpp v87, v87, v87 quad_perm:[1,0,3,2] row_mask:0xf bank_mask:0xf bound_ctrl:1
	s_nop 1
	v_add_f32_dpp v87, v87, v87 quad_perm:[2,3,0,1] row_mask:0xf bank_mask:0xf bound_ctrl:1
	s_nop 1
	v_add_f32_dpp v87, v87, v87 row_half_mirror row_mask:0xf bank_mask:0xf bound_ctrl:1
	s_nop 1
	v_mov_b32_dpp v92, v87 row_mirror row_mask:0xf bank_mask:0xf bound_ctrl:1
	s_and_saveexec_b64 s[10:11], s[4:5]
	s_cbranch_execz .LBB0_452
	v_add_f32_e32 v87, v87, v92
	v_mov_b32_e32 v92, 0x800
	v_lshl_add_u32 v96, v194, 4, v92
	v_ashrrev_i32_e32 v97, 31, v96
	v_lshl_add_u64 v[96:97], v[96:97], 2, v[150:151]
	global_store_dword v[96:97], v87, off

; #define STG_A(b, h, kt) stage_half_s(lds0 + ((b) * 2 + (h)) * HT_B, ((h) ? A1 : Ap) + (kt) * BK, off0, off1)
; #define STG_B(b, h, kt) stage_half_s(lds0 + (4 + (b) * 2 + (h)) * HT_B, ((h) ? B1p : Bp) + (kt) * BK, off0, off1)
; #define STG_A(b, h, kt) stage_half_s(lds0 + ((b) * 2 + (h)) * HT_B, ((h) ? A1 : Ap) + (kt) * BK, off0, off1)
; #define STG_B(b, h, kt) stage_half_s(lds0 + (4 + (b) * 2 + (h)) * HT_B, ((h) ? B1p : Bp) + (kt) * BK, off0, off1)
; __device__ __forceinline__ void gemm8_prefetch(const u16* __restrict__ Ap, const u16* __restrict__ Bp, int K, char* shm, const int tid) {
;   int r0, c0, r1, c1;
;   stage_rc(tid * 16, r0, c0);
;   stage_rc(tid * 16 + 8192, r1, c1);
;   const unsigned off0 = (unsigned)(r0 * K + c0) * 2u, off1 = (unsigned)(r1 * K + c1) * 2u;
;   const int wvoff = __builtin_amdgcn_readfirstlane(tid >> 6) * 1024;
;   const u16* A1 = Ap + (size_t)128 * K;
;   const u16* B1p = Bp + (size_t)128 * K;
;   const unsigned lds0 = (unsigned)(size_t)(__attribute__((address_space(3))) char*)shm + (unsigned)wvoff;
;     ...
;   STG_B(0, 0, 0); STG_A(0, 0, 0); STG_B(0, 1, 0); STG_A(0, 1, 0);
;   STG_B(1, 0, 1); STG_A(1, 0, 1); STG_B(1, 1, 1);
;     ...
; }
; template <int EPI, bool HS = false>
; __device__ __forceinline__ void gemm_phase(const Params& p, const GemmCfg& g, char* shm, const int wave_s) {
;     ...
;   if ((int)blockIdx.x < nwg) {
;     int mt, pn, arow0, orow0;
;     tile_coords(blockIdx.x, mt, pn, arow0, orow0);
;     gemm8_prefetch(g.A + (size_t)arow0 * g.K, g.Bt + (size_t)pn * 256 * g.K, g.K, shm, fresh_tid(wave_s));
;   }
.LBB0_571:
	s_and_b64 vcc, exec, s[0:1]
	s_cbranch_vccz .LBB0_900
	v_readlane_b32 s0, v254, 54
	s_cmp_gt_i32 s0, 1
	s_mov_b64 s[0:1], -1
	s_cbranch_scc0 .LBB0_865
	v_cndmask_b32_e64 v0, 0, 1, s[52:53]
	s_lshl_b32 s0, s41, 1
	s_waitcnt vmcnt(7)
	v_or_b32_e32 v162, s0, v0
	v_readlane_b32 s0, v254, 54
	s_cmp_lt_i32 s0, 3
	s_mov_b64 s[0:1], -1
	s_cbranch_scc1 .LBB0_850
	v_readlane_b32 s0, v254, 54
	s_cmp_gt_i32 s0, 3
	s_mov_b64 s[0:1], -1
	s_cbranch_scc0 .LBB0_631
	v_readlane_b32 s0, v252, 47
	v_readlane_b32 s1, v252, 48
	s_andn2_b64 vcc, exec, s[0:1]
	s_cbranch_vccnz .LBB0_630
	v_readlane_b32 s4, v252, 26
	s_mul_i32 s1, s50, 0xc00000
	v_readlane_b32 s6, v252, 28
	v_readlane_b32 s8, v252, 30
	s_mul_hi_i32 s0, s50, 0xc00000
	v_readlane_b32 s7, v252, 29
	v_readlane_b32 s9, v252, 31
	s_add_u32 s8, s6, s1
	s_addc_u32 s9, s7, s0
	s_mul_i32 s0, s50, 0x18000
	s_ashr_i32 s1, s0, 31
	s_lshl_b64 s[0:1], s[0:1], 2
	v_readlane_b32 s2, v253, 1
	s_add_u32 s0, s2, s0
	v_writelane_b32 v255, s0, 4
	v_readlane_b32 s0, v253, 2
	s_addc_u32 s0, s0, s1
	s_lshl_b32 s43, s43, 11
	v_writelane_b32 v255, s0, 5
	v_readlane_b32 s0, v253, 3
	s_add_i32 s0, s43, s0
	v_readlane_b32 s5, v252, 27
	s_ashr_i32 s1, s0, 31
	s_lshl_b64 s[0:1], s[0:1], 11
	v_readlane_b32 s4, v254, 47
	v_readlane_b32 s5, v254, 48
	s_add_u32 s2, s4, s0
	s_addc_u32 s3, s5, s1
	s_mov_b32 s4, s82
	s_mov_b32 s5, -1
	v_readlane_b32 s0, v253, 4
	v_mbcnt_lo_u32_b32 v0, s5, 0
	v_mbcnt_hi_u32_b32 v0, s5, v0
	v_lshl_add_u32 v0, s4, 6, v0
	v_readlane_b32 s1, v253, 5
	v_bfe_i32 v4, v0, 27, 1
	v_lshlrev_b32_e32 v2, 4, v0
	v_lshrrev_b32_e32 v4, 22, v4
	v_add_u32_e32 v4, v2, v4
	v_and_b32_e32 v4, 0xfffffc00, v4
	v_ashrrev_i32_e32 v3, 31, v0
	v_sub_u32_e32 v4, v2, v4
	v_lshrrev_b32_e32 v3, 26, v3
	v_lshrrev_b32_e32 v5, 4, v4
	v_add_u32_e32 v3, v0, v3
	v_bitop3_b32 v5, v5, v4, 32 bitop3:0x6c
	v_ashrrev_i32_e32 v4, 31, v4
	v_ashrrev_i32_e32 v3, 6, v3
	v_lshrrev_b32_e32 v4, 26, v4
	v_lshlrev_b32_e32 v6, 3, v3
	v_add_u32_e32 v4, v5, v4
	v_and_b32_e32 v6, 0x1ffff0, v6
	v_ashrrev_i32_e32 v4, 6, v4
	v_add_u32_e32 v6, v4, v6
	v_mul_i32_i24_e32 v4, 64, v4
	v_add_u32_e32 v2, 0x2000, v2
	v_sub_u32_e32 v4, v5, v4
	v_ashrrev_i32_e32 v5, 31, v2
	v_lshrrev_b32_e32 v5, 22, v5
	v_add_u32_e32 v5, v2, v5
	v_ashrrev_i32_e32 v5, 10, v5
	v_mul_i32_i24_e32 v7, 0x400, v5
	v_sub_u32_e32 v2, v2, v7
	s_add_u32 s0, s8, s0
	v_lshrrev_b32_e32 v7, 4, v2
	s_addc_u32 s1, s9, s1
	v_bitop3_b32 v2, v7, v2, 32 bitop3:0x6c
	v_ashrrev_i32_e32 v8, 31, v2
	s_add_u32 s4, s2, 0x40000
	v_readlane_b32 s6, v254, 49
	v_lshrrev_b32_e32 v8, 26, v8
	s_addc_u32 s5, s3, 0
	v_readlane_b32 s7, v254, 50
	v_writelane_b32 v255, s8, 7
	v_add_u32_e32 v8, v2, v8
	v_readfirstlane_b32 s8, v0
	s_add_u32 s6, s0, 0x40000
	v_lshlrev_b32_e32 v3, 5, v3
	v_lshlrev_b32_e32 v7, 3, v5
	v_lshrrev_b32_e32 v9, 6, v8
	v_and_b32_e32 v8, 0xc0, v8
	s_addc_u32 s7, s1, 0
	s_lshl_b32 s8, s8, 4
	v_and_b32_e32 v3, 32, v3
	v_ashrrev_i16_sdwa v4, v178, sext(v4) dst_sel:DWORD dst_unused:UNUSED_PAD src0_sel:DWORD src1_sel:BYTE_0
	v_and_b32_e32 v7, 0x1ffff0, v7
	v_lshlrev_b32_e32 v5, 5, v5
	v_sub_u32_e32 v2, v2, v8
	s_and_b32 s8, s8, 0xfffffc00
	v_readlane_b32 s10, v252, 32
	v_bfe_i32 v4, v4, 0, 16
	v_add_u32_e32 v7, v9, v7
	v_and_b32_e32 v5, 32, v5
	v_ashrrev_i16_sdwa v2, v178, sext(v2) dst_sel:DWORD dst_unused:UNUSED_PAD src0_sel:DWORD src1_sel:BYTE_0
	v_lshl_or_b32 v3, v6, 10, v3
	s_add_i32 s8, s8, 0
	v_writelane_b32 v255, s9, 8
	v_bfe_i32 v2, v2, 0, 16
	v_add_lshl_u32 v3, v3, v4, 1
	v_lshl_or_b32 v4, v7, 10, v5
	s_add_i32 s9, s8, 0x10000
	s_mov_b32 m0, s9
	s_nop 0
	global_load_lds_dwordx4 v3, s[0:1]
	v_add_lshl_u32 v2, v4, v2, 1
	s_add_i32 s9, s8, 0x12000
	s_mov_b32 m0, s9
	s_nop 0
	global_load_lds_dwordx4 v2, s[0:1]
	s_mov_b32 m0, s8
	s_nop 0
	global_load_lds_dwordx4 v3, s[2:3]
	s_add_i32 s9, s8, 0x2000
	s_mov_b32 m0, s9
	s_nop 0
	global_load_lds_dwordx4 v2, s[2:3]
	s_add_i32 s9, s8, 0x14000
	s_mov_b32 m0, s9
	s_nop 0
	global_load_lds_dwordx4 v3, s[6:7]
	s_add_i32 s9, s8, 0x16000
	s_mov_b32 m0, s9
	s_nop 0
	global_load_lds_dwordx4 v2, s[6:7]
	s_add_i32 s6, s8, 0x4000
	s_mov_b32 m0, s6
	s_nop 0
	global_load_lds_dwordx4 v3, s[4:5]
	s_add_i32 s6, s8, 0x6000
	s_mov_b32 m0, s6
	s_nop 0
	global_load_lds_dwordx4 v2, s[4:5]
	s_add_u32 s4, s0, 0x80
	s_addc_u32 s5, s1, 0
	s_add_i32 s6, s8, 0x18000
	s_mov_b32 m0, s6
	s_nop 0
	global_load_lds_dwordx4 v3, s[4:5]
	s_add_i32 s6, s8, 0x1a000
	s_add_u32 s2, s2, 0x80
	s_mov_b32 m0, s6
	s_nop 0
	global_load_lds_dwordx4 v2, s[4:5]
	s_addc_u32 s3, s3, 0
	s_add_i32 s4, s8, 0x8000
	s_mov_b32 m0, s4
	s_nop 0
	global_load_lds_dwordx4 v3, s[2:3]
	s_add_i32 s4, s8, 0xa000
	s_mov_b32 m0, s4
	s_nop 0
	global_load_lds_dwordx4 v2, s[2:3]
	s_add_u32 s0, s0, 0x40080
	s_addc_u32 s1, s1, 0
	s_add_i32 s2, s8, 0x1c000
	s_mov_b32 m0, s2
	s_nop 0
	global_load_lds_dwordx4 v3, s[0:1]
	s_add_i32 s8, s8, 0x1e000
	s_mov_b32 m0, s8
	s_nop 0
	global_load_lds_dwordx4 v2, s[0:1]
	s_mov_b32 s93, s45
	v_readlane_b32 s11, v252, 33
	v_readlane_b32 s12, v252, 34
	v_readlane_b32 s13, v252, 35
	v_readlane_b32 s14, v252, 36
	v_readlane_b32 s15, v252, 37
	v_readlane_b32 s16, v252, 38
	v_readlane_b32 s17, v252, 39
	v_readlane_b32 s18, v252, 40
	v_readlane_b32 s19, v252, 41
	s_branch .LBB0_578

; #define WAIT_V(n) asm volatile("s_waitcnt vmcnt(" #n ")" ::: "memory")
; #define WAIT_L(n) asm volatile("s_waitcnt lgkmcnt(" #n ")" ::: "memory")
; #define BAR __builtin_amdgcn_s_barrier()
; #define SCHED __builtin_amdgcn_sched_barrier(0)
; #define STG_A(b, h, kt) stage_half_s(lds0 + ((b) * 2 + (h)) * HT_B, ((h) ? A1 : Ap) + (kt) * BK, off0, off1)
; #define STG_B(b, h, kt) stage_half_s(lds0 + (4 + (b) * 2 + (h)) * HT_B, ((h) ? B1p : Bp) + (kt) * BK, off0, off1)
; #define STG_A(b, h, kt) stage_half_s(lds0 + ((b) * 2 + (h)) * HT_B, ((h) ? A1 : Ap) + (kt) * BK, off0, off1)
; #define STG_B(b, h, kt) stage_half_s(lds0 + (4 + (b) * 2 + (h)) * HT_B, ((h) ? B1p : Bp) + (kt) * BK, off0, off1)
; #define LDA8(b, h) _Pragma("unroll") for (int m = 0; m < 4; ++m) _Pragma("unroll") for (int k = 0; k < 2; ++k) \
;     At[m][k] = *(const bf16x8*)(SA_(shm, b, h) + abase + (m * 2 + k) * 1024)
; #define LDB8(dst, b, h) _Pragma("unroll") for (int n = 0; n < 2; ++n) _Pragma("unroll") for (int k = 0; k < 2; ++k) \
;     dst[n][k] = *(const bf16x8*)(SB_(shm, b, h) + bbase + (n * 2 + k) * 1024)
; #define MMA8(ai, bj, Bx) do { __builtin_amdgcn_s_setprio(1); \
;     _Pragma("unroll") for (int m = 0; m < 4; ++m) _Pragma("unroll") for (int n = 0; n < 2; ++n) _Pragma("unroll") for (int k = 0; k < 2; ++k) \
;       acc[ai][bj][m][n] = __builtin_amdgcn_mfma_f32_16x16x32_bf16(At[m][k], Bx[n][k], acc[ai][bj][m][n], 0, 0, 0); \
;     __builtin_amdgcn_s_setprio(0); } while (0)
; template <bool HS>
; __device__ __forceinline__ void gemm_tile8(const u16* __restrict__ Ap, const u16* __restrict__ Bp, int K,
;                                            f32x4 (&acc)[2][2][4][2], char* shm, const int tid, const float* hsr = nullptr) {
;     ...
;     LDB8(B0, 0, 0); SCHED; LDA8(0, 0); STG_A(1, 1, t + 1);
;     WAIT_L(8); BAR; WAIT_L(0); MMA8(0, 0, B0); BAR; SCHED;
;     LDB8(B1, 0, 1); STG_B(0, 0, t + 2);
;     BAR; WAIT_L(0); MMA8(0, 1, B1); BAR;
;     LDA8(0, 1); STG_A(0, 0, t + 2);
;     BAR; WAIT_L(0); MMA8(1, 0, B0); BAR; SCHED;
;     STG_B(0, 1, t + 2);
;     WAIT_V(6); BAR; MMA8(1, 1, B1); BAR;
;     LDB8(B0, 1, 0); SCHED; LDA8(1, 0); STG_A(0, 1, t + 2);
;     WAIT_L(8); BAR; WAIT_L(0); MMA8(0, 0, B0); BAR; SCHED;
;     LDB8(B1, 1, 1); STG_B(1, 0, t + 3);
.LBB0_583:
	s_add_i32 s89, 0, 0x10000
	v_add_u32_e32 v135, s89, v133
	ds_read_b128 v[142:145], v135
	ds_read_b128 v[146:149], v135 offset:1024
	ds_read_b128 v[150:153], v135 offset:2048
	ds_read_b128 v[154:157], v135 offset:3072
	ds_read_b128 v[158:161], v130
	ds_read_b128 v[164:167], v130 offset:1024
	ds_read_b128 v[168:171], v130 offset:2048
	ds_read_b128 v[172:175], v130 offset:3072
	ds_read_b128 v[180:183], v130 offset:4096
	ds_read_b128 v[184:187], v130 offset:5120
	ds_read_b128 v[188:191], v130 offset:6144
	ds_read_b128 v[192:195], v130 offset:7168
	s_add_u32 s21, s18, s6
	s_addc_u32 s22, s19, s7
	s_add_u32 s24, s21, 0x80
	s_addc_u32 s25, s22, 0
	s_add_i32 s21, s15, 0xc000
	s_mov_b32 m0, s21
	s_nop 0
	global_load_lds_dwordx4 v132, s[24:25]
	s_add_i32 s22, s15, 0xe000
	s_mov_b32 m0, s22
	s_nop 0
	global_load_lds_dwordx4 v131, s[24:25]
	s_waitcnt lgkmcnt(8)
	s_barrier
	s_waitcnt lgkmcnt(0)
	s_setprio 1
	s_waitcnt lgkmcnt(7)
	v_mfma_f32_16x16x32_bf16 v[126:129], v[158:161], v[142:145], v[126:129]
	v_mfma_f32_16x16x32_bf16 v[122:125], v[158:161], v[150:153], v[122:125]
	s_waitcnt lgkmcnt(5)
	v_mfma_f32_16x16x32_bf16 v[118:121], v[168:171], v[142:145], v[118:121]
	v_mfma_f32_16x16x32_bf16 v[114:117], v[168:171], v[150:153], v[114:117]
	s_waitcnt lgkmcnt(3)
	v_mfma_f32_16x16x32_bf16 v[110:113], v[180:183], v[142:145], v[110:113]
	v_mfma_f32_16x16x32_bf16 v[106:109], v[180:183], v[150:153], v[106:109]
	s_waitcnt lgkmcnt(1)
	v_mfma_f32_16x16x32_bf16 v[102:105], v[188:191], v[142:145], v[102:105]
	v_mfma_f32_16x16x32_bf16 v[98:101], v[188:191], v[150:153], v[98:101]
	v_mfma_f32_16x16x32_bf16 v[126:129], v[164:167], v[146:149], v[126:129]
	v_mfma_f32_16x16x32_bf16 v[122:125], v[164:167], v[154:157], v[122:125]
	v_mfma_f32_16x16x32_bf16 v[118:121], v[172:175], v[146:149], v[118:121]
	v_mfma_f32_16x16x32_bf16 v[114:117], v[172:175], v[154:157], v[114:117]
	v_mfma_f32_16x16x32_bf16 v[110:113], v[184:187], v[146:149], v[110:113]
	v_mfma_f32_16x16x32_bf16 v[106:109], v[184:187], v[154:157], v[106:109]
	s_waitcnt lgkmcnt(0)
	v_mfma_f32_16x16x32_bf16 v[102:105], v[192:195], v[146:149], v[102:105]
	v_mfma_f32_16x16x32_bf16 v[98:101], v[192:195], v[154:157], v[98:101]
	s_setprio 0
	s_barrier
	s_add_i32 s23, 0, 0x14000
	v_add_u32_e32 v135, s23, v133
	ds_read_b128 v[196:199], v135
	ds_read_b128 v[200:203], v135 offset:1024
	ds_read_b128 v[204:207], v135 offset:2048
	ds_read_b128 v[208:211], v135 offset:3072
	s_add_u32 s26, s3, s6
	s_addc_u32 s27, s10, s7
	s_add_u32 s24, s26, 0x100
	s_addc_u32 s25, s27, 0
	s_add_i32 s36, s11, s89
	s_mov_b32 m0, s36
	s_nop 0
	global_load_lds_dwordx4 v132, s[24:25]
	s_add_i32 s36, s15, 0x12000
	s_mov_b32 m0, s36
	s_nop 0
	global_load_lds_dwordx4 v131, s[24:25]
	s_barrier
	s_waitcnt lgkmcnt(0)
	s_setprio 1
	s_waitcnt lgkmcnt(3)
	v_mfma_f32_16x16x32_bf16 v[94:97], v[158:161], v[196:199], v[94:97]
	s_waitcnt lgkmcnt(1)
	v_mfma_f32_16x16x32_bf16 v[90:93], v[158:161], v[204:207], v[90:93]
	v_mfma_f32_16x16x32_bf16 v[86:89], v[168:171], v[196:199], v[86:89]
	v_mfma_f32_16x16x32_bf16 v[82:85], v[168:171], v[204:207], v[82:85]
	v_mfma_f32_16x16x32_bf16 v[78:81], v[180:183], v[196:199], v[78:81]
	v_mfma_f32_16x16x32_bf16 v[74:77], v[180:183], v[204:207], v[74:77]
	v_mfma_f32_16x16x32_bf16 v[70:73], v[188:191], v[196:199], v[70:73]
	v_mfma_f32_16x16x32_bf16 v[66:69], v[188:191], v[204:207], v[66:69]
	v_mfma_f32_16x16x32_bf16 v[94:97], v[164:167], v[200:203], v[94:97]
	s_waitcnt lgkmcnt(0)
	v_mfma_f32_16x16x32_bf16 v[90:93], v[164:167], v[208:211], v[90:93]
	v_mfma_f32_16x16x32_bf16 v[86:89], v[172:175], v[200:203], v[86:89]
	v_mfma_f32_16x16x32_bf16 v[82:85], v[172:175], v[208:211], v[82:85]
	v_mfma_f32_16x16x32_bf16 v[78:81], v[184:187], v[200:203], v[78:81]
	v_mfma_f32_16x16x32_bf16 v[74:77], v[184:187], v[208:211], v[74:77]
	v_mfma_f32_16x16x32_bf16 v[70:73], v[192:195], v[200:203], v[70:73]
	v_mfma_f32_16x16x32_bf16 v[66:69], v[192:195], v[208:211], v[66:69]
	s_setprio 0
	s_barrier
	ds_read_b128 v[158:161], v130 offset:16384
	ds_read_b128 v[164:167], v130 offset:17408
	ds_read_b128 v[168:171], v130 offset:18432
	ds_read_b128 v[172:175], v130 offset:19456
	ds_read_b128 v[180:183], v130 offset:20480
	ds_read_b128 v[184:187], v130 offset:21504
	ds_read_b128 v[188:191], v130 offset:22528
	ds_read_b128 v[192:195], v130 offset:23552
	s_add_u32 s36, s8, s6
	s_addc_u32 s37, s9, s7
	s_add_u32 s24, s36, 0x100
	s_addc_u32 s25, s37, 0
	s_mov_b32 m0, s15
	s_nop 0
	global_load_lds_dwordx4 v132, s[24:25]
	s_add_i32 s38, s15, 0x2000
	s_mov_b32 m0, s38
	s_nop 0
	global_load_lds_dwordx4 v131, s[24:25]
	s_barrier
	s_waitcnt lgkmcnt(0)
	s_setprio 1
	s_waitcnt lgkmcnt(7)
	v_mfma_f32_16x16x32_bf16 v[62:65], v[158:161], v[142:145], v[62:65]
	v_mfma_f32_16x16x32_bf16 v[58:61], v[158:161], v[150:153], v[58:61]
	s_waitcnt lgkmcnt(5)
	v_mfma_f32_16x16x32_bf16 v[54:57], v[168:171], v[142:145], v[54:57]
	v_mfma_f32_16x16x32_bf16 v[50:53], v[168:171], v[150:153], v[50:53]
	s_waitcnt lgkmcnt(3)
	v_mfma_f32_16x16x32_bf16 v[46:49], v[180:183], v[142:145], v[46:49]
	v_mfma_f32_16x16x32_bf16 v[42:45], v[180:183], v[150:153], v[42:45]
	s_waitcnt lgkmcnt(1)
	v_mfma_f32_16x16x32_bf16 v[38:41], v[188:191], v[142:145], v[38:41]
	v_mfma_f32_16x16x32_bf16 v[34:37], v[188:191], v[150:153], v[34:37]
	v_mfma_f32_16x16x32_bf16 v[62:65], v[164:167], v[146:149], v[62:65]
	v_mfma_f32_16x16x32_bf16 v[58:61], v[164:167], v[154:157], v[58:61]
	v_mfma_f32_16x16x32_bf16 v[54:57], v[172:175], v[146:149], v[54:57]
	v_mfma_f32_16x16x32_bf16 v[50:53], v[172:175], v[154:157], v[50:53]
	v_mfma_f32_16x16x32_bf16 v[46:49], v[184:187], v[146:149], v[46:49]
	v_mfma_f32_16x16x32_bf16 v[42:45], v[184:187], v[154:157], v[42:45]
	s_waitcnt lgkmcnt(0)
	v_mfma_f32_16x16x32_bf16 v[38:41], v[192:195], v[146:149], v[38:41]
	v_mfma_f32_16x16x32_bf16 v[34:37], v[192:195], v[154:157], v[34:37]
	s_setprio 0
	s_barrier
; #define WAIT_V(n) asm volatile("s_waitcnt vmcnt(" #n ")" ::: "memory")
; #define WAIT_L(n) asm volatile("s_waitcnt lgkmcnt(" #n ")" ::: "memory")
; #define BAR __builtin_amdgcn_s_barrier()
; #define SCHED __builtin_amdgcn_sched_barrier(0)
; #define STG_A(b, h, kt) stage_half_s(lds0 + ((b) * 2 + (h)) * HT_B, ((h) ? A1 : Ap) + (kt) * BK, off0, off1)
; #define STG_B(b, h, kt) stage_half_s(lds0 + (4 + (b) * 2 + (h)) * HT_B, ((h) ? B1p : Bp) + (kt) * BK, off0, off1)
; #define STG_A(b, h, kt) stage_half_s(lds0 + ((b) * 2 + (h)) * HT_B, ((h) ? A1 : Ap) + (kt) * BK, off0, off1)
; #define STG_B(b, h, kt) stage_half_s(lds0 + (4 + (b) * 2 + (h)) * HT_B, ((h) ? B1p : Bp) + (kt) * BK, off0, off1)
; #define LDA8(b, h) _Pragma("unroll") for (int m = 0; m < 4; ++m) _Pragma("unroll") for (int k = 0; k < 2; ++k) \
;     At[m][k] = *(const bf16x8*)(SA_(shm, b, h) + abase + (m * 2 + k) * 1024)
; #define LDB8(dst, b, h) _Pragma("unroll") for (int n = 0; n < 2; ++n) _Pragma("unroll") for (int k = 0; k < 2; ++k) \
;     dst[n][k] = *(const bf16x8*)(SB_(shm, b, h) + bbase + (n * 2 + k) * 1024)
; #define MMA8(ai, bj, Bx) do { __builtin_amdgcn_s_setprio(1); \
;     _Pragma("unroll") for (int m = 0; m < 4; ++m) _Pragma("unroll") for (int n = 0; n < 2; ++n) _Pragma("unroll") for (int k = 0; k < 2; ++k) \
;       acc[ai][bj][m][n] = __builtin_amdgcn_mfma_f32_16x16x32_bf16(At[m][k], Bx[n][k], acc[ai][bj][m][n], 0, 0, 0); \
;     __builtin_amdgcn_s_setprio(0); } while (0)
; template <bool HS>
; __device__ __forceinline__ void gemm_tile8(const u16* __restrict__ Ap, const u16* __restrict__ Bp, int K,
;                                            f32x4 (&acc)[2][2][4][2], char* shm, const int tid, const float* hsr = nullptr) {
;     ...
;     STG_B(0, 1, t + 2);
;     WAIT_V(6); BAR; MMA8(1, 1, B1); BAR;
;     LDB8(B0, 1, 0); SCHED; LDA8(1, 0); STG_A(0, 1, t + 2);
;     WAIT_L(8); BAR; WAIT_L(0); MMA8(0, 0, B0); BAR; SCHED;
;     LDB8(B1, 1, 1); STG_B(1, 0, t + 3);
;     BAR; WAIT_L(0); MMA8(0, 1, B1); BAR;
;     LDA8(1, 1); STG_A(1, 0, t + 3);
;     BAR; WAIT_L(0); MMA8(1, 0, B0); BAR; SCHED;
	s_add_u32 s38, s13, s6
	s_addc_u32 s39, s14, s7
	s_add_u32 s24, s38, 0x100
	s_addc_u32 s25, s39, 0
	s_add_i32 s23, s11, s23
	s_mov_b32 m0, s23
	s_nop 0
	global_load_lds_dwordx4 v132, s[24:25]
	s_add_i32 s23, s15, 0x16000
	s_mov_b32 m0, s23
	s_nop 0
	global_load_lds_dwordx4 v131, s[24:25]
	s_waitcnt vmcnt(6)
	s_barrier
	s_setprio 1
	v_mfma_f32_16x16x32_bf16 v[30:33], v[158:161], v[196:199], v[30:33]
	v_mfma_f32_16x16x32_bf16 v[26:29], v[158:161], v[204:207], v[26:29]
	v_mfma_f32_16x16x32_bf16 v[22:25], v[168:171], v[196:199], v[22:25]
	v_mfma_f32_16x16x32_bf16 v[18:21], v[168:171], v[204:207], v[18:21]
	v_mfma_f32_16x16x32_bf16 v[14:17], v[180:183], v[196:199], v[14:17]
	v_mfma_f32_16x16x32_bf16 v[10:13], v[180:183], v[204:207], v[10:13]
	v_mfma_f32_16x16x32_bf16 v[6:9], v[188:191], v[196:199], v[6:9]
	v_mfma_f32_16x16x32_bf16 v[2:5], v[188:191], v[204:207], v[2:5]
	v_mfma_f32_16x16x32_bf16 v[30:33], v[164:167], v[200:203], v[30:33]
	v_mfma_f32_16x16x32_bf16 v[26:29], v[164:167], v[208:211], v[26:29]
	v_mfma_f32_16x16x32_bf16 v[22:25], v[172:175], v[200:203], v[22:25]
	v_mfma_f32_16x16x32_bf16 v[18:21], v[172:175], v[208:211], v[18:21]
	v_mfma_f32_16x16x32_bf16 v[14:17], v[184:187], v[200:203], v[14:17]
	v_mfma_f32_16x16x32_bf16 v[10:13], v[184:187], v[208:211], v[10:13]
	v_mfma_f32_16x16x32_bf16 v[6:9], v[192:195], v[200:203], v[6:9]
	v_mfma_f32_16x16x32_bf16 v[2:5], v[192:195], v[208:211], v[2:5]
	s_setprio 0
	s_add_i32 s23, 0, 0x18000
	v_add_u32_e32 v135, s23, v133
	s_barrier
	ds_read_b128 v[142:145], v135
	ds_read_b128 v[146:149], v135 offset:1024
	ds_read_b128 v[150:153], v135 offset:2048
	ds_read_b128 v[154:157], v135 offset:3072
	ds_read_b128 v[158:161], v130 offset:32768
	ds_read_b128 v[164:167], v130 offset:33792
	ds_read_b128 v[168:171], v130 offset:34816
	ds_read_b128 v[172:175], v130 offset:35840
	ds_read_b128 v[180:183], v130 offset:36864
	ds_read_b128 v[184:187], v130 offset:37888
	ds_read_b128 v[188:191], v130 offset:38912
	ds_read_b128 v[192:195], v130 offset:39936
	s_add_u32 s24, s16, s6
	s_addc_u32 s25, s17, s7
	s_add_i32 s40, s15, 0x4000
	s_mov_b32 m0, s40
	s_nop 0
	global_load_lds_dwordx4 v132, s[24:25]
	s_add_i32 s40, s15, 0x6000
	s_mov_b32 m0, s40
	s_nop 0
	global_load_lds_dwordx4 v131, s[24:25]
	s_waitcnt lgkmcnt(8)
	s_barrier
	s_waitcnt lgkmcnt(0)
	s_setprio 1
	s_waitcnt lgkmcnt(7)
	v_mfma_f32_16x16x32_bf16 v[126:129], v[158:161], v[142:145], v[126:129]
	v_mfma_f32_16x16x32_bf16 v[122:125], v[158:161], v[150:153], v[122:125]
	s_waitcnt lgkmcnt(5)
	v_mfma_f32_16x16x32_bf16 v[118:121], v[168:171], v[142:145], v[118:121]
	v_mfma_f32_16x16x32_bf16 v[114:117], v[168:171], v[150:153], v[114:117]
	s_waitcnt lgkmcnt(3)
	v_mfma_f32_16x16x32_bf16 v[110:113], v[180:183], v[142:145], v[110:113]
	v_mfma_f32_16x16x32_bf16 v[106:109], v[180:183], v[150:153], v[106:109]
	s_waitcnt lgkmcnt(1)
	v_mfma_f32_16x16x32_bf16 v[102:105], v[188:191], v[142:145], v[102:105]
	v_mfma_f32_16x16x32_bf16 v[98:101], v[188:191], v[150:153], v[98:101]
	v_mfma_f32_16x16x32_bf16 v[126:129], v[164:167], v[146:149], v[126:129]
	v_mfma_f32_16x16x32_bf16 v[122:125], v[164:167], v[154:157], v[122:125]
	v_mfma_f32_16x16x32_bf16 v[118:121], v[172:175], v[146:149], v[118:121]
	v_mfma_f32_16x16x32_bf16 v[114:117], v[172:175], v[154:157], v[114:117]
	v_mfma_f32_16x16x32_bf16 v[110:113], v[184:187], v[146:149], v[110:113]
	v_mfma_f32_16x16x32_bf16 v[106:109], v[184:187], v[154:157], v[106:109]
	s_waitcnt lgkmcnt(0)
	v_mfma_f32_16x16x32_bf16 v[102:105], v[192:195], v[146:149], v[102:105]
	v_mfma_f32_16x16x32_bf16 v[98:101], v[192:195], v[154:157], v[98:101]
	s_setprio 0
	s_barrier
	s_add_i32 s40, 0, 0x1c000
	v_add_u32_e32 v135, s40, v133
	ds_read_b128 v[196:199], v135
	ds_read_b128 v[200:203], v135 offset:1024
	ds_read_b128 v[204:207], v135 offset:2048
	ds_read_b128 v[208:211], v135 offset:3072
	s_add_u32 s24, s26, 0x180
	s_addc_u32 s25, s27, 0
	s_add_i32 s23, s11, s23
	s_mov_b32 m0, s23
	s_nop 0
	global_load_lds_dwordx4 v132, s[24:25]
	s_add_i32 s23, s15, 0x1a000
	s_mov_b32 m0, s23
	s_nop 0
	global_load_lds_dwordx4 v131, s[24:25]
	s_barrier
	s_waitcnt lgkmcnt(0)
	s_setprio 1
	s_waitcnt lgkmcnt(3)
	v_mfma_f32_16x16x32_bf16 v[94:97], v[158:161], v[196:199], v[94:97]
	s_waitcnt lgkmcnt(1)
	v_mfma_f32_16x16x32_bf16 v[90:93], v[158:161], v[204:207], v[90:93]
	v_mfma_f32_16x16x32_bf16 v[86:89], v[168:171], v[196:199], v[86:89]
	v_mfma_f32_16x16x32_bf16 v[82:85], v[168:171], v[204:207], v[82:85]
	v_mfma_f32_16x16x32_bf16 v[78:81], v[180:183], v[196:199], v[78:81]
	v_mfma_f32_16x16x32_bf16 v[74:77], v[180:183], v[204:207], v[74:77]
	v_mfma_f32_16x16x32_bf16 v[70:73], v[188:191], v[196:199], v[70:73]
	v_mfma_f32_16x16x32_bf16 v[66:69], v[188:191], v[204:207], v[66:69]
	v_mfma_f32_16x16x32_bf16 v[94:97], v[164:167], v[200:203], v[94:97]
	s_waitcnt lgkmcnt(0)
	v_mfma_f32_16x16x32_bf16 v[90:93], v[164:167], v[208:211], v[90:93]
	v_mfma_f32_16x16x32_bf16 v[86:89], v[172:175], v[200:203], v[86:89]
	v_mfma_f32_16x16x32_bf16 v[82:85], v[172:175], v[208:211], v[82:85]
	v_mfma_f32_16x16x32_bf16 v[78:81], v[184:187], v[200:203], v[78:81]
	v_mfma_f32_16x16x32_bf16 v[74:77], v[184:187], v[208:211], v[74:77]
	v_mfma_f32_16x16x32_bf16 v[70:73], v[192:195], v[200:203], v[70:73]
	v_mfma_f32_16x16x32_bf16 v[66:69], v[192:195], v[208:211], v[66:69]
	s_setprio 0
	s_barrier
	ds_read_b128 v[158:161], v130 offset:49152
	ds_read_b128 v[164:167], v130 offset:50176
	ds_read_b128 v[168:171], v130 offset:51200
	ds_read_b128 v[172:175], v130 offset:52224
	ds_read_b128 v[180:183], v130 offset:53248
	ds_read_b128 v[184:187], v130 offset:54272
	ds_read_b128 v[188:191], v130 offset:55296
	ds_read_b128 v[192:195], v130 offset:56320
	s_add_u32 s24, s36, 0x180
	s_addc_u32 s25, s37, 0
	s_add_i32 s23, s15, 0x8000
	s_mov_b32 m0, s23
	s_nop 0
	global_load_lds_dwordx4 v132, s[24:25]
	s_add_i32 s23, s15, 0xa000
	s_mov_b32 m0, s23
	s_nop 0
	global_load_lds_dwordx4 v131, s[24:25]
	s_barrier
; #define WAIT_V(n) asm volatile("s_waitcnt vmcnt(" #n ")" ::: "memory")
; #define WAIT_L(n) asm volatile("s_waitcnt lgkmcnt(" #n ")" ::: "memory")
; #define BAR __builtin_amdgcn_s_barrier()
; #define SCHED __builtin_amdgcn_sched_barrier(0)
; #define STG_A(b, h, kt) stage_half_s(lds0 + ((b) * 2 + (h)) * HT_B, ((h) ? A1 : Ap) + (kt) * BK, off0, off1)
; #define STG_B(b, h, kt) stage_half_s(lds0 + (4 + (b) * 2 + (h)) * HT_B, ((h) ? B1p : Bp) + (kt) * BK, off0, off1)
; #define STG_A(b, h, kt) stage_half_s(lds0 + ((b) * 2 + (h)) * HT_B, ((h) ? A1 : Ap) + (kt) * BK, off0, off1)
; #define STG_B(b, h, kt) stage_half_s(lds0 + (4 + (b) * 2 + (h)) * HT_B, ((h) ? B1p : Bp) + (kt) * BK, off0, off1)
; #define LDA8(b, h) _Pragma("unroll") for (int m = 0; m < 4; ++m) _Pragma("unroll") for (int k = 0; k < 2; ++k) \
;     At[m][k] = *(const bf16x8*)(SA_(shm, b, h) + abase + (m * 2 + k) * 1024)
; #define LDB8(dst, b, h) _Pragma("unroll") for (int n = 0; n < 2; ++n) _Pragma("unroll") for (int k = 0; k < 2; ++k) \
;     dst[n][k] = *(const bf16x8*)(SB_(shm, b, h) + bbase + (n * 2 + k) * 1024)
; #define MMA8(ai, bj, Bx) do { __builtin_amdgcn_s_setprio(1); \
;     _Pragma("unroll") for (int m = 0; m < 4; ++m) _Pragma("unroll") for (int n = 0; n < 2; ++n) _Pragma("unroll") for (int k = 0; k < 2; ++k) \
;       acc[ai][bj][m][n] = __builtin_amdgcn_mfma_f32_16x16x32_bf16(At[m][k], Bx[n][k], acc[ai][bj][m][n], 0, 0, 0); \
;     __builtin_amdgcn_s_setprio(0); } while (0)
; template <bool HS>
; __device__ __forceinline__ void gemm_tile8(const u16* __restrict__ Ap, const u16* __restrict__ Bp, int K,
;                                            f32x4 (&acc)[2][2][4][2], char* shm, const int tid, const float* hsr = nullptr) {
;     ...
;     BAR; WAIT_L(0); MMA8(1, 0, B0); BAR; SCHED;
;     STG_B(1, 1, t + 3);
;     WAIT_V(6); BAR; MMA8(1, 1, B1); BAR;
;   }
;   { LDB8(B0, 0, 0); LDA8(0, 0); STG_A(1, 1, nt - 1);
;     BAR; WAIT_L(0); MMA8(0, 0, B0); BAR;
;     LDB8(B1, 0, 1); BAR; WAIT_L(0); MMA8(0, 1, B1); BAR;
;     LDA8(0, 1); WAIT_V(4); BAR; WAIT_L(0); MMA8(1, 0, B0); MMA8(1, 1, B1); BAR; }
	s_waitcnt lgkmcnt(0)
	s_setprio 1
	s_waitcnt lgkmcnt(7)
	v_mfma_f32_16x16x32_bf16 v[62:65], v[158:161], v[142:145], v[62:65]
	v_mfma_f32_16x16x32_bf16 v[58:61], v[158:161], v[150:153], v[58:61]
	s_waitcnt lgkmcnt(5)
	v_mfma_f32_16x16x32_bf16 v[54:57], v[168:171], v[142:145], v[54:57]
	v_mfma_f32_16x16x32_bf16 v[50:53], v[168:171], v[150:153], v[50:53]
	s_waitcnt lgkmcnt(3)
	v_mfma_f32_16x16x32_bf16 v[46:49], v[180:183], v[142:145], v[46:49]
	v_mfma_f32_16x16x32_bf16 v[42:45], v[180:183], v[150:153], v[42:45]
	s_waitcnt lgkmcnt(1)
	v_mfma_f32_16x16x32_bf16 v[38:41], v[188:191], v[142:145], v[38:41]
	v_mfma_f32_16x16x32_bf16 v[34:37], v[188:191], v[150:153], v[34:37]
	v_mfma_f32_16x16x32_bf16 v[62:65], v[164:167], v[146:149], v[62:65]
	v_mfma_f32_16x16x32_bf16 v[58:61], v[164:167], v[154:157], v[58:61]
	v_mfma_f32_16x16x32_bf16 v[54:57], v[172:175], v[146:149], v[54:57]
	v_mfma_f32_16x16x32_bf16 v[50:53], v[172:175], v[154:157], v[50:53]
	v_mfma_f32_16x16x32_bf16 v[46:49], v[184:187], v[146:149], v[46:49]
	v_mfma_f32_16x16x32_bf16 v[42:45], v[184:187], v[154:157], v[42:45]
	s_waitcnt lgkmcnt(0)
	v_mfma_f32_16x16x32_bf16 v[38:41], v[192:195], v[146:149], v[38:41]
	v_mfma_f32_16x16x32_bf16 v[34:37], v[192:195], v[154:157], v[34:37]
	s_setprio 0
	s_barrier
	s_add_u32 s24, s38, 0x180
	s_addc_u32 s25, s39, 0
	s_add_i32 s23, s11, s40
	s_mov_b32 m0, s23
	s_nop 0
	global_load_lds_dwordx4 v132, s[24:25]
	s_add_i32 s23, s15, 0x1e000
	s_mov_b32 m0, s23
	s_nop 0
	global_load_lds_dwordx4 v131, s[24:25]
	s_waitcnt vmcnt(6)
	s_barrier
	s_setprio 1
	v_mfma_f32_16x16x32_bf16 v[30:33], v[158:161], v[196:199], v[30:33]
	v_mfma_f32_16x16x32_bf16 v[26:29], v[158:161], v[204:207], v[26:29]
	v_mfma_f32_16x16x32_bf16 v[22:25], v[168:171], v[196:199], v[22:25]
	v_mfma_f32_16x16x32_bf16 v[18:21], v[168:171], v[204:207], v[18:21]
	v_mfma_f32_16x16x32_bf16 v[14:17], v[180:183], v[196:199], v[14:17]
	v_mfma_f32_16x16x32_bf16 v[10:13], v[180:183], v[204:207], v[10:13]
	v_mfma_f32_16x16x32_bf16 v[6:9], v[188:191], v[196:199], v[6:9]
	v_mfma_f32_16x16x32_bf16 v[2:5], v[188:191], v[204:207], v[2:5]
	v_mfma_f32_16x16x32_bf16 v[30:33], v[164:167], v[200:203], v[30:33]
	v_mfma_f32_16x16x32_bf16 v[26:29], v[164:167], v[208:211], v[26:29]
	v_mfma_f32_16x16x32_bf16 v[22:25], v[172:175], v[200:203], v[22:25]
	v_mfma_f32_16x16x32_bf16 v[18:21], v[172:175], v[208:211], v[18:21]
	v_mfma_f32_16x16x32_bf16 v[14:17], v[184:187], v[200:203], v[14:17]
	v_mfma_f32_16x16x32_bf16 v[10:13], v[184:187], v[208:211], v[10:13]
	v_mfma_f32_16x16x32_bf16 v[6:9], v[192:195], v[200:203], v[6:9]
	v_mfma_f32_16x16x32_bf16 v[2:5], v[192:195], v[208:211], v[2:5]
	s_setprio 0
	s_add_i32 s20, s20, 2
	s_add_u32 s6, s6, 0x100
	s_addc_u32 s7, s7, 0
	s_cmp_lt_u32 s20, 12
	s_barrier
	s_cbranch_scc1 .LBB0_583
	v_add_u32_e32 v133, 0, v133
	v_add_u32_e32 v135, 0x10000, v133
	ds_read_b128 v[142:145], v135
	ds_read_b128 v[146:149], v135 offset:1024
	ds_read_b128 v[150:153], v135 offset:2048
	ds_read_b128 v[154:157], v135 offset:3072
	ds_read_b128 v[158:161], v130
	ds_read_b128 v[164:167], v130 offset:1024
	ds_read_b128 v[168:171], v130 offset:2048
	ds_read_b128 v[172:175], v130 offset:3072
	ds_read_b128 v[180:183], v130 offset:4096
	ds_read_b128 v[184:187], v130 offset:5120
	ds_read_b128 v[188:191], v130 offset:6144
	ds_read_b128 v[192:195], v130 offset:7168
	s_add_u32 s6, s8, 0x40780
	s_addc_u32 s7, s9, 0
	s_mov_b32 m0, s21
	s_nop 0
	global_load_lds_dwordx4 v132, s[6:7]
	s_nop 0
	s_mov_b32 m0, s22
	s_nop 0
	global_load_lds_dwordx4 v131, s[6:7]
	s_barrier
	s_waitcnt lgkmcnt(0)
	s_setprio 1
	s_waitcnt lgkmcnt(7)
	v_mfma_f32_16x16x32_bf16 v[126:129], v[158:161], v[142:145], v[126:129]
	s_waitcnt lgkmcnt(5)
	v_mfma_f32_16x16x32_bf16 v[118:121], v[168:171], v[142:145], v[118:121]
	v_mfma_f32_16x16x32_bf16 v[114:117], v[168:171], v[150:153], v[114:117]
	s_waitcnt lgkmcnt(1)
	v_mfma_f32_16x16x32_bf16 v[102:105], v[188:191], v[142:145], v[102:105]
	v_mfma_f32_16x16x32_bf16 v[98:101], v[188:191], v[150:153], v[98:101]
	v_mfma_f32_16x16x32_bf16 v[126:129], v[164:167], v[146:149], v[126:129]
	v_mfma_f32_16x16x32_bf16 v[122:125], v[158:161], v[150:153], v[122:125]
	v_mfma_f32_16x16x32_bf16 v[118:121], v[172:175], v[146:149], v[118:121]
	v_mfma_f32_16x16x32_bf16 v[114:117], v[172:175], v[154:157], v[114:117]
	v_mfma_f32_16x16x32_bf16 v[110:113], v[180:183], v[142:145], v[110:113]
	v_mfma_f32_16x16x32_bf16 v[106:109], v[180:183], v[150:153], v[106:109]
	s_waitcnt lgkmcnt(0)
	v_mfma_f32_16x16x32_bf16 v[102:105], v[192:195], v[146:149], v[102:105]
	v_mfma_f32_16x16x32_bf16 v[98:101], v[192:195], v[154:157], v[98:101]
	v_mfma_f32_16x16x32_bf16 v[196:199], v[164:167], v[154:157], v[122:125]
	v_mfma_f32_16x16x32_bf16 v[200:203], v[184:187], v[146:149], v[110:113]
	v_mfma_f32_16x16x32_bf16 v[204:207], v[184:187], v[154:157], v[106:109]
	s_setprio 0
	v_add_u32_e32 v131, 0x14000, v133
	s_barrier
	ds_read_b128 v[106:109], v131
	ds_read_b128 v[110:113], v131 offset:1024
	ds_read_b128 v[122:125], v131 offset:2048
	ds_read_b128 v[208:211], v131 offset:3072
	s_barrier
; #define WAIT_V(n) asm volatile("s_waitcnt vmcnt(" #n ")" ::: "memory")
; #define WAIT_L(n) asm volatile("s_waitcnt lgkmcnt(" #n ")" ::: "memory")
; #define BAR __builtin_amdgcn_s_barrier()
; #define LDA8(b, h) _Pragma("unroll") for (int m = 0; m < 4; ++m) _Pragma("unroll") for (int k = 0; k < 2; ++k) \
;     At[m][k] = *(const bf16x8*)(SA_(shm, b, h) + abase + (m * 2 + k) * 1024)
; #define LDB8(dst, b, h) _Pragma("unroll") for (int n = 0; n < 2; ++n) _Pragma("unroll") for (int k = 0; k < 2; ++k) \
;     dst[n][k] = *(const bf16x8*)(SB_(shm, b, h) + bbase + (n * 2 + k) * 1024)
; #define MMA8(ai, bj, Bx) do { __builtin_amdgcn_s_setprio(1); \
;     _Pragma("unroll") for (int m = 0; m < 4; ++m) _Pragma("unroll") for (int n = 0; n < 2; ++n) _Pragma("unroll") for (int k = 0; k < 2; ++k) \
;       acc[ai][bj][m][n] = __builtin_amdgcn_mfma_f32_16x16x32_bf16(At[m][k], Bx[n][k], acc[ai][bj][m][n], 0, 0, 0); \
;     __builtin_amdgcn_s_setprio(0); } while (0)
; template <bool HS>
; __device__ __forceinline__ void gemm_tile8(const u16* __restrict__ Ap, const u16* __restrict__ Bp, int K,
;                                            f32x4 (&acc)[2][2][4][2], char* shm, const int tid, const float* hsr = nullptr) {
;     ...
;     BAR; WAIT_L(0); MMA8(0, 0, B0); BAR;
;     LDB8(B1, 0, 1); BAR; WAIT_L(0); MMA8(0, 1, B1); BAR;
;     LDA8(0, 1); WAIT_V(4); BAR; WAIT_L(0); MMA8(1, 0, B0); MMA8(1, 1, B1); BAR; }
;   { LDB8(B0, 1, 0); LDA8(1, 0); WAIT_V(2); BAR; WAIT_L(0); MMA8(0, 0, B0); BAR;
	s_waitcnt lgkmcnt(0)
	s_setprio 1
	s_waitcnt lgkmcnt(3)
	v_mfma_f32_16x16x32_bf16 v[86:89], v[168:171], v[106:109], v[86:89]
	s_waitcnt lgkmcnt(1)
	v_mfma_f32_16x16x32_bf16 v[82:85], v[168:171], v[122:125], v[82:85]
	v_mfma_f32_16x16x32_bf16 v[70:73], v[188:191], v[106:109], v[70:73]
	v_mfma_f32_16x16x32_bf16 v[94:97], v[158:161], v[106:109], v[94:97]
	v_mfma_f32_16x16x32_bf16 v[90:93], v[158:161], v[122:125], v[90:93]
	v_mfma_f32_16x16x32_bf16 v[86:89], v[172:175], v[110:113], v[86:89]
	s_waitcnt lgkmcnt(0)
	v_mfma_f32_16x16x32_bf16 v[82:85], v[172:175], v[208:211], v[82:85]
	v_mfma_f32_16x16x32_bf16 v[78:81], v[180:183], v[106:109], v[78:81]
	v_mfma_f32_16x16x32_bf16 v[74:77], v[180:183], v[122:125], v[74:77]
	v_mfma_f32_16x16x32_bf16 v[70:73], v[192:195], v[110:113], v[70:73]
	v_mfma_f32_16x16x32_bf16 v[66:69], v[188:191], v[122:125], v[66:69]
	v_mfma_f32_16x16x32_bf16 v[212:215], v[164:167], v[110:113], v[94:97]
	v_mfma_f32_16x16x32_bf16 v[158:161], v[164:167], v[208:211], v[90:93]
	v_mfma_f32_16x16x32_bf16 v[164:167], v[184:187], v[110:113], v[78:81]
	v_mfma_f32_16x16x32_bf16 v[168:171], v[184:187], v[208:211], v[74:77]
	v_mfma_f32_16x16x32_bf16 v[172:175], v[192:195], v[208:211], v[66:69]
	s_setprio 0
	s_barrier
	s_nop 0
	ds_read_b128 v[66:69], v130 offset:16384
	ds_read_b128 v[74:77], v130 offset:17408
	ds_read_b128 v[78:81], v130 offset:18432
	ds_read_b128 v[90:93], v130 offset:19456
	ds_read_b128 v[94:97], v130 offset:20480
	ds_read_b128 v[180:183], v130 offset:21504
	ds_read_b128 v[184:187], v130 offset:22528
	ds_read_b128 v[188:191], v130 offset:23552
	s_waitcnt vmcnt(4)
	s_barrier
	s_waitcnt lgkmcnt(0)
	s_setprio 1
	s_waitcnt lgkmcnt(7)
	v_mfma_f32_16x16x32_bf16 v[62:65], v[66:69], v[142:145], v[62:65]
	s_waitcnt lgkmcnt(5)
	v_mfma_f32_16x16x32_bf16 v[54:57], v[78:81], v[142:145], v[54:57]
	v_mfma_f32_16x16x32_bf16 v[50:53], v[78:81], v[150:153], v[50:53]
	s_waitcnt lgkmcnt(1)
	v_mfma_f32_16x16x32_bf16 v[38:41], v[184:187], v[142:145], v[38:41]
	v_mfma_f32_16x16x32_bf16 v[34:37], v[184:187], v[150:153], v[34:37]
	v_mfma_f32_16x16x32_bf16 v[62:65], v[74:77], v[146:149], v[62:65]
	v_mfma_f32_16x16x32_bf16 v[58:61], v[66:69], v[150:153], v[58:61]
	v_mfma_f32_16x16x32_bf16 v[54:57], v[90:93], v[146:149], v[54:57]
	v_mfma_f32_16x16x32_bf16 v[50:53], v[90:93], v[154:157], v[50:53]
	v_mfma_f32_16x16x32_bf16 v[46:49], v[94:97], v[142:145], v[46:49]
	v_mfma_f32_16x16x32_bf16 v[42:45], v[94:97], v[150:153], v[42:45]
	s_waitcnt lgkmcnt(0)
	v_mfma_f32_16x16x32_bf16 v[38:41], v[188:191], v[146:149], v[38:41]
	v_mfma_f32_16x16x32_bf16 v[34:37], v[188:191], v[154:157], v[34:37]
	v_mfma_f32_16x16x32_bf16 v[192:195], v[74:77], v[154:157], v[58:61]
	v_mfma_f32_16x16x32_bf16 v[220:223], v[180:183], v[146:149], v[46:49]
	v_mfma_f32_16x16x32_bf16 v[224:227], v[180:183], v[154:157], v[42:45]
	s_setprio 0
	s_setprio 1
	v_mfma_f32_16x16x32_bf16 v[22:25], v[78:81], v[106:109], v[22:25]
	v_mfma_f32_16x16x32_bf16 v[18:21], v[78:81], v[122:125], v[18:21]
	v_mfma_f32_16x16x32_bf16 v[6:9], v[184:187], v[106:109], v[6:9]
	v_mfma_f32_16x16x32_bf16 v[30:33], v[66:69], v[106:109], v[30:33]
	v_mfma_f32_16x16x32_bf16 v[26:29], v[66:69], v[122:125], v[26:29]
	v_mfma_f32_16x16x32_bf16 v[22:25], v[90:93], v[110:113], v[22:25]
	v_mfma_f32_16x16x32_bf16 v[18:21], v[90:93], v[208:211], v[18:21]
	v_mfma_f32_16x16x32_bf16 v[14:17], v[94:97], v[106:109], v[14:17]
	v_mfma_f32_16x16x32_bf16 v[10:13], v[94:97], v[122:125], v[10:13]
	v_mfma_f32_16x16x32_bf16 v[6:9], v[188:191], v[110:113], v[6:9]
	v_mfma_f32_16x16x32_bf16 v[2:5], v[184:187], v[122:125], v[2:5]
	v_mfma_f32_16x16x32_bf16 v[142:145], v[74:77], v[110:113], v[30:33]
	v_mfma_f32_16x16x32_bf16 v[146:149], v[74:77], v[208:211], v[26:29]
	v_mfma_f32_16x16x32_bf16 v[150:153], v[180:183], v[110:113], v[14:17]
	v_mfma_f32_16x16x32_bf16 v[154:157], v[180:183], v[208:211], v[10:13]
	v_mfma_f32_16x16x32_bf16 v[180:183], v[188:191], v[208:211], v[2:5]
	s_setprio 0
	v_add_u32_e32 v26, 0x18000, v133
	s_barrier
	ds_read_b128 v[2:5], v26
	ds_read_b128 v[10:13], v26 offset:1024
	ds_read_b128 v[14:17], v26 offset:2048
	ds_read_b128 v[184:187], v26 offset:3072
	ds_read_b128 v[26:29], v130 offset:32768
	ds_read_b128 v[30:33], v130 offset:33792
	ds_read_b128 v[42:45], v130 offset:34816
	ds_read_b128 v[46:49], v130 offset:35840
	ds_read_b128 v[58:61], v130 offset:36864
	ds_read_b128 v[66:69], v130 offset:37888
	ds_read_b128 v[188:191], v130 offset:38912
	ds_read_b128 v[208:211], v130 offset:39936
	s_waitcnt vmcnt(2)
	s_barrier
	s_waitcnt lgkmcnt(0)
	s_setprio 1
	s_waitcnt lgkmcnt(7)
	v_mfma_f32_16x16x32_bf16 v[74:77], v[26:29], v[2:5], v[126:129]
	s_waitcnt lgkmcnt(6)
	v_mfma_f32_16x16x32_bf16 v[122:125], v[30:33], v[10:13], v[74:77]
	v_mfma_f32_16x16x32_bf16 v[74:77], v[26:29], v[14:17], v[196:199]
	v_mfma_f32_16x16x32_bf16 v[126:129], v[30:33], v[184:187], v[74:77]
	s_waitcnt lgkmcnt(5)
	v_mfma_f32_16x16x32_bf16 v[74:77], v[42:45], v[2:5], v[118:121]
	s_waitcnt lgkmcnt(4)
	v_mfma_f32_16x16x32_bf16 v[106:109], v[46:49], v[10:13], v[74:77]
	v_mfma_f32_16x16x32_bf16 v[74:77], v[42:45], v[14:17], v[114:117]
	v_mfma_f32_16x16x32_bf16 v[110:113], v[46:49], v[184:187], v[74:77]
	s_waitcnt lgkmcnt(3)
	v_mfma_f32_16x16x32_bf16 v[74:77], v[58:61], v[2:5], v[200:203]
	s_waitcnt lgkmcnt(2)
	v_mfma_f32_16x16x32_bf16 v[90:93], v[66:69], v[10:13], v[74:77]
	v_mfma_f32_16x16x32_bf16 v[74:77], v[58:61], v[14:17], v[204:207]
	v_mfma_f32_16x16x32_bf16 v[94:97], v[66:69], v[184:187], v[74:77]
	s_waitcnt lgkmcnt(1)
	v_mfma_f32_16x16x32_bf16 v[74:77], v[188:191], v[2:5], v[102:105]
	v_mfma_f32_16x16x32_bf16 v[78:81], v[188:191], v[14:17], v[98:101]
	s_waitcnt lgkmcnt(0)
	v_mfma_f32_16x16x32_bf16 v[74:77], v[208:211], v[10:13], v[74:77]
	v_mfma_f32_16x16x32_bf16 v[78:81], v[208:211], v[184:187], v[78:81]
	s_setprio 0
	v_add_u32_e32 v98, 0x1c000, v133
	s_barrier
; #define WAIT_V(n) asm volatile("s_waitcnt vmcnt(" #n ")" ::: "memory")
; #define WAIT_L(n) asm volatile("s_waitcnt lgkmcnt(" #n ")" ::: "memory")
; #define BAR __builtin_amdgcn_s_barrier()
; #define LDA8(b, h) _Pragma("unroll") for (int m = 0; m < 4; ++m) _Pragma("unroll") for (int k = 0; k < 2; ++k) \
;     At[m][k] = *(const bf16x8*)(SA_(shm, b, h) + abase + (m * 2 + k) * 1024)
; #define LDB8(dst, b, h) _Pragma("unroll") for (int n = 0; n < 2; ++n) _Pragma("unroll") for (int k = 0; k < 2; ++k) \
;     dst[n][k] = *(const bf16x8*)(SB_(shm, b, h) + bbase + (n * 2 + k) * 1024)
; #define MMA8(ai, bj, Bx) do { __builtin_amdgcn_s_setprio(1); \
;     _Pragma("unroll") for (int m = 0; m < 4; ++m) _Pragma("unroll") for (int n = 0; n < 2; ++n) _Pragma("unroll") for (int k = 0; k < 2; ++k) \
;       acc[ai][bj][m][n] = __builtin_amdgcn_mfma_f32_16x16x32_bf16(At[m][k], Bx[n][k], acc[ai][bj][m][n], 0, 0, 0); \
;     __builtin_amdgcn_s_setprio(0); } while (0)
; template <bool HS>
; __device__ __forceinline__ void gemm_tile8(const u16* __restrict__ Ap, const u16* __restrict__ Bp, int K,
;                                            f32x4 (&acc)[2][2][4][2], char* shm, const int tid, const float* hsr = nullptr) {
;     ...
;   { LDB8(B0, 1, 0); LDA8(1, 0); WAIT_V(2); BAR; WAIT_L(0); MMA8(0, 0, B0); BAR;
;     LDB8(B1, 1, 1); WAIT_V(0); BAR; WAIT_L(0); MMA8(0, 1, B1); BAR;
;     LDA8(1, 1); BAR; WAIT_L(0); MMA8(1, 0, B0); MMA8(1, 1, B1); BAR; }
;   if (wr == 0) BAR;
	ds_read_b128 v[196:199], v98
	ds_read_b128 v[200:203], v98 offset:1024
	ds_read_b128 v[204:207], v98 offset:2048
	ds_read_b128 v[228:231], v98 offset:3072
	s_waitcnt vmcnt(0)
	s_barrier
	s_waitcnt lgkmcnt(0)
	s_setprio 1
	s_waitcnt lgkmcnt(3)
	v_mfma_f32_16x16x32_bf16 v[98:101], v[26:29], v[196:199], v[212:215]
	s_waitcnt lgkmcnt(1)
	v_mfma_f32_16x16x32_bf16 v[26:29], v[26:29], v[204:207], v[158:161]
	s_waitcnt lgkmcnt(0)
	v_mfma_f32_16x16x32_bf16 v[118:121], v[30:33], v[228:231], v[26:29]
	v_mfma_f32_16x16x32_bf16 v[26:29], v[42:45], v[196:199], v[86:89]
	v_mfma_f32_16x16x32_bf16 v[114:117], v[30:33], v[200:203], v[98:101]
	v_mfma_f32_16x16x32_bf16 v[98:101], v[46:49], v[200:203], v[26:29]
	v_mfma_f32_16x16x32_bf16 v[26:29], v[42:45], v[204:207], v[82:85]
	v_mfma_f32_16x16x32_bf16 v[102:105], v[46:49], v[228:231], v[26:29]
	v_mfma_f32_16x16x32_bf16 v[26:29], v[58:61], v[196:199], v[164:167]
	v_mfma_f32_16x16x32_bf16 v[82:85], v[66:69], v[200:203], v[26:29]
	v_mfma_f32_16x16x32_bf16 v[26:29], v[58:61], v[204:207], v[168:171]
	v_mfma_f32_16x16x32_bf16 v[86:89], v[66:69], v[228:231], v[26:29]
	v_mfma_f32_16x16x32_bf16 v[26:29], v[188:191], v[196:199], v[70:73]
	v_mfma_f32_16x16x32_bf16 v[66:69], v[208:211], v[200:203], v[26:29]
	v_mfma_f32_16x16x32_bf16 v[26:29], v[188:191], v[204:207], v[172:175]
	v_mfma_f32_16x16x32_bf16 v[70:73], v[208:211], v[228:231], v[26:29]
	s_setprio 0
	s_barrier
	ds_read_b128 v[158:161], v130 offset:49152
	ds_read_b128 v[164:167], v130 offset:50176
	ds_read_b128 v[168:171], v130 offset:51200
	ds_read_b128 v[172:175], v130 offset:52224
	ds_read_b128 v[188:191], v130 offset:53248
	ds_read_b128 v[208:211], v130 offset:54272
	ds_read_b128 v[212:215], v130 offset:55296
	ds_read_b128 v[130:133], v130 offset:56320
	s_barrier
	s_waitcnt lgkmcnt(0)
	s_setprio 1
	s_waitcnt lgkmcnt(7)
	v_mfma_f32_16x16x32_bf16 v[26:29], v[158:161], v[2:5], v[62:65]
	s_waitcnt lgkmcnt(6)
	v_mfma_f32_16x16x32_bf16 v[58:61], v[164:167], v[10:13], v[26:29]
	v_mfma_f32_16x16x32_bf16 v[26:29], v[158:161], v[14:17], v[192:195]
	v_mfma_f32_16x16x32_bf16 v[62:65], v[164:167], v[184:187], v[26:29]
	s_waitcnt lgkmcnt(5)
	v_mfma_f32_16x16x32_bf16 v[26:29], v[168:171], v[2:5], v[54:57]
	s_waitcnt lgkmcnt(4)
	v_mfma_f32_16x16x32_bf16 v[42:45], v[172:175], v[10:13], v[26:29]
	v_mfma_f32_16x16x32_bf16 v[26:29], v[168:171], v[14:17], v[50:53]
	v_mfma_f32_16x16x32_bf16 v[46:49], v[172:175], v[184:187], v[26:29]
	s_waitcnt lgkmcnt(3)
	v_mfma_f32_16x16x32_bf16 v[26:29], v[188:191], v[2:5], v[220:223]
	s_waitcnt lgkmcnt(1)
	v_mfma_f32_16x16x32_bf16 v[2:5], v[212:215], v[2:5], v[38:41]
	v_mfma_f32_16x16x32_bf16 v[26:29], v[208:211], v[10:13], v[26:29]
	v_mfma_f32_16x16x32_bf16 v[30:33], v[188:191], v[14:17], v[224:227]
	s_waitcnt lgkmcnt(0)
	v_mfma_f32_16x16x32_bf16 v[10:13], v[130:133], v[10:13], v[2:5]
	v_mfma_f32_16x16x32_bf16 v[2:5], v[212:215], v[14:17], v[34:37]
	v_mfma_f32_16x16x32_bf16 v[30:33], v[208:211], v[184:187], v[30:33]
	v_mfma_f32_16x16x32_bf16 v[14:17], v[130:133], v[184:187], v[2:5]
	s_setprio 0
	s_setprio 1
	v_mfma_f32_16x16x32_bf16 v[2:5], v[158:161], v[196:199], v[142:145]
	v_mfma_f32_16x16x32_bf16 v[50:53], v[164:167], v[200:203], v[2:5]
	v_mfma_f32_16x16x32_bf16 v[2:5], v[158:161], v[204:207], v[146:149]
	v_mfma_f32_16x16x32_bf16 v[54:57], v[164:167], v[228:231], v[2:5]
	v_mfma_f32_16x16x32_bf16 v[2:5], v[168:171], v[196:199], v[22:25]
	v_mfma_f32_16x16x32_bf16 v[34:37], v[172:175], v[200:203], v[2:5]
	v_mfma_f32_16x16x32_bf16 v[2:5], v[168:171], v[204:207], v[18:21]
	v_mfma_f32_16x16x32_bf16 v[38:41], v[172:175], v[228:231], v[2:5]
	v_mfma_f32_16x16x32_bf16 v[2:5], v[188:191], v[196:199], v[150:153]
	v_mfma_f32_16x16x32_bf16 v[18:21], v[208:211], v[200:203], v[2:5]
	v_mfma_f32_16x16x32_bf16 v[2:5], v[188:191], v[204:207], v[154:157]
	v_mfma_f32_16x16x32_bf16 v[22:25], v[208:211], v[228:231], v[2:5]
	v_mfma_f32_16x16x32_bf16 v[2:5], v[212:215], v[196:199], v[6:9]
	v_mfma_f32_16x16x32_bf16 v[6:9], v[212:215], v[204:207], v[180:183]
	v_mfma_f32_16x16x32_bf16 v[2:5], v[130:133], v[200:203], v[2:5]
	v_mfma_f32_16x16x32_bf16 v[6:9], v[130:133], v[228:231], v[6:9]
	s_setprio 0
	s_movk_i32 s3, 0x100
	v_cmp_gt_u32_e32 vcc, s3, v0
	s_barrier
	s_and_saveexec_b64 s[6:7], vcc
	s_cbranch_execz .LBB0_586
	s_barrier
; template <int EPI, bool HS = false>
; __device__ __forceinline__ void gemm_phase(const Params& p, const GemmCfg& g, char* shm, const int wave_s) {
;     ...
;   auto tile_coords = [&](int tile, int& mt, int& pn, int& arow0, int& orow0) {
;     int wgid = tile;
;     { int q = nwg / 8, r = nwg % 8, xcd = wgid % 8, off = wgid / 8;
;       wgid = (xcd < r ? xcd * (q + 1) : r * (q + 1) + (xcd - r) * q) + off; }
;     int nig = 8 * g.nN, gid = wgid / nig, fm = gid * 8, gsz = (g.nM - fm < 8) ? (g.nM - fm) : 8;
;     mt = fm + ((wgid % nig) % gsz); pn = (wgid % nig) / gsz;
;     if (g.rev) mt = g.nM - 1 - mt;
;     int hrow0 = (mt >> 3) * 4096 + g.hf * 2048 + (mt & 7) * 256;
;     arow0 = g.a_half ? hrow0 : mt * 256;
;     orow0 = g.o_half ? hrow0 : mt * 256;
;   };
;     ...
;     const bool defer_pf = (EPI == EPI_RESID) || (EPI == EPI_RETIN && pn < 8);
;     if (!defer_pf && tile + (int)gridDim.x < nwg) {
;       int mt2, pn2, arow2, orow2;
;       tile_coords(tile + gridDim.x, mt2, pn2, arow2, orow2);
;       gemm8_prefetch(g.A + (size_t)arow2 * g.K, g.Bt + (size_t)pn2 * 256 * g.K, g.K, shm, fresh_tid(wave_s));
;     }
.LBB0_586:
	s_or_b64 exec, exec, s[6:7]
	s_cmp_gt_i32 s88, 63
	s_cselect_b64 s[6:7], -1, 0
	s_cmp_lt_i32 s88, 64
	s_cbranch_scc1 .LBB0_589
	s_add_i32 s3, s93, s44
	s_cmpk_gt_i32 s3, 0xbff
	s_cbranch_scc1 .LBB0_589
	s_ashr_i32 s8, s3, 31
	s_lshr_b32 s8, s8, 29
	s_add_i32 s8, s3, s8
	s_ashr_i32 s9, s8, 3
	s_and_b32 s8, s8, -8
	s_sub_i32 s3, s3, s8
	s_cmp_lt_i32 s3, 0
	s_movk_i32 s8, 0x181
	s_cselect_b32 s8, s8, 0x180
	s_mul_i32 s3, s8, s3
	s_add_i32 s3, s3, s9
	s_mul_hi_i32 s8, s3, 0x2aaaaaab
	s_lshr_b32 s9, s8, 31
	s_ashr_i32 s8, s8, 5
	s_add_i32 s9, s8, s9
	s_mul_i32 s8, s9, 0xc0
	s_sub_i32 s3, s3, s8
	s_bfe_u32 s8, s3, 0x3001c
	s_add_i32 s10, s3, s8
	s_sext_i32_i16 s8, s10
	s_and_b32 s10, s10, 0xfff8
	s_sub_i32 s3, s3, s10
	s_sext_i32_i16 s3, s3
	s_lshl_b32 s9, s9, 12
	s_add_i32 s9, s9, s3
	s_and_b32 s9, s9, 0xfffff000
	s_lshl_b32 s3, s3, 8
	s_add_i32 s9, s9, s43
	s_and_b32 s3, s3, 0x700
	s_or_b32 s10, s9, s3
	s_ashr_i32 s11, s10, 31
	s_lshr_b32 s8, s8, 3
	s_lshl_b64 s[10:11], s[10:11], 11
	v_readlane_b32 s16, v254, 47
	v_readlane_b32 s17, v254, 48
	s_add_u32 s10, s16, s10
	s_addc_u32 s11, s17, s11
	s_bfe_i64 s[8:9], s[8:9], 0x100000
	s_lshl_b64 s[8:9], s[8:9], 19
	v_readlane_b32 s3, v255, 7
	s_add_u32 s8, s3, s8
	v_readlane_b32 s3, v255, 8
	s_addc_u32 s9, s3, s9
	s_mov_b32 s3, s82
	s_mov_b32 s13, -1
	s_add_u32 s14, s10, 0x40000
	v_mbcnt_lo_u32_b32 v0, s13, 0
	v_mbcnt_hi_u32_b32 v0, s13, v0
	v_lshl_add_u32 v0, s3, 6, v0
	s_addc_u32 s15, s11, 0
	v_bfe_i32 v132, v0, 27, 1
	v_lshlrev_b32_e32 v130, 4, v0
	v_lshrrev_b32_e32 v132, 22, v132
	v_add_u32_e32 v132, v130, v132
	v_and_b32_e32 v132, 0xfffffc00, v132
	v_ashrrev_i32_e32 v131, 31, v0
	v_sub_u32_e32 v132, v130, v132
	v_lshrrev_b32_e32 v131, 26, v131
	v_lshrrev_b32_e32 v133, 4, v132
	v_add_u32_e32 v131, v0, v131
	v_bitop3_b32 v133, v133, v132, 32 bitop3:0x6c
	v_ashrrev_i32_e32 v132, 31, v132
	v_ashrrev_i32_e32 v131, 6, v131
	v_lshrrev_b32_e32 v132, 26, v132
	v_lshlrev_b32_e32 v135, 3, v131
	v_add_u32_e32 v132, v133, v132
	v_and_b32_e32 v135, 0x1ffff0, v135
	v_ashrrev_i32_e32 v132, 6, v132
	v_add_u32_e32 v135, v132, v135
	v_mul_i32_i24_e32 v132, 64, v132
	v_add_u32_e32 v130, 0x2000, v130
	v_sub_u32_e32 v132, v133, v132
	v_ashrrev_i32_e32 v133, 31, v130
	v_lshrrev_b32_e32 v133, 22, v133
	v_add_u32_e32 v133, v130, v133
	v_ashrrev_i32_e32 v133, 10, v133
	v_mul_i32_i24_e32 v137, 0x400, v133
	v_sub_u32_e32 v130, v130, v137
	v_lshrrev_b32_e32 v137, 4, v130
	v_bitop3_b32 v130, v137, v130, 32 bitop3:0x6c
	v_ashrrev_i32_e32 v139, 31, v130
	v_lshrrev_b32_e32 v139, 26, v139
	v_add_u32_e32 v139, v130, v139
	v_readfirstlane_b32 s3, v0
	s_add_u32 s16, s8, 0x40000
	v_lshlrev_b32_e32 v131, 5, v131
	v_lshlrev_b32_e32 v137, 3, v133
	v_lshrrev_b32_e32 v141, 6, v139
	v_and_b32_e32 v139, 0xc0, v139
	s_addc_u32 s17, s9, 0
	s_lshl_b32 s3, s3, 4
	v_and_b32_e32 v131, 32, v131
	v_ashrrev_i16_sdwa v132, v178, sext(v132) dst_sel:DWORD dst_unused:UNUSED_PAD src0_sel:DWORD src1_sel:BYTE_0
	v_and_b32_e32 v137, 0x1ffff0, v137
	v_lshlrev_b32_e32 v133, 5, v133
	v_sub_u32_e32 v130, v130, v139
	s_and_b32 s3, s3, 0xfffffc00
	v_readlane_b32 s18, v254, 49
	v_bfe_i32 v132, v132, 0, 16
	v_add_u32_e32 v137, v141, v137
	v_and_b32_e32 v133, 32, v133
	v_ashrrev_i16_sdwa v130, v178, sext(v130) dst_sel:DWORD dst_unused:UNUSED_PAD src0_sel:DWORD src1_sel:BYTE_0
	v_lshl_or_b32 v131, v135, 10, v131
	s_add_i32 s3, s3, 0
	v_bfe_i32 v130, v130, 0, 16
	v_add_lshl_u32 v131, v131, v132, 1
	v_lshl_or_b32 v132, v137, 10, v133
	s_add_i32 s13, s3, 0x10000
	s_mov_b32 m0, s13
	s_nop 0
	global_load_lds_dwordx4 v131, s[8:9]
	v_add_lshl_u32 v130, v132, v130, 1
	s_add_i32 s13, s3, 0x12000
	s_mov_b32 m0, s13
	s_nop 0
	global_load_lds_dwordx4 v130, s[8:9]
	s_mov_b32 m0, s3
	s_nop 0
	global_load_lds_dwordx4 v131, s[10:11]
	s_add_i32 s13, s3, 0x2000
	s_mov_b32 m0, s13
	s_nop 0
	global_load_lds_dwordx4 v130, s[10:11]
	s_add_i32 s13, s3, 0x14000
	s_mov_b32 m0, s13
	s_nop 0
	global_load_lds_dwordx4 v131, s[16:17]
	s_add_i32 s13, s3, 0x16000
	s_mov_b32 m0, s13
	s_nop 0
	global_load_lds_dwordx4 v130, s[16:17]
	s_add_i32 s13, s3, 0x4000
	s_mov_b32 m0, s13
	s_nop 0
	global_load_lds_dwordx4 v131, s[14:15]
	s_add_i32 s13, s3, 0x6000
	s_mov_b32 m0, s13
	s_nop 0
	global_load_lds_dwordx4 v130, s[14:15]
	s_add_u32 s14, s8, 0x80
	s_addc_u32 s15, s9, 0
	s_add_i32 s13, s3, 0x18000
	s_mov_b32 m0, s13
	s_nop 0
	global_load_lds_dwordx4 v131, s[14:15]
	s_add_i32 s13, s3, 0x1a000
	s_add_u32 s10, s10, 0x80
	s_mov_b32 m0, s13
	s_nop 0
	global_load_lds_dwordx4 v130, s[14:15]
	s_addc_u32 s11, s11, 0
	s_add_i32 s13, s3, 0x8000
	s_mov_b32 m0, s13
	s_nop 0
	global_load_lds_dwordx4 v131, s[10:11]
	s_add_i32 s13, s3, 0xa000
	s_mov_b32 m0, s13
	s_nop 0
	global_load_lds_dwordx4 v130, s[10:11]
	s_add_u32 s8, s8, 0x40080
	s_addc_u32 s9, s9, 0
	s_add_i32 s10, s3, 0x1c000
	s_mov_b32 m0, s10
	s_nop 0
	global_load_lds_dwordx4 v131, s[8:9]
	s_add_i32 s3, s3, 0x1e000
	s_mov_b32 m0, s3
	s_nop 0
	global_load_lds_dwordx4 v130, s[8:9]
	v_readlane_b32 s19, v254, 50

; #define WAIT_V(n) asm volatile("s_waitcnt vmcnt(" #n ")" ::: "memory")
; template <int EPI, bool HS = false>
; __device__ __forceinline__ void gemm_phase(const Params& p, const GemmCfg& g, char* shm, const int wave_s) {
;     ...
;       if (pn < 8) {
;         const int hh = pn & 3;
;         const bool isk = pn >= 4;
;         u16* dst = (isk ? Kb : Qb) + (size_t)orow0 * 1024 + hh * 256;
;         u16* kt_t = KTb + ((size_t)((b * 4 + hh) * 16 + (mt & 7) * 2) * 256) * 128;
;         const float lg2 = log2f(1.0f - exp2f(-5.0f - (float)hh));
;         const float scl = isk ? 0.0625f : 1.0f;
;         const float* rc_t = p.ropec + (size_t)s0 * 128;
;         const float* rs_t = p.ropes + (size_t)s0 * 128;
;         const unsigned tb = (unsigned)((wr * 64 + fq * 4) * 1024 + wc * 32 + fr);
;         const unsigned kb = (unsigned)((wc * 32 + fr) * 128 + wr * 64 + fq * 4);
;         const unsigned ldsb = (unsigned)(size_t)(__attribute__((address_space(3))) char*)shm;
;         const int wv_s = __builtin_amdgcn_readfirstlane(wid);
;         const char* rl = shm + ((wr * 64 + fq * 4) * 128 + wc * 16 + fr) * 4;
; #pragma unroll
;         for (int ai = 0; ai < 2; ++ai) {
; #pragma unroll
;           for (int i = 0; i < 8; ++i) {
;             const int ch = wv_s * 8 + i;
;             glds_row(rc_t + (size_t)(ai * 128) * 128 + ch * 256, (unsigned)lane * 16u, ldsb + (unsigned)(ch * 1024));
;             glds_row(rs_t + (size_t)(ai * 128) * 128 + ch * 256, (unsigned)lane * 16u, ldsb + 65536u + (unsigned)(ch * 1024));
;           }
;           WAIT_V(0);
;           __syncthreads();
.LBB0_595:
	s_andn2_b64 vcc, exec, s[8:9]
	s_cbranch_vccnz .LBB0_577
	s_lshl_b32 s1, s3, 8
	s_or_b32 s6, s1, s43
	s_and_b32 s2, s2, 3
	s_cmp_gt_i32 s88, 31
	s_cselect_b64 s[4:5], -1, 0
	v_readlane_b32 s12, v254, 47
	s_and_b64 s[8:9], s[4:5], exec
	v_readlane_b32 s14, v254, 49
	s_cselect_b32 s1, 0x4000000, 0
	v_readlane_b32 s15, v254, 50
	s_add_u32 s7, s14, s1
	s_addc_u32 s8, s15, 0
	s_ashr_i32 s1, s0, 31
	s_lshl_b64 s[0:1], s[0:1], 11
	s_add_u32 s0, s7, s0
	s_addc_u32 s1, s8, s1
	s_lshl_b32 s7, s2, 9
	v_mov_b32_e32 v0, 0x3d800000
	s_add_u32 s0, s0, s7
	v_cndmask_b32_e64 v142, 1.0, v0, s[4:5]
	s_addc_u32 s1, s1, 0
	s_lshl_b32 s7, s10, 6
	s_lshl_b32 s8, s2, 4
	v_cvt_f32_ubyte0_e32 v0, s2
	s_or_b32 s7, s7, s8
	s_lshl_b32 s3, s3, 1
	v_sub_f32_e32 v0, 0xc0a00000, v0
	s_mov_b32 s2, 0xc2fc0000
	s_or_b32 s8, s7, s3
	v_cmp_gt_f32_e32 vcc, s2, v0
	v_mov_b32_e32 v130, 0x42800000
	s_ashr_i32 s9, s8, 31
	v_cndmask_b32_e32 v130, 0, v130, vcc
	s_mov_b64 s[16:17], s[46:47]
	s_lshl_b64 s[8:9], s[8:9], 16
	v_add_f32_e32 v0, v0, v130
	s_add_u32 s10, s16, s8
	v_exp_f32_e32 v0, v0
	s_addc_u32 s11, s17, s9
	s_and_b64 s[2:3], vcc, exec
	s_cselect_b32 s2, 0xffffffc0, 0
	v_ldexp_f32 v0, v0, s2
	v_sub_f32_e32 v130, 1.0, v0
	v_cmp_gt_f32_e32 vcc, s42, v130
	s_and_b64 s[2:3], vcc, exec
	s_mov_b32 s92, s45
	s_cselect_b32 s45, 32, 0
	s_ashr_i32 s7, s6, 31
	v_readlane_b32 s52, v252, 26
	s_lshl_b64 s[2:3], s[6:7], 9
	v_readlane_b32 s64, v252, 38
	v_readlane_b32 s65, v252, 39
	s_add_u32 s27, s64, s2
	v_readlane_b32 s66, v252, 40
	s_addc_u32 s90, s65, s3
	v_readlane_b32 s67, v252, 41
	s_add_u32 s91, s66, s2
	v_readfirstlane_b32 s8, v147
	s_addc_u32 s84, s67, s3
	s_lshl_b32 s2, s8, 11
	s_ashr_i32 s3, s2, 31
	s_mov_b32 s47, s44
	s_lshl_b32 s44, s8, 3
	s_lshl_b64 s[76:77], s[2:3], 2
	s_add_u32 s6, s27, s76
	s_addc_u32 s7, s90, s77
	s_lshl_b32 s2, s8, 13
	s_add_i32 s85, s2, 0
	s_add_u32 s68, s91, s76
	v_readlane_b32 s62, v252, 36
	s_addc_u32 s69, s84, s77
	s_or_b32 s8, s44, 1
	s_add_i32 s62, s2, s89
	s_lshl_b32 s2, s8, 8
	s_ashr_i32 s3, s2, 31
	s_lshl_b64 s[74:75], s[2:3], 2
	v_readlane_b32 s13, v254, 48
	s_add_u32 s12, s27, s74
	s_addc_u32 s13, s90, s75
	s_lshl_b32 s2, s8, 10
	s_add_i32 s26, s2, 0
	s_add_u32 s14, s91, s74
	v_readlane_b32 s60, v252, 34
	s_addc_u32 s15, s84, s75
	s_or_b32 s8, s44, 2
	s_add_i32 s60, s2, s89
	s_lshl_b32 s2, s8, 8
	s_ashr_i32 s3, s2, 31
	s_lshl_b64 s[72:73], s[2:3], 2
	s_mov_b64 s[48:49], s[16:17]
	s_add_u32 s16, s27, s72
	v_readlane_b32 s61, v252, 35
	s_addc_u32 s17, s90, s73
	s_lshl_b32 s2, s8, 10
	s_add_i32 s61, s2, 0
	s_add_u32 s18, s91, s72
	v_readlane_b32 s57, v252, 31
	s_addc_u32 s19, s84, s73
	s_or_b32 s8, s44, 3
	s_add_i32 s57, s2, s89
	s_lshl_b32 s2, s8, 8
	s_ashr_i32 s3, s2, 31
	s_lshl_b64 s[70:71], s[2:3], 2
	s_add_u32 s20, s27, s70
	v_readlane_b32 s58, v252, 32
	s_addc_u32 s21, s90, s71
	s_lshl_b32 s2, s8, 10
	s_add_i32 s58, s2, 0
	s_add_u32 s22, s91, s70
	v_readlane_b32 s55, v252, 29
	s_addc_u32 s23, s84, s71
	s_or_b32 s36, s44, 4
	s_add_i32 s55, s2, s89
	s_lshl_b32 s2, s36, 8
	s_ashr_i32 s3, s2, 31
	s_lshl_b64 s[8:9], s[2:3], 2
	s_add_u32 s24, s27, s8
	v_readlane_b32 s56, v252, 30
	s_addc_u32 s25, s90, s9
	s_lshl_b32 s2, s36, 10
	s_add_i32 s56, s2, 0
	s_add_u32 s36, s91, s8
	v_readlane_b32 s53, v252, 27
	s_addc_u32 s37, s84, s9
	s_or_b32 s40, s44, 5
	s_add_i32 s53, s2, s89
	s_lshl_b32 s2, s40, 8
	s_ashr_i32 s3, s2, 31
	s_lshl_b64 s[2:3], s[2:3], 2
	v_mov_b32_e32 v0, 0x42000000
	s_add_u32 s38, s27, s2
	v_lshlrev_b32_e32 v132, 5, v137
	v_cndmask_b32_e32 v131, 0, v0, vcc
	v_readlane_b32 s54, v252, 28
	s_addc_u32 s39, s90, s3
	s_lshl_b32 s42, s40, 10
	v_or_b32_e32 v0, v132, v135
	s_add_i32 s54, s42, 0
	v_lshl_add_u32 v0, v0, 7, v139
	s_add_u32 s40, s91, s2
	v_or_b32_e32 v0, v0, v141
	s_addc_u32 s41, s84, s3
	s_add_i32 s52, s42, s89
	v_lshl_add_u64 v[144:145], v[0:1], 1, s[10:11]
	s_or_b32 s42, s44, 6
	v_lshlrev_b32_e32 v0, 4, v146
	v_and_b32_e32 v156, 0x3f0, v0
	s_mov_b32 m0, s85
	s_nop 0
	global_load_lds_dwordx4 v156, s[6:7]
	s_lshl_b32 s6, s42, 8
	s_ashr_i32 s7, s6, 31
	s_lshl_b64 s[10:11], s[6:7], 2
	s_mov_b32 m0, s62
	s_nop 0
	global_load_lds_dwordx4 v156, s[68:69]
	s_add_u32 s6, s27, s10
	v_readlane_b32 s59, v252, 33
	s_addc_u32 s7, s90, s11
	s_lshl_b32 s46, s42, 10
	v_ldexp_f32 v0, v130, s45
	s_add_i32 s59, s46, 0
	s_mov_b32 m0, s26
	s_nop 0
	global_load_lds_dwordx4 v156, s[12:13]
	v_log_f32_e32 v0, v0
	s_add_u32 s42, s91, s10
	s_mov_b32 s50, s43
	s_addc_u32 s43, s84, s11
	s_or_b32 s13, s44, 7
	s_mov_b32 m0, s60
	s_nop 0
	global_load_lds_dwordx4 v156, s[14:15]
	s_lshl_b32 s14, s13, 8
	v_or_b32_e32 v161, v139, v141
	s_ashr_i32 s15, s14, 31
	v_sub_f32_e32 v160, v0, v131
	v_lshlrev_b32_e32 v0, 10, v161
	v_lshlrev_b32_e32 v130, 7, v161
	v_lshlrev_b32_e32 v131, 4, v137
	s_lshl_b64 s[68:69], s[14:15], 2
	s_mov_b32 m0, s61
	s_nop 0
	global_load_lds_dwordx4 v156, s[16:17]
	v_or3_b32 v130, v130, v131, v135
	v_or3_b32 v146, v0, v135, v132
	v_sub_u32_e32 v0, 0x7f, v161
	v_lshl_add_u32 v155, v130, 2, 0
	s_mov_b32 m0, s57
	s_nop 0
	global_load_lds_dwordx4 v156, s[18:19]
	v_cvt_f32_i32_e32 v0, v0
	v_sub_u32_e32 v130, 0x7e, v161
	s_mov_b32 m0, s58
	s_nop 0
	global_load_lds_dwordx4 v156, s[20:21]
	v_cvt_f32_i32_e32 v130, v130
	s_mov_b32 m0, s55
	s_nop 0
	global_load_lds_dwordx4 v156, s[22:23]
	v_mul_f32_e32 v0, v160, v0
	s_mov_b32 m0, s56
	s_nop 0
	global_load_lds_dwordx4 v156, s[24:25]
	s_add_i32 s12, s46, s89
	s_mov_b32 m0, s53
	s_nop 0
	global_load_lds_dwordx4 v156, s[36:37]
	v_exp_f32_e32 v148, v0
	s_mov_b32 m0, s54
	s_nop 0
	global_load_lds_dwordx4 v156, s[38:39]
	v_mul_f32_e32 v0, v160, v130
	v_sub_u32_e32 v130, 0x7d, v161
	s_add_u32 s16, s27, s68
	s_mov_b32 m0, s52
	s_nop 0
	global_load_lds_dwordx4 v156, s[40:41]
	v_cvt_f32_i32_e32 v130, v130
	v_sub_u32_e32 v131, 0x7c, v161
	s_addc_u32 s17, s90, s69
	s_lshl_b32 s13, s13, 10
	s_mov_b32 m0, s59
	s_nop 0
	global_load_lds_dwordx4 v156, s[6:7]
	v_cvt_f32_i32_e32 v131, v131
	s_add_i32 s14, s13, 0
	s_mov_b32 m0, s12
	s_nop 0
	global_load_lds_dwordx4 v156, s[42:43]
	s_add_u32 s44, s91, s68
	s_mov_b32 m0, s14
	s_nop 0
	global_load_lds_dwordx4 v156, s[16:17]
	s_addc_u32 s45, s84, s69
	s_add_i32 s13, s13, s89
	s_mov_b32 m0, s13
	s_nop 0
	global_load_lds_dwordx4 v156, s[44:45]
	v_exp_f32_e32 v150, v0
	v_mul_f32_e32 v0, v160, v130
	v_mov_b32_e32 v147, v1
	v_add_u32_e32 v157, 0x10000, v155
	s_waitcnt vmcnt(0)
	s_waitcnt vmcnt(63) expcnt(7) lgkmcnt(15)
	s_barrier
; __device__ __forceinline__ unsigned pack2(float a, float b) { return (unsigned)f2bf(a) | ((unsigned)f2bf(b) << 16); }
; __device__ __forceinline__ float fexp2(float x) { return __builtin_amdgcn_exp2f(x); }
; template <int EPI, bool HS = false>
; __device__ __forceinline__ void gemm_phase(const Params& p, const GemmCfg& g, char* shm, const int wave_s) {
;     ...
;           for (int m = 0; m < 4; ++m) {
;             const int jj0 = wr * 64 + m * 16 + fq * 4;
;             const float k0 = fexp2(lg2 * (float)(127 - jj0));
;             const f32x4 r4 = *(const f32x4*)(rsw + ai * 128 + m * 16);
; #pragma unroll
;             for (int bj = 0; bj < 2; ++bj) {
;               float y1[4], y2[4];
; #pragma unroll
;               for (int j = 0; j < 4; ++j) {
;                 const int lr = ai * 128 + m * 16 + j;
;                 float cs = *(const float*)(rl + ((m * 16 + j) * 128 + bj * 64) * 4), sn = *(const float*)(rl + 65536 + ((m * 16 + j) * 128 + bj * 64) * 4);
;                 float x1 = r4[j] * acc[ai][bj][m][0][j] + swv[bj][0], x2 = r4[j] * acc[ai][bj][m][1][j] + swv[bj][1];
;                 y1[j] = (x1 * cs - x2 * sn) * scl;
;                 y2[j] = (x2 * cs + x1 * sn) * scl;
;                 dst[tb + lr * 1024 + bj * 128] = f2bf(y1[j]);
;                 dst[tb + lr * 1024 + bj * 128 + 16] = f2bf(y2[j]);
;               }
;               if (isk) {
;                 float d0 = k0, d1 = fexp2(lg2 * (float)(126 - jj0)), d2 = fexp2(lg2 * (float)(125 - jj0)),
;                       d3 = fexp2(lg2 * (float)(124 - jj0));
;                 uint2 v1, v2;
;                 v1.x = pack2(y1[0] * d0, y1[1] * d1); v1.y = pack2(y1[2] * d2, y1[3] * d3);
;                 v2.x = pack2(y2[0] * d0, y2[1] * d1); v2.y = pack2(y2[2] * d2, y2[3] * d3);
;                 *(uint2*)(kt_t + kb + ai * 256 * 128 + (bj * 128) * 128 + m * 16) = v1;
;                 *(uint2*)(kt_t + kb + ai * 256 * 128 + (bj * 128 + 16) * 128 + m * 16) = v2;
;               }
	v_exp_f32_e32 v149, v0
	v_mul_f32_e32 v0, v160, v131
	ds_read2st64_b32 v[164:165], v155 offset1:2
	v_lshl_add_u64 v[152:153], v[146:147], 1, s[0:1]
	v_add_u32_e32 v147, 0x10200, v155
	ds_read2st64_b32 v[166:167], v155 offset0:4 offset1:6
	v_add_u32_e32 v158, 0x10400, v155
	ds_read_b128 v[130:133], v154
	ds_read_b32 v168, v157
	ds_read_b32 v170, v147
	ds_read_b32 v169, v158
	v_add_u32_e32 v159, 0x10600, v155
	ds_read_b32 v171, v159
	s_waitcnt lgkmcnt(4)
	v_pk_mul_f32 v[128:129], v[128:129], v[132:133]
	v_pk_mul_f32 v[126:127], v[126:127], v[130:131]
	v_mov_b32_e32 v177, v128
	v_mov_b32_e32 v176, v126
	v_pk_mul_f32 v[124:125], v[124:125], v[132:133]
	v_pk_mul_f32 v[180:181], v[122:123], v[130:131]
	v_pk_add_f32 v[176:177], v[140:141], v[176:177] op_sel_hi:[0,1]
	v_mov_b32_e32 v122, v180
	v_mov_b32_e32 v123, v124
	v_pk_add_f32 v[182:183], v[138:139], v[122:123] op_sel_hi:[0,1]
	v_mov_b32_e32 v184, v164
	v_mov_b32_e32 v185, v166
	s_waitcnt lgkmcnt(1)
	v_pk_mul_f32 v[122:123], v[168:169], v[176:177]
	v_mov_b32_e32 v128, v127
	v_exp_f32_e32 v151, v0
	v_or_b32_e32 v0, 0x800, v146
	v_pk_fma_f32 v[122:123], v[184:185], v[182:183], v[122:123] neg_lo:[0,0,1] neg_hi:[0,0,1]
	v_pk_add_f32 v[128:129], v[140:141], v[128:129] op_sel_hi:[0,1]
	v_mov_b32_e32 v124, v181
	v_lshl_add_u64 v[172:173], v[0:1], 1, s[0:1]
	v_or_b32_e32 v0, 0x810, v146
	v_pk_mul_f32 v[122:123], v[142:143], v[122:123] op_sel_hi:[0,1]
	v_pk_add_f32 v[180:181], v[138:139], v[124:125] op_sel_hi:[0,1]
	v_mov_b32_e32 v166, v165
	s_waitcnt lgkmcnt(0)
	v_pk_mul_f32 v[124:125], v[128:129], v[170:171]
	v_lshl_add_u64 v[174:175], v[0:1], 1, s[0:1]
	v_bfe_u32 v0, v122, 16, 1
	v_pk_fma_f32 v[124:125], v[180:181], v[166:167], v[124:125] neg_lo:[0,0,1] neg_hi:[0,0,1]
	v_add3_u32 v0, v122, v0, s81
	v_pk_mul_f32 v[124:125], v[142:143], v[124:125] op_sel_hi:[0,1]
	global_store_short_d16_hi v[152:153], v0, off
	v_bfe_u32 v0, v124, 16, 1
	v_add3_u32 v0, v124, v0, s81
	v_pk_mul_f32 v[126:127], v[168:169], v[182:183]
	global_store_short_d16_hi v[152:153], v0, off offset:2048
	v_bfe_u32 v0, v123, 16, 1
	v_pk_fma_f32 v[126:127], v[184:185], v[176:177], v[126:127]
	v_add3_u32 v0, v123, v0, s81
	v_pk_mul_f32 v[126:127], v[142:143], v[126:127] op_sel_hi:[0,1]
	v_pk_mul_f32 v[164:165], v[180:181], v[170:171]
	global_store_short_d16_hi v[172:173], v0, off
	v_bfe_u32 v0, v126, 16, 1
	v_pk_fma_f32 v[128:129], v[128:129], v[166:167], v[164:165]
	v_add3_u32 v0, v126, v0, s81
	v_pk_mul_f32 v[128:129], v[142:143], v[128:129] op_sel_hi:[0,1]
	global_store_short_d16_hi v[152:153], v0, off offset:32
	v_bfe_u32 v0, v128, 16, 1
	v_add3_u32 v0, v128, v0, s81
	global_store_short_d16_hi v[152:153], v0, off offset:2080
	v_bfe_u32 v0, v127, 16, 1
	v_add3_u32 v0, v127, v0, s81
	global_store_short_d16_hi v[174:175], v0, off
	v_bfe_u32 v0, v125, 16, 1
	v_add3_u32 v135, v125, v0, s81
	v_or_b32_e32 v0, 0xc00, v146
	v_lshl_add_u64 v[164:165], v[0:1], 1, s[0:1]
	v_bfe_u32 v0, v129, 16, 1
	global_store_short_d16_hi v[164:165], v135, off
	v_add3_u32 v135, v129, v0, s81
	v_or_b32_e32 v0, 0xc10, v146
	s_cmp_lt_i32 s88, 32
	v_lshl_add_u64 v[164:165], v[0:1], 1, s[0:1]
	v_readlane_b32 s63, v252, 37
	global_store_short_d16_hi v[164:165], v135, off
	s_cbranch_scc1 .LBB0_598
	v_pk_mul_f32 v[122:123], v[148:149], v[122:123]
	v_pk_mul_f32 v[124:125], v[150:151], v[124:125]
	v_and_b32_sdwa v0, v123, v178 dst_sel:DWORD dst_unused:UNUSED_PAD src0_sel:WORD_1 src1_sel:DWORD
	v_and_b32_sdwa v135, v122, v178 dst_sel:DWORD dst_unused:UNUSED_PAD src0_sel:WORD_1 src1_sel:DWORD
	v_add3_u32 v122, v122, v135, s81
	v_add3_u32 v0, v123, v0, s81
	v_and_b32_sdwa v123, v125, v178 dst_sel:DWORD dst_unused:UNUSED_PAD src0_sel:WORD_1 src1_sel:DWORD
	v_and_b32_sdwa v135, v124, v178 dst_sel:DWORD dst_unused:UNUSED_PAD src0_sel:WORD_1 src1_sel:DWORD
	v_add3_u32 v123, v125, v123, s81
	v_add3_u32 v124, v124, v135, s81
	v_pk_mul_f32 v[128:129], v[150:151], v[128:129]
	v_and_b32_e32 v123, 0xffff0000, v123
	v_and_b32_e32 v124, 0xffff0000, v124
	v_pk_mul_f32 v[126:127], v[148:149], v[126:127]
	v_or_b32_sdwa v123, v123, v0 dst_sel:DWORD dst_unused:UNUSED_PAD src0_sel:DWORD src1_sel:WORD_1
	v_or_b32_sdwa v122, v124, v122 dst_sel:DWORD dst_unused:UNUSED_PAD src0_sel:DWORD src1_sel:WORD_1
	v_and_b32_sdwa v124, v128, v178 dst_sel:DWORD dst_unused:UNUSED_PAD src0_sel:WORD_1 src1_sel:DWORD
	global_store_dwordx2 v[144:145], v[122:123], off
	v_and_b32_sdwa v122, v126, v178 dst_sel:DWORD dst_unused:UNUSED_PAD src0_sel:WORD_1 src1_sel:DWORD
	v_and_b32_sdwa v123, v129, v178 dst_sel:DWORD dst_unused:UNUSED_PAD src0_sel:WORD_1 src1_sel:DWORD
	v_add3_u32 v124, v128, v124, s81
	v_and_b32_sdwa v0, v127, v178 dst_sel:DWORD dst_unused:UNUSED_PAD src0_sel:WORD_1 src1_sel:DWORD
	v_add3_u32 v122, v126, v122, s81
	v_add3_u32 v123, v129, v123, s81
	v_and_b32_e32 v124, 0xffff0000, v124
	v_add3_u32 v0, v127, v0, s81
	v_and_b32_e32 v123, 0xffff0000, v123
	v_or_b32_sdwa v122, v124, v122 dst_sel:DWORD dst_unused:UNUSED_PAD src0_sel:DWORD src1_sel:WORD_1
	v_add_co_u32_e32 v124, vcc, 0x1000, v144
	v_or_b32_sdwa v123, v123, v0 dst_sel:DWORD dst_unused:UNUSED_PAD src0_sel:DWORD src1_sel:WORD_1
	s_nop 0
	v_addc_co_u32_e32 v125, vcc, 0, v145, vcc
	global_store_dwordx2 v[124:125], v[122:123], off

; __device__ __forceinline__ unsigned pack2(float a, float b) { return (unsigned)f2bf(a) | ((unsigned)f2bf(b) << 16); }
; template <int EPI, bool HS = false>
; __device__ __forceinline__ void gemm_phase(const Params& p, const GemmCfg& g, char* shm, const int wave_s) {
;     ...
;         for (int ai = 0; ai < 2; ++ai) {
; #pragma unroll
;           for (int i = 0; i < 8; ++i) {
;             const int ch = wv_s * 8 + i;
;             glds_row(rc_t + (size_t)(ai * 128) * 128 + ch * 256, (unsigned)lane * 16u, ldsb + (unsigned)(ch * 1024));
;             glds_row(rs_t + (size_t)(ai * 128) * 128 + ch * 256, (unsigned)lane * 16u, ldsb + 65536u + (unsigned)(ch * 1024));
;           }
;           WAIT_V(0);
;           __syncthreads();
; #pragma unroll
;           for (int m = 0; m < 4; ++m) {
;             const int jj0 = wr * 64 + m * 16 + fq * 4;
;             const float k0 = fexp2(lg2 * (float)(127 - jj0));
;             const f32x4 r4 = *(const f32x4*)(rsw + ai * 128 + m * 16);
; #pragma unroll
;             for (int bj = 0; bj < 2; ++bj) {
;               float y1[4], y2[4];
; #pragma unroll
;               for (int j = 0; j < 4; ++j) {
;                 const int lr = ai * 128 + m * 16 + j;
;                 float cs = *(const float*)(rl + ((m * 16 + j) * 128 + bj * 64) * 4), sn = *(const float*)(rl + 65536 + ((m * 16 + j) * 128 + bj * 64) * 4);
;                 float x1 = r4[j] * acc[ai][bj][m][0][j] + swv[bj][0], x2 = r4[j] * acc[ai][bj][m][1][j] + swv[bj][1];
;                 y1[j] = (x1 * cs - x2 * sn) * scl;
;                 y2[j] = (x2 * cs + x1 * sn) * scl;
;                 dst[tb + lr * 1024 + bj * 128] = f2bf(y1[j]);
;                 dst[tb + lr * 1024 + bj * 128 + 16] = f2bf(y2[j]);
;               }
;               if (isk) {
;                 float d0 = k0, d1 = fexp2(lg2 * (float)(126 - jj0)), d2 = fexp2(lg2 * (float)(125 - jj0)),
;                       d3 = fexp2(lg2 * (float)(124 - jj0));
;                 uint2 v1, v2;
;                 v1.x = pack2(y1[0] * d0, y1[1] * d1); v1.y = pack2(y1[2] * d2, y1[3] * d3);
;                 v2.x = pack2(y2[0] * d0, y2[1] * d1); v2.y = pack2(y2[2] * d2, y2[3] * d3);
;                 *(uint2*)(kt_t + kb + ai * 256 * 128 + (bj * 128) * 128 + m * 16) = v1;
;                 *(uint2*)(kt_t + kb + ai * 256 * 128 + (bj * 128 + 16) * 128 + m * 16) = v2;
;               }
.LBB0_612:
	s_add_u32 s15, s27, 0x10000
	s_addc_u32 s16, s90, 0
	s_add_u32 s17, s91, 0x10000
	s_addc_u32 s18, s84, 0
	s_add_u32 s4, s15, s76
	s_addc_u32 s5, s16, s77
	s_waitcnt vmcnt(63) expcnt(7) lgkmcnt(15)
	s_barrier
	s_mov_b32 m0, s85
	s_nop 0
	global_load_lds_dwordx4 v156, s[4:5]
	s_add_u32 s4, s17, s76
	s_addc_u32 s5, s18, s77
	s_mov_b32 m0, s62
	s_nop 0
	global_load_lds_dwordx4 v156, s[4:5]
	s_add_u32 s4, s15, s74
	s_addc_u32 s5, s16, s75
	s_mov_b32 m0, s26
	s_nop 0
	global_load_lds_dwordx4 v156, s[4:5]
	s_add_u32 s4, s17, s74
	s_addc_u32 s5, s18, s75
	s_mov_b32 m0, s60
	s_nop 0
	global_load_lds_dwordx4 v156, s[4:5]
	s_add_u32 s4, s15, s72
	s_addc_u32 s5, s16, s73
	s_mov_b32 m0, s61
	s_nop 0
	global_load_lds_dwordx4 v156, s[4:5]
	s_add_u32 s4, s17, s72
	s_addc_u32 s5, s18, s73
	s_mov_b32 m0, s57
	s_nop 0
	global_load_lds_dwordx4 v156, s[4:5]
	s_add_u32 s4, s15, s70
	s_addc_u32 s5, s16, s71
	s_mov_b32 m0, s58
	s_nop 0
	global_load_lds_dwordx4 v156, s[4:5]
	s_add_u32 s4, s17, s70
	s_addc_u32 s5, s18, s71
	s_mov_b32 m0, s55
	s_nop 0
	global_load_lds_dwordx4 v156, s[4:5]
	s_add_u32 s4, s15, s8
	s_addc_u32 s5, s16, s9
	s_mov_b32 m0, s56
	s_nop 0
	global_load_lds_dwordx4 v156, s[4:5]
	s_add_u32 s4, s17, s8
	s_addc_u32 s5, s18, s9
	s_mov_b32 m0, s53
	s_nop 0
	global_load_lds_dwordx4 v156, s[4:5]
	s_add_u32 s4, s15, s2
	s_addc_u32 s5, s16, s3
	s_add_u32 s2, s17, s2
	s_mov_b32 m0, s54
	s_nop 0
	global_load_lds_dwordx4 v156, s[4:5]
	s_addc_u32 s3, s18, s3
	s_mov_b32 m0, s52
	s_nop 0
	global_load_lds_dwordx4 v156, s[2:3]
	s_add_u32 s2, s15, s10
	s_addc_u32 s3, s16, s11
	s_mov_b32 m0, s59
	s_nop 0
	global_load_lds_dwordx4 v156, s[2:3]
	s_add_u32 s2, s17, s10
	s_addc_u32 s3, s18, s11
	s_mov_b32 m0, s12
	s_nop 0
	global_load_lds_dwordx4 v156, s[2:3]
	s_add_u32 s2, s15, s68
	s_addc_u32 s3, s16, s69
	s_mov_b32 m0, s14
	s_nop 0
	global_load_lds_dwordx4 v156, s[2:3]
	s_add_u32 s2, s17, s68
	s_addc_u32 s3, s18, s69
	s_mov_b32 m0, s13
	s_nop 0
	global_load_lds_dwordx4 v156, s[2:3]
	s_waitcnt vmcnt(0)
	s_barrier
	ds_read2st64_b32 v[70:71], v155 offset1:2
	ds_read2st64_b32 v[80:81], v155 offset0:4 offset1:6
	ds_read_b128 v[66:69], v154 offset:512
	ds_read_b32 v82, v157
	ds_read_b32 v84, v147
	ds_read_b32 v83, v158
	ds_read_b32 v85, v159
	s_waitcnt lgkmcnt(4)
	v_pk_mul_f32 v[64:65], v[64:65], v[68:69]
	v_pk_mul_f32 v[62:63], v[62:63], v[66:67]
	v_mov_b32_e32 v101, v64
	v_mov_b32_e32 v100, v62
	v_pk_mul_f32 v[60:61], v[60:61], v[68:69]
	v_pk_mul_f32 v[114:115], v[58:59], v[66:67]
	v_pk_add_f32 v[100:101], v[140:141], v[100:101]
	v_mov_b32_e32 v58, v114
	v_mov_b32_e32 v59, v60
	v_add_u32_e32 v0, 0x20000, v146
	v_pk_add_f32 v[116:117], v[138:139], v[58:59]
	v_mov_b32_e32 v130, v70
	v_mov_b32_e32 v131, v80
	s_waitcnt lgkmcnt(1)
	v_pk_mul_f32 v[58:59], v[82:83], v[100:101]
	v_mov_b32_e32 v64, v63
	v_lshl_add_u64 v[72:73], v[0:1], 1, s[0:1]
	v_add_u32_e32 v0, 0x20400, v146
	v_pk_fma_f32 v[58:59], v[130:131], v[116:117], v[58:59] neg_lo:[0,0,1] neg_hi:[0,0,1]
	v_pk_add_f32 v[64:65], v[140:141], v[64:65]
	v_mov_b32_e32 v60, v115
	v_lshl_add_u64 v[78:79], v[0:1], 1, s[0:1]
	v_add_u32_e32 v0, 0x20800, v146
	v_pk_mul_f32 v[58:59], v[142:143], v[58:59]
	v_pk_add_f32 v[114:115], v[138:139], v[60:61]
	v_mov_b32_e32 v80, v71
	s_waitcnt lgkmcnt(0)
	v_pk_mul_f32 v[60:61], v[64:65], v[84:85]
	v_lshl_add_u64 v[98:99], v[0:1], 1, s[0:1]
	v_bfe_u32 v0, v58, 16, 1
	v_pk_fma_f32 v[60:61], v[114:115], v[80:81], v[60:61] neg_lo:[0,0,1] neg_hi:[0,0,1]
	v_add3_u32 v0, v58, v0, s81
	v_pk_mul_f32 v[60:61], v[142:143], v[60:61]
	global_store_short_d16_hi v[72:73], v0, off
	v_bfe_u32 v0, v60, 16, 1
	v_add3_u32 v0, v60, v0, s81
	v_pk_mul_f32 v[62:63], v[82:83], v[116:117]
	global_store_short_d16_hi v[78:79], v0, off
	v_bfe_u32 v0, v59, 16, 1
	v_pk_fma_f32 v[62:63], v[130:131], v[100:101], v[62:63]
	v_add3_u32 v0, v59, v0, s81
	v_pk_mul_f32 v[62:63], v[142:143], v[62:63]
	v_pk_mul_f32 v[70:71], v[114:115], v[84:85]
	global_store_short_d16_hi v[98:99], v0, off
	v_bfe_u32 v0, v62, 16, 1
	v_pk_fma_f32 v[64:65], v[64:65], v[80:81], v[70:71]
	v_add3_u32 v0, v62, v0, s81
	v_pk_mul_f32 v[64:65], v[142:143], v[64:65]
	global_store_short_d16_hi v[72:73], v0, off offset:32
	v_bfe_u32 v0, v64, 16, 1
	v_add3_u32 v0, v64, v0, s81
	global_store_short_d16_hi v[78:79], v0, off offset:32
	v_bfe_u32 v0, v63, 16, 1
	v_add3_u32 v0, v63, v0, s81
	global_store_short_d16_hi v[98:99], v0, off offset:32
	v_bfe_u32 v0, v61, 16, 1
	v_add3_u32 v72, v61, v0, s81
	v_add_u32_e32 v0, 0x20c00, v146
	v_lshl_add_u64 v[70:71], v[0:1], 1, s[0:1]
	v_bfe_u32 v0, v65, 16, 1
	v_add3_u32 v0, v65, v0, s81
	s_and_b64 vcc, exec, s[6:7]
	global_store_short_d16_hi v[70:71], v72, off
	global_store_short_d16_hi v[70:71], v0, off offset:32
	s_cbranch_vccnz .LBB0_614
	v_pk_mul_f32 v[58:59], v[148:149], v[58:59]
	v_pk_mul_f32 v[60:61], v[150:151], v[60:61]
	v_and_b32_sdwa v70, v58, v178 dst_sel:DWORD dst_unused:UNUSED_PAD src0_sel:WORD_1 src1_sel:DWORD
	v_and_b32_sdwa v0, v59, v178 dst_sel:DWORD dst_unused:UNUSED_PAD src0_sel:WORD_1 src1_sel:DWORD
	v_add3_u32 v58, v58, v70, s81
	v_and_b32_sdwa v70, v60, v178 dst_sel:DWORD dst_unused:UNUSED_PAD src0_sel:WORD_1 src1_sel:DWORD
	v_add3_u32 v0, v59, v0, s81
	v_and_b32_sdwa v59, v61, v178 dst_sel:DWORD dst_unused:UNUSED_PAD src0_sel:WORD_1 src1_sel:DWORD
	v_add3_u32 v60, v60, v70, s81
	v_add3_u32 v59, v61, v59, s81
	v_and_b32_e32 v60, 0xffff0000, v60
	v_and_b32_e32 v59, 0xffff0000, v59
	v_or_b32_sdwa v58, v60, v58 dst_sel:DWORD dst_unused:UNUSED_PAD src0_sel:DWORD src1_sel:WORD_1
	v_add_co_u32_e32 v60, vcc, s51, v144
	v_pk_mul_f32 v[64:65], v[150:151], v[64:65]
	v_or_b32_sdwa v59, v59, v0 dst_sel:DWORD dst_unused:UNUSED_PAD src0_sel:DWORD src1_sel:WORD_1
	v_addc_co_u32_e32 v61, vcc, 0, v145, vcc
	v_pk_mul_f32 v[62:63], v[148:149], v[62:63]
	global_store_dwordx2 v[60:61], v[58:59], off
	v_and_b32_sdwa v60, v64, v178 dst_sel:DWORD dst_unused:UNUSED_PAD src0_sel:WORD_1 src1_sel:DWORD
	v_and_b32_sdwa v58, v62, v178 dst_sel:DWORD dst_unused:UNUSED_PAD src0_sel:WORD_1 src1_sel:DWORD
	v_and_b32_sdwa v59, v65, v178 dst_sel:DWORD dst_unused:UNUSED_PAD src0_sel:WORD_1 src1_sel:DWORD
	v_add3_u32 v60, v64, v60, s81
	v_and_b32_sdwa v0, v63, v178 dst_sel:DWORD dst_unused:UNUSED_PAD src0_sel:WORD_1 src1_sel:DWORD
	v_add3_u32 v58, v62, v58, s81
	v_add3_u32 v59, v65, v59, s81
	v_and_b32_e32 v60, 0xffff0000, v60
	v_add3_u32 v0, v63, v0, s81
	v_and_b32_e32 v59, 0xffff0000, v59
	v_or_b32_sdwa v58, v60, v58 dst_sel:DWORD dst_unused:UNUSED_PAD src0_sel:DWORD src1_sel:WORD_1
	v_add_co_u32_e32 v60, vcc, 0x11000, v144
	v_or_b32_sdwa v59, v59, v0 dst_sel:DWORD dst_unused:UNUSED_PAD src0_sel:DWORD src1_sel:WORD_1
	s_nop 0
	v_addc_co_u32_e32 v61, vcc, 0, v145, vcc
	global_store_dwordx2 v[60:61], v[58:59], off

; template <int EPI, bool HS = false>
; __device__ __forceinline__ void gemm_phase(const Params& p, const GemmCfg& g, char* shm, const int wave_s) {
;     ...
;   auto tile_coords = [&](int tile, int& mt, int& pn, int& arow0, int& orow0) {
;     int wgid = tile;
;     { int q = nwg / 8, r = nwg % 8, xcd = wgid % 8, off = wgid / 8;
;       wgid = (xcd < r ? xcd * (q + 1) : r * (q + 1) + (xcd - r) * q) + off; }
;     int nig = 8 * g.nN, gid = wgid / nig, fm = gid * 8, gsz = (g.nM - fm < 8) ? (g.nM - fm) : 8;
;     mt = fm + ((wgid % nig) % gsz); pn = (wgid % nig) / gsz;
;     if (g.rev) mt = g.nM - 1 - mt;
;     int hrow0 = (mt >> 3) * 4096 + g.hf * 2048 + (mt & 7) * 256;
;     arow0 = g.a_half ? hrow0 : mt * 256;
;     orow0 = g.o_half ? hrow0 : mt * 256;
;   };
;     ...
;         if (tile + (int)gridDim.x < nwg) {
;           int mt2, pn2, arow2, orow2;
;           tile_coords(tile + gridDim.x, mt2, pn2, arow2, orow2);
;           gemm8_prefetch(g.A + (size_t)arow2 * g.K, g.Bt + (size_t)pn2 * 256 * g.K, g.K, shm, fresh_tid(wave_s));
;         }
.LBB0_628:
	s_add_i32 s0, s93, s44
	s_cmpk_gt_i32 s0, 0xbff
	s_waitcnt vmcnt(63) expcnt(7) lgkmcnt(15)
	s_barrier
	s_cbranch_scc1 .LBB0_577
	s_ashr_i32 s1, s0, 31
	s_lshr_b32 s1, s1, 29
	s_add_i32 s1, s0, s1
	s_ashr_i32 s2, s1, 3
	s_and_b32 s1, s1, -8
	s_sub_i32 s0, s0, s1
	s_cmp_lt_i32 s0, 0
	s_movk_i32 s1, 0x181
	s_cselect_b32 s1, s1, 0x180
	s_mul_i32 s0, s1, s0
	s_add_i32 s0, s0, s2
	s_mul_hi_i32 s1, s0, 0x2aaaaaab
	s_lshr_b32 s2, s1, 31
	s_ashr_i32 s1, s1, 5
	s_add_i32 s1, s1, s2
	s_mul_i32 s2, s1, 0xc0
	s_sub_i32 s2, s0, s2
	s_bfe_u32 s0, s2, 0x3001c
	s_add_i32 s3, s2, s0
	s_sext_i32_i16 s0, s3
	s_and_b32 s3, s3, 0xfff8
	s_sub_i32 s2, s2, s3
	s_sext_i32_i16 s2, s2
	s_lshl_b32 s1, s1, 12
	s_add_i32 s1, s1, s2
	s_and_b32 s1, s1, 0xfffff000
	s_lshl_b32 s2, s2, 8
	s_add_i32 s1, s1, s43
	s_and_b32 s2, s2, 0x700
	s_or_b32 s2, s1, s2
	s_ashr_i32 s3, s2, 31
	s_lshr_b32 s0, s0, 3
	s_lshl_b64 s[2:3], s[2:3], 11
	s_add_u32 s2, s8, s2
	s_addc_u32 s3, s9, s3
	s_bfe_i64 s[0:1], s[0:1], 0x100000
	s_lshl_b64 s[0:1], s[0:1], 19
	v_readlane_b32 s4, v255, 7
	s_add_u32 s0, s4, s0
	v_readlane_b32 s4, v255, 8
	s_addc_u32 s1, s4, s1
	s_mov_b32 s4, s82
	s_mov_b32 s5, -1
	s_nop 0
	v_mbcnt_lo_u32_b32 v0, s5, 0
	v_mbcnt_hi_u32_b32 v0, s5, v0
	v_lshl_add_u32 v0, s4, 6, v0
	s_add_u32 s4, s2, 0x40000
	v_bfe_i32 v4, v0, 27, 1
	v_lshlrev_b32_e32 v2, 4, v0
	v_lshrrev_b32_e32 v4, 22, v4
	v_add_u32_e32 v4, v2, v4
	v_and_b32_e32 v4, 0xfffffc00, v4
	v_ashrrev_i32_e32 v3, 31, v0
	v_sub_u32_e32 v4, v2, v4
	v_lshrrev_b32_e32 v3, 26, v3
	v_lshrrev_b32_e32 v5, 4, v4
	v_add_u32_e32 v3, v0, v3
	v_bitop3_b32 v5, v5, v4, 32 bitop3:0x6c
	v_ashrrev_i32_e32 v4, 31, v4
	v_ashrrev_i32_e32 v3, 6, v3
	v_lshrrev_b32_e32 v4, 26, v4
	v_lshlrev_b32_e32 v6, 3, v3
	v_add_u32_e32 v4, v5, v4
	v_and_b32_e32 v6, 0x1ffff0, v6
	v_ashrrev_i32_e32 v4, 6, v4
	v_add_u32_e32 v6, v4, v6
	v_mul_i32_i24_e32 v4, 64, v4
	v_add_u32_e32 v2, 0x2000, v2
	v_sub_u32_e32 v4, v5, v4
	v_ashrrev_i32_e32 v5, 31, v2
	v_lshrrev_b32_e32 v5, 22, v5
	v_add_u32_e32 v5, v2, v5
	v_ashrrev_i32_e32 v5, 10, v5
	v_mul_i32_i24_e32 v7, 0x400, v5
	v_sub_u32_e32 v2, v2, v7
	v_lshrrev_b32_e32 v7, 4, v2
	v_bitop3_b32 v2, v7, v2, 32 bitop3:0x6c
	v_ashrrev_i32_e32 v8, 31, v2
	v_lshrrev_b32_e32 v8, 26, v8
	s_addc_u32 s5, s3, 0
	v_add_u32_e32 v8, v2, v8
	v_readfirstlane_b32 s8, v0
	s_add_u32 s6, s0, 0x40000
	v_lshlrev_b32_e32 v3, 5, v3
	v_lshlrev_b32_e32 v7, 3, v5
	v_lshrrev_b32_e32 v9, 6, v8
	v_and_b32_e32 v8, 0xc0, v8
	s_addc_u32 s7, s1, 0
	s_lshl_b32 s8, s8, 4
	v_and_b32_e32 v3, 32, v3
	v_ashrrev_i16_sdwa v4, v178, sext(v4) dst_sel:DWORD dst_unused:UNUSED_PAD src0_sel:DWORD src1_sel:BYTE_0
	v_and_b32_e32 v7, 0x1ffff0, v7
	v_lshlrev_b32_e32 v5, 5, v5
	v_sub_u32_e32 v2, v2, v8
	s_and_b32 s8, s8, 0xfffffc00
	v_bfe_i32 v4, v4, 0, 16
	v_add_u32_e32 v7, v9, v7
	v_and_b32_e32 v5, 32, v5
	v_ashrrev_i16_sdwa v2, v178, sext(v2) dst_sel:DWORD dst_unused:UNUSED_PAD src0_sel:DWORD src1_sel:BYTE_0
	v_lshl_or_b32 v3, v6, 10, v3
	s_add_i32 s8, s8, 0
	v_bfe_i32 v2, v2, 0, 16
	v_add_lshl_u32 v3, v3, v4, 1
	v_lshl_or_b32 v4, v7, 10, v5
	s_add_i32 s9, s8, 0x10000
	s_mov_b32 m0, s9
	s_nop 0
	global_load_lds_dwordx4 v3, s[0:1]
	v_add_lshl_u32 v2, v4, v2, 1
	s_add_i32 s9, s8, 0x12000
	s_mov_b32 m0, s9
	s_nop 0
	global_load_lds_dwordx4 v2, s[0:1]
	s_mov_b32 m0, s8
	s_nop 0
	global_load_lds_dwordx4 v3, s[2:3]
	s_add_i32 s9, s8, 0x2000
	s_mov_b32 m0, s9
	s_nop 0
	global_load_lds_dwordx4 v2, s[2:3]
	s_add_i32 s9, s8, 0x14000
	s_mov_b32 m0, s9
	s_nop 0
	global_load_lds_dwordx4 v3, s[6:7]
	s_add_i32 s9, s8, 0x16000
	s_mov_b32 m0, s9
	s_nop 0
	global_load_lds_dwordx4 v2, s[6:7]
	s_add_i32 s6, s8, 0x4000
	s_mov_b32 m0, s6
	s_nop 0
	global_load_lds_dwordx4 v3, s[4:5]
	s_add_i32 s6, s8, 0x6000
	s_mov_b32 m0, s6
	s_nop 0
	global_load_lds_dwordx4 v2, s[4:5]
	s_add_u32 s4, s0, 0x80
	s_addc_u32 s5, s1, 0
	s_add_i32 s6, s8, 0x18000
	s_mov_b32 m0, s6
	s_nop 0
	global_load_lds_dwordx4 v3, s[4:5]
	s_add_i32 s6, s8, 0x1a000
	s_add_u32 s2, s2, 0x80
	s_mov_b32 m0, s6
	s_nop 0
	global_load_lds_dwordx4 v2, s[4:5]
	s_addc_u32 s3, s3, 0
	s_add_i32 s4, s8, 0x8000
	s_mov_b32 m0, s4
	s_nop 0
	global_load_lds_dwordx4 v3, s[2:3]
	s_add_i32 s4, s8, 0xa000
	s_mov_b32 m0, s4
	s_nop 0
	global_load_lds_dwordx4 v2, s[2:3]
	s_add_u32 s0, s0, 0x40080
	s_addc_u32 s1, s1, 0
	s_add_i32 s2, s8, 0x1c000
	s_mov_b32 m0, s2
	s_nop 0
	global_load_lds_dwordx4 v3, s[0:1]
	s_add_i32 s8, s8, 0x1e000
	s_mov_b32 m0, s8
	s_nop 0
	global_load_lds_dwordx4 v2, s[0:1]
	s_branch .LBB0_577

; #define STG_A(b, h, kt) stage_half_s(lds0 + ((b) * 2 + (h)) * HT_B, ((h) ? A1 : Ap) + (kt) * BK, off0, off1)
; #define STG_B(b, h, kt) stage_half_s(lds0 + (4 + (b) * 2 + (h)) * HT_B, ((h) ? B1p : Bp) + (kt) * BK, off0, off1)
; #define STG_A(b, h, kt) stage_half_s(lds0 + ((b) * 2 + (h)) * HT_B, ((h) ? A1 : Ap) + (kt) * BK, off0, off1)
; #define STG_B(b, h, kt) stage_half_s(lds0 + (4 + (b) * 2 + (h)) * HT_B, ((h) ? B1p : Bp) + (kt) * BK, off0, off1)
; __device__ __forceinline__ void gemm8_prefetch(const u16* __restrict__ Ap, const u16* __restrict__ Bp, int K, char* shm, const int tid) {
;   int r0, c0, r1, c1;
;   stage_rc(tid * 16, r0, c0);
;   stage_rc(tid * 16 + 8192, r1, c1);
;   const unsigned off0 = (unsigned)(r0 * K + c0) * 2u, off1 = (unsigned)(r1 * K + c1) * 2u;
;   const int wvoff = __builtin_amdgcn_readfirstlane(tid >> 6) * 1024;
;   const u16* A1 = Ap + (size_t)128 * K;
;   const u16* B1p = Bp + (size_t)128 * K;
;   const unsigned lds0 = (unsigned)(size_t)(__attribute__((address_space(3))) char*)shm + (unsigned)wvoff;
;     ...
;   STG_B(0, 0, 0); STG_A(0, 0, 0); STG_B(0, 1, 0); STG_A(0, 1, 0);
;   STG_B(1, 0, 1); STG_A(1, 0, 1); STG_B(1, 1, 1);
;     ...
; }
; template <int EPI, bool HS = false>
; __device__ __forceinline__ void gemm_phase(const Params& p, const GemmCfg& g, char* shm, const int wave_s) {
;     ...
;   if ((int)blockIdx.x < nwg) {
;     int mt, pn, arow0, orow0;
;     tile_coords(blockIdx.x, mt, pn, arow0, orow0);
;     gemm8_prefetch(g.A + (size_t)arow0 * g.K, g.Bt + (size_t)pn * 256 * g.K, g.K, shm, fresh_tid(wave_s));
;   }
.LBB0_631:
	s_andn2_b64 vcc, exec, s[0:1]
	s_cbranch_vccnz .LBB0_849
	v_readlane_b32 s0, v252, 42
	v_readlane_b32 s1, v252, 43
	s_andn2_b64 vcc, exec, s[0:1]
	s_cbranch_vccnz .LBB0_849
	s_mov_b32 s0, 0x580000
	v_mul_hi_i32 v3, v162, s0
	v_mul_lo_u32 v2, v162, s0
	v_readlane_b32 s0, v252, 26
	v_readlane_b32 s1, v252, 27
	v_readlane_b32 s2, v252, 28
	v_readlane_b32 s3, v252, 29
	v_lshl_add_u64 v[146:147], s[0:1], 0, v[2:3]
	v_readlane_b32 s0, v254, 19
	v_readlane_b32 s1, v254, 20
	v_readlane_b32 s4, v252, 30
	v_readlane_b32 s5, v252, 31
	v_lshl_add_u64 v[2:3], v[146:147], 0, s[0:1]
	s_mov_b32 s0, s82
	s_mov_b32 s1, -1
	s_mov_b32 s70, s45
	v_mbcnt_lo_u32_b32 v0, s1, 0
	v_mbcnt_hi_u32_b32 v0, s1, v0
	v_lshl_add_u32 v0, s0, 6, v0
	s_movk_i32 s0, 0xb00
	v_bfe_i32 v6, v0, 27, 1
	v_lshlrev_b32_e32 v4, 4, v0
	v_lshrrev_b32_e32 v6, 22, v6
	v_add_u32_e32 v6, v4, v6
	v_and_b32_e32 v6, 0xfffffc00, v6
	v_ashrrev_i32_e32 v5, 31, v0
	v_sub_u32_e32 v6, v4, v6
	v_lshrrev_b32_e32 v5, 26, v5
	v_lshrrev_b32_e32 v7, 4, v6
	v_add_u32_e32 v5, v0, v5
	v_bitop3_b32 v7, v7, v6, 32 bitop3:0x6c
	v_ashrrev_i32_e32 v6, 31, v6
	v_ashrrev_i32_e32 v5, 6, v5
	v_lshrrev_b32_e32 v6, 26, v6
	v_lshlrev_b32_e32 v8, 3, v5
	v_add_u32_e32 v6, v7, v6
	v_and_b32_e32 v8, 0xfffff0, v8
	v_ashrrev_i32_e32 v6, 6, v6
	v_add_u32_e32 v8, v6, v8
	v_mul_i32_i24_e32 v6, 64, v6
	v_add_u32_e32 v4, 0x2000, v4
	v_sub_u32_e32 v6, v7, v6
	v_ashrrev_i32_e32 v7, 31, v4
	v_lshrrev_b32_e32 v7, 22, v7
	v_add_u32_e32 v7, v4, v7
	v_ashrrev_i32_e32 v7, 10, v7
	v_mul_i32_i24_e32 v9, 0x400, v7
	v_sub_u32_e32 v4, v4, v9
	v_lshrrev_b32_e32 v9, 4, v4
	v_bitop3_b32 v4, v9, v4, 32 bitop3:0x6c
	v_ashrrev_i32_e32 v10, 31, v4
	v_lshrrev_b32_e32 v10, 26, v10
	v_lshlrev_b32_e32 v9, 3, v7
	v_add_u32_e32 v10, v4, v10
	v_lshlrev_b32_e32 v5, 5, v5
	v_ashrrev_i16_sdwa v6, v178, sext(v6) dst_sel:DWORD dst_unused:UNUSED_PAD src0_sel:DWORD src1_sel:BYTE_0
	v_and_b32_e32 v9, 0xfffff0, v9
	v_lshrrev_b32_e32 v11, 6, v10
	v_and_b32_e32 v10, 0xc0, v10
	v_mul_lo_u32 v8, v8, s0
	v_readfirstlane_b32 s2, v0
	v_bfe_i32 v6, v6, 0, 16
	v_add_u32_e32 v9, v11, v9
	v_sub_u32_e32 v4, v4, v10
	v_and_or_b32 v5, v5, 32, v8
	s_lshl_b32 s2, s2, 4
	v_lshlrev_b32_e32 v7, 5, v7
	v_ashrrev_i16_sdwa v4, v178, sext(v4) dst_sel:DWORD dst_unused:UNUSED_PAD src0_sel:DWORD src1_sel:BYTE_0
	v_add_lshl_u32 v6, v5, v6, 1
	v_mul_lo_u32 v5, v9, s0
	s_and_b32 s2, s2, 0xfffffc00
	v_bfe_i32 v4, v4, 0, 16
	v_and_or_b32 v5, v7, 32, v5
	s_mov_b64 s[0:1], 0xb0000
	s_add_i32 s2, s2, 0
	v_add_lshl_u32 v7, v5, v4, 1
	v_lshl_add_u64 v[4:5], v[2:3], 0, s[0:1]
	v_readfirstlane_b32 s1, v3
	v_readfirstlane_b32 s0, v2
	s_add_i32 s3, s2, 0x10000
	s_mov_b32 m0, s3
	s_nop 2
	global_load_lds_dwordx4 v6, s[0:1]
	s_add_i32 s3, s2, 0x12000
	s_mov_b32 m0, s3
	s_nop 0
	global_load_lds_dwordx4 v7, s[0:1]
	s_add_i32 s3, s2, 0x14000
	v_readlane_b32 s4, v254, 23
	v_readlane_b32 s5, v254, 24
	s_mov_b32 m0, s2
	s_nop 3
	global_load_lds_dwordx4 v6, s[4:5]
	s_add_i32 s0, s2, 0x2000
	s_mov_b32 m0, s0
	s_nop 0
	global_load_lds_dwordx4 v7, s[4:5]
	v_readfirstlane_b32 s0, v4
	v_readfirstlane_b32 s1, v5
	s_mov_b32 m0, s3
	s_nop 3
	global_load_lds_dwordx4 v6, s[0:1]
	s_add_i32 s3, s2, 0x16000
	s_mov_b32 m0, s3
	s_nop 0
	global_load_lds_dwordx4 v7, s[0:1]
	s_add_i32 s0, s2, 0x4000
	v_readlane_b32 s4, v254, 21
	v_readlane_b32 s5, v254, 22
	s_mov_b32 m0, s0
	s_nop 3
	global_load_lds_dwordx4 v6, s[4:5]
	s_add_i32 s0, s2, 0x6000
	s_mov_b32 m0, s0
	s_nop 0
	global_load_lds_dwordx4 v7, s[4:5]
	s_mov_b64 s[0:1], 0x80
	v_lshl_add_u64 v[4:5], v[2:3], 0, s[0:1]
	s_add_i32 s3, s2, 0x18000
	v_readfirstlane_b32 s1, v5
	v_readfirstlane_b32 s0, v4
	s_mov_b32 m0, s3
	s_nop 3
	global_load_lds_dwordx4 v6, s[0:1]
	s_add_i32 s3, s2, 0x1a000
	s_mov_b32 m0, s3
	s_nop 0
	global_load_lds_dwordx4 v7, s[0:1]
	s_add_i32 s0, s2, 0x8000
	v_readlane_b32 s4, v254, 25
	v_readlane_b32 s5, v254, 26
	s_mov_b32 m0, s0
	s_nop 3
	global_load_lds_dwordx4 v6, s[4:5]
	s_add_i32 s0, s2, 0xa000
	s_mov_b32 m0, s0
	s_nop 0
	global_load_lds_dwordx4 v7, s[4:5]
	s_mov_b64 s[0:1], 0xb0080
	v_lshl_add_u64 v[2:3], v[2:3], 0, s[0:1]
	s_add_i32 s3, s2, 0x1c000
	v_readfirstlane_b32 s1, v3
	v_readfirstlane_b32 s0, v2
	s_mov_b32 m0, s3
	s_nop 3
	global_load_lds_dwordx4 v6, s[0:1]
	s_add_i32 s2, s2, 0x1e000
	s_mov_b32 m0, s2
	s_nop 0
	global_load_lds_dwordx4 v7, s[0:1]
	v_readlane_b32 s0, v254, 59
	s_mulk_i32 s0, 0xc00
	s_ashr_i32 s1, s0, 31
	s_lshl_b64 s[0:1], s[0:1], 2
	v_readlane_b32 s2, v254, 57
	s_add_u32 s68, s2, s0
	v_readlane_b32 s0, v254, 58
	s_addc_u32 s69, s0, s1
	v_readlane_b32 s6, v252, 32
	v_readlane_b32 s7, v252, 33
	v_readlane_b32 s8, v252, 34
	v_readlane_b32 s9, v252, 35
	v_readlane_b32 s10, v252, 36
	v_readlane_b32 s11, v252, 37
	v_readlane_b32 s12, v252, 38
	v_readlane_b32 s13, v252, 39
	v_readlane_b32 s14, v252, 40
	v_readlane_b32 s15, v252, 41
	s_branch .LBB0_636
; template <int EPI, bool HS = false>
; __device__ __forceinline__ void gemm_phase(const Params& p, const GemmCfg& g, char* shm, const int wave_s) {
;     ...
;   auto tile_coords = [&](int tile, int& mt, int& pn, int& arow0, int& orow0) {
;     int wgid = tile;
;     { int q = nwg / 8, r = nwg % 8, xcd = wgid % 8, off = wgid / 8;
;       wgid = (xcd < r ? xcd * (q + 1) : r * (q + 1) + (xcd - r) * q) + off; }
;     int nig = 8 * g.nN, gid = wgid / nig, fm = gid * 8, gsz = (g.nM - fm < 8) ? (g.nM - fm) : 8;
;     mt = fm + ((wgid % nig) % gsz); pn = (wgid % nig) / gsz;
;     if (g.rev) mt = g.nM - 1 - mt;
;     int hrow0 = (mt >> 3) * 4096 + g.hf * 2048 + (mt & 7) * 256;
;     arow0 = g.a_half ? hrow0 : mt * 256;
;     orow0 = g.o_half ? hrow0 : mt * 256;
;   };
;     ...
;       if (tile + (int)gridDim.x < nwg) {
;         int mt2, pn2, arow2, orow2;
;         tile_coords(tile + gridDim.x, mt2, pn2, arow2, orow2);
;         gemm8_prefetch(g.A + (size_t)arow2 * g.K, g.Bt + (size_t)pn2 * 256 * g.K, g.K, shm, fresh_tid(wave_s));
;       }
.LBB0_634:
	s_add_i32 s0, s3, s0
	s_ashr_i32 s1, s0, 31
	s_lshr_b32 s1, s1, 27
	s_add_i32 s1, s0, s1
	s_lshr_b32 s2, s1, 5
	s_andn2_b32 s1, s1, 31
	s_sub_i32 s0, s0, s1
	s_bfe_i32 s1, s0, 0x80000
	s_bfe_u32 s1, s1, 0x3000c
	s_add_i32 s1, s0, s1
	s_bfe_i32 s3, s1, 0x80000
	s_and_b32 s1, s1, 0xf8
	s_sub_i32 s0, s0, s1
	s_sub_i32 s2, 0, s2
	s_sext_i32_i8 s0, s0
	s_lshl_b32 s1, s2, 11
	s_lshl_b32 s0, s0, 8
	s_sub_i32 s0, s1, s0
	s_add_i32 s0, s0, 0xff00
	s_mul_hi_i32 s1, s0, 0x1600
	s_mulk_i32 s0, 0x1600
	s_sext_i32_i16 s3, s3
	s_add_u32 s0, s90, s0
	s_addc_u32 s1, s91, s1
	s_ashr_i32 s2, s3, 3
	s_mul_hi_i32 s3, s2, 0x160000
	s_mul_i32 s2, s2, 0x160000
	v_lshl_add_u64 v[2:3], v[146:147], 0, s[2:3]
	s_mov_b32 s2, s82
	s_mov_b32 s3, -1
	s_mov_b64 s[4:5], 0xb0000
	v_mbcnt_lo_u32_b32 v0, s3, 0
	v_mbcnt_hi_u32_b32 v0, s3, v0
	v_lshl_add_u32 v0, s2, 6, v0
	s_movk_i32 s2, 0xb00
	v_bfe_i32 v6, v0, 27, 1
	v_lshlrev_b32_e32 v4, 4, v0
	v_lshrrev_b32_e32 v6, 22, v6
	v_add_u32_e32 v6, v4, v6
	v_and_b32_e32 v6, 0xfffffc00, v6
	v_ashrrev_i32_e32 v5, 31, v0
	v_sub_u32_e32 v6, v4, v6
	v_lshrrev_b32_e32 v5, 26, v5
	v_lshrrev_b32_e32 v7, 4, v6
	v_add_u32_e32 v5, v0, v5
	v_bitop3_b32 v7, v7, v6, 32 bitop3:0x6c
	v_ashrrev_i32_e32 v6, 31, v6
	v_ashrrev_i32_e32 v5, 6, v5
	v_lshrrev_b32_e32 v6, 26, v6
	v_lshlrev_b32_e32 v8, 3, v5
	v_add_u32_e32 v6, v7, v6
	v_and_b32_e32 v8, 0xfffff0, v8
	v_ashrrev_i32_e32 v6, 6, v6
	v_add_u32_e32 v8, v6, v8
	v_mul_i32_i24_e32 v6, 64, v6
	v_add_u32_e32 v4, 0x2000, v4
	v_sub_u32_e32 v6, v7, v6
	v_ashrrev_i32_e32 v7, 31, v4
	v_lshrrev_b32_e32 v7, 22, v7
	v_add_u32_e32 v7, v4, v7
	v_ashrrev_i32_e32 v7, 10, v7
	v_mul_i32_i24_e32 v9, 0x400, v7
	v_sub_u32_e32 v4, v4, v9
	v_lshrrev_b32_e32 v9, 4, v4
	v_bitop3_b32 v4, v9, v4, 32 bitop3:0x6c
	v_ashrrev_i32_e32 v10, 31, v4
	v_lshrrev_b32_e32 v10, 26, v10
	v_lshlrev_b32_e32 v9, 3, v7
	v_add_u32_e32 v10, v4, v10
	v_lshlrev_b32_e32 v5, 5, v5
	v_ashrrev_i16_sdwa v6, v178, sext(v6) dst_sel:DWORD dst_unused:UNUSED_PAD src0_sel:DWORD src1_sel:BYTE_0
	v_and_b32_e32 v9, 0xfffff0, v9
	v_lshrrev_b32_e32 v11, 6, v10
	v_mul_lo_u32 v8, v8, s2
	v_bfe_i32 v6, v6, 0, 16
	v_add_u32_e32 v9, v11, v9
	v_and_or_b32 v5, v5, 32, v8
	v_and_b32_e32 v10, 0xc0, v10
	v_add_lshl_u32 v6, v5, v6, 1
	v_mul_lo_u32 v5, v9, s2
	v_readfirstlane_b32 s6, v0
	s_add_u32 s2, s0, 0xb0000
	v_sub_u32_e32 v4, v4, v10
	s_addc_u32 s3, s1, 0
	s_lshl_b32 s6, s6, 4
	v_lshlrev_b32_e32 v7, 5, v7
	v_ashrrev_i16_sdwa v4, v178, sext(v4) dst_sel:DWORD dst_unused:UNUSED_PAD src0_sel:DWORD src1_sel:BYTE_0
	s_and_b32 s6, s6, 0xfffffc00
	v_bfe_i32 v4, v4, 0, 16
	v_and_or_b32 v5, v7, 32, v5
	s_add_i32 s6, s6, 0
	v_add_lshl_u32 v7, v5, v4, 1
	v_lshl_add_u64 v[4:5], v[2:3], 0, s[4:5]
	v_readfirstlane_b32 s5, v3
	v_readfirstlane_b32 s4, v2
	s_add_i32 s7, s6, 0x10000
	s_mov_b32 m0, s7
	s_nop 2
	global_load_lds_dwordx4 v6, s[4:5]
	s_add_i32 s7, s6, 0x12000
	s_mov_b32 m0, s7
	s_nop 0
	global_load_lds_dwordx4 v7, s[4:5]
	s_mov_b32 m0, s6
	s_nop 0
	global_load_lds_dwordx4 v6, s[0:1]
	s_add_i32 s4, s6, 0x2000
	s_mov_b32 m0, s4
	s_nop 0
	global_load_lds_dwordx4 v7, s[0:1]
	v_readfirstlane_b32 s4, v4
	v_readfirstlane_b32 s5, v5
	s_add_i32 s7, s6, 0x14000
	s_mov_b32 m0, s7
	s_nop 2
	global_load_lds_dwordx4 v6, s[4:5]
	s_add_i32 s7, s6, 0x16000
	s_mov_b32 m0, s7
	s_nop 0
	global_load_lds_dwordx4 v7, s[4:5]
	s_add_i32 s4, s6, 0x4000
	s_mov_b32 m0, s4
	s_nop 0
	global_load_lds_dwordx4 v6, s[2:3]
	s_add_i32 s4, s6, 0x6000
	s_mov_b32 m0, s4
	s_nop 0
	global_load_lds_dwordx4 v7, s[2:3]
	s_mov_b64 s[2:3], 0x80
	v_lshl_add_u64 v[4:5], v[2:3], 0, s[2:3]
	s_add_i32 s4, s6, 0x18000
	v_readfirstlane_b32 s3, v5
	v_readfirstlane_b32 s2, v4
	s_mov_b32 m0, s4
	s_nop 3
	global_load_lds_dwordx4 v6, s[2:3]
	s_add_i32 s4, s6, 0x1a000
	s_mov_b32 m0, s4
	s_nop 0
	global_load_lds_dwordx4 v7, s[2:3]
	s_add_u32 s0, s0, 0x80
	s_addc_u32 s1, s1, 0
	s_add_i32 s2, s6, 0x8000
	s_mov_b32 m0, s2
	s_nop 0
	global_load_lds_dwordx4 v6, s[0:1]
	s_add_i32 s2, s6, 0xa000
	s_mov_b32 m0, s2
	s_nop 0
	global_load_lds_dwordx4 v7, s[0:1]
	s_mov_b64 s[0:1], 0xb0080
	v_lshl_add_u64 v[2:3], v[2:3], 0, s[0:1]
	s_add_i32 s2, s6, 0x1c000
	v_readfirstlane_b32 s1, v3
	v_readfirstlane_b32 s0, v2
	s_mov_b32 m0, s2
	s_nop 3
	global_load_lds_dwordx4 v6, s[0:1]
	s_add_i32 s6, s6, 0x1e000
	s_mov_b32 m0, s6
	s_nop 0
	global_load_lds_dwordx4 v7, s[0:1]
	s_mov_b64 s[0:1], 0

; #define WAIT_V(n) asm volatile("s_waitcnt vmcnt(" #n ")" ::: "memory")
; #define WAIT_L(n) asm volatile("s_waitcnt lgkmcnt(" #n ")" ::: "memory")
; #define BAR __builtin_amdgcn_s_barrier()
; #define SCHED __builtin_amdgcn_sched_barrier(0)
; #define STG_A(b, h, kt) stage_half_s(lds0 + ((b) * 2 + (h)) * HT_B, ((h) ? A1 : Ap) + (kt) * BK, off0, off1)
; #define STG_B(b, h, kt) stage_half_s(lds0 + (4 + (b) * 2 + (h)) * HT_B, ((h) ? B1p : Bp) + (kt) * BK, off0, off1)
; #define STG_A(b, h, kt) stage_half_s(lds0 + ((b) * 2 + (h)) * HT_B, ((h) ? A1 : Ap) + (kt) * BK, off0, off1)
; #define STG_B(b, h, kt) stage_half_s(lds0 + (4 + (b) * 2 + (h)) * HT_B, ((h) ? B1p : Bp) + (kt) * BK, off0, off1)
; #define LDA8(b, h) _Pragma("unroll") for (int m = 0; m < 4; ++m) _Pragma("unroll") for (int k = 0; k < 2; ++k) \
;     At[m][k] = *(const bf16x8*)(SA_(shm, b, h) + abase + (m * 2 + k) * 1024)
; #define LDB8(dst, b, h) _Pragma("unroll") for (int n = 0; n < 2; ++n) _Pragma("unroll") for (int k = 0; k < 2; ++k) \
;     dst[n][k] = *(const bf16x8*)(SB_(shm, b, h) + bbase + (n * 2 + k) * 1024)
; #define MMA8(ai, bj, Bx) do { __builtin_amdgcn_s_setprio(1); \
;     _Pragma("unroll") for (int m = 0; m < 4; ++m) _Pragma("unroll") for (int n = 0; n < 2; ++n) _Pragma("unroll") for (int k = 0; k < 2; ++k) \
;       acc[ai][bj][m][n] = __builtin_amdgcn_mfma_f32_16x16x32_bf16(At[m][k], Bx[n][k], acc[ai][bj][m][n], 0, 0, 0); \
;     __builtin_amdgcn_s_setprio(0); } while (0)
; template <bool HS>
; __device__ __forceinline__ void gemm_tile8(const u16* __restrict__ Ap, const u16* __restrict__ Bp, int K,
;                                            f32x4 (&acc)[2][2][4][2], char* shm, const int tid, const float* hsr = nullptr) {
;     ...
;     LDB8(B0, 0, 0); SCHED; LDA8(0, 0); STG_A(1, 1, t + 1);
;     WAIT_L(8); BAR; WAIT_L(0); MMA8(0, 0, B0); BAR; SCHED;
;     LDB8(B1, 0, 1); STG_B(0, 0, t + 2);
;     BAR; WAIT_L(0); MMA8(0, 1, B1); BAR;
;     LDA8(0, 1); STG_A(0, 0, t + 2);
;     BAR; WAIT_L(0); MMA8(1, 0, B0); BAR; SCHED;
;     STG_B(0, 1, t + 2);
;     WAIT_V(6); BAR; MMA8(1, 1, B1); BAR;
;     LDB8(B0, 1, 0); SCHED; LDA8(1, 0); STG_A(0, 1, t + 2);
;     WAIT_L(8); BAR; WAIT_L(0); MMA8(0, 0, B0); BAR; SCHED;
;     LDB8(B1, 1, 1); STG_B(1, 0, t + 3);
.LBB0_651:
	s_add_i32 s19, 0, 0x10000
	v_add_u32_e32 v160, s19, v137
	ds_read_b128 v[138:141], v160
	ds_read_b128 v[142:145], v160 offset:1024
	ds_read_b128 v[156:159], v160 offset:2048
	ds_read_b128 v[164:167], v160 offset:3072
	ds_read_b128 v[168:171], v134
	ds_read_b128 v[172:175], v134 offset:1024
	ds_read_b128 v[180:183], v134 offset:2048
	ds_read_b128 v[184:187], v134 offset:3072
	ds_read_b128 v[188:191], v134 offset:4096
	ds_read_b128 v[192:195], v134 offset:5120
	ds_read_b128 v[196:199], v134 offset:6144
	ds_read_b128 v[200:203], v134 offset:7168
	s_add_u32 s17, s9, s0
	s_addc_u32 s18, s11, s1
	s_add_u32 s20, s17, 0x80
	s_addc_u32 s21, s18, 0
	s_add_i32 s17, s13, 0xc000
	s_mov_b32 m0, s17
	s_nop 0
	global_load_lds_dwordx4 v136, s[20:21]
	s_add_i32 s18, s13, 0xe000
	s_mov_b32 m0, s18
	s_nop 0
	global_load_lds_dwordx4 v135, s[20:21]
	s_waitcnt lgkmcnt(8)
	s_barrier
	s_waitcnt lgkmcnt(0)
	s_setprio 1
	s_waitcnt lgkmcnt(7)
	v_mfma_f32_16x16x32_bf16 v[126:129], v[168:171], v[138:141], v[126:129]
	v_mfma_f32_16x16x32_bf16 v[122:125], v[168:171], v[156:159], v[122:125]
	s_waitcnt lgkmcnt(5)
	v_mfma_f32_16x16x32_bf16 v[118:121], v[180:183], v[138:141], v[118:121]
	v_mfma_f32_16x16x32_bf16 v[114:117], v[180:183], v[156:159], v[114:117]
	s_waitcnt lgkmcnt(3)
	v_mfma_f32_16x16x32_bf16 v[110:113], v[188:191], v[138:141], v[110:113]
	v_mfma_f32_16x16x32_bf16 v[106:109], v[188:191], v[156:159], v[106:109]
	s_waitcnt lgkmcnt(1)
	v_mfma_f32_16x16x32_bf16 v[102:105], v[196:199], v[138:141], v[102:105]
	v_mfma_f32_16x16x32_bf16 v[98:101], v[196:199], v[156:159], v[98:101]
	v_mfma_f32_16x16x32_bf16 v[126:129], v[172:175], v[142:145], v[126:129]
	v_mfma_f32_16x16x32_bf16 v[122:125], v[172:175], v[164:167], v[122:125]
	v_mfma_f32_16x16x32_bf16 v[118:121], v[184:187], v[142:145], v[118:121]
	v_mfma_f32_16x16x32_bf16 v[114:117], v[184:187], v[164:167], v[114:117]
	v_mfma_f32_16x16x32_bf16 v[110:113], v[192:195], v[142:145], v[110:113]
	v_mfma_f32_16x16x32_bf16 v[106:109], v[192:195], v[164:167], v[106:109]
	s_waitcnt lgkmcnt(0)
	v_mfma_f32_16x16x32_bf16 v[102:105], v[200:203], v[142:145], v[102:105]
	v_mfma_f32_16x16x32_bf16 v[98:101], v[200:203], v[164:167], v[98:101]
	s_setprio 0
	s_barrier
	s_add_i32 s22, 0, 0x14000
	v_add_u32_e32 v160, s22, v137
	ds_read_b128 v[204:207], v160
	ds_read_b128 v[208:211], v160 offset:1024
	ds_read_b128 v[212:215], v160 offset:2048
	ds_read_b128 v[220:223], v160 offset:3072
	v_lshl_add_u64 v[160:161], v[130:131], 0, s[0:1]
	v_lshl_add_u64 v[176:177], v[160:161], 0, s[78:79]
	s_add_i32 s19, s12, s19
	v_readfirstlane_b32 s21, v177
	v_readfirstlane_b32 s20, v176
	s_mov_b32 m0, s19
	s_nop 3
	global_load_lds_dwordx4 v136, s[20:21]
	s_add_i32 s19, s13, 0x12000
	s_mov_b32 m0, s19
	s_nop 0
	global_load_lds_dwordx4 v135, s[20:21]
	s_barrier
	s_waitcnt lgkmcnt(0)
	s_setprio 1
	s_waitcnt lgkmcnt(3)
	v_mfma_f32_16x16x32_bf16 v[94:97], v[168:171], v[204:207], v[94:97]
	s_waitcnt lgkmcnt(1)
	v_mfma_f32_16x16x32_bf16 v[90:93], v[168:171], v[212:215], v[90:93]
	v_mfma_f32_16x16x32_bf16 v[86:89], v[180:183], v[204:207], v[86:89]
	v_mfma_f32_16x16x32_bf16 v[82:85], v[180:183], v[212:215], v[82:85]
	v_mfma_f32_16x16x32_bf16 v[78:81], v[188:191], v[204:207], v[78:81]
	v_mfma_f32_16x16x32_bf16 v[74:77], v[188:191], v[212:215], v[74:77]
	v_mfma_f32_16x16x32_bf16 v[70:73], v[196:199], v[204:207], v[70:73]
	v_mfma_f32_16x16x32_bf16 v[66:69], v[196:199], v[212:215], v[66:69]
	v_mfma_f32_16x16x32_bf16 v[94:97], v[172:175], v[208:211], v[94:97]
	s_waitcnt lgkmcnt(0)
	v_mfma_f32_16x16x32_bf16 v[90:93], v[172:175], v[220:223], v[90:93]
	v_mfma_f32_16x16x32_bf16 v[86:89], v[184:187], v[208:211], v[86:89]
	v_mfma_f32_16x16x32_bf16 v[82:85], v[184:187], v[220:223], v[82:85]
	v_mfma_f32_16x16x32_bf16 v[78:81], v[192:195], v[208:211], v[78:81]
	v_mfma_f32_16x16x32_bf16 v[74:77], v[192:195], v[220:223], v[74:77]
	v_mfma_f32_16x16x32_bf16 v[70:73], v[200:203], v[208:211], v[70:73]
	v_mfma_f32_16x16x32_bf16 v[66:69], v[200:203], v[220:223], v[66:69]
	s_setprio 0
	s_barrier
	ds_read_b128 v[168:171], v134 offset:16384
	ds_read_b128 v[172:175], v134 offset:17408
	ds_read_b128 v[180:183], v134 offset:18432
	ds_read_b128 v[184:187], v134 offset:19456
	ds_read_b128 v[188:191], v134 offset:20480
	ds_read_b128 v[192:195], v134 offset:21504
	ds_read_b128 v[196:199], v134 offset:22528
	ds_read_b128 v[200:203], v134 offset:23552
	s_add_u32 s19, s3, s0
	s_addc_u32 s23, s8, s1
	s_add_u32 s20, s19, 0x100
	s_addc_u32 s21, s23, 0
	s_mov_b32 m0, s13
	s_nop 0
	global_load_lds_dwordx4 v136, s[20:21]
	s_add_i32 s24, s13, 0x2000
	s_mov_b32 m0, s24
	s_nop 0
	global_load_lds_dwordx4 v135, s[20:21]
	s_barrier
	s_waitcnt lgkmcnt(0)
	s_setprio 1
	s_waitcnt lgkmcnt(7)
	v_mfma_f32_16x16x32_bf16 v[62:65], v[168:171], v[138:141], v[62:65]
	v_mfma_f32_16x16x32_bf16 v[58:61], v[168:171], v[156:159], v[58:61]
	s_waitcnt lgkmcnt(5)
	v_mfma_f32_16x16x32_bf16 v[54:57], v[180:183], v[138:141], v[54:57]
	v_mfma_f32_16x16x32_bf16 v[50:53], v[180:183], v[156:159], v[50:53]
	s_waitcnt lgkmcnt(3)
	v_mfma_f32_16x16x32_bf16 v[46:49], v[188:191], v[138:141], v[46:49]
	v_mfma_f32_16x16x32_bf16 v[42:45], v[188:191], v[156:159], v[42:45]
	s_waitcnt lgkmcnt(1)
	v_mfma_f32_16x16x32_bf16 v[38:41], v[196:199], v[138:141], v[38:41]
	v_mfma_f32_16x16x32_bf16 v[34:37], v[196:199], v[156:159], v[34:37]
	v_mfma_f32_16x16x32_bf16 v[62:65], v[172:175], v[142:145], v[62:65]
	v_mfma_f32_16x16x32_bf16 v[58:61], v[172:175], v[164:167], v[58:61]
	v_mfma_f32_16x16x32_bf16 v[54:57], v[184:187], v[142:145], v[54:57]
	v_mfma_f32_16x16x32_bf16 v[50:53], v[184:187], v[164:167], v[50:53]
	v_mfma_f32_16x16x32_bf16 v[46:49], v[192:195], v[142:145], v[46:49]
	v_mfma_f32_16x16x32_bf16 v[42:45], v[192:195], v[164:167], v[42:45]
	s_waitcnt lgkmcnt(0)
	v_mfma_f32_16x16x32_bf16 v[38:41], v[200:203], v[142:145], v[38:41]
	v_mfma_f32_16x16x32_bf16 v[34:37], v[200:203], v[164:167], v[34:37]
	s_setprio 0
	s_barrier
; #define WAIT_V(n) asm volatile("s_waitcnt vmcnt(" #n ")" ::: "memory")
; #define WAIT_L(n) asm volatile("s_waitcnt lgkmcnt(" #n ")" ::: "memory")
; #define BAR __builtin_amdgcn_s_barrier()
; #define SCHED __builtin_amdgcn_sched_barrier(0)
; #define STG_A(b, h, kt) stage_half_s(lds0 + ((b) * 2 + (h)) * HT_B, ((h) ? A1 : Ap) + (kt) * BK, off0, off1)
; #define STG_B(b, h, kt) stage_half_s(lds0 + (4 + (b) * 2 + (h)) * HT_B, ((h) ? B1p : Bp) + (kt) * BK, off0, off1)
; __device__ __forceinline__ void glds16_s(const void* sbase, unsigned voff, unsigned lds_dst) {
;   unsigned keep;
;   asm volatile("s_mov_b32 %0, m0\n\ts_mov_b32 m0, %3\n\ts_nop 2\n\tglobal_load_lds_dwordx4 %1, %2\n\ts_mov_b32 m0, %0"
;                : "=&s"(keep) : "v"(voff), "s"(sbase), "s"(lds_dst) : "memory");
; }
; __device__ __forceinline__ void stage_half_s(unsigned lds_half, const u16* gsrc, unsigned off0, unsigned off1) {
;   const unsigned long long ga = (unsigned long long)(size_t)gsrc;
;   const unsigned lo = __builtin_amdgcn_readfirstlane((unsigned)ga), hi = __builtin_amdgcn_readfirstlane((unsigned)(ga >> 32));
;   const void* sb = (const void*)(size_t)(((unsigned long long)hi << 32) | lo);
;   const unsigned la = __builtin_amdgcn_readfirstlane(lds_half);
;   glds16_s(sb, off0, la);
;   glds16_s(sb, off1, la + 8192u);
; template <bool HS>
; __device__ __forceinline__ void gemm_tile8(const u16* __restrict__ Ap, const u16* __restrict__ Bp, int K,
;                                            f32x4 (&acc)[2][2][4][2], char* shm, const int tid, const float* hsr = nullptr) {
;     ...
;     LDB8(B0, 0, 0); SCHED; LDA8(0, 0); STG_A(1, 1, t + 1);
;     WAIT_L(8); BAR; WAIT_L(0); MMA8(0, 0, B0); BAR; SCHED;
;     LDB8(B1, 0, 1); STG_B(0, 0, t + 2);
;     BAR; WAIT_L(0); MMA8(0, 1, B1); BAR;
;     LDA8(0, 1); STG_A(0, 0, t + 2);
;     BAR; WAIT_L(0); MMA8(1, 0, B0); BAR; SCHED;
;     STG_B(0, 1, t + 2);
;     WAIT_V(6); BAR; MMA8(1, 1, B1); BAR;
;     LDB8(B0, 1, 0); SCHED; LDA8(1, 0); STG_A(0, 1, t + 2);
;     WAIT_L(8); BAR; WAIT_L(0); MMA8(0, 0, B0); BAR; SCHED;
;     LDB8(B1, 1, 1); STG_B(1, 0, t + 3);
;     BAR; WAIT_L(0); MMA8(0, 1, B1); BAR;
;     LDA8(1, 1); STG_A(1, 0, t + 3);
;     BAR; WAIT_L(0); MMA8(1, 0, B0); BAR; SCHED;
;     STG_B(1, 1, t + 3);
;     WAIT_V(6); BAR; MMA8(1, 1, B1); BAR;
	v_lshl_add_u64 v[176:177], v[132:133], 0, s[0:1]
	v_lshl_add_u64 v[138:139], v[176:177], 0, s[78:79]
	s_add_i32 s22, s12, s22
	v_readfirstlane_b32 s21, v139
	v_readfirstlane_b32 s20, v138
	s_mov_b32 m0, s22
	s_nop 3
	global_load_lds_dwordx4 v136, s[20:21]
	s_add_i32 s22, s13, 0x16000
	s_mov_b32 m0, s22
	s_nop 0
	global_load_lds_dwordx4 v135, s[20:21]
	s_waitcnt vmcnt(6)
	s_barrier
	s_setprio 1
	v_mfma_f32_16x16x32_bf16 v[30:33], v[168:171], v[204:207], v[30:33]
	v_mfma_f32_16x16x32_bf16 v[26:29], v[168:171], v[212:215], v[26:29]
	v_mfma_f32_16x16x32_bf16 v[22:25], v[180:183], v[204:207], v[22:25]
	v_mfma_f32_16x16x32_bf16 v[18:21], v[180:183], v[212:215], v[18:21]
	v_mfma_f32_16x16x32_bf16 v[14:17], v[188:191], v[204:207], v[14:17]
	v_mfma_f32_16x16x32_bf16 v[10:13], v[188:191], v[212:215], v[10:13]
	v_mfma_f32_16x16x32_bf16 v[6:9], v[196:199], v[204:207], v[6:9]
	v_mfma_f32_16x16x32_bf16 v[2:5], v[196:199], v[212:215], v[2:5]
	v_mfma_f32_16x16x32_bf16 v[30:33], v[172:175], v[208:211], v[30:33]
	v_mfma_f32_16x16x32_bf16 v[26:29], v[172:175], v[220:223], v[26:29]
	v_mfma_f32_16x16x32_bf16 v[22:25], v[184:187], v[208:211], v[22:25]
	v_mfma_f32_16x16x32_bf16 v[18:21], v[184:187], v[220:223], v[18:21]
	v_mfma_f32_16x16x32_bf16 v[14:17], v[192:195], v[208:211], v[14:17]
	v_mfma_f32_16x16x32_bf16 v[10:13], v[192:195], v[220:223], v[10:13]
	v_mfma_f32_16x16x32_bf16 v[6:9], v[200:203], v[208:211], v[6:9]
	v_mfma_f32_16x16x32_bf16 v[2:5], v[200:203], v[220:223], v[2:5]
	s_setprio 0
	s_add_i32 s22, 0, 0x18000
	v_add_u32_e32 v163, s22, v137
	s_barrier
	ds_read_b128 v[138:141], v163
	ds_read_b128 v[142:145], v163 offset:1024
	ds_read_b128 v[156:159], v163 offset:2048
	ds_read_b128 v[164:167], v163 offset:3072
	ds_read_b128 v[168:171], v134 offset:32768
	ds_read_b128 v[172:175], v134 offset:33792
	ds_read_b128 v[180:183], v134 offset:34816
	ds_read_b128 v[184:187], v134 offset:35840
	ds_read_b128 v[188:191], v134 offset:36864
	ds_read_b128 v[192:195], v134 offset:37888
	ds_read_b128 v[196:199], v134 offset:38912
	ds_read_b128 v[200:203], v134 offset:39936
	s_add_u32 s20, s14, s0
	s_addc_u32 s21, s15, s1
	s_add_i32 s24, s13, 0x4000
	s_mov_b32 m0, s24
	s_nop 0
	global_load_lds_dwordx4 v136, s[20:21]
	s_add_i32 s24, s13, 0x6000
	s_mov_b32 m0, s24
	s_nop 0
	global_load_lds_dwordx4 v135, s[20:21]
	s_waitcnt lgkmcnt(8)
	s_barrier
	s_waitcnt lgkmcnt(0)
	s_setprio 1
	s_waitcnt lgkmcnt(7)
	v_mfma_f32_16x16x32_bf16 v[126:129], v[168:171], v[138:141], v[126:129]
	v_mfma_f32_16x16x32_bf16 v[122:125], v[168:171], v[156:159], v[122:125]
	s_waitcnt lgkmcnt(5)
	v_mfma_f32_16x16x32_bf16 v[118:121], v[180:183], v[138:141], v[118:121]
	v_mfma_f32_16x16x32_bf16 v[114:117], v[180:183], v[156:159], v[114:117]
	s_waitcnt lgkmcnt(3)
	v_mfma_f32_16x16x32_bf16 v[110:113], v[188:191], v[138:141], v[110:113]
	v_mfma_f32_16x16x32_bf16 v[106:109], v[188:191], v[156:159], v[106:109]
	s_waitcnt lgkmcnt(1)
	v_mfma_f32_16x16x32_bf16 v[102:105], v[196:199], v[138:141], v[102:105]
	v_mfma_f32_16x16x32_bf16 v[98:101], v[196:199], v[156:159], v[98:101]
	v_mfma_f32_16x16x32_bf16 v[126:129], v[172:175], v[142:145], v[126:129]
	v_mfma_f32_16x16x32_bf16 v[122:125], v[172:175], v[164:167], v[122:125]
	v_mfma_f32_16x16x32_bf16 v[118:121], v[184:187], v[142:145], v[118:121]
	v_mfma_f32_16x16x32_bf16 v[114:117], v[184:187], v[164:167], v[114:117]
	v_mfma_f32_16x16x32_bf16 v[110:113], v[192:195], v[142:145], v[110:113]
	v_mfma_f32_16x16x32_bf16 v[106:109], v[192:195], v[164:167], v[106:109]
	s_waitcnt lgkmcnt(0)
	v_mfma_f32_16x16x32_bf16 v[102:105], v[200:203], v[142:145], v[102:105]
	v_mfma_f32_16x16x32_bf16 v[98:101], v[200:203], v[164:167], v[98:101]
	s_setprio 0
	s_barrier
	s_add_i32 s24, 0, 0x1c000
	v_add_u32_e32 v163, s24, v137
	ds_read_b128 v[204:207], v163
	ds_read_b128 v[208:211], v163 offset:1024
	ds_read_b128 v[212:215], v163 offset:2048
	ds_read_b128 v[220:223], v163 offset:3072
	v_lshl_add_u64 v[160:161], v[160:161], 0, s[86:87]
	s_add_i32 s22, s12, s22
	v_readfirstlane_b32 s21, v161
	v_readfirstlane_b32 s20, v160
	s_mov_b32 m0, s22
	s_nop 3
	global_load_lds_dwordx4 v136, s[20:21]
	s_add_i32 s22, s13, 0x1a000
	s_mov_b32 m0, s22
	s_nop 0
	global_load_lds_dwordx4 v135, s[20:21]
	s_barrier
	s_waitcnt lgkmcnt(0)
	s_setprio 1
	s_waitcnt lgkmcnt(3)
	v_mfma_f32_16x16x32_bf16 v[94:97], v[168:171], v[204:207], v[94:97]
	s_waitcnt lgkmcnt(1)
	v_mfma_f32_16x16x32_bf16 v[90:93], v[168:171], v[212:215], v[90:93]
	v_mfma_f32_16x16x32_bf16 v[86:89], v[180:183], v[204:207], v[86:89]
	v_mfma_f32_16x16x32_bf16 v[82:85], v[180:183], v[212:215], v[82:85]
	v_mfma_f32_16x16x32_bf16 v[78:81], v[188:191], v[204:207], v[78:81]
	v_mfma_f32_16x16x32_bf16 v[74:77], v[188:191], v[212:215], v[74:77]
	v_mfma_f32_16x16x32_bf16 v[70:73], v[196:199], v[204:207], v[70:73]
	v_mfma_f32_16x16x32_bf16 v[66:69], v[196:199], v[212:215], v[66:69]
	v_mfma_f32_16x16x32_bf16 v[94:97], v[172:175], v[208:211], v[94:97]
	s_waitcnt lgkmcnt(0)
	v_mfma_f32_16x16x32_bf16 v[90:93], v[172:175], v[220:223], v[90:93]
	v_mfma_f32_16x16x32_bf16 v[86:89], v[184:187], v[208:211], v[86:89]
	v_mfma_f32_16x16x32_bf16 v[82:85], v[184:187], v[220:223], v[82:85]
	v_mfma_f32_16x16x32_bf16 v[78:81], v[192:195], v[208:211], v[78:81]
	v_mfma_f32_16x16x32_bf16 v[74:77], v[192:195], v[220:223], v[74:77]
	v_mfma_f32_16x16x32_bf16 v[70:73], v[200:203], v[208:211], v[70:73]
	v_mfma_f32_16x16x32_bf16 v[66:69], v[200:203], v[220:223], v[66:69]
	s_setprio 0
	s_barrier
; #define WAIT_V(n) asm volatile("s_waitcnt vmcnt(" #n ")" ::: "memory")
; #define WAIT_L(n) asm volatile("s_waitcnt lgkmcnt(" #n ")" ::: "memory")
; #define BAR __builtin_amdgcn_s_barrier()
; #define SCHED __builtin_amdgcn_sched_barrier(0)
; #define STG_A(b, h, kt) stage_half_s(lds0 + ((b) * 2 + (h)) * HT_B, ((h) ? A1 : Ap) + (kt) * BK, off0, off1)
; #define STG_B(b, h, kt) stage_half_s(lds0 + (4 + (b) * 2 + (h)) * HT_B, ((h) ? B1p : Bp) + (kt) * BK, off0, off1)
; #define STG_A(b, h, kt) stage_half_s(lds0 + ((b) * 2 + (h)) * HT_B, ((h) ? A1 : Ap) + (kt) * BK, off0, off1)
; #define STG_B(b, h, kt) stage_half_s(lds0 + (4 + (b) * 2 + (h)) * HT_B, ((h) ? B1p : Bp) + (kt) * BK, off0, off1)
; #define LDA8(b, h) _Pragma("unroll") for (int m = 0; m < 4; ++m) _Pragma("unroll") for (int k = 0; k < 2; ++k) \
;     At[m][k] = *(const bf16x8*)(SA_(shm, b, h) + abase + (m * 2 + k) * 1024)
; #define LDB8(dst, b, h) _Pragma("unroll") for (int n = 0; n < 2; ++n) _Pragma("unroll") for (int k = 0; k < 2; ++k) \
;     dst[n][k] = *(const bf16x8*)(SB_(shm, b, h) + bbase + (n * 2 + k) * 1024)
; template <bool HS>
; __device__ __forceinline__ void gemm_tile8(const u16* __restrict__ Ap, const u16* __restrict__ Bp, int K,
;                                            f32x4 (&acc)[2][2][4][2], char* shm, const int tid, const float* hsr = nullptr) {
;     ...
;     LDB8(B0, 0, 0); SCHED; LDA8(0, 0); STG_A(1, 1, t + 1);
;     WAIT_L(8); BAR; WAIT_L(0); MMA8(0, 0, B0); BAR; SCHED;
;     LDB8(B1, 0, 1); STG_B(0, 0, t + 2);
;     BAR; WAIT_L(0); MMA8(0, 1, B1); BAR;
;     LDA8(0, 1); STG_A(0, 0, t + 2);
;     BAR; WAIT_L(0); MMA8(1, 0, B0); BAR; SCHED;
;     STG_B(0, 1, t + 2);
;     WAIT_V(6); BAR; MMA8(1, 1, B1); BAR;
;     LDB8(B0, 1, 0); SCHED; LDA8(1, 0); STG_A(0, 1, t + 2);
;     WAIT_L(8); BAR; WAIT_L(0); MMA8(0, 0, B0); BAR; SCHED;
;     LDB8(B1, 1, 1); STG_B(1, 0, t + 3);
;     BAR; WAIT_L(0); MMA8(0, 1, B1); BAR;
;     LDA8(1, 1); STG_A(1, 0, t + 3);
;     BAR; WAIT_L(0); MMA8(1, 0, B0); BAR; SCHED;
;     STG_B(1, 1, t + 3);
;     WAIT_V(6); BAR; MMA8(1, 1, B1); BAR;
;   }
;   { LDB8(B0, 0, 0); LDA8(0, 0); STG_A(1, 1, nt - 1);
;     BAR; WAIT_L(0); MMA8(0, 0, B0); BAR;
;     LDB8(B1, 0, 1); BAR; WAIT_L(0); MMA8(0, 1, B1); BAR;
;     LDA8(0, 1); WAIT_V(4); BAR; WAIT_L(0); MMA8(1, 0, B0); MMA8(1, 1, B1); BAR; }
	ds_read_b128 v[168:171], v134 offset:49152
	ds_read_b128 v[172:175], v134 offset:50176
	ds_read_b128 v[180:183], v134 offset:51200
	ds_read_b128 v[184:187], v134 offset:52224
	ds_read_b128 v[188:191], v134 offset:53248
	ds_read_b128 v[192:195], v134 offset:54272
	ds_read_b128 v[196:199], v134 offset:55296
	ds_read_b128 v[200:203], v134 offset:56320
	s_add_u32 s20, s19, 0x180
	s_addc_u32 s21, s23, 0
	s_add_i32 s19, s13, 0x8000
	s_mov_b32 m0, s19
	s_nop 0
	global_load_lds_dwordx4 v136, s[20:21]
	s_add_i32 s19, s13, 0xa000
	s_mov_b32 m0, s19
	s_nop 0
	global_load_lds_dwordx4 v135, s[20:21]
	s_barrier
	s_waitcnt lgkmcnt(0)
	s_setprio 1
	s_waitcnt lgkmcnt(7)
	v_mfma_f32_16x16x32_bf16 v[62:65], v[168:171], v[138:141], v[62:65]
	v_mfma_f32_16x16x32_bf16 v[58:61], v[168:171], v[156:159], v[58:61]
	s_waitcnt lgkmcnt(5)
	v_mfma_f32_16x16x32_bf16 v[54:57], v[180:183], v[138:141], v[54:57]
	v_mfma_f32_16x16x32_bf16 v[50:53], v[180:183], v[156:159], v[50:53]
	s_waitcnt lgkmcnt(3)
	v_mfma_f32_16x16x32_bf16 v[46:49], v[188:191], v[138:141], v[46:49]
	v_mfma_f32_16x16x32_bf16 v[42:45], v[188:191], v[156:159], v[42:45]
	s_waitcnt lgkmcnt(1)
	v_mfma_f32_16x16x32_bf16 v[38:41], v[196:199], v[138:141], v[38:41]
	v_mfma_f32_16x16x32_bf16 v[34:37], v[196:199], v[156:159], v[34:37]
	v_mfma_f32_16x16x32_bf16 v[62:65], v[172:175], v[142:145], v[62:65]
	v_mfma_f32_16x16x32_bf16 v[58:61], v[172:175], v[164:167], v[58:61]
	v_mfma_f32_16x16x32_bf16 v[54:57], v[184:187], v[142:145], v[54:57]
	v_mfma_f32_16x16x32_bf16 v[50:53], v[184:187], v[164:167], v[50:53]
	v_mfma_f32_16x16x32_bf16 v[46:49], v[192:195], v[142:145], v[46:49]
	v_mfma_f32_16x16x32_bf16 v[42:45], v[192:195], v[164:167], v[42:45]
	s_waitcnt lgkmcnt(0)
	v_mfma_f32_16x16x32_bf16 v[38:41], v[200:203], v[142:145], v[38:41]
	v_mfma_f32_16x16x32_bf16 v[34:37], v[200:203], v[164:167], v[34:37]
	s_setprio 0
	s_barrier
	v_lshl_add_u64 v[138:139], v[176:177], 0, s[86:87]
	s_add_i32 s19, s12, s24
	v_readfirstlane_b32 s21, v139
	v_readfirstlane_b32 s20, v138
	s_mov_b32 m0, s19
	s_nop 3
	global_load_lds_dwordx4 v136, s[20:21]
	s_add_i32 s19, s13, 0x1e000
	s_mov_b32 m0, s19
	s_nop 0
	global_load_lds_dwordx4 v135, s[20:21]
	s_waitcnt vmcnt(6)
	s_barrier
	s_setprio 1
	v_mfma_f32_16x16x32_bf16 v[30:33], v[168:171], v[204:207], v[30:33]
	v_mfma_f32_16x16x32_bf16 v[26:29], v[168:171], v[212:215], v[26:29]
	v_mfma_f32_16x16x32_bf16 v[22:25], v[180:183], v[204:207], v[22:25]
	v_mfma_f32_16x16x32_bf16 v[18:21], v[180:183], v[212:215], v[18:21]
	v_mfma_f32_16x16x32_bf16 v[14:17], v[188:191], v[204:207], v[14:17]
	v_mfma_f32_16x16x32_bf16 v[10:13], v[188:191], v[212:215], v[10:13]
	v_mfma_f32_16x16x32_bf16 v[6:9], v[196:199], v[204:207], v[6:9]
	v_mfma_f32_16x16x32_bf16 v[2:5], v[196:199], v[212:215], v[2:5]
	v_mfma_f32_16x16x32_bf16 v[30:33], v[172:175], v[208:211], v[30:33]
	v_mfma_f32_16x16x32_bf16 v[26:29], v[172:175], v[220:223], v[26:29]
	v_mfma_f32_16x16x32_bf16 v[22:25], v[184:187], v[208:211], v[22:25]
	v_mfma_f32_16x16x32_bf16 v[18:21], v[184:187], v[220:223], v[18:21]
	v_mfma_f32_16x16x32_bf16 v[14:17], v[192:195], v[208:211], v[14:17]
	v_mfma_f32_16x16x32_bf16 v[10:13], v[192:195], v[220:223], v[10:13]
	v_mfma_f32_16x16x32_bf16 v[6:9], v[200:203], v[208:211], v[6:9]
	v_mfma_f32_16x16x32_bf16 v[2:5], v[200:203], v[220:223], v[2:5]
	s_setprio 0
	s_add_i32 s16, s16, 2
	s_add_u32 s0, s0, 0x100
	s_addc_u32 s1, s1, 0
	s_cmp_lt_u32 s16, 40
	s_barrier
	s_cbranch_scc1 .LBB0_651
	v_add_u32_e32 v160, 0, v137
	v_add_u32_e32 v137, 0x10000, v160
	ds_read_b128 v[130:133], v137
	ds_read_b128 v[138:141], v137 offset:1024
	ds_read_b128 v[142:145], v137 offset:2048
	ds_read_b128 v[156:159], v137 offset:3072
	ds_read_b128 v[164:167], v134
	ds_read_b128 v[168:171], v134 offset:1024
	ds_read_b128 v[172:175], v134 offset:2048
	ds_read_b128 v[180:183], v134 offset:3072
	ds_read_b128 v[184:187], v134 offset:4096
	ds_read_b128 v[188:191], v134 offset:5120
	ds_read_b128 v[192:195], v134 offset:6144
	ds_read_b128 v[196:199], v134 offset:7168
	s_add_u32 s0, s3, 0xb1580
	s_addc_u32 s1, s8, 0
	s_mov_b32 m0, s17
	s_nop 0
	global_load_lds_dwordx4 v136, s[0:1]
	s_nop 0
	s_mov_b32 m0, s18
	s_nop 0
	global_load_lds_dwordx4 v135, s[0:1]
	s_barrier
	s_waitcnt lgkmcnt(0)
	s_setprio 1
	s_waitcnt lgkmcnt(7)
	v_mfma_f32_16x16x32_bf16 v[126:129], v[164:167], v[130:133], v[126:129]
	s_waitcnt lgkmcnt(5)
	v_mfma_f32_16x16x32_bf16 v[118:121], v[172:175], v[130:133], v[118:121]
	v_mfma_f32_16x16x32_bf16 v[114:117], v[172:175], v[142:145], v[114:117]
	s_waitcnt lgkmcnt(1)
	v_mfma_f32_16x16x32_bf16 v[102:105], v[192:195], v[130:133], v[102:105]
	v_mfma_f32_16x16x32_bf16 v[98:101], v[192:195], v[142:145], v[98:101]
	v_mfma_f32_16x16x32_bf16 v[126:129], v[168:171], v[138:141], v[126:129]
	v_mfma_f32_16x16x32_bf16 v[122:125], v[164:167], v[142:145], v[122:125]
	v_mfma_f32_16x16x32_bf16 v[118:121], v[180:183], v[138:141], v[118:121]
	v_mfma_f32_16x16x32_bf16 v[114:117], v[180:183], v[156:159], v[114:117]
	v_mfma_f32_16x16x32_bf16 v[110:113], v[184:187], v[130:133], v[110:113]
	v_mfma_f32_16x16x32_bf16 v[106:109], v[184:187], v[142:145], v[106:109]
	s_waitcnt lgkmcnt(0)
	v_mfma_f32_16x16x32_bf16 v[102:105], v[196:199], v[138:141], v[102:105]
	v_mfma_f32_16x16x32_bf16 v[98:101], v[196:199], v[156:159], v[98:101]
	v_mfma_f32_16x16x32_bf16 v[200:203], v[168:171], v[156:159], v[122:125]
	v_mfma_f32_16x16x32_bf16 v[204:207], v[188:191], v[138:141], v[110:113]
	v_mfma_f32_16x16x32_bf16 v[208:211], v[188:191], v[156:159], v[106:109]
	s_setprio 0
	v_add_u32_e32 v135, 0x14000, v160
	s_barrier
; #define WAIT_V(n) asm volatile("s_waitcnt vmcnt(" #n ")" ::: "memory")
; #define WAIT_L(n) asm volatile("s_waitcnt lgkmcnt(" #n ")" ::: "memory")
; #define BAR __builtin_amdgcn_s_barrier()
; #define STG_A(b, h, kt) stage_half_s(lds0 + ((b) * 2 + (h)) * HT_B, ((h) ? A1 : Ap) + (kt) * BK, off0, off1)
; #define STG_A(b, h, kt) stage_half_s(lds0 + ((b) * 2 + (h)) * HT_B, ((h) ? A1 : Ap) + (kt) * BK, off0, off1)
; #define LDA8(b, h) _Pragma("unroll") for (int m = 0; m < 4; ++m) _Pragma("unroll") for (int k = 0; k < 2; ++k) \
;     At[m][k] = *(const bf16x8*)(SA_(shm, b, h) + abase + (m * 2 + k) * 1024)
; #define LDB8(dst, b, h) _Pragma("unroll") for (int n = 0; n < 2; ++n) _Pragma("unroll") for (int k = 0; k < 2; ++k) \
;     dst[n][k] = *(const bf16x8*)(SB_(shm, b, h) + bbase + (n * 2 + k) * 1024)
; #define MMA8(ai, bj, Bx) do { __builtin_amdgcn_s_setprio(1); \
;     _Pragma("unroll") for (int m = 0; m < 4; ++m) _Pragma("unroll") for (int n = 0; n < 2; ++n) _Pragma("unroll") for (int k = 0; k < 2; ++k) \
;       acc[ai][bj][m][n] = __builtin_amdgcn_mfma_f32_16x16x32_bf16(At[m][k], Bx[n][k], acc[ai][bj][m][n], 0, 0, 0); \
;     __builtin_amdgcn_s_setprio(0); } while (0)
; template <bool HS>
; __device__ __forceinline__ void gemm_tile8(const u16* __restrict__ Ap, const u16* __restrict__ Bp, int K,
;                                            f32x4 (&acc)[2][2][4][2], char* shm, const int tid, const float* hsr = nullptr) {
;     ...
;   { LDB8(B0, 0, 0); LDA8(0, 0); STG_A(1, 1, nt - 1);
;     BAR; WAIT_L(0); MMA8(0, 0, B0); BAR;
;     LDB8(B1, 0, 1); BAR; WAIT_L(0); MMA8(0, 1, B1); BAR;
;     LDA8(0, 1); WAIT_V(4); BAR; WAIT_L(0); MMA8(1, 0, B0); MMA8(1, 1, B1); BAR; }
;   { LDB8(B0, 1, 0); LDA8(1, 0); WAIT_V(2); BAR; WAIT_L(0); MMA8(0, 0, B0); BAR;
	ds_read_b128 v[106:109], v135
	ds_read_b128 v[110:113], v135 offset:1024
	ds_read_b128 v[122:125], v135 offset:2048
	ds_read_b128 v[212:215], v135 offset:3072
	s_barrier
	s_waitcnt lgkmcnt(0)
	s_setprio 1
	s_waitcnt lgkmcnt(3)
	v_mfma_f32_16x16x32_bf16 v[86:89], v[172:175], v[106:109], v[86:89]
	s_waitcnt lgkmcnt(1)
	v_mfma_f32_16x16x32_bf16 v[82:85], v[172:175], v[122:125], v[82:85]
	v_mfma_f32_16x16x32_bf16 v[70:73], v[192:195], v[106:109], v[70:73]
	v_mfma_f32_16x16x32_bf16 v[94:97], v[164:167], v[106:109], v[94:97]
	v_mfma_f32_16x16x32_bf16 v[90:93], v[164:167], v[122:125], v[90:93]
	v_mfma_f32_16x16x32_bf16 v[86:89], v[180:183], v[110:113], v[86:89]
	s_waitcnt lgkmcnt(0)
	v_mfma_f32_16x16x32_bf16 v[82:85], v[180:183], v[212:215], v[82:85]
	v_mfma_f32_16x16x32_bf16 v[78:81], v[184:187], v[106:109], v[78:81]
	v_mfma_f32_16x16x32_bf16 v[74:77], v[184:187], v[122:125], v[74:77]
	v_mfma_f32_16x16x32_bf16 v[70:73], v[196:199], v[110:113], v[70:73]
	v_mfma_f32_16x16x32_bf16 v[66:69], v[192:195], v[122:125], v[66:69]
	v_mfma_f32_16x16x32_bf16 v[220:223], v[168:171], v[110:113], v[94:97]
	v_mfma_f32_16x16x32_bf16 v[164:167], v[168:171], v[212:215], v[90:93]
	v_mfma_f32_16x16x32_bf16 v[168:171], v[188:191], v[110:113], v[78:81]
	v_mfma_f32_16x16x32_bf16 v[172:175], v[188:191], v[212:215], v[74:77]
	v_mfma_f32_16x16x32_bf16 v[180:183], v[196:199], v[212:215], v[66:69]
	s_setprio 0
	s_barrier
	s_nop 0
	ds_read_b128 v[66:69], v134 offset:16384
	ds_read_b128 v[74:77], v134 offset:17408
	ds_read_b128 v[78:81], v134 offset:18432
	ds_read_b128 v[90:93], v134 offset:19456
	ds_read_b128 v[94:97], v134 offset:20480
	ds_read_b128 v[184:187], v134 offset:21504
	ds_read_b128 v[188:191], v134 offset:22528
	ds_read_b128 v[192:195], v134 offset:23552
	s_waitcnt vmcnt(4)
	s_barrier
	s_waitcnt lgkmcnt(0)
	s_setprio 1
	s_waitcnt lgkmcnt(7)
	v_mfma_f32_16x16x32_bf16 v[62:65], v[66:69], v[130:133], v[62:65]
	s_waitcnt lgkmcnt(5)
	v_mfma_f32_16x16x32_bf16 v[54:57], v[78:81], v[130:133], v[54:57]
	v_mfma_f32_16x16x32_bf16 v[50:53], v[78:81], v[142:145], v[50:53]
	s_waitcnt lgkmcnt(1)
	v_mfma_f32_16x16x32_bf16 v[38:41], v[188:191], v[130:133], v[38:41]
	v_mfma_f32_16x16x32_bf16 v[34:37], v[188:191], v[142:145], v[34:37]
	v_mfma_f32_16x16x32_bf16 v[62:65], v[74:77], v[138:141], v[62:65]
	v_mfma_f32_16x16x32_bf16 v[58:61], v[66:69], v[142:145], v[58:61]
	v_mfma_f32_16x16x32_bf16 v[54:57], v[90:93], v[138:141], v[54:57]
	v_mfma_f32_16x16x32_bf16 v[50:53], v[90:93], v[156:159], v[50:53]
	v_mfma_f32_16x16x32_bf16 v[46:49], v[94:97], v[130:133], v[46:49]
	v_mfma_f32_16x16x32_bf16 v[42:45], v[94:97], v[142:145], v[42:45]
	s_waitcnt lgkmcnt(0)
	v_mfma_f32_16x16x32_bf16 v[38:41], v[192:195], v[138:141], v[38:41]
	v_mfma_f32_16x16x32_bf16 v[34:37], v[192:195], v[156:159], v[34:37]
	v_mfma_f32_16x16x32_bf16 v[196:199], v[74:77], v[156:159], v[58:61]
	v_mfma_f32_16x16x32_bf16 v[242:245], v[184:187], v[138:141], v[46:49]
	v_mfma_f32_16x16x32_bf16 v[246:249], v[184:187], v[156:159], v[42:45]
	s_setprio 0
	s_setprio 1
	v_mfma_f32_16x16x32_bf16 v[22:25], v[78:81], v[106:109], v[22:25]
	v_mfma_f32_16x16x32_bf16 v[18:21], v[78:81], v[122:125], v[18:21]
	v_mfma_f32_16x16x32_bf16 v[6:9], v[188:191], v[106:109], v[6:9]
	v_mfma_f32_16x16x32_bf16 v[30:33], v[66:69], v[106:109], v[30:33]
	v_mfma_f32_16x16x32_bf16 v[26:29], v[66:69], v[122:125], v[26:29]
	v_mfma_f32_16x16x32_bf16 v[22:25], v[90:93], v[110:113], v[22:25]
	v_mfma_f32_16x16x32_bf16 v[18:21], v[90:93], v[212:215], v[18:21]
	v_mfma_f32_16x16x32_bf16 v[14:17], v[94:97], v[106:109], v[14:17]
	v_mfma_f32_16x16x32_bf16 v[10:13], v[94:97], v[122:125], v[10:13]
	v_mfma_f32_16x16x32_bf16 v[6:9], v[192:195], v[110:113], v[6:9]
	v_mfma_f32_16x16x32_bf16 v[2:5], v[188:191], v[122:125], v[2:5]
	v_mfma_f32_16x16x32_bf16 v[130:133], v[74:77], v[110:113], v[30:33]
	v_mfma_f32_16x16x32_bf16 v[136:139], v[74:77], v[212:215], v[26:29]
	v_mfma_f32_16x16x32_bf16 v[140:143], v[184:187], v[110:113], v[14:17]
	v_mfma_f32_16x16x32_bf16 v[156:159], v[184:187], v[212:215], v[10:13]
	v_mfma_f32_16x16x32_bf16 v[184:187], v[192:195], v[212:215], v[2:5]
	s_setprio 0
	v_add_u32_e32 v26, 0x18000, v160
	s_barrier
	ds_read_b128 v[2:5], v26
	ds_read_b128 v[10:13], v26 offset:1024
	ds_read_b128 v[14:17], v26 offset:2048
	ds_read_b128 v[188:191], v26 offset:3072
	ds_read_b128 v[26:29], v134 offset:32768
	ds_read_b128 v[30:33], v134 offset:33792
	ds_read_b128 v[42:45], v134 offset:34816
	ds_read_b128 v[46:49], v134 offset:35840
	ds_read_b128 v[58:61], v134 offset:36864
	ds_read_b128 v[66:69], v134 offset:37888
	ds_read_b128 v[192:195], v134 offset:38912
	ds_read_b128 v[212:215], v134 offset:39936
	s_waitcnt vmcnt(2)
	s_barrier
	s_waitcnt lgkmcnt(0)
	s_setprio 1
	s_waitcnt lgkmcnt(7)
	v_mfma_f32_16x16x32_bf16 v[74:77], v[26:29], v[2:5], v[126:129]
	s_waitcnt lgkmcnt(6)
	v_mfma_f32_16x16x32_bf16 v[122:125], v[30:33], v[10:13], v[74:77]
	v_mfma_f32_16x16x32_bf16 v[74:77], v[26:29], v[14:17], v[200:203]
	v_mfma_f32_16x16x32_bf16 v[126:129], v[30:33], v[188:191], v[74:77]
	s_waitcnt lgkmcnt(5)
	v_mfma_f32_16x16x32_bf16 v[74:77], v[42:45], v[2:5], v[118:121]
	s_waitcnt lgkmcnt(4)
	v_mfma_f32_16x16x32_bf16 v[106:109], v[46:49], v[10:13], v[74:77]
	v_mfma_f32_16x16x32_bf16 v[74:77], v[42:45], v[14:17], v[114:117]
	v_mfma_f32_16x16x32_bf16 v[110:113], v[46:49], v[188:191], v[74:77]
	s_waitcnt lgkmcnt(3)
	v_mfma_f32_16x16x32_bf16 v[74:77], v[58:61], v[2:5], v[204:207]
	s_waitcnt lgkmcnt(2)
	v_mfma_f32_16x16x32_bf16 v[90:93], v[66:69], v[10:13], v[74:77]
	v_mfma_f32_16x16x32_bf16 v[74:77], v[58:61], v[14:17], v[208:211]
	v_mfma_f32_16x16x32_bf16 v[94:97], v[66:69], v[188:191], v[74:77]
	s_waitcnt lgkmcnt(1)
	v_mfma_f32_16x16x32_bf16 v[74:77], v[192:195], v[2:5], v[102:105]
	v_mfma_f32_16x16x32_bf16 v[78:81], v[192:195], v[14:17], v[98:101]
	s_waitcnt lgkmcnt(0)
	v_mfma_f32_16x16x32_bf16 v[74:77], v[212:215], v[10:13], v[74:77]
	v_mfma_f32_16x16x32_bf16 v[78:81], v[212:215], v[188:191], v[78:81]
	s_setprio 0
	v_add_u32_e32 v98, 0x1c000, v160
	s_barrier
; #define WAIT_V(n) asm volatile("s_waitcnt vmcnt(" #n ")" ::: "memory")
; #define WAIT_L(n) asm volatile("s_waitcnt lgkmcnt(" #n ")" ::: "memory")
; #define BAR __builtin_amdgcn_s_barrier()
; #define LDA8(b, h) _Pragma("unroll") for (int m = 0; m < 4; ++m) _Pragma("unroll") for (int k = 0; k < 2; ++k) \
;     At[m][k] = *(const bf16x8*)(SA_(shm, b, h) + abase + (m * 2 + k) * 1024)
; #define LDB8(dst, b, h) _Pragma("unroll") for (int n = 0; n < 2; ++n) _Pragma("unroll") for (int k = 0; k < 2; ++k) \
;     dst[n][k] = *(const bf16x8*)(SB_(shm, b, h) + bbase + (n * 2 + k) * 1024)
; #define MMA8(ai, bj, Bx) do { __builtin_amdgcn_s_setprio(1); \
;     _Pragma("unroll") for (int m = 0; m < 4; ++m) _Pragma("unroll") for (int n = 0; n < 2; ++n) _Pragma("unroll") for (int k = 0; k < 2; ++k) \
;       acc[ai][bj][m][n] = __builtin_amdgcn_mfma_f32_16x16x32_bf16(At[m][k], Bx[n][k], acc[ai][bj][m][n], 0, 0, 0); \
;     __builtin_amdgcn_s_setprio(0); } while (0)
; template <bool HS>
; __device__ __forceinline__ void gemm_tile8(const u16* __restrict__ Ap, const u16* __restrict__ Bp, int K,
;                                            f32x4 (&acc)[2][2][4][2], char* shm, const int tid, const float* hsr = nullptr) {
;     ...
;     LDA8(0, 1); WAIT_V(4); BAR; WAIT_L(0); MMA8(1, 0, B0); MMA8(1, 1, B1); BAR; }
;   { LDB8(B0, 1, 0); LDA8(1, 0); WAIT_V(2); BAR; WAIT_L(0); MMA8(0, 0, B0); BAR;
;     LDB8(B1, 1, 1); WAIT_V(0); BAR; WAIT_L(0); MMA8(0, 1, B1); BAR;
;     LDA8(1, 1); BAR; WAIT_L(0); MMA8(1, 0, B0); MMA8(1, 1, B1); BAR; }
;   if (wr == 0) BAR;
	ds_read_b128 v[200:203], v98
	ds_read_b128 v[204:207], v98 offset:1024
	ds_read_b128 v[208:211], v98 offset:2048
	ds_read_b128 v[224:227], v98 offset:3072
	s_waitcnt vmcnt(0)
	s_barrier
	s_waitcnt lgkmcnt(0)
	s_setprio 1
	s_waitcnt lgkmcnt(3)
	v_mfma_f32_16x16x32_bf16 v[98:101], v[26:29], v[200:203], v[220:223]
	s_waitcnt lgkmcnt(1)
	v_mfma_f32_16x16x32_bf16 v[26:29], v[26:29], v[208:211], v[164:167]
	s_waitcnt lgkmcnt(0)
	v_mfma_f32_16x16x32_bf16 v[118:121], v[30:33], v[224:227], v[26:29]
	v_mfma_f32_16x16x32_bf16 v[26:29], v[42:45], v[200:203], v[86:89]
	v_mfma_f32_16x16x32_bf16 v[114:117], v[30:33], v[204:207], v[98:101]
	v_mfma_f32_16x16x32_bf16 v[98:101], v[46:49], v[204:207], v[26:29]
	v_mfma_f32_16x16x32_bf16 v[26:29], v[42:45], v[208:211], v[82:85]
	v_mfma_f32_16x16x32_bf16 v[102:105], v[46:49], v[224:227], v[26:29]
	v_mfma_f32_16x16x32_bf16 v[26:29], v[58:61], v[200:203], v[168:171]
	v_mfma_f32_16x16x32_bf16 v[82:85], v[66:69], v[204:207], v[26:29]
	v_mfma_f32_16x16x32_bf16 v[26:29], v[58:61], v[208:211], v[172:175]
	v_mfma_f32_16x16x32_bf16 v[86:89], v[66:69], v[224:227], v[26:29]
	v_mfma_f32_16x16x32_bf16 v[26:29], v[192:195], v[200:203], v[70:73]
	v_mfma_f32_16x16x32_bf16 v[66:69], v[212:215], v[204:207], v[26:29]
	v_mfma_f32_16x16x32_bf16 v[26:29], v[192:195], v[208:211], v[180:183]
	v_mfma_f32_16x16x32_bf16 v[70:73], v[212:215], v[224:227], v[26:29]
	s_setprio 0
	s_barrier
	ds_read_b128 v[164:167], v134 offset:49152
	ds_read_b128 v[168:171], v134 offset:50176
	ds_read_b128 v[172:175], v134 offset:51200
	ds_read_b128 v[180:183], v134 offset:52224
	ds_read_b128 v[192:195], v134 offset:53248
	ds_read_b128 v[212:215], v134 offset:54272
	ds_read_b128 v[220:223], v134 offset:55296
	ds_read_b128 v[228:231], v134 offset:56320
	s_barrier
	s_waitcnt lgkmcnt(0)
	s_setprio 1
	s_waitcnt lgkmcnt(7)
	v_mfma_f32_16x16x32_bf16 v[26:29], v[164:167], v[2:5], v[62:65]
	s_waitcnt lgkmcnt(6)
	v_mfma_f32_16x16x32_bf16 v[58:61], v[168:171], v[10:13], v[26:29]
	v_mfma_f32_16x16x32_bf16 v[26:29], v[164:167], v[14:17], v[196:199]
	v_mfma_f32_16x16x32_bf16 v[62:65], v[168:171], v[188:191], v[26:29]
	s_waitcnt lgkmcnt(5)
	v_mfma_f32_16x16x32_bf16 v[26:29], v[172:175], v[2:5], v[54:57]
	s_waitcnt lgkmcnt(4)
	v_mfma_f32_16x16x32_bf16 v[42:45], v[180:183], v[10:13], v[26:29]
	v_mfma_f32_16x16x32_bf16 v[26:29], v[172:175], v[14:17], v[50:53]
	v_mfma_f32_16x16x32_bf16 v[46:49], v[180:183], v[188:191], v[26:29]
	s_waitcnt lgkmcnt(3)
	v_mfma_f32_16x16x32_bf16 v[26:29], v[192:195], v[2:5], v[242:245]
	s_waitcnt lgkmcnt(1)
	v_mfma_f32_16x16x32_bf16 v[2:5], v[220:223], v[2:5], v[38:41]
	v_mfma_f32_16x16x32_bf16 v[26:29], v[212:215], v[10:13], v[26:29]
	v_mfma_f32_16x16x32_bf16 v[30:33], v[192:195], v[14:17], v[246:249]
	s_waitcnt lgkmcnt(0)
	v_mfma_f32_16x16x32_bf16 v[10:13], v[228:231], v[10:13], v[2:5]
	v_mfma_f32_16x16x32_bf16 v[2:5], v[220:223], v[14:17], v[34:37]
	v_mfma_f32_16x16x32_bf16 v[30:33], v[212:215], v[188:191], v[30:33]
	v_mfma_f32_16x16x32_bf16 v[14:17], v[228:231], v[188:191], v[2:5]
	s_setprio 0
	s_setprio 1
	v_mfma_f32_16x16x32_bf16 v[2:5], v[164:167], v[200:203], v[130:133]
	v_mfma_f32_16x16x32_bf16 v[50:53], v[168:171], v[204:207], v[2:5]
	v_mfma_f32_16x16x32_bf16 v[2:5], v[164:167], v[208:211], v[136:139]
	v_mfma_f32_16x16x32_bf16 v[54:57], v[168:171], v[224:227], v[2:5]
	v_mfma_f32_16x16x32_bf16 v[2:5], v[172:175], v[200:203], v[22:25]
	v_mfma_f32_16x16x32_bf16 v[34:37], v[180:183], v[204:207], v[2:5]
	v_mfma_f32_16x16x32_bf16 v[2:5], v[172:175], v[208:211], v[18:21]
	v_mfma_f32_16x16x32_bf16 v[38:41], v[180:183], v[224:227], v[2:5]
	v_mfma_f32_16x16x32_bf16 v[2:5], v[192:195], v[200:203], v[140:143]
	v_mfma_f32_16x16x32_bf16 v[18:21], v[212:215], v[204:207], v[2:5]
	v_mfma_f32_16x16x32_bf16 v[2:5], v[192:195], v[208:211], v[156:159]
	v_mfma_f32_16x16x32_bf16 v[22:25], v[212:215], v[224:227], v[2:5]
	v_mfma_f32_16x16x32_bf16 v[2:5], v[220:223], v[200:203], v[6:9]
	v_mfma_f32_16x16x32_bf16 v[6:9], v[220:223], v[208:211], v[184:187]
	v_mfma_f32_16x16x32_bf16 v[2:5], v[228:231], v[204:207], v[2:5]
	v_mfma_f32_16x16x32_bf16 v[6:9], v[228:231], v[224:227], v[6:9]
	s_setprio 0
	s_movk_i32 s0, 0x100
	v_cmp_gt_u32_e32 vcc, s0, v0
	s_barrier
	s_and_saveexec_b64 s[0:1], vcc
	s_cbranch_execz .LBB0_654
	s_barrier
; __device__ __forceinline__ unsigned pack2(float a, float b) { return (unsigned)f2bf(a) | ((unsigned)f2bf(b) << 16); }
; #define WAIT_V(n) asm volatile("s_waitcnt vmcnt(" #n ")" ::: "memory")
; template <int EPI, bool HS = false>
; __device__ __forceinline__ void gemm_phase(const Params& p, const GemmCfg& g, char* shm, const int wave_s) {
;     ...
;       const float* xin_t = g.xin + (size_t)orow0 * 1024 + pn * 256;
;       float* xout_t = g.xout + (size_t)orow0 * 1024 + pn * 256;
;       u16* xg_t = p.h + (size_t)orow0 * 1024 + pn * 256;
;       float* rss_t = p.rowss + (size_t)orow0 * 16 + pn * 4 + wc;
;       const unsigned tb = (unsigned)((wr * 64 + fq * 4) * 1024 + wc * 32 + 2 * fr);
;       const unsigned ldsb = (unsigned)(size_t)(__attribute__((address_space(3))) char*)shm;
;       const int wv_s = __builtin_amdgcn_readfirstlane(wid);
;       constexpr int XROW = 1040;
;       const char* xl = shm + (wr * 64 + fq * 4) * XROW + (wc * 32 + 2 * fr) * 4;
; #pragma unroll
;       for (int ai = 0; ai < 2; ++ai) {
; #pragma unroll
;         for (int i = 0; i < 16; ++i) {
;           const int r = wv_s * 16 + i;
;           glds_row(xin_t + (size_t)(ai * 128 + r) * 1024, (unsigned)lane * 16u, ldsb + (unsigned)(r * XROW));
;         }
;         WAIT_V(0);
;         __syncthreads();
; #pragma unroll
;         for (int m = 0; m < 4; ++m) {
;           float2 xv[4][2];
; #pragma unroll
;           for (int j = 0; j < 4; ++j)
; #pragma unroll
;             for (int bj = 0; bj < 2; ++bj) xv[j][bj] = *(const float2*)(xl + (m * 16 + j) * XROW + bj * 512);
; #pragma unroll
;           for (int j = 0; j < 4; ++j) {
;             float ss = 0.f;
; #pragma unroll
;             for (int bj = 0; bj < 2; ++bj) {
;               float2 xn;
;               xn.x = xv[j][bj].x + gt[bj][0] * acc[ai][bj][m][0][j];
;               xn.y = xv[j][bj].y + gt[bj][1] * acc[ai][bj][m][1][j];
;               const unsigned o = tb + (unsigned)((ai * 128 + m * 16 + j) * 1024 + bj * 128);
;               *(float2*)(xout_t + o) = xn;
;               if (g.has_next) *(unsigned*)(xg_t + o) = pack2(xn.x * gn[bj][0], xn.y * gn[bj][1]);
;               ss += xn.x * xn.x + xn.y * xn.y;
;             }
;             if (g.has_next) {
;               ss = dpp_row_sum16(ss);
;               if (fr == 0) rss_t[(wr * 64 + fq * 4 + ai * 128 + m * 16 + j) * 16] = ss;
;             }
.LBB0_654:
	s_or_b64 exec, exec, s[0:1]
	s_mov_b32 s0, s82
	s_mov_b32 s1, -1
	v_readlane_b32 s3, v254, 56
	v_mbcnt_lo_u32_b32 v0, s1, 0
	v_mbcnt_hi_u32_b32 v0, s1, v0
	v_lshl_add_u32 v0, s0, 6, v0
	s_lshl_b64 s[0:1], s[4:5], 12
	s_add_u32 s11, s3, s0
	v_readlane_b32 s3, v254, 55
	s_addc_u32 s12, s3, s1
	s_ashr_i32 s3, s2, 31
	s_lshl_b64 s[8:9], s[2:3], 2
	s_add_u32 s71, s11, s8
	s_addc_u32 s72, s12, s9
	v_readlane_b32 s12, v253, 25
	v_readlane_b32 s24, v253, 37
	v_readlane_b32 s25, v253, 38
	s_add_u32 s0, s24, s0
	s_addc_u32 s1, s25, s1
	s_add_u32 s0, s0, s8
	s_addc_u32 s1, s1, s9
	s_lshl_b64 s[8:9], s[4:5], 11
	s_add_u32 s8, s88, s8
	s_addc_u32 s9, s89, s9
	v_lshrrev_b32_e32 v132, 2, v0
	s_lshl_b64 s[2:3], s[2:3], 1
	v_ashrrev_i32_e32 v130, 6, v0
	v_ashrrev_i32_e32 v131, 2, v0
	v_and_b32_e32 v132, 12, v132
	s_add_u32 s2, s8, s2
	s_movk_i32 s8, 0xffc0
	v_and_or_b32 v163, v131, s8, v132
	v_readfirstlane_b32 s8, v130
	s_addc_u32 s3, s9, s3
	s_movk_i32 s9, 0x410
	s_lshl_b32 s8, s8, 4
	v_and_b32_e32 v169, 3, v130
	v_readlane_b32 s13, v253, 26
	v_mul_lo_u32 v130, v163, s9
	s_ashr_i32 s9, s8, 31
	s_lshl_b64 s[12:13], s[8:9], 12
	v_and_b32_e32 v168, 15, v0
	v_lshlrev_b32_e32 v0, 4, v0
	s_add_u32 s12, s71, s12
	s_mul_i32 s73, s8, 0x410
	v_and_b32_e32 v167, 0x3f0, v0
	s_addc_u32 s13, s72, s13
	s_add_i32 s73, s73, 0
	s_mov_b32 m0, s73
	s_nop 0
	global_load_lds_dwordx4 v167, s[12:13]
	s_or_b32 s12, s8, 1
	v_readlane_b32 s14, v253, 27
	v_readlane_b32 s15, v253, 28
	s_ashr_i32 s13, s12, 31
	s_lshl_b64 s[14:15], s[12:13], 12
	s_add_u32 s14, s71, s14
	s_addc_u32 s15, s72, s15
	s_mul_i32 s74, s12, 0x410
	s_or_b32 s12, s8, 2
	s_ashr_i32 s13, s12, 31
	s_add_i32 s74, s74, 0
	s_mov_b32 m0, s74
	s_nop 0
	global_load_lds_dwordx4 v167, s[14:15]
	s_lshl_b64 s[14:15], s[12:13], 12
	s_add_u32 s14, s71, s14
	s_mulk_i32 s12, 0x410
	s_addc_u32 s15, s72, s15
	s_add_i32 s12, s12, 0
	s_mov_b32 m0, s12
	s_nop 0
	global_load_lds_dwordx4 v167, s[14:15]
	s_or_b32 s14, s8, 3
	v_readlane_b32 s16, v253, 29
	v_readlane_b32 s17, v253, 30
	s_ashr_i32 s15, s14, 31
	s_lshl_b64 s[16:17], s[14:15], 12
	s_add_u32 s16, s71, s16
	s_addc_u32 s17, s72, s17
	s_mul_i32 s13, s14, 0x410
	s_or_b32 s14, s8, 4
	s_ashr_i32 s15, s14, 31
	s_add_i32 s13, s13, 0
	s_mov_b32 m0, s13
	s_nop 0
	global_load_lds_dwordx4 v167, s[16:17]
	s_lshl_b64 s[16:17], s[14:15], 12
	s_add_u32 s16, s71, s16
	s_mulk_i32 s14, 0x410
	s_addc_u32 s17, s72, s17
	s_add_i32 s14, s14, 0
	s_mov_b32 m0, s14
	s_nop 0
	global_load_lds_dwordx4 v167, s[16:17]
	s_or_b32 s16, s8, 5
	v_readlane_b32 s18, v253, 31
	v_readlane_b32 s19, v253, 32
	s_ashr_i32 s17, s16, 31
	s_lshl_b64 s[18:19], s[16:17], 12
	s_add_u32 s18, s71, s18
	s_addc_u32 s19, s72, s19
	s_mul_i32 s15, s16, 0x410
	s_or_b32 s16, s8, 6
	s_ashr_i32 s17, s16, 31
	s_add_i32 s15, s15, 0
	s_mov_b32 m0, s15
	s_nop 0
	global_load_lds_dwordx4 v167, s[18:19]
	s_lshl_b64 s[18:19], s[16:17], 12
	s_add_u32 s18, s71, s18
	s_mulk_i32 s16, 0x410
	s_addc_u32 s19, s72, s19
	s_add_i32 s16, s16, 0
	s_mov_b32 m0, s16
	s_nop 0
	global_load_lds_dwordx4 v167, s[18:19]
	s_or_b32 s18, s8, 7
	v_readlane_b32 s20, v253, 33
	v_readlane_b32 s21, v253, 34
	s_ashr_i32 s19, s18, 31
	s_lshl_b64 s[20:21], s[18:19], 12
	s_add_u32 s20, s71, s20
	s_addc_u32 s21, s72, s21
	s_mul_i32 s17, s18, 0x410
	s_or_b32 s18, s8, 8
	s_ashr_i32 s19, s18, 31
	s_add_i32 s17, s17, 0
	s_mov_b32 m0, s17
	s_nop 0
	global_load_lds_dwordx4 v167, s[20:21]
	s_lshl_b64 s[20:21], s[18:19], 12
	s_add_u32 s20, s71, s20
	s_mulk_i32 s18, 0x410
	s_addc_u32 s21, s72, s21
	s_add_i32 s18, s18, 0
	s_mov_b32 m0, s18
	s_nop 0
	global_load_lds_dwordx4 v167, s[20:21]
	s_or_b32 s20, s8, 9
	v_readlane_b32 s22, v253, 35
	v_readlane_b32 s23, v253, 36
	s_ashr_i32 s21, s20, 31
	s_lshl_b64 s[22:23], s[20:21], 12
	s_add_u32 s22, s71, s22
	s_addc_u32 s23, s72, s23
	s_mul_i32 s19, s20, 0x410
	s_or_b32 s20, s8, 10
	s_ashr_i32 s21, s20, 31
	s_add_i32 s19, s19, 0
	s_mov_b32 m0, s19
	s_nop 0
	global_load_lds_dwordx4 v167, s[22:23]
	s_lshl_b64 s[22:23], s[20:21], 12
	s_add_u32 s22, s71, s22
	s_mulk_i32 s20, 0x410
	s_addc_u32 s23, s72, s23
	s_add_i32 s20, s20, 0
	s_mov_b32 m0, s20
	s_nop 0
	global_load_lds_dwordx4 v167, s[22:23]
	s_or_b32 s22, s8, 11
	s_ashr_i32 s23, s22, 31
	s_lshl_b64 s[24:25], s[22:23], 12
	s_add_u32 s24, s71, s24
	s_addc_u32 s25, s72, s25
	s_mul_i32 s21, s22, 0x410
	s_or_b32 s22, s8, 12
	s_ashr_i32 s23, s22, 31
	s_add_i32 s21, s21, 0
	s_mov_b32 m0, s21
	s_nop 0
	global_load_lds_dwordx4 v167, s[24:25]
	s_lshl_b64 s[24:25], s[22:23], 12
	s_add_u32 s24, s71, s24
	s_mulk_i32 s22, 0x410
	s_addc_u32 s25, s72, s25
	s_add_i32 s22, s22, 0
	s_mov_b32 m0, s22
	s_nop 0
	global_load_lds_dwordx4 v167, s[24:25]
	s_or_b32 s24, s8, 13
	v_readlane_b32 s26, v253, 39
	v_readlane_b32 s27, v253, 40
	s_ashr_i32 s25, s24, 31
	s_lshl_b64 s[26:27], s[24:25], 12
	s_add_u32 s26, s71, s26
	s_addc_u32 s27, s72, s27
	s_mul_i32 s23, s24, 0x410
	s_or_b32 s24, s8, 14
	s_ashr_i32 s25, s24, 31
	s_add_i32 s23, s23, 0
	s_mov_b32 m0, s23
	s_nop 0
	global_load_lds_dwordx4 v167, s[26:27]
	s_lshl_b64 s[26:27], s[24:25], 12
	s_add_u32 s26, s71, s26
	s_mulk_i32 s24, 0x410
	v_lshlrev_b32_e32 v132, 5, v169
	v_lshlrev_b32_e32 v133, 1, v168
	s_addc_u32 s27, s72, s27
	s_add_i32 s24, s24, 0
	s_mov_b32 m0, s24
	s_nop 0
	global_load_lds_dwordx4 v167, s[26:27]
	s_or_b32 s26, s8, 15
	v_or_b32_e32 v134, v132, v133
	s_ashr_i32 s27, s26, 31
	v_add_u32_e32 v130, 0, v130
	v_lshlrev_b32_e32 v134, 2, v134
	s_lshl_b64 s[76:77], s[26:27], 12
	v_add_u32_e32 v164, v130, v134
	s_add_u32 s76, s71, s76
	s_mul_i32 s25, s26, 0x410
	v_lshlrev_b32_e32 v131, 10, v163
	s_addc_u32 s77, s72, s77
	s_add_i32 s25, s25, 0
	s_mov_b32 m0, s25
	s_nop 0
	global_load_lds_dwordx4 v167, s[76:77]
	v_add_u32_e32 v165, 32, v164
	v_add_u32_e32 v166, 48, v164
	v_or3_b32 v0, v131, v133, v132
	s_waitcnt vmcnt(0)
	s_barrier
	ds_read2st64_b64 v[142:145], v164 offset1:1
	ds_read2_b64 v[138:141], v164 offset0:130 offset1:194
	ds_read2st64_b64 v[134:137], v165 offset0:4 offset1:5
	ds_read2st64_b64 v[130:133], v166 offset0:6 offset1:7
	v_readlane_b32 s26, v254, 60
	v_mov_b32_e32 v156, v122
	v_mov_b32_e32 v157, v126
	v_readlane_b32 s27, v254, 61
	s_waitcnt lgkmcnt(3)
	v_pk_fma_f32 v[158:159], v[154:155], v[156:157], v[142:143]
	v_lshl_add_u64 v[160:161], v[0:1], 2, s[0:1]
	s_and_b64 vcc, exec, s[26:27]
	v_lshl_add_u64 v[156:157], v[0:1], 1, s[2:3]
	global_store_dwordx2 v[160:161], v[158:159], off
	s_cbranch_vccz .LBB0_656
	v_pk_mul_f32 v[142:143], v[148:149], v[158:159]
	s_nop 0
	v_and_b32_sdwa v126, v142, v178 dst_sel:DWORD dst_unused:UNUSED_PAD src0_sel:WORD_1 src1_sel:DWORD
	v_and_b32_sdwa v122, v143, v178 dst_sel:DWORD dst_unused:UNUSED_PAD src0_sel:WORD_1 src1_sel:DWORD
	v_add3_u32 v126, v142, v126, s81
	v_add3_u32 v122, v143, v122, s81
	v_lshrrev_b32_e32 v126, 16, v126
	v_and_or_b32 v122, v122, s28, v126
	global_store_dword v[156:157], v122, off

; __device__ __forceinline__ unsigned pack2(float a, float b) { return (unsigned)f2bf(a) | ((unsigned)f2bf(b) << 16); }
; #define WAIT_V(n) asm volatile("s_waitcnt vmcnt(" #n ")" ::: "memory")
; template <int EPI, bool HS = false>
; __device__ __forceinline__ void gemm_phase(const Params& p, const GemmCfg& g, char* shm, const int wave_s) {
;     ...
; #pragma unroll
;       for (int ai = 0; ai < 2; ++ai) {
; #pragma unroll
;         for (int i = 0; i < 16; ++i) {
;           const int r = wv_s * 16 + i;
;           glds_row(xin_t + (size_t)(ai * 128 + r) * 1024, (unsigned)lane * 16u, ldsb + (unsigned)(r * XROW));
;         }
;         WAIT_V(0);
;         __syncthreads();
; #pragma unroll
;         for (int m = 0; m < 4; ++m) {
;           float2 xv[4][2];
; #pragma unroll
;           for (int j = 0; j < 4; ++j)
; #pragma unroll
;             for (int bj = 0; bj < 2; ++bj) xv[j][bj] = *(const float2*)(xl + (m * 16 + j) * XROW + bj * 512);
; #pragma unroll
;           for (int j = 0; j < 4; ++j) {
;             float ss = 0.f;
; #pragma unroll
;             for (int bj = 0; bj < 2; ++bj) {
;               float2 xn;
;               xn.x = xv[j][bj].x + gt[bj][0] * acc[ai][bj][m][0][j];
;               xn.y = xv[j][bj].y + gt[bj][1] * acc[ai][bj][m][1][j];
;               const unsigned o = tb + (unsigned)((ai * 128 + m * 16 + j) * 1024 + bj * 128);
;               *(float2*)(xout_t + o) = xn;
;               if (g.has_next) *(unsigned*)(xg_t + o) = pack2(xn.x * gn[bj][0], xn.y * gn[bj][1]);
;               ss += xn.x * xn.x + xn.y * xn.y;
;             }
;             if (g.has_next) {
;               ss = dpp_row_sum16(ss);
;               if (fr == 0) rss_t[(wr * 64 + fq * 4 + ai * 128 + m * 16 + j) * 16] = ss;
;             }
.LBB0_748:
	s_lshl_b64 s[8:9], s[8:9], 12
	s_add_u32 s10, s71, s8
	s_addc_u32 s11, s72, s9
	s_add_u32 s8, s10, 0x80000
	s_addc_u32 s9, s11, 0
	s_waitcnt vmcnt(63) expcnt(7) lgkmcnt(15)
	s_barrier
	s_mov_b32 m0, s73
	s_nop 0
	global_load_lds_dwordx4 v167, s[8:9]
	s_add_u32 s8, s10, 0x81000
	s_addc_u32 s9, s11, 0
	s_mov_b32 m0, s74
	s_nop 0
	global_load_lds_dwordx4 v167, s[8:9]
	s_add_u32 s8, s10, 0x82000
	s_addc_u32 s9, s11, 0
	s_mov_b32 m0, s12
	s_nop 0
	global_load_lds_dwordx4 v167, s[8:9]
	s_add_u32 s8, s10, 0x83000
	s_addc_u32 s9, s11, 0
	s_mov_b32 m0, s13
	s_nop 0
	global_load_lds_dwordx4 v167, s[8:9]
	s_add_u32 s8, s10, 0x84000
	s_addc_u32 s9, s11, 0
	s_mov_b32 m0, s14
	s_nop 0
	global_load_lds_dwordx4 v167, s[8:9]
	s_add_u32 s8, s10, 0x85000
	s_addc_u32 s9, s11, 0
	s_mov_b32 m0, s15
	s_nop 0
	global_load_lds_dwordx4 v167, s[8:9]
	s_add_u32 s8, s10, 0x86000
	s_addc_u32 s9, s11, 0
	s_mov_b32 m0, s16
	s_nop 0
	global_load_lds_dwordx4 v167, s[8:9]
	s_add_u32 s8, s10, 0x87000
	s_addc_u32 s9, s11, 0
	s_mov_b32 m0, s17
	s_nop 0
	global_load_lds_dwordx4 v167, s[8:9]
	s_add_u32 s8, s10, 0x88000
	s_addc_u32 s9, s11, 0
	s_mov_b32 m0, s18
	s_nop 0
	global_load_lds_dwordx4 v167, s[8:9]
	s_add_u32 s8, s10, 0x89000
	s_addc_u32 s9, s11, 0
	s_mov_b32 m0, s19
	s_nop 0
	global_load_lds_dwordx4 v167, s[8:9]
	s_add_u32 s8, s10, 0x8a000
	s_addc_u32 s9, s11, 0
	s_mov_b32 m0, s20
	s_nop 0
	global_load_lds_dwordx4 v167, s[8:9]
	s_add_u32 s8, s10, 0x8b000
	s_addc_u32 s9, s11, 0
	s_mov_b32 m0, s21
	s_nop 0
	global_load_lds_dwordx4 v167, s[8:9]
	s_add_u32 s8, s10, 0x8c000
	s_addc_u32 s9, s11, 0
	s_mov_b32 m0, s22
	s_nop 0
	global_load_lds_dwordx4 v167, s[8:9]
	s_add_u32 s8, s10, 0x8d000
	s_addc_u32 s9, s11, 0
	s_mov_b32 m0, s23
	s_nop 0
	global_load_lds_dwordx4 v167, s[8:9]
	s_add_u32 s8, s10, 0x8e000
	s_addc_u32 s9, s11, 0
	s_mov_b32 m0, s24
	s_nop 0
	global_load_lds_dwordx4 v167, s[8:9]
	s_add_u32 s8, s10, 0x8f000
	s_addc_u32 s9, s11, 0
	s_mov_b32 m0, s25
	s_nop 0
	global_load_lds_dwordx4 v167, s[8:9]
	s_waitcnt vmcnt(0)
	s_barrier
	ds_read2st64_b64 v[78:81], v164 offset1:1
	ds_read2_b64 v[74:77], v164 offset0:130 offset1:194
	ds_read2st64_b64 v[70:73], v165 offset0:4 offset1:5
	ds_read2st64_b64 v[66:69], v166 offset0:6 offset1:7
	v_add_u32_e32 v84, 0x20000, v0
	v_mov_b32_e32 v82, v58
	v_mov_b32_e32 v83, v62
	v_mov_b32_e32 v85, v1
	s_waitcnt lgkmcnt(3)
	v_pk_fma_f32 v[82:83], v[154:155], v[82:83], v[78:79]
	v_lshl_add_u64 v[78:79], v[84:85], 2, s[0:1]
	global_store_dwordx2 v[78:79], v[82:83], off
	s_mov_b64 s[8:9], -1
	s_and_b64 vcc, exec, s[6:7]
	v_add_u32_e32 v78, 0x20080, v0
	s_cbranch_vccnz .LBB0_752
	v_pk_mul_f32 v[86:87], v[148:149], v[82:83]
	v_lshl_add_u64 v[84:85], v[84:85], 1, s[2:3]
	v_and_b32_sdwa v62, v86, v178 dst_sel:DWORD dst_unused:UNUSED_PAD src0_sel:WORD_1 src1_sel:DWORD
	v_and_b32_sdwa v58, v87, v178 dst_sel:DWORD dst_unused:UNUSED_PAD src0_sel:WORD_1 src1_sel:DWORD
	v_add3_u32 v62, v86, v62, s81
	v_add3_u32 v58, v87, v58, s81
	v_lshrrev_b32_e32 v62, 16, v62
	v_and_or_b32 v58, v58, s28, v62
	global_store_dword v[84:85], v58, off
	v_mov_b32_e32 v84, v50
	v_mov_b32_e32 v85, v54
	v_mov_b32_e32 v79, v1
	v_pk_fma_f32 v[84:85], v[150:151], v[84:85], v[80:81]
	v_lshl_add_u64 v[86:87], v[78:79], 2, s[0:1]
	global_store_dwordx2 v[86:87], v[84:85], off
	v_pk_mul_f32 v[86:87], v[152:153], v[84:85]
	v_pk_mul_f32 v[82:83], v[82:83], v[82:83]
	v_and_b32_sdwa v62, v86, v178 dst_sel:DWORD dst_unused:UNUSED_PAD src0_sel:WORD_1 src1_sel:DWORD
	v_and_b32_sdwa v58, v87, v178 dst_sel:DWORD dst_unused:UNUSED_PAD src0_sel:WORD_1 src1_sel:DWORD
	v_add3_u32 v62, v86, v62, s81
	v_add3_u32 v58, v87, v58, s81
	v_lshrrev_b32_e32 v62, 16, v62
	v_and_or_b32 v58, v58, s28, v62
	v_lshl_add_u64 v[86:87], v[78:79], 1, s[2:3]
	v_pk_mul_f32 v[84:85], v[84:85], v[84:85]
	global_store_dword v[86:87], v58, off
	v_add_f32_e32 v58, v84, v85
	v_add_f32_e32 v62, v82, v83
	v_add_f32_e32 v58, v62, v58
	s_nop 1
	v_add_f32_dpp v58, v58, v58 quad_perm:[1,0,3,2] row_mask:0xf bank_mask:0xf bound_ctrl:1
	s_nop 1
	v_add_f32_dpp v58, v58, v58 quad_perm:[2,3,0,1] row_mask:0xf bank_mask:0xf bound_ctrl:1
	s_nop 1
	v_add_f32_dpp v58, v58, v58 row_half_mirror row_mask:0xf bank_mask:0xf bound_ctrl:1
	s_nop 1
	v_mov_b32_dpp v62, v58 row_mirror row_mask:0xf bank_mask:0xf bound_ctrl:1
	s_and_saveexec_b64 s[8:9], s[4:5]
	s_cbranch_execz .LBB0_751
	v_add_f32_e32 v58, v58, v62
	v_mov_b32_e32 v62, 0x800
	v_lshl_add_u32 v82, v163, 4, v62
	v_ashrrev_i32_e32 v83, 31, v82
	v_lshl_add_u64 v[82:83], v[82:83], 2, v[142:143]
	global_store_dword v[82:83], v58, off

; #define STG_A(b, h, kt) stage_half_s(lds0 + ((b) * 2 + (h)) * HT_B, ((h) ? A1 : Ap) + (kt) * BK, off0, off1)
; #define STG_B(b, h, kt) stage_half_s(lds0 + (4 + (b) * 2 + (h)) * HT_B, ((h) ? B1p : Bp) + (kt) * BK, off0, off1)
; #define STG_A(b, h, kt) stage_half_s(lds0 + ((b) * 2 + (h)) * HT_B, ((h) ? A1 : Ap) + (kt) * BK, off0, off1)
; #define STG_B(b, h, kt) stage_half_s(lds0 + (4 + (b) * 2 + (h)) * HT_B, ((h) ? B1p : Bp) + (kt) * BK, off0, off1)
; __device__ __forceinline__ void stage_half_s(unsigned lds_half, const u16* gsrc, unsigned off0, unsigned off1) {
;   const unsigned long long ga = (unsigned long long)(size_t)gsrc;
;   const unsigned lo = __builtin_amdgcn_readfirstlane((unsigned)ga), hi = __builtin_amdgcn_readfirstlane((unsigned)(ga >> 32));
;   const void* sb = (const void*)(size_t)(((unsigned long long)hi << 32) | lo);
;   const unsigned la = __builtin_amdgcn_readfirstlane(lds_half);
;   glds16_s(sb, off0, la);
;   glds16_s(sb, off1, la + 8192u);
; }
; __device__ __forceinline__ void gemm8_prefetch(const u16* __restrict__ Ap, const u16* __restrict__ Bp, int K, char* shm, const int tid) {
;   int r0, c0, r1, c1;
;   stage_rc(tid * 16, r0, c0);
;   stage_rc(tid * 16 + 8192, r1, c1);
;   const unsigned off0 = (unsigned)(r0 * K + c0) * 2u, off1 = (unsigned)(r1 * K + c1) * 2u;
;   const int wvoff = __builtin_amdgcn_readfirstlane(tid >> 6) * 1024;
;   const u16* A1 = Ap + (size_t)128 * K;
;   const u16* B1p = Bp + (size_t)128 * K;
;   const unsigned lds0 = (unsigned)(size_t)(__attribute__((address_space(3))) char*)shm + (unsigned)wvoff;
;     ...
;   STG_B(0, 0, 0); STG_A(0, 0, 0); STG_B(0, 1, 0); STG_A(0, 1, 0);
;   STG_B(1, 0, 1); STG_A(1, 0, 1); STG_B(1, 1, 1);
;     ...
; }
.LBB0_850:
	s_andn2_b64 vcc, exec, s[0:1]
	s_cbranch_vccnz .LBB0_864
	v_readlane_b32 s0, v253, 6
	v_readlane_b32 s1, v253, 7
	s_andn2_b64 vcc, exec, s[0:1]
	s_cbranch_vccnz .LBB0_864
	s_mov_b32 s0, 0xb00000
	v_mul_hi_i32 v3, v162, s0
	v_mul_lo_u32 v2, v162, s0
	v_readlane_b32 s0, v253, 25
	v_readlane_b32 s1, v253, 26
	v_readlane_b32 s2, v253, 27
	v_readlane_b32 s3, v253, 28
	v_readlane_b32 s4, v253, 29
	v_readlane_b32 s5, v253, 30
	v_readlane_b32 s6, v253, 31
	v_readlane_b32 s7, v253, 32
	v_readlane_b32 s14, v253, 39
	v_readlane_b32 s15, v253, 40
	s_mov_b32 s0, 0x16000
	v_readlane_b32 s8, v253, 33
	v_lshl_add_u64 v[134:135], s[14:15], 0, v[2:3]
	v_mul_lo_u32 v2, v162, s0
	v_readlane_b32 s0, v252, 0
	v_readlane_b32 s1, v252, 1
	v_ashrrev_i32_e32 v3, 31, v2
	v_readlane_b32 s0, v253, 8
	v_lshlrev_b64 v[2:3], 2, v[2:3]
	v_readlane_b32 s4, v252, 4
	v_readlane_b32 s5, v252, 5
	v_readlane_b32 s1, v253, 9
	v_readlane_b32 s2, v252, 2
	v_lshl_add_u64 v[136:137], s[4:5], 0, v[2:3]
	v_lshl_add_u64 v[2:3], v[134:135], 0, s[0:1]
	s_mov_b32 s0, s82
	s_mov_b32 s1, -1
	v_readlane_b32 s3, v252, 3
	v_mbcnt_lo_u32_b32 v0, s1, 0
	v_mbcnt_hi_u32_b32 v0, s1, v0
	v_lshl_add_u32 v0, s0, 6, v0
	s_mov_b64 s[0:1], 0x40000
	v_bfe_i32 v6, v0, 27, 1
	v_lshlrev_b32_e32 v4, 4, v0
	v_lshrrev_b32_e32 v6, 22, v6
	v_add_u32_e32 v6, v4, v6
	v_and_b32_e32 v6, 0xfffffc00, v6
	v_ashrrev_i32_e32 v5, 31, v0
	v_sub_u32_e32 v6, v4, v6
	v_lshrrev_b32_e32 v5, 26, v5
	v_lshrrev_b32_e32 v7, 4, v6
	v_add_u32_e32 v5, v0, v5
	v_bitop3_b32 v7, v7, v6, 32 bitop3:0x6c
	v_ashrrev_i32_e32 v6, 31, v6
	v_ashrrev_i32_e32 v5, 6, v5
	v_lshrrev_b32_e32 v6, 26, v6
	v_lshlrev_b32_e32 v8, 3, v5
	v_add_u32_e32 v6, v7, v6
	v_and_b32_e32 v8, 0x1ffff0, v8
	v_ashrrev_i32_e32 v6, 6, v6
	v_add_u32_e32 v8, v6, v8
	v_mul_i32_i24_e32 v6, 64, v6
	v_add_u32_e32 v4, 0x2000, v4
	v_sub_u32_e32 v6, v7, v6
	v_ashrrev_i32_e32 v7, 31, v4
	v_lshrrev_b32_e32 v7, 22, v7
	v_add_u32_e32 v7, v4, v7
	v_ashrrev_i32_e32 v7, 10, v7
	v_mul_i32_i24_e32 v9, 0x400, v7
	v_sub_u32_e32 v4, v4, v9
	v_lshrrev_b32_e32 v9, 4, v4
	v_bitop3_b32 v4, v9, v4, 32 bitop3:0x6c
	v_ashrrev_i32_e32 v10, 31, v4
	v_lshrrev_b32_e32 v10, 26, v10
	v_add_u32_e32 v10, v4, v10
	v_lshlrev_b32_e32 v5, 5, v5
	v_lshlrev_b32_e32 v9, 3, v7
	v_lshrrev_b32_e32 v11, 6, v10
	v_and_b32_e32 v10, 0xc0, v10
	v_readfirstlane_b32 s2, v0
	v_and_b32_e32 v5, 32, v5
	v_ashrrev_i16_sdwa v6, v178, sext(v6) dst_sel:DWORD dst_unused:UNUSED_PAD src0_sel:DWORD src1_sel:BYTE_0
	v_and_b32_e32 v9, 0x1ffff0, v9
	v_lshlrev_b32_e32 v7, 5, v7
	v_sub_u32_e32 v4, v4, v10
	s_lshl_b32 s2, s2, 4
	v_bfe_i32 v6, v6, 0, 16
	v_add_u32_e32 v9, v11, v9
	v_and_b32_e32 v7, 32, v7
	v_ashrrev_i16_sdwa v4, v178, sext(v4) dst_sel:DWORD dst_unused:UNUSED_PAD src0_sel:DWORD src1_sel:BYTE_0
	v_lshl_or_b32 v5, v8, 10, v5
	s_and_b32 s2, s2, 0xfffffc00
	v_bfe_i32 v4, v4, 0, 16
	v_add_lshl_u32 v6, v5, v6, 1
	v_lshl_or_b32 v5, v9, 10, v7
	s_add_i32 s2, s2, 0
	v_add_lshl_u32 v7, v5, v4, 1
	v_lshl_add_u64 v[4:5], v[2:3], 0, s[0:1]
	v_readfirstlane_b32 s1, v3
	v_readfirstlane_b32 s0, v2
	s_add_i32 s3, s2, 0x10000
	s_mov_b32 m0, s3
	s_nop 2
	global_load_lds_dwordx4 v6, s[0:1]
	s_add_i32 s3, s2, 0x12000
	s_mov_b32 m0, s3
	s_nop 0
	global_load_lds_dwordx4 v7, s[0:1]
	s_add_i32 s3, s2, 0x14000
	v_readlane_b32 s4, v253, 12
	v_readlane_b32 s5, v253, 13
	s_mov_b32 m0, s2
	s_nop 3
	global_load_lds_dwordx4 v6, s[4:5]
	s_add_i32 s0, s2, 0x2000
	s_mov_b32 m0, s0
	s_nop 0
	global_load_lds_dwordx4 v7, s[4:5]
	v_readfirstlane_b32 s0, v4
	v_readfirstlane_b32 s1, v5
	s_mov_b32 m0, s3
	s_nop 3
	global_load_lds_dwordx4 v6, s[0:1]
	s_add_i32 s3, s2, 0x16000
	s_mov_b32 m0, s3
	s_nop 0
	global_load_lds_dwordx4 v7, s[0:1]
	s_add_i32 s0, s2, 0x4000
	v_readlane_b32 s4, v253, 10
	v_readlane_b32 s5, v253, 11
	s_mov_b32 m0, s0
	s_nop 3
	global_load_lds_dwordx4 v6, s[4:5]
	s_add_i32 s0, s2, 0x6000
	s_mov_b32 m0, s0
	s_nop 0
	global_load_lds_dwordx4 v7, s[4:5]
	s_mov_b64 s[0:1], 0x80
	v_lshl_add_u64 v[4:5], v[2:3], 0, s[0:1]
	s_add_i32 s3, s2, 0x18000
	v_readfirstlane_b32 s1, v5
	v_readfirstlane_b32 s0, v4
	s_mov_b32 m0, s3
	s_nop 3
	global_load_lds_dwordx4 v6, s[0:1]
	s_add_i32 s3, s2, 0x1a000
	s_mov_b32 m0, s3
	s_nop 0
	global_load_lds_dwordx4 v7, s[0:1]
	s_add_i32 s0, s2, 0x8000
	v_readlane_b32 s4, v253, 14
	v_readlane_b32 s5, v253, 15
	s_mov_b32 m0, s0
	s_nop 3
	global_load_lds_dwordx4 v6, s[4:5]
	s_add_i32 s0, s2, 0xa000
	s_mov_b32 m0, s0
	s_nop 0
	global_load_lds_dwordx4 v7, s[4:5]
	s_mov_b64 s[0:1], 0x40080
	v_lshl_add_u64 v[2:3], v[2:3], 0, s[0:1]
	s_add_i32 s3, s2, 0x1c000
	v_readfirstlane_b32 s1, v3
	v_readfirstlane_b32 s0, v2
	s_mov_b32 m0, s3
	s_nop 3
	global_load_lds_dwordx4 v6, s[0:1]
	s_add_i32 s2, s2, 0x1e000
	s_mov_b32 m0, s2
	s_nop 0
	global_load_lds_dwordx4 v7, s[0:1]
	s_mov_b32 s8, s45
	v_readlane_b32 s9, v253, 34
	v_readlane_b32 s10, v253, 35
	v_readlane_b32 s11, v253, 36
	v_readlane_b32 s12, v253, 37
	v_readlane_b32 s13, v253, 38
	v_readlane_b32 s6, v252, 6
	v_readlane_b32 s7, v252, 7
	s_branch .LBB0_854
; #define SCHED __builtin_amdgcn_sched_barrier(0)
; __device__ __forceinline__ float silu_f(float g) {
;   return g * __builtin_amdgcn_rcpf(1.0f + __builtin_amdgcn_exp2f(-1.4426950408889634f * g));
; }
; template <int EPI, bool HS = false>
; __device__ __forceinline__ void gemm_phase(const Params& p, const GemmCfg& g, char* shm, const int wave_s) {
;     ...
;     } else if constexpr (EPI == EPI_SWIGLU) {
;       u16* ot = g.o16 + (size_t)orow0 * DFF + pn * 128;
;       const unsigned tb = (unsigned)((wr * 64 + fq * 4) * DFF + wc * 16 + fr);
; #pragma unroll
;       for (int ai = 0; ai < 2; ++ai)
; #pragma unroll
;         for (int m = 0; m < 4; ++m) {
;           const f32x4 r4 = *(const f32x4*)(rsw + ai * 128 + m * 16);
; #pragma unroll
;           for (int j = 0; j < 4; ++j)
; #pragma unroll
;             for (int bj = 0; bj < 2; ++bj) {
;               float gv = r4[j] * acc[ai][bj][m][0][j] + swv[bj][0], uv = r4[j] * acc[ai][bj][m][1][j] + swv[bj][1];
;               ot[tb + (ai * 128 + m * 16 + j) * DFF + bj * 64] = f2bf(silu_f(gv) * uv);
;             }
;           SCHED;
;         }
.LBB0_853:
	s_mov_b32 s5, -1
	v_mbcnt_lo_u32_b32 v0, s5, 0
	v_mbcnt_hi_u32_b32 v0, s5, v0
	s_mul_hi_i32 s3, s4, 0x1600
	s_mulk_i32 s4, 0x1600
	s_add_u32 s4, s90, s4
	s_addc_u32 s5, s91, s3
	s_lshl_b32 s2, s2, 7
	s_ashr_i32 s3, s2, 31
	s_lshl_b64 s[2:3], s[2:3], 1
	s_add_u32 s2, s4, s2
	s_addc_u32 s3, s5, s3
	v_and_b32_e32 v130, 15, v0
	v_lshrrev_b32_e32 v131, 4, v0
	v_lshrrev_b32_e32 v132, 2, v0
	v_and_b32_e32 v133, 3, v0
	s_andn2_b32 s4, s82, 3
	s_lshl_b32 s4, s4, 6
	v_lshl_add_u32 v142, v131, 4, s9
	v_add_u32_e32 v142, s4, v142
	ds_read_b128 v[146:149], v142
	ds_read_b128 v[150:153], v142 offset:64
	ds_read_b128 v[154:157], v142 offset:128
	ds_read_b128 v[158:161], v142 offset:192
	ds_read_b128 v[162:165], v142 offset:512
	ds_read_b128 v[166:169], v142 offset:576
	ds_read_b128 v[170:173], v142 offset:640
	ds_read_b128 v[174:177], v142 offset:704
	s_mul_i32 s4, s4, 0x580
	v_mul_u32_u24_e32 v145, 0x1600, v132
	v_add_u32_e32 v145, s4, v145
	s_and_b32 s5, s82, 3
	s_lshl_b32 s5, s5, 6
	v_lshl_add_u32 v145, v133, 4, v145
	v_add_u32_e32 v145, s5, v145
	s_lshl_b32 s5, s82, 10
	s_add_i32 s5, s5, 0x20800
	v_lshlrev_b32_e32 v143, 8, v131
	v_lshl_add_u32 v143, v130, 2, v143
	v_add_u32_e32 v143, s5, v143
	v_lshl_add_u32 v144, v0, 4, s5
	s_waitcnt lgkmcnt(0)
	v_fma_f32 v122, v122, v146, v140
	v_fma_f32 v114, v114, v146, v138
	v_mul_f32_e32 v188, 0xbfb8aa3b, v122
	v_mul_f32_e32 v189, 0xbfb8aa3b, v114
	v_exp_f32_e32 v188, v188
	v_exp_f32_e32 v189, v189
	v_fma_f32 v126, v126, v146, v141
	v_add_f32_e32 v188, 1.0, v188
	v_add_f32_e32 v189, 1.0, v189
	v_rcp_f32_e32 v188, v188
	v_rcp_f32_e32 v189, v189
	v_fma_f32 v118, v118, v146, v139
	v_mul_f32_e32 v122, v122, v188
	v_mul_f32_e32 v114, v114, v189
	v_mul_f32_e32 v122, v126, v122
	v_mul_f32_e32 v114, v118, v114
	v_cvt_pk_bf16_f32 v190, v122, v114
	v_fma_f32 v123, v123, v147, v140
	v_fma_f32 v115, v115, v147, v138
	v_mul_f32_e32 v188, 0xbfb8aa3b, v123
	v_mul_f32_e32 v189, 0xbfb8aa3b, v115
	v_exp_f32_e32 v188, v188
	v_exp_f32_e32 v189, v189
	v_fma_f32 v127, v127, v147, v141
	v_add_f32_e32 v188, 1.0, v188
	v_add_f32_e32 v189, 1.0, v189
	v_rcp_f32_e32 v188, v188
	v_rcp_f32_e32 v189, v189
	v_fma_f32 v119, v119, v147, v139
	v_mul_f32_e32 v123, v123, v188
	v_mul_f32_e32 v115, v115, v189
	v_mul_f32_e32 v123, v127, v123
	v_mul_f32_e32 v115, v119, v115
	v_cvt_pk_bf16_f32 v191, v123, v115
	v_fma_f32 v124, v124, v148, v140
	v_fma_f32 v116, v116, v148, v138
	v_mul_f32_e32 v188, 0xbfb8aa3b, v124
	v_mul_f32_e32 v189, 0xbfb8aa3b, v116
	v_exp_f32_e32 v188, v188
	v_exp_f32_e32 v189, v189
	v_fma_f32 v128, v128, v148, v141
	v_add_f32_e32 v188, 1.0, v188
	v_add_f32_e32 v189, 1.0, v189
	v_rcp_f32_e32 v188, v188
	v_rcp_f32_e32 v189, v189
	v_fma_f32 v120, v120, v148, v139
	v_mul_f32_e32 v124, v124, v188
	v_mul_f32_e32 v116, v116, v189
	v_mul_f32_e32 v124, v128, v124
	v_mul_f32_e32 v116, v120, v116
	v_cvt_pk_bf16_f32 v192, v124, v116
	v_fma_f32 v125, v125, v149, v140
	v_fma_f32 v117, v117, v149, v138
	v_mul_f32_e32 v188, 0xbfb8aa3b, v125
	v_mul_f32_e32 v189, 0xbfb8aa3b, v117
	v_exp_f32_e32 v188, v188
	v_exp_f32_e32 v189, v189
	v_fma_f32 v129, v129, v149, v141
	v_add_f32_e32 v188, 1.0, v188
	v_add_f32_e32 v189, 1.0, v189
	v_rcp_f32_e32 v188, v188
	v_rcp_f32_e32 v189, v189
	v_fma_f32 v121, v121, v149, v139
	v_mul_f32_e32 v125, v125, v188
	v_mul_f32_e32 v117, v117, v189
	v_mul_f32_e32 v125, v129, v125
	v_mul_f32_e32 v117, v121, v117
	v_cvt_pk_bf16_f32 v193, v125, v117
	s_waitcnt lgkmcnt(0)
	ds_write_b32 v143, v190
	ds_write_b32 v143, v191 offset:64
	ds_write_b32 v143, v192 offset:128
	ds_write_b32 v143, v193 offset:192
	ds_read_b128 v[180:183], v144
	v_fma_f32 v106, v106, v150, v140
	v_fma_f32 v98, v98, v150, v138
	v_mul_f32_e32 v188, 0xbfb8aa3b, v106
	v_mul_f32_e32 v189, 0xbfb8aa3b, v98
	v_exp_f32_e32 v188, v188
	v_exp_f32_e32 v189, v189
	v_fma_f32 v110, v110, v150, v141
	v_add_f32_e32 v188, 1.0, v188
	v_add_f32_e32 v189, 1.0, v189
	v_rcp_f32_e32 v188, v188
	v_rcp_f32_e32 v189, v189
	v_fma_f32 v102, v102, v150, v139
	v_mul_f32_e32 v106, v106, v188
	v_mul_f32_e32 v98, v98, v189
	v_mul_f32_e32 v106, v110, v106
	v_mul_f32_e32 v98, v102, v98
	v_cvt_pk_bf16_f32 v190, v106, v98
	v_fma_f32 v107, v107, v151, v140
	v_fma_f32 v99, v99, v151, v138
	v_mul_f32_e32 v188, 0xbfb8aa3b, v107
	v_mul_f32_e32 v189, 0xbfb8aa3b, v99
	v_exp_f32_e32 v188, v188
	v_exp_f32_e32 v189, v189
	v_fma_f32 v111, v111, v151, v141
	v_add_f32_e32 v188, 1.0, v188
	v_add_f32_e32 v189, 1.0, v189
	v_rcp_f32_e32 v188, v188
	v_rcp_f32_e32 v189, v189
	v_fma_f32 v103, v103, v151, v139
	v_mul_f32_e32 v107, v107, v188
	v_mul_f32_e32 v99, v99, v189
	v_mul_f32_e32 v107, v111, v107
	v_mul_f32_e32 v99, v103, v99
	v_cvt_pk_bf16_f32 v191, v107, v99
	v_fma_f32 v108, v108, v152, v140
	v_fma_f32 v100, v100, v152, v138
	v_mul_f32_e32 v188, 0xbfb8aa3b, v108
	v_mul_f32_e32 v189, 0xbfb8aa3b, v100
	v_exp_f32_e32 v188, v188
	v_exp_f32_e32 v189, v189
	v_fma_f32 v112, v112, v152, v141
	v_add_f32_e32 v188, 1.0, v188
	v_add_f32_e32 v189, 1.0, v189
	v_rcp_f32_e32 v188, v188
	v_rcp_f32_e32 v189, v189
	v_fma_f32 v104, v104, v152, v139
	v_mul_f32_e32 v108, v108, v188
	v_mul_f32_e32 v100, v100, v189
	v_mul_f32_e32 v108, v112, v108
	v_mul_f32_e32 v100, v104, v100
	v_cvt_pk_bf16_f32 v192, v108, v100
	v_fma_f32 v109, v109, v153, v140
	v_fma_f32 v101, v101, v153, v138
	v_mul_f32_e32 v188, 0xbfb8aa3b, v109
	v_mul_f32_e32 v189, 0xbfb8aa3b, v101
	v_exp_f32_e32 v188, v188
	v_exp_f32_e32 v189, v189
	v_fma_f32 v113, v113, v153, v141
	v_add_f32_e32 v188, 1.0, v188
	v_add_f32_e32 v189, 1.0, v189
	v_rcp_f32_e32 v188, v188
	v_rcp_f32_e32 v189, v189
	v_fma_f32 v105, v105, v153, v139
	v_mul_f32_e32 v109, v109, v188
	v_mul_f32_e32 v101, v101, v189
	v_mul_f32_e32 v109, v113, v109
	v_mul_f32_e32 v101, v105, v101
	v_cvt_pk_bf16_f32 v193, v109, v101
	s_waitcnt lgkmcnt(0)
; #define SCHED __builtin_amdgcn_sched_barrier(0)
; template <int EPI, bool HS = false>
; __device__ __forceinline__ void gemm_phase(const Params& p, const GemmCfg& g, char* shm, const int wave_s) {
;     ...
; #pragma unroll
;           for (int j = 0; j < 4; ++j)
; #pragma unroll
;             for (int bj = 0; bj < 2; ++bj) {
;               float gv = r4[j] * acc[ai][bj][m][0][j] + swv[bj][0], uv = r4[j] * acc[ai][bj][m][1][j] + swv[bj][1];
;               ot[tb + (ai * 128 + m * 16 + j) * DFF + bj * 64] = f2bf(silu_f(gv) * uv);
;             }
;           SCHED;
	global_store_dwordx4 v145, v[180:183], s[2:3]
	s_add_u32 s2, s2, 0x16000
	s_addc_u32 s3, s3, 0
	ds_write_b32 v143, v190
	ds_write_b32 v143, v191 offset:64
	ds_write_b32 v143, v192 offset:128
	ds_write_b32 v143, v193 offset:192
	ds_read_b128 v[184:187], v144
	v_fma_f32 v90, v90, v154, v140
	v_fma_f32 v82, v82, v154, v138
	v_mul_f32_e32 v188, 0xbfb8aa3b, v90
	v_mul_f32_e32 v189, 0xbfb8aa3b, v82
	v_exp_f32_e32 v188, v188
	v_exp_f32_e32 v189, v189
	v_fma_f32 v94, v94, v154, v141
	v_add_f32_e32 v188, 1.0, v188
	v_add_f32_e32 v189, 1.0, v189
	v_rcp_f32_e32 v188, v188
	v_rcp_f32_e32 v189, v189
	v_fma_f32 v86, v86, v154, v139
	v_mul_f32_e32 v90, v90, v188
	v_mul_f32_e32 v82, v82, v189
	v_mul_f32_e32 v90, v94, v90
	v_mul_f32_e32 v82, v86, v82
	v_cvt_pk_bf16_f32 v190, v90, v82
	v_fma_f32 v91, v91, v155, v140
	v_fma_f32 v83, v83, v155, v138
	v_mul_f32_e32 v188, 0xbfb8aa3b, v91
	v_mul_f32_e32 v189, 0xbfb8aa3b, v83
	v_exp_f32_e32 v188, v188
	v_exp_f32_e32 v189, v189
	v_fma_f32 v95, v95, v155, v141
	v_add_f32_e32 v188, 1.0, v188
	v_add_f32_e32 v189, 1.0, v189
	v_rcp_f32_e32 v188, v188
	v_rcp_f32_e32 v189, v189
	v_fma_f32 v87, v87, v155, v139
	v_mul_f32_e32 v91, v91, v188
	v_mul_f32_e32 v83, v83, v189
	v_mul_f32_e32 v91, v95, v91
	v_mul_f32_e32 v83, v87, v83
	v_cvt_pk_bf16_f32 v191, v91, v83
	v_fma_f32 v92, v92, v156, v140
	v_fma_f32 v84, v84, v156, v138
	v_mul_f32_e32 v188, 0xbfb8aa3b, v92
	v_mul_f32_e32 v189, 0xbfb8aa3b, v84
	v_exp_f32_e32 v188, v188
	v_exp_f32_e32 v189, v189
	v_fma_f32 v96, v96, v156, v141
	v_add_f32_e32 v188, 1.0, v188
	v_add_f32_e32 v189, 1.0, v189
	v_rcp_f32_e32 v188, v188
	v_rcp_f32_e32 v189, v189
	v_fma_f32 v88, v88, v156, v139
	v_mul_f32_e32 v92, v92, v188
	v_mul_f32_e32 v84, v84, v189
	v_mul_f32_e32 v92, v96, v92
	v_mul_f32_e32 v84, v88, v84
	v_cvt_pk_bf16_f32 v192, v92, v84
	v_fma_f32 v93, v93, v157, v140
	v_fma_f32 v85, v85, v157, v138
	v_mul_f32_e32 v188, 0xbfb8aa3b, v93
	v_mul_f32_e32 v189, 0xbfb8aa3b, v85
	v_exp_f32_e32 v188, v188
	v_exp_f32_e32 v189, v189
	v_fma_f32 v97, v97, v157, v141
	v_add_f32_e32 v188, 1.0, v188
	v_add_f32_e32 v189, 1.0, v189
	v_rcp_f32_e32 v188, v188
	v_rcp_f32_e32 v189, v189
	v_fma_f32 v89, v89, v157, v139
	v_mul_f32_e32 v93, v93, v188
	v_mul_f32_e32 v85, v85, v189
	v_mul_f32_e32 v93, v97, v93
	v_mul_f32_e32 v85, v89, v85
	v_cvt_pk_bf16_f32 v193, v93, v85
	s_waitcnt lgkmcnt(0)
	global_store_dwordx4 v145, v[184:187], s[2:3]
	s_add_u32 s2, s2, 0x16000
	s_addc_u32 s3, s3, 0
	ds_write_b32 v143, v190
	ds_write_b32 v143, v191 offset:64
	ds_write_b32 v143, v192 offset:128
	ds_write_b32 v143, v193 offset:192
	ds_read_b128 v[180:183], v144
	v_fma_f32 v74, v74, v158, v140
	v_fma_f32 v66, v66, v158, v138
	v_mul_f32_e32 v188, 0xbfb8aa3b, v74
	v_mul_f32_e32 v189, 0xbfb8aa3b, v66
	v_exp_f32_e32 v188, v188
	v_exp_f32_e32 v189, v189
	v_fma_f32 v78, v78, v158, v141
	v_add_f32_e32 v188, 1.0, v188
	v_add_f32_e32 v189, 1.0, v189
	v_rcp_f32_e32 v188, v188
	v_rcp_f32_e32 v189, v189
	v_fma_f32 v70, v70, v158, v139
	v_mul_f32_e32 v74, v74, v188
	v_mul_f32_e32 v66, v66, v189
	v_mul_f32_e32 v74, v78, v74
	v_mul_f32_e32 v66, v70, v66
	v_cvt_pk_bf16_f32 v190, v74, v66
	v_fma_f32 v75, v75, v159, v140
	v_fma_f32 v67, v67, v159, v138
	v_mul_f32_e32 v188, 0xbfb8aa3b, v75
	v_mul_f32_e32 v189, 0xbfb8aa3b, v67
	v_exp_f32_e32 v188, v188
	v_exp_f32_e32 v189, v189
	v_fma_f32 v79, v79, v159, v141
	v_add_f32_e32 v188, 1.0, v188
	v_add_f32_e32 v189, 1.0, v189
	v_rcp_f32_e32 v188, v188
	v_rcp_f32_e32 v189, v189
	v_fma_f32 v71, v71, v159, v139
	v_mul_f32_e32 v75, v75, v188
	v_mul_f32_e32 v67, v67, v189
	v_mul_f32_e32 v75, v79, v75
	v_mul_f32_e32 v67, v71, v67
	v_cvt_pk_bf16_f32 v191, v75, v67
	v_fma_f32 v76, v76, v160, v140
	v_fma_f32 v68, v68, v160, v138
	v_mul_f32_e32 v188, 0xbfb8aa3b, v76
	v_mul_f32_e32 v189, 0xbfb8aa3b, v68
	v_exp_f32_e32 v188, v188
	v_exp_f32_e32 v189, v189
	v_fma_f32 v80, v80, v160, v141
	v_add_f32_e32 v188, 1.0, v188
	v_add_f32_e32 v189, 1.0, v189
	v_rcp_f32_e32 v188, v188
	v_rcp_f32_e32 v189, v189
	v_fma_f32 v72, v72, v160, v139
	v_mul_f32_e32 v76, v76, v188
	v_mul_f32_e32 v68, v68, v189
	v_mul_f32_e32 v76, v80, v76
	v_mul_f32_e32 v68, v72, v68
	v_cvt_pk_bf16_f32 v192, v76, v68
	v_fma_f32 v77, v77, v161, v140
	v_fma_f32 v69, v69, v161, v138
	v_mul_f32_e32 v188, 0xbfb8aa3b, v77
	v_mul_f32_e32 v189, 0xbfb8aa3b, v69
	v_exp_f32_e32 v188, v188
	v_exp_f32_e32 v189, v189
	v_fma_f32 v81, v81, v161, v141
	v_add_f32_e32 v188, 1.0, v188
	v_add_f32_e32 v189, 1.0, v189
	v_rcp_f32_e32 v188, v188
	v_rcp_f32_e32 v189, v189
	v_fma_f32 v73, v73, v161, v139
	v_mul_f32_e32 v77, v77, v188
	v_mul_f32_e32 v69, v69, v189
	v_mul_f32_e32 v77, v81, v77
	v_mul_f32_e32 v69, v73, v69
	v_cvt_pk_bf16_f32 v193, v77, v69
	s_waitcnt lgkmcnt(0)
; #define SCHED __builtin_amdgcn_sched_barrier(0)
; template <int EPI, bool HS = false>
; __device__ __forceinline__ void gemm_phase(const Params& p, const GemmCfg& g, char* shm, const int wave_s) {
;     ...
; #pragma unroll
;           for (int j = 0; j < 4; ++j)
; #pragma unroll
;             for (int bj = 0; bj < 2; ++bj) {
;               float gv = r4[j] * acc[ai][bj][m][0][j] + swv[bj][0], uv = r4[j] * acc[ai][bj][m][1][j] + swv[bj][1];
;               ot[tb + (ai * 128 + m * 16 + j) * DFF + bj * 64] = f2bf(silu_f(gv) * uv);
;             }
;           SCHED;
	global_store_dwordx4 v145, v[180:183], s[2:3]
	s_add_u32 s2, s2, 0x16000
	s_addc_u32 s3, s3, 0
	ds_write_b32 v143, v190
	ds_write_b32 v143, v191 offset:64
	ds_write_b32 v143, v192 offset:128
	ds_write_b32 v143, v193 offset:192
	ds_read_b128 v[184:187], v144
	v_fma_f32 v58, v58, v162, v140
	v_fma_f32 v50, v50, v162, v138
	v_mul_f32_e32 v188, 0xbfb8aa3b, v58
	v_mul_f32_e32 v189, 0xbfb8aa3b, v50
	v_exp_f32_e32 v188, v188
	v_exp_f32_e32 v189, v189
	v_fma_f32 v62, v62, v162, v141
	v_add_f32_e32 v188, 1.0, v188
	v_add_f32_e32 v189, 1.0, v189
	v_rcp_f32_e32 v188, v188
	v_rcp_f32_e32 v189, v189
	v_fma_f32 v54, v54, v162, v139
	v_mul_f32_e32 v58, v58, v188
	v_mul_f32_e32 v50, v50, v189
	v_mul_f32_e32 v58, v62, v58
	v_mul_f32_e32 v50, v54, v50
	v_cvt_pk_bf16_f32 v190, v58, v50
	v_fma_f32 v59, v59, v163, v140
	v_fma_f32 v51, v51, v163, v138
	v_mul_f32_e32 v188, 0xbfb8aa3b, v59
	v_mul_f32_e32 v189, 0xbfb8aa3b, v51
	v_exp_f32_e32 v188, v188
	v_exp_f32_e32 v189, v189
	v_fma_f32 v63, v63, v163, v141
	v_add_f32_e32 v188, 1.0, v188
	v_add_f32_e32 v189, 1.0, v189
	v_rcp_f32_e32 v188, v188
	v_rcp_f32_e32 v189, v189
	v_fma_f32 v55, v55, v163, v139
	v_mul_f32_e32 v59, v59, v188
	v_mul_f32_e32 v51, v51, v189
	v_mul_f32_e32 v59, v63, v59
	v_mul_f32_e32 v51, v55, v51
	v_cvt_pk_bf16_f32 v191, v59, v51
	v_fma_f32 v60, v60, v164, v140
	v_fma_f32 v52, v52, v164, v138
	v_mul_f32_e32 v188, 0xbfb8aa3b, v60
	v_mul_f32_e32 v189, 0xbfb8aa3b, v52
	v_exp_f32_e32 v188, v188
	v_exp_f32_e32 v189, v189
	v_fma_f32 v64, v64, v164, v141
	v_add_f32_e32 v188, 1.0, v188
	v_add_f32_e32 v189, 1.0, v189
	v_rcp_f32_e32 v188, v188
	v_rcp_f32_e32 v189, v189
	v_fma_f32 v56, v56, v164, v139
	v_mul_f32_e32 v60, v60, v188
	v_mul_f32_e32 v52, v52, v189
	v_mul_f32_e32 v60, v64, v60
	v_mul_f32_e32 v52, v56, v52
	v_cvt_pk_bf16_f32 v192, v60, v52
	v_fma_f32 v61, v61, v165, v140
	v_fma_f32 v53, v53, v165, v138
	v_mul_f32_e32 v188, 0xbfb8aa3b, v61
	v_mul_f32_e32 v189, 0xbfb8aa3b, v53
	v_exp_f32_e32 v188, v188
	v_exp_f32_e32 v189, v189
	v_fma_f32 v65, v65, v165, v141
	v_add_f32_e32 v188, 1.0, v188
	v_add_f32_e32 v189, 1.0, v189
	v_rcp_f32_e32 v188, v188
	v_rcp_f32_e32 v189, v189
	v_fma_f32 v57, v57, v165, v139
	v_mul_f32_e32 v61, v61, v188
	v_mul_f32_e32 v53, v53, v189
	v_mul_f32_e32 v61, v65, v61
	v_mul_f32_e32 v53, v57, v53
	v_cvt_pk_bf16_f32 v193, v61, v53
	s_waitcnt lgkmcnt(0)
	global_store_dwordx4 v145, v[184:187], s[2:3]
	s_add_u32 s2, s2, 0x6e000
	s_addc_u32 s3, s3, 0
	ds_write_b32 v143, v190
	ds_write_b32 v143, v191 offset:64
	ds_write_b32 v143, v192 offset:128
	ds_write_b32 v143, v193 offset:192
	ds_read_b128 v[180:183], v144
	v_fma_f32 v42, v42, v166, v140
	v_fma_f32 v34, v34, v166, v138
	v_mul_f32_e32 v188, 0xbfb8aa3b, v42
	v_mul_f32_e32 v189, 0xbfb8aa3b, v34
	v_exp_f32_e32 v188, v188
	v_exp_f32_e32 v189, v189
	v_fma_f32 v46, v46, v166, v141
	v_add_f32_e32 v188, 1.0, v188
	v_add_f32_e32 v189, 1.0, v189
	v_rcp_f32_e32 v188, v188
	v_rcp_f32_e32 v189, v189
	v_fma_f32 v38, v38, v166, v139
	v_mul_f32_e32 v42, v42, v188
	v_mul_f32_e32 v34, v34, v189
	v_mul_f32_e32 v42, v46, v42
	v_mul_f32_e32 v34, v38, v34
	v_cvt_pk_bf16_f32 v190, v42, v34
	v_fma_f32 v43, v43, v167, v140
	v_fma_f32 v35, v35, v167, v138
	v_mul_f32_e32 v188, 0xbfb8aa3b, v43
	v_mul_f32_e32 v189, 0xbfb8aa3b, v35
	v_exp_f32_e32 v188, v188
	v_exp_f32_e32 v189, v189
	v_fma_f32 v47, v47, v167, v141
	v_add_f32_e32 v188, 1.0, v188
	v_add_f32_e32 v189, 1.0, v189
	v_rcp_f32_e32 v188, v188
	v_rcp_f32_e32 v189, v189
	v_fma_f32 v39, v39, v167, v139
	v_mul_f32_e32 v43, v43, v188
	v_mul_f32_e32 v35, v35, v189
	v_mul_f32_e32 v43, v47, v43
	v_mul_f32_e32 v35, v39, v35
	v_cvt_pk_bf16_f32 v191, v43, v35
	v_fma_f32 v44, v44, v168, v140
	v_fma_f32 v36, v36, v168, v138
	v_mul_f32_e32 v188, 0xbfb8aa3b, v44
	v_mul_f32_e32 v189, 0xbfb8aa3b, v36
	v_exp_f32_e32 v188, v188
	v_exp_f32_e32 v189, v189
	v_fma_f32 v48, v48, v168, v141
	v_add_f32_e32 v188, 1.0, v188
	v_add_f32_e32 v189, 1.0, v189
	v_rcp_f32_e32 v188, v188
	v_rcp_f32_e32 v189, v189
	v_fma_f32 v40, v40, v168, v139
	v_mul_f32_e32 v44, v44, v188
	v_mul_f32_e32 v36, v36, v189
	v_mul_f32_e32 v44, v48, v44
	v_mul_f32_e32 v36, v40, v36
	v_cvt_pk_bf16_f32 v192, v44, v36
	v_fma_f32 v45, v45, v169, v140
	v_fma_f32 v37, v37, v169, v138
	v_mul_f32_e32 v188, 0xbfb8aa3b, v45
	v_mul_f32_e32 v189, 0xbfb8aa3b, v37
	v_exp_f32_e32 v188, v188
	v_exp_f32_e32 v189, v189
	v_fma_f32 v49, v49, v169, v141
	v_add_f32_e32 v188, 1.0, v188
	v_add_f32_e32 v189, 1.0, v189
	v_rcp_f32_e32 v188, v188
	v_rcp_f32_e32 v189, v189
	v_fma_f32 v41, v41, v169, v139
	v_mul_f32_e32 v45, v45, v188
	v_mul_f32_e32 v37, v37, v189
	v_mul_f32_e32 v45, v49, v45
	v_mul_f32_e32 v37, v41, v37
	v_cvt_pk_bf16_f32 v193, v45, v37
	s_waitcnt lgkmcnt(0)
; #define SCHED __builtin_amdgcn_sched_barrier(0)
; template <int EPI, bool HS = false>
; __device__ __forceinline__ void gemm_phase(const Params& p, const GemmCfg& g, char* shm, const int wave_s) {
;     ...
; #pragma unroll
;           for (int j = 0; j < 4; ++j)
; #pragma unroll
;             for (int bj = 0; bj < 2; ++bj) {
;               float gv = r4[j] * acc[ai][bj][m][0][j] + swv[bj][0], uv = r4[j] * acc[ai][bj][m][1][j] + swv[bj][1];
;               ot[tb + (ai * 128 + m * 16 + j) * DFF + bj * 64] = f2bf(silu_f(gv) * uv);
;             }
;           SCHED;
;         }
	global_store_dwordx4 v145, v[180:183], s[2:3]
	s_add_u32 s2, s2, 0x16000
	s_addc_u32 s3, s3, 0
	ds_write_b32 v143, v190
	ds_write_b32 v143, v191 offset:64
	ds_write_b32 v143, v192 offset:128
	ds_write_b32 v143, v193 offset:192
	ds_read_b128 v[184:187], v144
	v_fma_f32 v26, v26, v170, v140
	v_fma_f32 v18, v18, v170, v138
	v_mul_f32_e32 v188, 0xbfb8aa3b, v26
	v_mul_f32_e32 v189, 0xbfb8aa3b, v18
	v_exp_f32_e32 v188, v188
	v_exp_f32_e32 v189, v189
	v_fma_f32 v30, v30, v170, v141
	v_add_f32_e32 v188, 1.0, v188
	v_add_f32_e32 v189, 1.0, v189
	v_rcp_f32_e32 v188, v188
	v_rcp_f32_e32 v189, v189
	v_fma_f32 v22, v22, v170, v139
	v_mul_f32_e32 v26, v26, v188
	v_mul_f32_e32 v18, v18, v189
	v_mul_f32_e32 v26, v30, v26
	v_mul_f32_e32 v18, v22, v18
	v_cvt_pk_bf16_f32 v190, v26, v18
	v_fma_f32 v27, v27, v171, v140
	v_fma_f32 v19, v19, v171, v138
	v_mul_f32_e32 v188, 0xbfb8aa3b, v27
	v_mul_f32_e32 v189, 0xbfb8aa3b, v19
	v_exp_f32_e32 v188, v188
	v_exp_f32_e32 v189, v189
	v_fma_f32 v31, v31, v171, v141
	v_add_f32_e32 v188, 1.0, v188
	v_add_f32_e32 v189, 1.0, v189
	v_rcp_f32_e32 v188, v188
	v_rcp_f32_e32 v189, v189
	v_fma_f32 v23, v23, v171, v139
	v_mul_f32_e32 v27, v27, v188
	v_mul_f32_e32 v19, v19, v189
	v_mul_f32_e32 v27, v31, v27
	v_mul_f32_e32 v19, v23, v19
	v_cvt_pk_bf16_f32 v191, v27, v19
	v_fma_f32 v28, v28, v172, v140
	v_fma_f32 v20, v20, v172, v138
	v_mul_f32_e32 v188, 0xbfb8aa3b, v28
	v_mul_f32_e32 v189, 0xbfb8aa3b, v20
	v_exp_f32_e32 v188, v188
	v_exp_f32_e32 v189, v189
	v_fma_f32 v32, v32, v172, v141
	v_add_f32_e32 v188, 1.0, v188
	v_add_f32_e32 v189, 1.0, v189
	v_rcp_f32_e32 v188, v188
	v_rcp_f32_e32 v189, v189
	v_fma_f32 v24, v24, v172, v139
	v_mul_f32_e32 v28, v28, v188
	v_mul_f32_e32 v20, v20, v189
	v_mul_f32_e32 v28, v32, v28
	v_mul_f32_e32 v20, v24, v20
	v_cvt_pk_bf16_f32 v192, v28, v20
	v_fma_f32 v29, v29, v173, v140
	v_fma_f32 v21, v21, v173, v138
	v_mul_f32_e32 v188, 0xbfb8aa3b, v29
	v_mul_f32_e32 v189, 0xbfb8aa3b, v21
	v_exp_f32_e32 v188, v188
	v_exp_f32_e32 v189, v189
	v_fma_f32 v33, v33, v173, v141
	v_add_f32_e32 v188, 1.0, v188
	v_add_f32_e32 v189, 1.0, v189
	v_rcp_f32_e32 v188, v188
	v_rcp_f32_e32 v189, v189
	v_fma_f32 v25, v25, v173, v139
	v_mul_f32_e32 v29, v29, v188
	v_mul_f32_e32 v21, v21, v189
	v_mul_f32_e32 v29, v33, v29
	v_mul_f32_e32 v21, v25, v21
	v_cvt_pk_bf16_f32 v193, v29, v21
	s_waitcnt lgkmcnt(0)
	global_store_dwordx4 v145, v[184:187], s[2:3]
	s_add_u32 s2, s2, 0x16000
	s_addc_u32 s3, s3, 0
	ds_write_b32 v143, v190
	ds_write_b32 v143, v191 offset:64
	ds_write_b32 v143, v192 offset:128
	ds_write_b32 v143, v193 offset:192
	ds_read_b128 v[180:183], v144
	v_fma_f32 v10, v10, v174, v140
	v_fma_f32 v2, v2, v174, v138
	v_mul_f32_e32 v188, 0xbfb8aa3b, v10
	v_mul_f32_e32 v189, 0xbfb8aa3b, v2
	v_exp_f32_e32 v188, v188
	v_exp_f32_e32 v189, v189
	v_fma_f32 v14, v14, v174, v141
	v_add_f32_e32 v188, 1.0, v188
	v_add_f32_e32 v189, 1.0, v189
	v_rcp_f32_e32 v188, v188
	v_rcp_f32_e32 v189, v189
	v_fma_f32 v6, v6, v174, v139
	v_mul_f32_e32 v10, v10, v188
	v_mul_f32_e32 v2, v2, v189
	v_mul_f32_e32 v10, v14, v10
	v_mul_f32_e32 v2, v6, v2
	v_cvt_pk_bf16_f32 v190, v10, v2
	v_fma_f32 v11, v11, v175, v140
	v_fma_f32 v3, v3, v175, v138
	v_mul_f32_e32 v188, 0xbfb8aa3b, v11
	v_mul_f32_e32 v189, 0xbfb8aa3b, v3
	v_exp_f32_e32 v188, v188
	v_exp_f32_e32 v189, v189
	v_fma_f32 v15, v15, v175, v141
	v_add_f32_e32 v188, 1.0, v188
	v_add_f32_e32 v189, 1.0, v189
	v_rcp_f32_e32 v188, v188
	v_rcp_f32_e32 v189, v189
	v_fma_f32 v7, v7, v175, v139
	v_mul_f32_e32 v11, v11, v188
	v_mul_f32_e32 v3, v3, v189
	v_mul_f32_e32 v11, v15, v11
	v_mul_f32_e32 v3, v7, v3
	v_cvt_pk_bf16_f32 v191, v11, v3
	v_fma_f32 v12, v12, v176, v140
	v_fma_f32 v4, v4, v176, v138
	v_mul_f32_e32 v188, 0xbfb8aa3b, v12
	v_mul_f32_e32 v189, 0xbfb8aa3b, v4
	v_exp_f32_e32 v188, v188
	v_exp_f32_e32 v189, v189
	v_fma_f32 v16, v16, v176, v141
	v_add_f32_e32 v188, 1.0, v188
	v_add_f32_e32 v189, 1.0, v189
	v_rcp_f32_e32 v188, v188
	v_rcp_f32_e32 v189, v189
	v_fma_f32 v8, v8, v176, v139
	v_mul_f32_e32 v12, v12, v188
	v_mul_f32_e32 v4, v4, v189
	v_mul_f32_e32 v12, v16, v12
	v_mul_f32_e32 v4, v8, v4
	v_cvt_pk_bf16_f32 v192, v12, v4
	v_fma_f32 v13, v13, v177, v140
	v_fma_f32 v5, v5, v177, v138
	v_mul_f32_e32 v188, 0xbfb8aa3b, v13
	v_mul_f32_e32 v189, 0xbfb8aa3b, v5
	v_exp_f32_e32 v188, v188
	v_exp_f32_e32 v189, v189
	v_fma_f32 v17, v17, v177, v141
	v_add_f32_e32 v188, 1.0, v188
	v_add_f32_e32 v189, 1.0, v189
	v_rcp_f32_e32 v188, v188
	v_rcp_f32_e32 v189, v189
	v_fma_f32 v9, v9, v177, v139
	v_mul_f32_e32 v13, v13, v188
	v_mul_f32_e32 v5, v5, v189
	v_mul_f32_e32 v13, v17, v13
	v_mul_f32_e32 v5, v9, v5
	v_cvt_pk_bf16_f32 v193, v13, v5
	s_waitcnt lgkmcnt(0)
	global_store_dwordx4 v145, v[180:183], s[2:3]
	s_add_u32 s2, s2, 0x16000
	s_addc_u32 s3, s3, 0
	ds_write_b32 v143, v190
	ds_write_b32 v143, v191 offset:64
	ds_write_b32 v143, v192 offset:128
	ds_write_b32 v143, v193 offset:192
	ds_read_b128 v[184:187], v144
	s_waitcnt lgkmcnt(0)
	global_store_dwordx4 v145, v[184:187], s[2:3]
	s_and_b64 vcc, exec, s[0:1]
	s_cbranch_vccnz .LBB0_864

; #define WAIT_V(n) asm volatile("s_waitcnt vmcnt(" #n ")" ::: "memory")
; #define BAR __builtin_amdgcn_s_barrier()
; template <bool HS>
; __device__ __forceinline__ void gemm_tile8(const u16* __restrict__ Ap, const u16* __restrict__ Bp, int K,
;                                            f32x4 (&acc)[2][2][4][2], char* shm, const int tid, const float* hsr = nullptr) {
;   const int wid = tid >> 6, lane = tid & 63, wr = wid >> 2, wc = wid & 3, fr = lane & 15, fq = lane >> 4;
;   int r0, c0, r1, c1;
;   stage_rc(tid * 16, r0, c0);
;   stage_rc(tid * 16 + 8192, r1, c1);
;   const unsigned off0 = (unsigned)(r0 * K + c0) * 2u, off1 = (unsigned)(r1 * K + c1) * 2u;
;   const int wvoff = __builtin_amdgcn_readfirstlane(tid >> 6) * 1024;
;   const u16* A1 = Ap + (size_t)128 * K;
;   const u16* B1p = Bp + (size_t)128 * K;
; #pragma unroll
;   for (int a = 0; a < 2; ++a)
; #pragma unroll
;     for (int b = 0; b < 2; ++b)
; #pragma unroll
;       for (int m = 0; m < 4; ++m)
; #pragma unroll
;         for (int n = 0; n < 2; ++n) acc[a][b][m][n] = f32x4{0.f, 0.f, 0.f, 0.f};
;   const int abase = lds_byte(wr * 64 + fr, fq * 8), bbase = lds_byte(wc * 32 + fr, fq * 8);
;   bf16x8 At[4][2], B0[2][2], B1[2][2];
;   const unsigned lds0 = (unsigned)(size_t)(__attribute__((address_space(3))) char*)shm + (unsigned)wvoff;
;     ...
;   const int nt = K / BK;
;   WAIT_V(0);
;   if (wr == 1) BAR;
;   BAR;
;   BAR;
.LBB0_858:
	s_or_b64 exec, exec, s[0:1]
	v_bfe_i32 v6, v0, 27, 1
	v_lshlrev_b32_e32 v4, 4, v0
	v_lshrrev_b32_e32 v6, 22, v6
	v_add_u32_e32 v6, v4, v6
	v_and_b32_e32 v6, 0xfffffc00, v6
	v_ashrrev_i32_e32 v5, 31, v0
	v_sub_u32_e32 v6, v4, v6
	v_lshrrev_b32_e32 v5, 26, v5
	v_lshrrev_b32_e32 v7, 4, v6
	v_add_u32_e32 v5, v0, v5
	v_bitop3_b32 v7, v7, v6, 32 bitop3:0x6c
	v_ashrrev_i32_e32 v6, 31, v6
	v_ashrrev_i32_e32 v5, 6, v5
	v_lshrrev_b32_e32 v6, 26, v6
	v_lshlrev_b32_e32 v8, 3, v5
	v_add_u32_e32 v6, v7, v6
	v_and_b32_e32 v8, 0x1ffff0, v8
	v_ashrrev_i32_e32 v6, 6, v6
	v_add_u32_e32 v8, v6, v8
	v_mul_i32_i24_e32 v6, 64, v6
	v_add_u32_e32 v4, 0x2000, v4
	v_sub_u32_e32 v6, v7, v6
	v_ashrrev_i32_e32 v7, 31, v4
	v_lshrrev_b32_e32 v7, 22, v7
	v_add_u32_e32 v7, v4, v7
	v_ashrrev_i32_e32 v7, 10, v7
	v_mul_i32_i24_e32 v9, 0x400, v7
	v_sub_u32_e32 v4, v4, v9
	v_lshrrev_b32_e32 v9, 4, v4
	v_bitop3_b32 v4, v9, v4, 32 bitop3:0x6c
	v_ashrrev_i32_e32 v10, 31, v4
	v_lshrrev_b32_e32 v10, 26, v10
	v_add_u32_e32 v10, v4, v10
	v_lshlrev_b32_e32 v9, 3, v7
	v_lshrrev_b32_e32 v11, 6, v10
	v_and_b32_e32 v10, 0xc0, v10
	v_and_b32_e32 v9, 0x1ffff0, v9
	v_lshlrev_b32_e32 v7, 5, v7
	v_sub_u32_e32 v4, v4, v10
	s_ashr_i32 s5, s4, 31
	v_lshlrev_b32_e32 v5, 5, v5
	v_add_u32_e32 v9, v11, v9
	v_and_b32_e32 v7, 32, v7
	v_ashrrev_i16_sdwa v4, v178, sext(v4) dst_sel:DWORD dst_unused:UNUSED_PAD src0_sel:DWORD src1_sel:BYTE_0
	s_lshl_b64 s[0:1], s[4:5], 11
	v_and_b32_e32 v5, 32, v5
	v_ashrrev_i16_sdwa v6, v178, sext(v6) dst_sel:DWORD dst_unused:UNUSED_PAD src0_sel:DWORD src1_sel:BYTE_0
	v_bfe_i32 v4, v4, 0, 16
	v_lshl_or_b32 v7, v9, 10, v7
	s_add_u32 s5, s88, s0
	v_bfe_i32 v6, v6, 0, 16
	v_lshl_or_b32 v5, v8, 10, v5
	v_and_b32_e32 v8, 15, v0
	v_add_lshl_u32 v143, v7, v4, 1
	v_lshlrev_b32_e32 v7, 2, v0
	s_addc_u32 s6, s89, s1
	s_ashr_i32 s3, s2, 31
	v_add_lshl_u32 v144, v5, v6, 1
	v_and_b32_e32 v4, 48, v0
	v_lshlrev_b32_e32 v5, 6, v8
	v_and_b32_e32 v7, 32, v7
	s_lshl_b64 s[10:11], s[2:3], 19
	s_lshl_b32 s3, s7, 10
	v_or_b32_e32 v6, v5, v4
	v_bitop3_b32 v4, v5, v7, v4 bitop3:0x36
	v_lshlrev_b32_e32 v2, 12, v2
	s_movk_i32 s7, 0x3000
	v_lshl_add_u64 v[130:131], v[134:135], 0, s[10:11]
	s_mov_b64 s[10:11], 0x40000
	v_and_or_b32 v145, v2, s7, v4
	s_add_i32 s7, s3, 0
	v_lshl_add_u64 v[132:133], v[130:131], 0, s[10:11]
	s_add_u32 s10, s5, 0x40100
	v_lshlrev_b32_e32 v3, 13, v3
	s_addc_u32 s11, s6, 0
	v_readlane_b32 s12, v254, 34
	v_bitop3_b32 v3, v6, v3, v7 bitop3:0xde
	s_add_u32 s12, s12, s0
	v_readlane_b32 s0, v254, 35
	v_mov_b32_e32 v2, 0
	s_addc_u32 s13, s0, s1
	s_mov_b32 s14, -2
	s_mov_b64 s[0:1], 0
	v_add_u32_e32 v142, 0, v3
	v_mov_b32_e32 v3, v2
	v_mov_b32_e32 v4, v2
	v_mov_b32_e32 v5, v2
	v_mov_b32_e32 v6, v2
	v_mov_b32_e32 v7, v2
	v_mov_b32_e32 v8, v2
	v_mov_b32_e32 v9, v2
	v_mov_b32_e32 v10, v2
	v_mov_b32_e32 v11, v2
	v_mov_b32_e32 v12, v2
	v_mov_b32_e32 v13, v2
	v_mov_b32_e32 v14, v2
	v_mov_b32_e32 v15, v2
	v_mov_b32_e32 v16, v2
	v_mov_b32_e32 v17, v2
	v_mov_b32_e32 v18, v2
	v_mov_b32_e32 v19, v2
	v_mov_b32_e32 v20, v2
	v_mov_b32_e32 v21, v2
	v_mov_b32_e32 v22, v2
	v_mov_b32_e32 v23, v2
	v_mov_b32_e32 v24, v2
	v_mov_b32_e32 v25, v2
	v_mov_b32_e32 v26, v2
	v_mov_b32_e32 v27, v2
	v_mov_b32_e32 v28, v2
	s_waitcnt lgkmcnt(0)
	v_mov_b32_e32 v29, v2
	v_mov_b32_e32 v30, v2
	v_mov_b32_e32 v31, v2
	v_mov_b32_e32 v32, v2
	v_mov_b32_e32 v33, v2
	v_mov_b32_e32 v34, v2
	v_mov_b32_e32 v35, v2
	v_mov_b32_e32 v36, v2
	v_mov_b32_e32 v37, v2
	v_mov_b32_e32 v38, v2
	v_mov_b32_e32 v39, v2
	v_mov_b32_e32 v40, v2
	v_mov_b32_e32 v41, v2
	v_mov_b32_e32 v42, v2
	v_mov_b32_e32 v43, v2
	v_mov_b32_e32 v44, v2
	v_mov_b32_e32 v45, v2
	v_mov_b32_e32 v46, v2
	v_mov_b32_e32 v47, v2
	v_mov_b32_e32 v48, v2
	v_mov_b32_e32 v49, v2
	v_mov_b32_e32 v50, v2
	v_mov_b32_e32 v51, v2
	v_mov_b32_e32 v52, v2
	v_mov_b32_e32 v53, v2
	v_mov_b32_e32 v54, v2
	v_mov_b32_e32 v55, v2
	v_mov_b32_e32 v56, v2
	v_mov_b32_e32 v57, v2
	v_mov_b32_e32 v58, v2
	v_mov_b32_e32 v59, v2
	v_mov_b32_e32 v60, v2
	v_mov_b32_e32 v61, v2
	v_mov_b32_e32 v62, v2
	v_mov_b32_e32 v63, v2
	v_mov_b32_e32 v64, v2
	v_mov_b32_e32 v65, v2
	v_mov_b32_e32 v66, v2
	v_mov_b32_e32 v67, v2
	v_mov_b32_e32 v68, v2
	v_mov_b32_e32 v69, v2
	v_mov_b32_e32 v70, v2
	v_mov_b32_e32 v71, v2
	v_mov_b32_e32 v72, v2
	v_mov_b32_e32 v73, v2
	v_mov_b32_e32 v74, v2
	v_mov_b32_e32 v75, v2
	v_mov_b32_e32 v76, v2
	v_mov_b32_e32 v77, v2
	v_mov_b32_e32 v78, v2
	v_mov_b32_e32 v79, v2
	v_mov_b32_e32 v80, v2
	v_mov_b32_e32 v81, v2
	v_mov_b32_e32 v82, v2
	v_mov_b32_e32 v83, v2
	v_mov_b32_e32 v84, v2
	v_mov_b32_e32 v85, v2
	v_mov_b32_e32 v86, v2
	v_mov_b32_e32 v87, v2
	v_mov_b32_e32 v88, v2
	v_mov_b32_e32 v89, v2
	v_mov_b32_e32 v90, v2
	v_mov_b32_e32 v91, v2
	v_mov_b32_e32 v92, v2
	v_mov_b32_e32 v93, v2
	v_mov_b32_e32 v94, v2
	v_mov_b32_e32 v95, v2
	v_mov_b32_e32 v96, v2
	v_mov_b32_e32 v97, v2
	v_mov_b32_e32 v98, v2
	v_mov_b32_e32 v99, v2
	v_mov_b32_e32 v100, v2
	v_mov_b32_e32 v101, v2
	v_mov_b32_e32 v102, v2
	v_mov_b32_e32 v103, v2
	v_mov_b32_e32 v104, v2
	v_mov_b32_e32 v105, v2
	v_mov_b32_e32 v106, v2
	v_mov_b32_e32 v107, v2
	v_mov_b32_e32 v108, v2
	v_mov_b32_e32 v109, v2
	v_mov_b32_e32 v110, v2
	v_mov_b32_e32 v111, v2
	v_mov_b32_e32 v112, v2
	v_mov_b32_e32 v113, v2
	v_mov_b32_e32 v114, v2
	v_mov_b32_e32 v115, v2
	v_mov_b32_e32 v116, v2
	v_mov_b32_e32 v117, v2
	v_mov_b32_e32 v118, v2
	v_mov_b32_e32 v119, v2
	v_mov_b32_e32 v120, v2
	v_mov_b32_e32 v121, v2
	v_mov_b32_e32 v122, v2
	v_mov_b32_e32 v123, v2
	v_mov_b32_e32 v124, v2
	v_mov_b32_e32 v125, v2
	v_mov_b32_e32 v126, v2
	v_mov_b32_e32 v127, v2
	v_mov_b32_e32 v128, v2
	v_mov_b32_e32 v129, v2
	v_readfirstlane_b32 s20, v130
	v_readfirstlane_b32 s21, v131
	v_readfirstlane_b32 s22, v132
	v_readfirstlane_b32 s23, v133
	s_mov_b32 s16, s5
	s_mov_b32 s17, s6
	s_mov_b32 s18, s12
	s_mov_b32 s19, s13
	s_barrier
	s_barrier
; #define WAIT_V(n) asm volatile("s_waitcnt vmcnt(" #n ")" ::: "memory")
; #define WAIT_L(n) asm volatile("s_waitcnt lgkmcnt(" #n ")" ::: "memory")
; #define BAR __builtin_amdgcn_s_barrier()
; #define SCHED __builtin_amdgcn_sched_barrier(0)
; #define STG_A(b, h, kt) stage_half_s(lds0 + ((b) * 2 + (h)) * HT_B, ((h) ? A1 : Ap) + (kt) * BK, off0, off1)
; #define STG_B(b, h, kt) stage_half_s(lds0 + (4 + (b) * 2 + (h)) * HT_B, ((h) ? B1p : Bp) + (kt) * BK, off0, off1)
; #define STG_A(b, h, kt) stage_half_s(lds0 + ((b) * 2 + (h)) * HT_B, ((h) ? A1 : Ap) + (kt) * BK, off0, off1)
; #define STG_B(b, h, kt) stage_half_s(lds0 + (4 + (b) * 2 + (h)) * HT_B, ((h) ? B1p : Bp) + (kt) * BK, off0, off1)
; #define LDA8(b, h) _Pragma("unroll") for (int m = 0; m < 4; ++m) _Pragma("unroll") for (int k = 0; k < 2; ++k) \
;     At[m][k] = *(const bf16x8*)(SA_(shm, b, h) + abase + (m * 2 + k) * 1024)
; #define LDB8(dst, b, h) _Pragma("unroll") for (int n = 0; n < 2; ++n) _Pragma("unroll") for (int k = 0; k < 2; ++k) \
;     dst[n][k] = *(const bf16x8*)(SB_(shm, b, h) + bbase + (n * 2 + k) * 1024)
; template <bool HS>
; __device__ __forceinline__ void gemm_tile8(const u16* __restrict__ Ap, const u16* __restrict__ Bp, int K,
;                                            f32x4 (&acc)[2][2][4][2], char* shm, const int tid, const float* hsr = nullptr) {
;     ...
;   for (int t = 0; t < nt - 2; t += 2) {
;     if constexpr (HS) {
;       if (t > 0 && (t & 7) == 0) {
;         const float* rt = hsr + ((t >> 3) - 1) * 256 + wr * 64 + fq * 4;
; #pragma unroll
;         for (int ai = 0; ai < 2; ++ai)
; #pragma unroll
;           for (int m = 0; m < 4; ++m) {
;             const f32x4 q4 = *(const f32x4*)(rt + ai * 128 + m * 16);
; #pragma unroll
;             for (int bj = 0; bj < 2; ++bj)
; #pragma unroll
;               for (int n = 0; n < 2; ++n) acc[ai][bj][m][n] *= q4;
;             SCHED;
;           }
;       }
;     }
;     LDB8(B0, 0, 0); SCHED; LDA8(0, 0); STG_A(1, 1, t + 1);
;     WAIT_L(8); BAR; WAIT_L(0); MMA8(0, 0, B0); BAR; SCHED;
;     LDB8(B1, 0, 1); STG_B(0, 0, t + 2);
;     BAR; WAIT_L(0); MMA8(0, 1, B1); BAR;
;     LDA8(0, 1); STG_A(0, 0, t + 2);
;     BAR; WAIT_L(0); MMA8(1, 0, B0); BAR; SCHED;
;     STG_B(0, 1, t + 2);
;     WAIT_V(6); BAR; MMA8(1, 1, B1); BAR;
.Lk_ffn_in:
	v_add_u32_e32 v158, 0x10000, v145
	ds_read_b128 v[146:149], v158
	ds_read_b128 v[150:153], v158 offset:1024
	ds_read_b128 v[154:157], v158 offset:2048
	ds_read_b128 v[158:161], v158 offset:3072
	ds_read_b128 v[162:165], v142
	ds_read_b128 v[166:169], v142 offset:1024
	ds_read_b128 v[170:173], v142 offset:2048
	ds_read_b128 v[174:177], v142 offset:3072
	ds_read_b128 v[180:183], v142 offset:4096
	ds_read_b128 v[184:187], v142 offset:5120
	ds_read_b128 v[188:191], v142 offset:6144
	ds_read_b128 v[192:195], v142 offset:7168
	v_add_u32_e32 v208, 0x14000, v145
	ds_read_b128 v[196:199], v208
	ds_read_b128 v[200:203], v208 offset:1024
	ds_read_b128 v[204:207], v208 offset:2048
	ds_read_b128 v[208:211], v208 offset:3072
	s_add_u32 s0, s18, 0x80
	s_addc_u32 s1, s19, 0
	s_add_i32 s3, s7, 0xc000
	s_mov_b32 m0, s3
	s_nop 0
	global_load_lds_dwordx4 v144, s[0:1]
	s_add_i32 s3, s7, 0xe000
	s_mov_b32 m0, s3
	s_nop 0
	global_load_lds_dwordx4 v143, s[0:1]
	s_waitcnt vmcnt(8) lgkmcnt(0)
	s_barrier
	s_setprio 1
	v_mfma_f32_16x16x32_bf16 v[126:129], v[162:165], v[146:149], v[126:129]
	v_mfma_f32_16x16x32_bf16 v[122:125], v[162:165], v[154:157], v[122:125]
	v_mfma_f32_16x16x32_bf16 v[118:121], v[170:173], v[146:149], v[118:121]
	v_mfma_f32_16x16x32_bf16 v[114:117], v[170:173], v[154:157], v[114:117]
	v_mfma_f32_16x16x32_bf16 v[110:113], v[180:183], v[146:149], v[110:113]
	v_mfma_f32_16x16x32_bf16 v[106:109], v[180:183], v[154:157], v[106:109]
	v_mfma_f32_16x16x32_bf16 v[102:105], v[188:191], v[146:149], v[102:105]
	v_mfma_f32_16x16x32_bf16 v[98:101], v[188:191], v[154:157], v[98:101]
	v_mfma_f32_16x16x32_bf16 v[126:129], v[166:169], v[150:153], v[126:129]
	v_mfma_f32_16x16x32_bf16 v[122:125], v[166:169], v[158:161], v[122:125]
	v_mfma_f32_16x16x32_bf16 v[118:121], v[174:177], v[150:153], v[118:121]
	v_mfma_f32_16x16x32_bf16 v[114:117], v[174:177], v[158:161], v[114:117]
	v_mfma_f32_16x16x32_bf16 v[110:113], v[184:187], v[150:153], v[110:113]
	v_mfma_f32_16x16x32_bf16 v[106:109], v[184:187], v[158:161], v[106:109]
	v_mfma_f32_16x16x32_bf16 v[102:105], v[192:195], v[150:153], v[102:105]
	v_mfma_f32_16x16x32_bf16 v[98:101], v[192:195], v[158:161], v[98:101]
	v_mfma_f32_16x16x32_bf16 v[94:97], v[162:165], v[196:199], v[94:97]
	v_mfma_f32_16x16x32_bf16 v[90:93], v[162:165], v[204:207], v[90:93]
	v_mfma_f32_16x16x32_bf16 v[86:89], v[170:173], v[196:199], v[86:89]
	v_mfma_f32_16x16x32_bf16 v[82:85], v[170:173], v[204:207], v[82:85]
	v_mfma_f32_16x16x32_bf16 v[78:81], v[180:183], v[196:199], v[78:81]
	v_mfma_f32_16x16x32_bf16 v[74:77], v[180:183], v[204:207], v[74:77]
	v_mfma_f32_16x16x32_bf16 v[70:73], v[188:191], v[196:199], v[70:73]
	v_mfma_f32_16x16x32_bf16 v[66:69], v[188:191], v[204:207], v[66:69]
	v_mfma_f32_16x16x32_bf16 v[94:97], v[166:169], v[200:203], v[94:97]
	v_mfma_f32_16x16x32_bf16 v[90:93], v[166:169], v[208:211], v[90:93]
	v_mfma_f32_16x16x32_bf16 v[86:89], v[174:177], v[200:203], v[86:89]
	v_mfma_f32_16x16x32_bf16 v[82:85], v[174:177], v[208:211], v[82:85]
	v_mfma_f32_16x16x32_bf16 v[78:81], v[184:187], v[200:203], v[78:81]
	v_mfma_f32_16x16x32_bf16 v[74:77], v[184:187], v[208:211], v[74:77]
	v_mfma_f32_16x16x32_bf16 v[70:73], v[192:195], v[200:203], v[70:73]
	v_mfma_f32_16x16x32_bf16 v[66:69], v[192:195], v[208:211], v[66:69]
	s_setprio 0
	s_barrier
	ds_read_b128 v[162:165], v142 offset:16384
	ds_read_b128 v[166:169], v142 offset:17408
	ds_read_b128 v[170:173], v142 offset:18432
	ds_read_b128 v[174:177], v142 offset:19456
	ds_read_b128 v[180:183], v142 offset:20480
	ds_read_b128 v[184:187], v142 offset:21504
	ds_read_b128 v[188:191], v142 offset:22528
	ds_read_b128 v[192:195], v142 offset:23552
	s_add_u32 s0, s20, 0x100
	s_addc_u32 s1, s21, 0
	s_add_i32 s3, s7, 0x10000
	s_mov_b32 m0, s3
	s_nop 0
	global_load_lds_dwordx4 v144, s[0:1]
	s_add_i32 s3, s7, 0x12000
	s_mov_b32 m0, s3
	s_nop 0
	global_load_lds_dwordx4 v143, s[0:1]
	s_add_u32 s0, s16, 0x100
	s_addc_u32 s1, s17, 0
	s_mov_b32 m0, s7
	s_nop 0
	global_load_lds_dwordx4 v144, s[0:1]
	s_add_i32 s3, s7, 0x2000
	s_mov_b32 m0, s3
	s_nop 0
	global_load_lds_dwordx4 v143, s[0:1]
	s_add_u32 s0, s22, 0x100
	s_addc_u32 s1, s23, 0
	s_add_i32 s3, s7, 0x14000
	s_mov_b32 m0, s3
	s_nop 0
	global_load_lds_dwordx4 v144, s[0:1]
	s_add_i32 s3, s7, 0x16000
	s_mov_b32 m0, s3
	s_nop 0
	global_load_lds_dwordx4 v143, s[0:1]
	s_waitcnt vmcnt(8) lgkmcnt(0)
	s_barrier
	s_setprio 1
	v_mfma_f32_16x16x32_bf16 v[62:65], v[162:165], v[146:149], v[62:65]
	v_mfma_f32_16x16x32_bf16 v[58:61], v[162:165], v[154:157], v[58:61]
	v_mfma_f32_16x16x32_bf16 v[54:57], v[170:173], v[146:149], v[54:57]
	v_mfma_f32_16x16x32_bf16 v[50:53], v[170:173], v[154:157], v[50:53]
	v_mfma_f32_16x16x32_bf16 v[46:49], v[180:183], v[146:149], v[46:49]
	v_mfma_f32_16x16x32_bf16 v[42:45], v[180:183], v[154:157], v[42:45]
	v_mfma_f32_16x16x32_bf16 v[38:41], v[188:191], v[146:149], v[38:41]
	v_mfma_f32_16x16x32_bf16 v[34:37], v[188:191], v[154:157], v[34:37]
	v_mfma_f32_16x16x32_bf16 v[62:65], v[166:169], v[150:153], v[62:65]
	v_mfma_f32_16x16x32_bf16 v[58:61], v[166:169], v[158:161], v[58:61]
	v_mfma_f32_16x16x32_bf16 v[54:57], v[174:177], v[150:153], v[54:57]
	v_mfma_f32_16x16x32_bf16 v[50:53], v[174:177], v[158:161], v[50:53]
	v_mfma_f32_16x16x32_bf16 v[46:49], v[184:187], v[150:153], v[46:49]
	v_mfma_f32_16x16x32_bf16 v[42:45], v[184:187], v[158:161], v[42:45]
	v_mfma_f32_16x16x32_bf16 v[38:41], v[192:195], v[150:153], v[38:41]
	v_mfma_f32_16x16x32_bf16 v[34:37], v[192:195], v[158:161], v[34:37]
	v_mfma_f32_16x16x32_bf16 v[30:33], v[162:165], v[196:199], v[30:33]
	v_mfma_f32_16x16x32_bf16 v[26:29], v[162:165], v[204:207], v[26:29]
	v_mfma_f32_16x16x32_bf16 v[22:25], v[170:173], v[196:199], v[22:25]
	v_mfma_f32_16x16x32_bf16 v[18:21], v[170:173], v[204:207], v[18:21]
	v_mfma_f32_16x16x32_bf16 v[14:17], v[180:183], v[196:199], v[14:17]
	v_mfma_f32_16x16x32_bf16 v[10:13], v[180:183], v[204:207], v[10:13]
	v_mfma_f32_16x16x32_bf16 v[6:9], v[188:191], v[196:199], v[6:9]
	v_mfma_f32_16x16x32_bf16 v[2:5], v[188:191], v[204:207], v[2:5]
	v_mfma_f32_16x16x32_bf16 v[30:33], v[166:169], v[200:203], v[30:33]
	v_mfma_f32_16x16x32_bf16 v[26:29], v[166:169], v[208:211], v[26:29]
	v_mfma_f32_16x16x32_bf16 v[22:25], v[174:177], v[200:203], v[22:25]
	v_mfma_f32_16x16x32_bf16 v[18:21], v[174:177], v[208:211], v[18:21]
	v_mfma_f32_16x16x32_bf16 v[14:17], v[184:187], v[200:203], v[14:17]
	v_mfma_f32_16x16x32_bf16 v[10:13], v[184:187], v[208:211], v[10:13]
	v_mfma_f32_16x16x32_bf16 v[6:9], v[192:195], v[200:203], v[6:9]
	v_mfma_f32_16x16x32_bf16 v[2:5], v[192:195], v[208:211], v[2:5]
	s_setprio 0
	s_barrier
; #define WAIT_V(n) asm volatile("s_waitcnt vmcnt(" #n ")" ::: "memory")
; #define WAIT_L(n) asm volatile("s_waitcnt lgkmcnt(" #n ")" ::: "memory")
; #define BAR __builtin_amdgcn_s_barrier()
; #define SCHED __builtin_amdgcn_sched_barrier(0)
; #define STG_A(b, h, kt) stage_half_s(lds0 + ((b) * 2 + (h)) * HT_B, ((h) ? A1 : Ap) + (kt) * BK, off0, off1)
; #define STG_B(b, h, kt) stage_half_s(lds0 + (4 + (b) * 2 + (h)) * HT_B, ((h) ? B1p : Bp) + (kt) * BK, off0, off1)
; #define STG_A(b, h, kt) stage_half_s(lds0 + ((b) * 2 + (h)) * HT_B, ((h) ? A1 : Ap) + (kt) * BK, off0, off1)
; #define STG_B(b, h, kt) stage_half_s(lds0 + (4 + (b) * 2 + (h)) * HT_B, ((h) ? B1p : Bp) + (kt) * BK, off0, off1)
; #define LDA8(b, h) _Pragma("unroll") for (int m = 0; m < 4; ++m) _Pragma("unroll") for (int k = 0; k < 2; ++k) \
;     At[m][k] = *(const bf16x8*)(SA_(shm, b, h) + abase + (m * 2 + k) * 1024)
; #define LDB8(dst, b, h) _Pragma("unroll") for (int n = 0; n < 2; ++n) _Pragma("unroll") for (int k = 0; k < 2; ++k) \
;     dst[n][k] = *(const bf16x8*)(SB_(shm, b, h) + bbase + (n * 2 + k) * 1024)
; #define MMA8(ai, bj, Bx) do { __builtin_amdgcn_s_setprio(1); \
;     _Pragma("unroll") for (int m = 0; m < 4; ++m) _Pragma("unroll") for (int n = 0; n < 2; ++n) _Pragma("unroll") for (int k = 0; k < 2; ++k) \
;       acc[ai][bj][m][n] = __builtin_amdgcn_mfma_f32_16x16x32_bf16(At[m][k], Bx[n][k], acc[ai][bj][m][n], 0, 0, 0); \
;     __builtin_amdgcn_s_setprio(0); } while (0)
; template <bool HS>
; __device__ __forceinline__ void gemm_tile8(const u16* __restrict__ Ap, const u16* __restrict__ Bp, int K,
;                                            f32x4 (&acc)[2][2][4][2], char* shm, const int tid, const float* hsr = nullptr) {
;     ...
;     LDB8(B0, 1, 0); SCHED; LDA8(1, 0); STG_A(0, 1, t + 2);
;     WAIT_L(8); BAR; WAIT_L(0); MMA8(0, 0, B0); BAR; SCHED;
;     LDB8(B1, 1, 1); STG_B(1, 0, t + 3);
;     BAR; WAIT_L(0); MMA8(0, 1, B1); BAR;
;     LDA8(1, 1); STG_A(1, 0, t + 3);
;     BAR; WAIT_L(0); MMA8(1, 0, B0); BAR; SCHED;
;     STG_B(1, 1, t + 3);
;     WAIT_V(6); BAR; MMA8(1, 1, B1); BAR;
	v_add_u32_e32 v158, 0x18000, v145
	ds_read_b128 v[146:149], v158
	ds_read_b128 v[150:153], v158 offset:1024
	ds_read_b128 v[154:157], v158 offset:2048
	ds_read_b128 v[158:161], v158 offset:3072
	ds_read_b128 v[162:165], v142 offset:32768
	ds_read_b128 v[166:169], v142 offset:33792
	ds_read_b128 v[170:173], v142 offset:34816
	ds_read_b128 v[174:177], v142 offset:35840
	ds_read_b128 v[180:183], v142 offset:36864
	ds_read_b128 v[184:187], v142 offset:37888
	ds_read_b128 v[188:191], v142 offset:38912
	ds_read_b128 v[192:195], v142 offset:39936
	v_add_u32_e32 v208, 0x1c000, v145
	ds_read_b128 v[196:199], v208
	ds_read_b128 v[200:203], v208 offset:1024
	ds_read_b128 v[204:207], v208 offset:2048
	ds_read_b128 v[208:211], v208 offset:3072
	s_add_u32 s0, s18, 0x100
	s_addc_u32 s1, s19, 0
	s_add_i32 s3, s7, 0x4000
	s_mov_b32 m0, s3
	s_nop 0
	global_load_lds_dwordx4 v144, s[0:1]
	s_add_i32 s3, s7, 0x6000
	s_mov_b32 m0, s3
	s_nop 0
	global_load_lds_dwordx4 v143, s[0:1]
	s_waitcnt vmcnt(8) lgkmcnt(0)
	s_barrier
	s_setprio 1
	v_mfma_f32_16x16x32_bf16 v[126:129], v[162:165], v[146:149], v[126:129]
	v_mfma_f32_16x16x32_bf16 v[122:125], v[162:165], v[154:157], v[122:125]
	v_mfma_f32_16x16x32_bf16 v[118:121], v[170:173], v[146:149], v[118:121]
	v_mfma_f32_16x16x32_bf16 v[114:117], v[170:173], v[154:157], v[114:117]
	v_mfma_f32_16x16x32_bf16 v[110:113], v[180:183], v[146:149], v[110:113]
	v_mfma_f32_16x16x32_bf16 v[106:109], v[180:183], v[154:157], v[106:109]
	v_mfma_f32_16x16x32_bf16 v[102:105], v[188:191], v[146:149], v[102:105]
	v_mfma_f32_16x16x32_bf16 v[98:101], v[188:191], v[154:157], v[98:101]
	v_mfma_f32_16x16x32_bf16 v[126:129], v[166:169], v[150:153], v[126:129]
	v_mfma_f32_16x16x32_bf16 v[122:125], v[166:169], v[158:161], v[122:125]
	v_mfma_f32_16x16x32_bf16 v[118:121], v[174:177], v[150:153], v[118:121]
	v_mfma_f32_16x16x32_bf16 v[114:117], v[174:177], v[158:161], v[114:117]
	v_mfma_f32_16x16x32_bf16 v[110:113], v[184:187], v[150:153], v[110:113]
	v_mfma_f32_16x16x32_bf16 v[106:109], v[184:187], v[158:161], v[106:109]
	v_mfma_f32_16x16x32_bf16 v[102:105], v[192:195], v[150:153], v[102:105]
	v_mfma_f32_16x16x32_bf16 v[98:101], v[192:195], v[158:161], v[98:101]
	v_mfma_f32_16x16x32_bf16 v[94:97], v[162:165], v[196:199], v[94:97]
	v_mfma_f32_16x16x32_bf16 v[90:93], v[162:165], v[204:207], v[90:93]
	v_mfma_f32_16x16x32_bf16 v[86:89], v[170:173], v[196:199], v[86:89]
	v_mfma_f32_16x16x32_bf16 v[82:85], v[170:173], v[204:207], v[82:85]
	v_mfma_f32_16x16x32_bf16 v[78:81], v[180:183], v[196:199], v[78:81]
	v_mfma_f32_16x16x32_bf16 v[74:77], v[180:183], v[204:207], v[74:77]
	v_mfma_f32_16x16x32_bf16 v[70:73], v[188:191], v[196:199], v[70:73]
	v_mfma_f32_16x16x32_bf16 v[66:69], v[188:191], v[204:207], v[66:69]
	v_mfma_f32_16x16x32_bf16 v[94:97], v[166:169], v[200:203], v[94:97]
	v_mfma_f32_16x16x32_bf16 v[90:93], v[166:169], v[208:211], v[90:93]
	v_mfma_f32_16x16x32_bf16 v[86:89], v[174:177], v[200:203], v[86:89]
	v_mfma_f32_16x16x32_bf16 v[82:85], v[174:177], v[208:211], v[82:85]
	v_mfma_f32_16x16x32_bf16 v[78:81], v[184:187], v[200:203], v[78:81]
	v_mfma_f32_16x16x32_bf16 v[74:77], v[184:187], v[208:211], v[74:77]
	v_mfma_f32_16x16x32_bf16 v[70:73], v[192:195], v[200:203], v[70:73]
	v_mfma_f32_16x16x32_bf16 v[66:69], v[192:195], v[208:211], v[66:69]
	s_setprio 0
	s_barrier
	ds_read_b128 v[162:165], v142 offset:49152
	ds_read_b128 v[166:169], v142 offset:50176
	ds_read_b128 v[170:173], v142 offset:51200
	ds_read_b128 v[174:177], v142 offset:52224
	ds_read_b128 v[180:183], v142 offset:53248
	ds_read_b128 v[184:187], v142 offset:54272
	ds_read_b128 v[188:191], v142 offset:55296
	ds_read_b128 v[192:195], v142 offset:56320
	s_add_u32 s0, s20, 0x180
	s_addc_u32 s1, s21, 0
	s_add_i32 s3, s7, 0x18000
	s_mov_b32 m0, s3
	s_nop 0
	global_load_lds_dwordx4 v144, s[0:1]
	s_add_i32 s3, s7, 0x1a000
	s_mov_b32 m0, s3
	s_nop 0
	global_load_lds_dwordx4 v143, s[0:1]
	s_add_u32 s0, s16, 0x180
	s_addc_u32 s1, s17, 0
	s_add_i32 s3, s7, 0x8000
	s_mov_b32 m0, s3
	s_nop 0
	global_load_lds_dwordx4 v144, s[0:1]
	s_add_i32 s3, s7, 0xa000
	s_mov_b32 m0, s3
	s_nop 0
	global_load_lds_dwordx4 v143, s[0:1]
	s_add_u32 s0, s22, 0x180
	s_addc_u32 s1, s23, 0
	s_add_i32 s3, s7, 0x1c000
	s_mov_b32 m0, s3
	s_nop 0
	global_load_lds_dwordx4 v144, s[0:1]
	s_add_i32 s3, s7, 0x1e000
	s_mov_b32 m0, s3
	s_nop 0
	global_load_lds_dwordx4 v143, s[0:1]
	s_waitcnt vmcnt(8) lgkmcnt(0)
	s_barrier
; #define WAIT_V(n) asm volatile("s_waitcnt vmcnt(" #n ")" ::: "memory")
; #define WAIT_L(n) asm volatile("s_waitcnt lgkmcnt(" #n ")" ::: "memory")
; #define BAR __builtin_amdgcn_s_barrier()
; #define SCHED __builtin_amdgcn_sched_barrier(0)
; #define STG_A(b, h, kt) stage_half_s(lds0 + ((b) * 2 + (h)) * HT_B, ((h) ? A1 : Ap) + (kt) * BK, off0, off1)
; #define STG_B(b, h, kt) stage_half_s(lds0 + (4 + (b) * 2 + (h)) * HT_B, ((h) ? B1p : Bp) + (kt) * BK, off0, off1)
; #define STG_A(b, h, kt) stage_half_s(lds0 + ((b) * 2 + (h)) * HT_B, ((h) ? A1 : Ap) + (kt) * BK, off0, off1)
; #define STG_B(b, h, kt) stage_half_s(lds0 + (4 + (b) * 2 + (h)) * HT_B, ((h) ? B1p : Bp) + (kt) * BK, off0, off1)
; #define LDA8(b, h) _Pragma("unroll") for (int m = 0; m < 4; ++m) _Pragma("unroll") for (int k = 0; k < 2; ++k) \
;     At[m][k] = *(const bf16x8*)(SA_(shm, b, h) + abase + (m * 2 + k) * 1024)
; #define LDB8(dst, b, h) _Pragma("unroll") for (int n = 0; n < 2; ++n) _Pragma("unroll") for (int k = 0; k < 2; ++k) \
;     dst[n][k] = *(const bf16x8*)(SB_(shm, b, h) + bbase + (n * 2 + k) * 1024)
; #define MMA8(ai, bj, Bx) do { __builtin_amdgcn_s_setprio(1); \
;     _Pragma("unroll") for (int m = 0; m < 4; ++m) _Pragma("unroll") for (int n = 0; n < 2; ++n) _Pragma("unroll") for (int k = 0; k < 2; ++k) \
;       acc[ai][bj][m][n] = __builtin_amdgcn_mfma_f32_16x16x32_bf16(At[m][k], Bx[n][k], acc[ai][bj][m][n], 0, 0, 0); \
;     __builtin_amdgcn_s_setprio(0); } while (0)
; template <bool HS>
; __device__ __forceinline__ void gemm_tile8(const u16* __restrict__ Ap, const u16* __restrict__ Bp, int K,
;                                            f32x4 (&acc)[2][2][4][2], char* shm, const int tid, const float* hsr = nullptr) {
;     ...
;     BAR; WAIT_L(0); MMA8(0, 1, B1); BAR;
;     LDA8(1, 1); STG_A(1, 0, t + 3);
;     BAR; WAIT_L(0); MMA8(1, 0, B0); BAR; SCHED;
;     STG_B(1, 1, t + 3);
;     WAIT_V(6); BAR; MMA8(1, 1, B1); BAR;
;   }
;   { LDB8(B0, 0, 0); LDA8(0, 0); STG_A(1, 1, nt - 1);
;     BAR; WAIT_L(0); MMA8(0, 0, B0); BAR;
	s_setprio 1
	v_mfma_f32_16x16x32_bf16 v[62:65], v[162:165], v[146:149], v[62:65]
	v_mfma_f32_16x16x32_bf16 v[58:61], v[162:165], v[154:157], v[58:61]
	v_mfma_f32_16x16x32_bf16 v[54:57], v[170:173], v[146:149], v[54:57]
	v_mfma_f32_16x16x32_bf16 v[50:53], v[170:173], v[154:157], v[50:53]
	v_mfma_f32_16x16x32_bf16 v[46:49], v[180:183], v[146:149], v[46:49]
	v_mfma_f32_16x16x32_bf16 v[42:45], v[180:183], v[154:157], v[42:45]
	v_mfma_f32_16x16x32_bf16 v[38:41], v[188:191], v[146:149], v[38:41]
	v_mfma_f32_16x16x32_bf16 v[34:37], v[188:191], v[154:157], v[34:37]
	v_mfma_f32_16x16x32_bf16 v[62:65], v[166:169], v[150:153], v[62:65]
	v_mfma_f32_16x16x32_bf16 v[58:61], v[166:169], v[158:161], v[58:61]
	v_mfma_f32_16x16x32_bf16 v[54:57], v[174:177], v[150:153], v[54:57]
	v_mfma_f32_16x16x32_bf16 v[50:53], v[174:177], v[158:161], v[50:53]
	v_mfma_f32_16x16x32_bf16 v[46:49], v[184:187], v[150:153], v[46:49]
	v_mfma_f32_16x16x32_bf16 v[42:45], v[184:187], v[158:161], v[42:45]
	v_mfma_f32_16x16x32_bf16 v[38:41], v[192:195], v[150:153], v[38:41]
	v_mfma_f32_16x16x32_bf16 v[34:37], v[192:195], v[158:161], v[34:37]
	v_mfma_f32_16x16x32_bf16 v[30:33], v[162:165], v[196:199], v[30:33]
	v_mfma_f32_16x16x32_bf16 v[26:29], v[162:165], v[204:207], v[26:29]
	v_mfma_f32_16x16x32_bf16 v[22:25], v[170:173], v[196:199], v[22:25]
	v_mfma_f32_16x16x32_bf16 v[18:21], v[170:173], v[204:207], v[18:21]
	v_mfma_f32_16x16x32_bf16 v[14:17], v[180:183], v[196:199], v[14:17]
	v_mfma_f32_16x16x32_bf16 v[10:13], v[180:183], v[204:207], v[10:13]
	v_mfma_f32_16x16x32_bf16 v[6:9], v[188:191], v[196:199], v[6:9]
	v_mfma_f32_16x16x32_bf16 v[2:5], v[188:191], v[204:207], v[2:5]
	v_mfma_f32_16x16x32_bf16 v[30:33], v[166:169], v[200:203], v[30:33]
	v_mfma_f32_16x16x32_bf16 v[26:29], v[166:169], v[208:211], v[26:29]
	v_mfma_f32_16x16x32_bf16 v[22:25], v[174:177], v[200:203], v[22:25]
	v_mfma_f32_16x16x32_bf16 v[18:21], v[174:177], v[208:211], v[18:21]
	v_mfma_f32_16x16x32_bf16 v[14:17], v[184:187], v[200:203], v[14:17]
	v_mfma_f32_16x16x32_bf16 v[10:13], v[184:187], v[208:211], v[10:13]
	v_mfma_f32_16x16x32_bf16 v[6:9], v[192:195], v[200:203], v[6:9]
	v_mfma_f32_16x16x32_bf16 v[2:5], v[192:195], v[208:211], v[2:5]
	s_setprio 0
	s_add_u32 s16, s16, 0x100
	s_addc_u32 s17, s17, 0
	s_add_u32 s18, s18, 0x100
	s_addc_u32 s19, s19, 0
	s_add_u32 s20, s20, 0x100
	s_addc_u32 s21, s21, 0
	s_add_u32 s22, s22, 0x100
	s_addc_u32 s23, s23, 0
	s_add_i32 s14, s14, 2
	s_cmp_lt_u32 s14, 12
	s_barrier
	s_cbranch_scc1 .Lk_ffn_in
	s_waitcnt vmcnt(6)
	s_add_i32 s15, s7, 0xc000
	s_add_i32 s16, s7, 0xe000
	v_add_u32_e32 v216, 0, v145
	v_add_u32_e32 v145, 0x10000, v216
	ds_read_b128 v[130:133], v145
	ds_read_b128 v[146:149], v145 offset:1024
	ds_read_b128 v[150:153], v145 offset:2048
	ds_read_b128 v[154:157], v145 offset:3072
	ds_read_b128 v[158:161], v142
	ds_read_b128 v[162:165], v142 offset:1024
	ds_read_b128 v[166:169], v142 offset:2048
	ds_read_b128 v[170:173], v142 offset:3072
	ds_read_b128 v[174:177], v142 offset:4096
	ds_read_b128 v[180:183], v142 offset:5120
	ds_read_b128 v[184:187], v142 offset:6144
	ds_read_b128 v[188:191], v142 offset:7168
	s_add_u32 s0, s5, 0x40780
	s_addc_u32 s1, s6, 0
	s_mov_b32 m0, s15
	s_nop 0
	global_load_lds_dwordx4 v144, s[0:1]
	s_nop 0
	s_mov_b32 m0, s16
	s_nop 0
	global_load_lds_dwordx4 v143, s[0:1]
	s_barrier
	s_waitcnt lgkmcnt(0)
	s_setprio 1
	s_waitcnt lgkmcnt(7)
	v_mfma_f32_16x16x32_bf16 v[126:129], v[158:161], v[130:133], v[126:129]
	s_waitcnt lgkmcnt(5)
	v_mfma_f32_16x16x32_bf16 v[118:121], v[166:169], v[130:133], v[118:121]
	v_mfma_f32_16x16x32_bf16 v[114:117], v[166:169], v[150:153], v[114:117]
	s_waitcnt lgkmcnt(1)
	v_mfma_f32_16x16x32_bf16 v[102:105], v[184:187], v[130:133], v[102:105]
	v_mfma_f32_16x16x32_bf16 v[98:101], v[184:187], v[150:153], v[98:101]
	v_mfma_f32_16x16x32_bf16 v[126:129], v[162:165], v[146:149], v[126:129]
	v_mfma_f32_16x16x32_bf16 v[122:125], v[158:161], v[150:153], v[122:125]
	v_mfma_f32_16x16x32_bf16 v[118:121], v[170:173], v[146:149], v[118:121]
	v_mfma_f32_16x16x32_bf16 v[114:117], v[170:173], v[154:157], v[114:117]
	v_mfma_f32_16x16x32_bf16 v[110:113], v[174:177], v[130:133], v[110:113]
	v_mfma_f32_16x16x32_bf16 v[106:109], v[174:177], v[150:153], v[106:109]
	s_waitcnt lgkmcnt(0)
	v_mfma_f32_16x16x32_bf16 v[102:105], v[188:191], v[146:149], v[102:105]
	v_mfma_f32_16x16x32_bf16 v[98:101], v[188:191], v[154:157], v[98:101]
	v_mfma_f32_16x16x32_bf16 v[192:195], v[162:165], v[154:157], v[122:125]
	v_mfma_f32_16x16x32_bf16 v[196:199], v[180:183], v[146:149], v[110:113]
	v_mfma_f32_16x16x32_bf16 v[200:203], v[180:183], v[154:157], v[106:109]
	s_setprio 0
	v_add_u32_e32 v143, 0x14000, v216
	s_barrier
	ds_read_b128 v[106:109], v143
	ds_read_b128 v[110:113], v143 offset:1024
	ds_read_b128 v[122:125], v143 offset:2048
	ds_read_b128 v[204:207], v143 offset:3072
	s_barrier
	s_waitcnt lgkmcnt(0)
	s_setprio 1
	s_waitcnt lgkmcnt(3)
	v_mfma_f32_16x16x32_bf16 v[86:89], v[166:169], v[106:109], v[86:89]
	s_waitcnt lgkmcnt(1)
	v_mfma_f32_16x16x32_bf16 v[82:85], v[166:169], v[122:125], v[82:85]
	v_mfma_f32_16x16x32_bf16 v[70:73], v[184:187], v[106:109], v[70:73]
	v_mfma_f32_16x16x32_bf16 v[94:97], v[158:161], v[106:109], v[94:97]
	v_mfma_f32_16x16x32_bf16 v[90:93], v[158:161], v[122:125], v[90:93]
	v_mfma_f32_16x16x32_bf16 v[86:89], v[170:173], v[110:113], v[86:89]
	s_waitcnt lgkmcnt(0)
	v_mfma_f32_16x16x32_bf16 v[82:85], v[170:173], v[204:207], v[82:85]
	v_mfma_f32_16x16x32_bf16 v[78:81], v[174:177], v[106:109], v[78:81]
	v_mfma_f32_16x16x32_bf16 v[74:77], v[174:177], v[122:125], v[74:77]
	v_mfma_f32_16x16x32_bf16 v[70:73], v[188:191], v[110:113], v[70:73]
	v_mfma_f32_16x16x32_bf16 v[66:69], v[184:187], v[122:125], v[66:69]
	v_mfma_f32_16x16x32_bf16 v[208:211], v[162:165], v[110:113], v[94:97]
	v_mfma_f32_16x16x32_bf16 v[158:161], v[162:165], v[204:207], v[90:93]
	v_mfma_f32_16x16x32_bf16 v[162:165], v[180:183], v[110:113], v[78:81]
	v_mfma_f32_16x16x32_bf16 v[166:169], v[180:183], v[204:207], v[74:77]
	v_mfma_f32_16x16x32_bf16 v[170:173], v[188:191], v[204:207], v[66:69]
	s_setprio 0
	s_barrier
; #define WAIT_V(n) asm volatile("s_waitcnt vmcnt(" #n ")" ::: "memory")
; #define WAIT_L(n) asm volatile("s_waitcnt lgkmcnt(" #n ")" ::: "memory")
; #define BAR __builtin_amdgcn_s_barrier()
; #define STG_A(b, h, kt) stage_half_s(lds0 + ((b) * 2 + (h)) * HT_B, ((h) ? A1 : Ap) + (kt) * BK, off0, off1)
; #define STG_A(b, h, kt) stage_half_s(lds0 + ((b) * 2 + (h)) * HT_B, ((h) ? A1 : Ap) + (kt) * BK, off0, off1)
; #define LDA8(b, h) _Pragma("unroll") for (int m = 0; m < 4; ++m) _Pragma("unroll") for (int k = 0; k < 2; ++k) \
;     At[m][k] = *(const bf16x8*)(SA_(shm, b, h) + abase + (m * 2 + k) * 1024)
; #define LDB8(dst, b, h) _Pragma("unroll") for (int n = 0; n < 2; ++n) _Pragma("unroll") for (int k = 0; k < 2; ++k) \
;     dst[n][k] = *(const bf16x8*)(SB_(shm, b, h) + bbase + (n * 2 + k) * 1024)
; #define MMA8(ai, bj, Bx) do { __builtin_amdgcn_s_setprio(1); \
;     _Pragma("unroll") for (int m = 0; m < 4; ++m) _Pragma("unroll") for (int n = 0; n < 2; ++n) _Pragma("unroll") for (int k = 0; k < 2; ++k) \
;       acc[ai][bj][m][n] = __builtin_amdgcn_mfma_f32_16x16x32_bf16(At[m][k], Bx[n][k], acc[ai][bj][m][n], 0, 0, 0); \
;     __builtin_amdgcn_s_setprio(0); } while (0)
; template <bool HS>
; __device__ __forceinline__ void gemm_tile8(const u16* __restrict__ Ap, const u16* __restrict__ Bp, int K,
;                                            f32x4 (&acc)[2][2][4][2], char* shm, const int tid, const float* hsr = nullptr) {
;     ...
;   { LDB8(B0, 0, 0); LDA8(0, 0); STG_A(1, 1, nt - 1);
;     BAR; WAIT_L(0); MMA8(0, 0, B0); BAR;
;     LDB8(B1, 0, 1); BAR; WAIT_L(0); MMA8(0, 1, B1); BAR;
;     LDA8(0, 1); WAIT_V(4); BAR; WAIT_L(0); MMA8(1, 0, B0); MMA8(1, 1, B1); BAR; }
;   { LDB8(B0, 1, 0); LDA8(1, 0); WAIT_V(2); BAR; WAIT_L(0); MMA8(0, 0, B0); BAR;
;     LDB8(B1, 1, 1); WAIT_V(0); BAR; WAIT_L(0); MMA8(0, 1, B1); BAR;
	s_nop 0
	ds_read_b128 v[66:69], v142 offset:16384
	ds_read_b128 v[74:77], v142 offset:17408
	ds_read_b128 v[78:81], v142 offset:18432
	ds_read_b128 v[90:93], v142 offset:19456
	ds_read_b128 v[94:97], v142 offset:20480
	ds_read_b128 v[174:177], v142 offset:21504
	ds_read_b128 v[180:183], v142 offset:22528
	ds_read_b128 v[184:187], v142 offset:23552
	s_waitcnt vmcnt(4)
	s_barrier
	s_waitcnt lgkmcnt(0)
	s_setprio 1
	s_waitcnt lgkmcnt(7)
	v_mfma_f32_16x16x32_bf16 v[62:65], v[66:69], v[130:133], v[62:65]
	s_waitcnt lgkmcnt(5)
	v_mfma_f32_16x16x32_bf16 v[54:57], v[78:81], v[130:133], v[54:57]
	v_mfma_f32_16x16x32_bf16 v[50:53], v[78:81], v[150:153], v[50:53]
	s_waitcnt lgkmcnt(1)
	v_mfma_f32_16x16x32_bf16 v[38:41], v[180:183], v[130:133], v[38:41]
	v_mfma_f32_16x16x32_bf16 v[34:37], v[180:183], v[150:153], v[34:37]
	v_mfma_f32_16x16x32_bf16 v[62:65], v[74:77], v[146:149], v[62:65]
	v_mfma_f32_16x16x32_bf16 v[58:61], v[66:69], v[150:153], v[58:61]
	v_mfma_f32_16x16x32_bf16 v[54:57], v[90:93], v[146:149], v[54:57]
	v_mfma_f32_16x16x32_bf16 v[50:53], v[90:93], v[154:157], v[50:53]
	v_mfma_f32_16x16x32_bf16 v[46:49], v[94:97], v[130:133], v[46:49]
	v_mfma_f32_16x16x32_bf16 v[42:45], v[94:97], v[150:153], v[42:45]
	s_waitcnt lgkmcnt(0)
	v_mfma_f32_16x16x32_bf16 v[38:41], v[184:187], v[146:149], v[38:41]
	v_mfma_f32_16x16x32_bf16 v[34:37], v[184:187], v[154:157], v[34:37]
	v_mfma_f32_16x16x32_bf16 v[188:191], v[74:77], v[154:157], v[58:61]
	v_mfma_f32_16x16x32_bf16 v[212:215], v[174:177], v[146:149], v[46:49]
	v_mfma_f32_16x16x32_bf16 v[242:245], v[174:177], v[154:157], v[42:45]
	s_setprio 0
	s_setprio 1
	v_mfma_f32_16x16x32_bf16 v[22:25], v[78:81], v[106:109], v[22:25]
	v_mfma_f32_16x16x32_bf16 v[18:21], v[78:81], v[122:125], v[18:21]
	v_mfma_f32_16x16x32_bf16 v[6:9], v[180:183], v[106:109], v[6:9]
	v_mfma_f32_16x16x32_bf16 v[30:33], v[66:69], v[106:109], v[30:33]
	v_mfma_f32_16x16x32_bf16 v[26:29], v[66:69], v[122:125], v[26:29]
	v_mfma_f32_16x16x32_bf16 v[22:25], v[90:93], v[110:113], v[22:25]
	v_mfma_f32_16x16x32_bf16 v[18:21], v[90:93], v[204:207], v[18:21]
	v_mfma_f32_16x16x32_bf16 v[14:17], v[94:97], v[106:109], v[14:17]
	v_mfma_f32_16x16x32_bf16 v[10:13], v[94:97], v[122:125], v[10:13]
	v_mfma_f32_16x16x32_bf16 v[6:9], v[184:187], v[110:113], v[6:9]
	v_mfma_f32_16x16x32_bf16 v[2:5], v[180:183], v[122:125], v[2:5]
	v_mfma_f32_16x16x32_bf16 v[130:133], v[74:77], v[110:113], v[30:33]
	v_mfma_f32_16x16x32_bf16 v[144:147], v[74:77], v[204:207], v[26:29]
	v_mfma_f32_16x16x32_bf16 v[148:151], v[174:177], v[110:113], v[14:17]
	v_mfma_f32_16x16x32_bf16 v[152:155], v[174:177], v[204:207], v[10:13]
	v_mfma_f32_16x16x32_bf16 v[174:177], v[184:187], v[204:207], v[2:5]
	s_setprio 0
	v_add_u32_e32 v26, 0x18000, v216
	s_barrier
	ds_read_b128 v[2:5], v26
	ds_read_b128 v[10:13], v26 offset:1024
	ds_read_b128 v[14:17], v26 offset:2048
	ds_read_b128 v[180:183], v26 offset:3072
	ds_read_b128 v[26:29], v142 offset:32768
	ds_read_b128 v[30:33], v142 offset:33792
	ds_read_b128 v[42:45], v142 offset:34816
	ds_read_b128 v[46:49], v142 offset:35840
	ds_read_b128 v[58:61], v142 offset:36864
	ds_read_b128 v[66:69], v142 offset:37888
	ds_read_b128 v[184:187], v142 offset:38912
	ds_read_b128 v[204:207], v142 offset:39936
	s_waitcnt vmcnt(2)
	s_barrier
	s_waitcnt lgkmcnt(0)
	s_setprio 1
	s_waitcnt lgkmcnt(7)
	v_mfma_f32_16x16x32_bf16 v[74:77], v[26:29], v[2:5], v[126:129]
	s_waitcnt lgkmcnt(6)
	v_mfma_f32_16x16x32_bf16 v[122:125], v[30:33], v[10:13], v[74:77]
	v_mfma_f32_16x16x32_bf16 v[74:77], v[26:29], v[14:17], v[192:195]
	v_mfma_f32_16x16x32_bf16 v[126:129], v[30:33], v[180:183], v[74:77]
	s_waitcnt lgkmcnt(5)
	v_mfma_f32_16x16x32_bf16 v[74:77], v[42:45], v[2:5], v[118:121]
	s_waitcnt lgkmcnt(4)
	v_mfma_f32_16x16x32_bf16 v[106:109], v[46:49], v[10:13], v[74:77]
	v_mfma_f32_16x16x32_bf16 v[74:77], v[42:45], v[14:17], v[114:117]
	v_mfma_f32_16x16x32_bf16 v[110:113], v[46:49], v[180:183], v[74:77]
	s_waitcnt lgkmcnt(3)
	v_mfma_f32_16x16x32_bf16 v[74:77], v[58:61], v[2:5], v[196:199]
	s_waitcnt lgkmcnt(2)
	v_mfma_f32_16x16x32_bf16 v[90:93], v[66:69], v[10:13], v[74:77]
	v_mfma_f32_16x16x32_bf16 v[74:77], v[58:61], v[14:17], v[200:203]
	v_mfma_f32_16x16x32_bf16 v[94:97], v[66:69], v[180:183], v[74:77]
	s_waitcnt lgkmcnt(1)
	v_mfma_f32_16x16x32_bf16 v[74:77], v[184:187], v[2:5], v[102:105]
	v_mfma_f32_16x16x32_bf16 v[78:81], v[184:187], v[14:17], v[98:101]
	s_waitcnt lgkmcnt(0)
	v_mfma_f32_16x16x32_bf16 v[74:77], v[204:207], v[10:13], v[74:77]
	v_mfma_f32_16x16x32_bf16 v[78:81], v[204:207], v[180:183], v[78:81]
	s_setprio 0
	v_add_u32_e32 v98, 0x1c000, v216
	s_barrier
	ds_read_b128 v[192:195], v98
	ds_read_b128 v[196:199], v98 offset:1024
	ds_read_b128 v[200:203], v98 offset:2048
	ds_read_b128 v[246:249], v98 offset:3072
	s_waitcnt vmcnt(0)
	s_barrier
	s_waitcnt lgkmcnt(0)
	s_setprio 1
	s_waitcnt lgkmcnt(3)
	v_mfma_f32_16x16x32_bf16 v[98:101], v[26:29], v[192:195], v[208:211]
	s_waitcnt lgkmcnt(1)
	v_mfma_f32_16x16x32_bf16 v[26:29], v[26:29], v[200:203], v[158:161]
	s_waitcnt lgkmcnt(0)
	v_mfma_f32_16x16x32_bf16 v[118:121], v[30:33], v[246:249], v[26:29]
	v_mfma_f32_16x16x32_bf16 v[26:29], v[42:45], v[192:195], v[86:89]
	v_mfma_f32_16x16x32_bf16 v[114:117], v[30:33], v[196:199], v[98:101]
	v_mfma_f32_16x16x32_bf16 v[98:101], v[46:49], v[196:199], v[26:29]
	v_mfma_f32_16x16x32_bf16 v[26:29], v[42:45], v[200:203], v[82:85]
	v_mfma_f32_16x16x32_bf16 v[102:105], v[46:49], v[246:249], v[26:29]
	v_mfma_f32_16x16x32_bf16 v[26:29], v[58:61], v[192:195], v[162:165]
	v_mfma_f32_16x16x32_bf16 v[82:85], v[66:69], v[196:199], v[26:29]
	v_mfma_f32_16x16x32_bf16 v[26:29], v[58:61], v[200:203], v[166:169]
	v_mfma_f32_16x16x32_bf16 v[86:89], v[66:69], v[246:249], v[26:29]
	v_mfma_f32_16x16x32_bf16 v[26:29], v[184:187], v[192:195], v[70:73]
	v_mfma_f32_16x16x32_bf16 v[66:69], v[204:207], v[196:199], v[26:29]
	v_mfma_f32_16x16x32_bf16 v[26:29], v[184:187], v[200:203], v[170:173]
	v_mfma_f32_16x16x32_bf16 v[70:73], v[204:207], v[246:249], v[26:29]
	s_setprio 0
	s_barrier
; #define WAIT_V(n) asm volatile("s_waitcnt vmcnt(" #n ")" ::: "memory")
; #define WAIT_L(n) asm volatile("s_waitcnt lgkmcnt(" #n ")" ::: "memory")
; #define BAR __builtin_amdgcn_s_barrier()
; #define LDA8(b, h) _Pragma("unroll") for (int m = 0; m < 4; ++m) _Pragma("unroll") for (int k = 0; k < 2; ++k) \
;     At[m][k] = *(const bf16x8*)(SA_(shm, b, h) + abase + (m * 2 + k) * 1024)
; #define LDB8(dst, b, h) _Pragma("unroll") for (int n = 0; n < 2; ++n) _Pragma("unroll") for (int k = 0; k < 2; ++k) \
;     dst[n][k] = *(const bf16x8*)(SB_(shm, b, h) + bbase + (n * 2 + k) * 1024)
; #define MMA8(ai, bj, Bx) do { __builtin_amdgcn_s_setprio(1); \
;     _Pragma("unroll") for (int m = 0; m < 4; ++m) _Pragma("unroll") for (int n = 0; n < 2; ++n) _Pragma("unroll") for (int k = 0; k < 2; ++k) \
;       acc[ai][bj][m][n] = __builtin_amdgcn_mfma_f32_16x16x32_bf16(At[m][k], Bx[n][k], acc[ai][bj][m][n], 0, 0, 0); \
;     __builtin_amdgcn_s_setprio(0); } while (0)
; template <bool HS>
; __device__ __forceinline__ void gemm_tile8(const u16* __restrict__ Ap, const u16* __restrict__ Bp, int K,
;                                            f32x4 (&acc)[2][2][4][2], char* shm, const int tid, const float* hsr = nullptr) {
;     ...
;     LDB8(B1, 1, 1); WAIT_V(0); BAR; WAIT_L(0); MMA8(0, 1, B1); BAR;
;     LDA8(1, 1); BAR; WAIT_L(0); MMA8(1, 0, B0); MMA8(1, 1, B1); BAR; }
;   if (wr == 0) BAR;
	ds_read_b128 v[156:159], v142 offset:49152
	ds_read_b128 v[160:163], v142 offset:50176
	ds_read_b128 v[164:167], v142 offset:51200
	ds_read_b128 v[168:171], v142 offset:52224
	ds_read_b128 v[184:187], v142 offset:53248
	ds_read_b128 v[204:207], v142 offset:54272
	ds_read_b128 v[208:211], v142 offset:55296
	ds_read_b128 v[220:223], v142 offset:56320
	s_barrier
	s_waitcnt lgkmcnt(0)
	s_setprio 1
	s_waitcnt lgkmcnt(7)
	v_mfma_f32_16x16x32_bf16 v[26:29], v[156:159], v[2:5], v[62:65]
	s_waitcnt lgkmcnt(6)
	v_mfma_f32_16x16x32_bf16 v[58:61], v[160:163], v[10:13], v[26:29]
	v_mfma_f32_16x16x32_bf16 v[26:29], v[156:159], v[14:17], v[188:191]
	v_mfma_f32_16x16x32_bf16 v[62:65], v[160:163], v[180:183], v[26:29]
	s_waitcnt lgkmcnt(5)
	v_mfma_f32_16x16x32_bf16 v[26:29], v[164:167], v[2:5], v[54:57]
	s_waitcnt lgkmcnt(4)
	v_mfma_f32_16x16x32_bf16 v[42:45], v[168:171], v[10:13], v[26:29]
	v_mfma_f32_16x16x32_bf16 v[26:29], v[164:167], v[14:17], v[50:53]
	v_mfma_f32_16x16x32_bf16 v[46:49], v[168:171], v[180:183], v[26:29]
	s_waitcnt lgkmcnt(3)
	v_mfma_f32_16x16x32_bf16 v[26:29], v[184:187], v[2:5], v[212:215]
	s_waitcnt lgkmcnt(1)
	v_mfma_f32_16x16x32_bf16 v[2:5], v[208:211], v[2:5], v[38:41]
	v_mfma_f32_16x16x32_bf16 v[26:29], v[204:207], v[10:13], v[26:29]
	v_mfma_f32_16x16x32_bf16 v[30:33], v[184:187], v[14:17], v[242:245]
	s_waitcnt lgkmcnt(0)
	v_mfma_f32_16x16x32_bf16 v[10:13], v[220:223], v[10:13], v[2:5]
	v_mfma_f32_16x16x32_bf16 v[2:5], v[208:211], v[14:17], v[34:37]
	v_mfma_f32_16x16x32_bf16 v[30:33], v[204:207], v[180:183], v[30:33]
	v_mfma_f32_16x16x32_bf16 v[14:17], v[220:223], v[180:183], v[2:5]
	s_setprio 0
	s_setprio 1
	v_mfma_f32_16x16x32_bf16 v[2:5], v[156:159], v[192:195], v[130:133]
	v_mfma_f32_16x16x32_bf16 v[50:53], v[160:163], v[196:199], v[2:5]
	v_mfma_f32_16x16x32_bf16 v[2:5], v[156:159], v[200:203], v[144:147]
	v_mfma_f32_16x16x32_bf16 v[54:57], v[160:163], v[246:249], v[2:5]
	v_mfma_f32_16x16x32_bf16 v[2:5], v[164:167], v[192:195], v[22:25]
	v_mfma_f32_16x16x32_bf16 v[34:37], v[168:171], v[196:199], v[2:5]
	v_mfma_f32_16x16x32_bf16 v[2:5], v[164:167], v[200:203], v[18:21]
	v_mfma_f32_16x16x32_bf16 v[38:41], v[168:171], v[246:249], v[2:5]
	v_mfma_f32_16x16x32_bf16 v[2:5], v[184:187], v[192:195], v[148:151]
	v_mfma_f32_16x16x32_bf16 v[18:21], v[204:207], v[196:199], v[2:5]
	v_mfma_f32_16x16x32_bf16 v[2:5], v[184:187], v[200:203], v[152:155]
	v_mfma_f32_16x16x32_bf16 v[22:25], v[204:207], v[246:249], v[2:5]
	v_mfma_f32_16x16x32_bf16 v[2:5], v[208:211], v[192:195], v[6:9]
	v_mfma_f32_16x16x32_bf16 v[6:9], v[208:211], v[200:203], v[174:177]
	v_mfma_f32_16x16x32_bf16 v[2:5], v[220:223], v[196:199], v[2:5]
	v_mfma_f32_16x16x32_bf16 v[6:9], v[220:223], v[246:249], v[6:9]
	s_setprio 0
	s_movk_i32 s0, 0x100
	v_cmp_gt_u32_e32 vcc, s0, v0
	s_barrier
	s_and_saveexec_b64 s[0:1], vcc
	s_cbranch_execz .LBB0_862
	s_barrier
; #define STG_A(b, h, kt) stage_half_s(lds0 + ((b) * 2 + (h)) * HT_B, ((h) ? A1 : Ap) + (kt) * BK, off0, off1)
; #define STG_B(b, h, kt) stage_half_s(lds0 + (4 + (b) * 2 + (h)) * HT_B, ((h) ? B1p : Bp) + (kt) * BK, off0, off1)
; #define STG_A(b, h, kt) stage_half_s(lds0 + ((b) * 2 + (h)) * HT_B, ((h) ? A1 : Ap) + (kt) * BK, off0, off1)
; #define STG_B(b, h, kt) stage_half_s(lds0 + (4 + (b) * 2 + (h)) * HT_B, ((h) ? B1p : Bp) + (kt) * BK, off0, off1)
; __device__ __forceinline__ void gemm8_prefetch(const u16* __restrict__ Ap, const u16* __restrict__ Bp, int K, char* shm, const int tid) {
;   int r0, c0, r1, c1;
;   stage_rc(tid * 16, r0, c0);
;   stage_rc(tid * 16 + 8192, r1, c1);
;   const unsigned off0 = (unsigned)(r0 * K + c0) * 2u, off1 = (unsigned)(r1 * K + c1) * 2u;
;   const int wvoff = __builtin_amdgcn_readfirstlane(tid >> 6) * 1024;
;   const u16* A1 = Ap + (size_t)128 * K;
;   const u16* B1p = Bp + (size_t)128 * K;
;   const unsigned lds0 = (unsigned)(size_t)(__attribute__((address_space(3))) char*)shm + (unsigned)wvoff;
;     ...
;   STG_B(0, 0, 0); STG_A(0, 0, 0); STG_B(0, 1, 0); STG_A(0, 1, 0);
;   STG_B(1, 0, 1); STG_A(1, 0, 1); STG_B(1, 1, 1);
; template <int EPI, bool HS = false>
; __device__ __forceinline__ void gemm_phase(const Params& p, const GemmCfg& g, char* shm, const int wave_s) {
;     ...
;     if (!defer_pf && tile + (int)gridDim.x < nwg) {
;       int mt2, pn2, arow2, orow2;
;       tile_coords(tile + gridDim.x, mt2, pn2, arow2, orow2);
;       gemm8_prefetch(g.A + (size_t)arow2 * g.K, g.Bt + (size_t)pn2 * 256 * g.K, g.K, shm, fresh_tid(wave_s));
;     }
.LBB0_862:
	s_or_b64 exec, exec, s[0:1]
	s_add_i32 s8, s8, s44
	s_cmpk_gt_i32 s8, 0x15ff
	s_cselect_b64 s[0:1], -1, 0
	s_and_b64 vcc, exec, s[0:1]
	s_cbranch_vccnz .LBB0_853
	s_ashr_i32 s3, s8, 31
	s_lshr_b32 s3, s3, 29
	s_add_i32 s3, s8, s3
	s_ashr_i32 s5, s3, 3
	s_and_b32 s3, s3, -8
	s_sub_i32 s3, s8, s3
	s_cmp_lt_i32 s3, 0
	s_movk_i32 s6, 0x2c1
	s_cselect_b32 s6, s6, 0x2c0
	s_mul_i32 s3, s6, s3
	s_add_i32 s3, s3, s5
	s_mul_hi_i32 s5, s3, 0x2e8ba2e9
	s_lshr_b32 s6, s5, 31
	s_ashr_i32 s5, s5, 5
	s_add_i32 s5, s5, s6
	s_mul_i32 s6, s5, 0xb0
	s_sub_i32 s3, s3, s6
	s_bfe_u32 s6, s3, 0x3001c
	s_add_i32 s6, s3, s6
	s_sext_i32_i16 s7, s6
	s_and_b32 s6, s6, 0xfff8
	s_sub_i32 s3, s3, s6
	s_sext_i32_i16 s3, s3
	s_lshl_b32 s5, s5, 11
	s_lshl_b32 s3, s3, 8
	s_add_i32 s6, s3, s5
	s_mov_b32 s3, s82
	s_mov_b32 s5, -1
	s_lshr_b32 s10, s7, 3
	v_mbcnt_lo_u32_b32 v0, s5, 0
	v_mbcnt_hi_u32_b32 v0, s5, v0
	v_lshl_add_u32 v0, s3, 6, v0
	s_ashr_i32 s7, s6, 31
	v_bfe_i32 v142, v0, 27, 1
	v_lshlrev_b32_e32 v132, 4, v0
	v_lshrrev_b32_e32 v142, 22, v142
	v_add_u32_e32 v142, v132, v142
	v_and_b32_e32 v142, 0xfffffc00, v142
	v_ashrrev_i32_e32 v133, 31, v0
	v_sub_u32_e32 v142, v132, v142
	v_lshrrev_b32_e32 v133, 26, v133
	v_lshrrev_b32_e32 v143, 4, v142
	v_add_u32_e32 v133, v0, v133
	v_bitop3_b32 v143, v143, v142, 32 bitop3:0x6c
	v_ashrrev_i32_e32 v142, 31, v142
	v_ashrrev_i32_e32 v133, 6, v133
	v_lshrrev_b32_e32 v142, 26, v142
	v_lshlrev_b32_e32 v144, 3, v133
	v_add_u32_e32 v142, v143, v142
	v_and_b32_e32 v144, 0x1ffff0, v144
	v_ashrrev_i32_e32 v142, 6, v142
	v_add_u32_e32 v144, v142, v144
	v_mul_i32_i24_e32 v142, 64, v142
	v_add_u32_e32 v132, 0x2000, v132
	v_sub_u32_e32 v142, v143, v142
	v_ashrrev_i32_e32 v143, 31, v132
	v_lshrrev_b32_e32 v143, 22, v143
	v_add_u32_e32 v143, v132, v143
	v_ashrrev_i32_e32 v143, 10, v143
	v_mul_i32_i24_e32 v145, 0x400, v143
	v_sub_u32_e32 v132, v132, v145
	v_lshrrev_b32_e32 v145, 4, v132
	s_lshl_b64 s[6:7], s[6:7], 11
	v_bitop3_b32 v132, v145, v132, 32 bitop3:0x6c
	s_add_u32 s6, s88, s6
	v_ashrrev_i32_e32 v146, 31, v132
	s_addc_u32 s7, s89, s7
	s_bfe_i64 s[10:11], s[10:11], 0x100000
	v_lshrrev_b32_e32 v146, 26, v146
	s_lshl_b64 s[10:11], s[10:11], 19
	v_add_u32_e32 v146, v132, v146
	v_lshl_add_u64 v[130:131], v[134:135], 0, s[10:11]
	v_lshlrev_b32_e32 v133, 5, v133
	v_lshlrev_b32_e32 v145, 3, v143
	v_lshrrev_b32_e32 v147, 6, v146
	v_and_b32_e32 v146, 0xc0, v146
	v_readfirstlane_b32 s3, v0
	s_add_u32 s10, s6, 0x40000
	v_and_b32_e32 v133, 32, v133
	v_ashrrev_i16_sdwa v142, v178, sext(v142) dst_sel:DWORD dst_unused:UNUSED_PAD src0_sel:DWORD src1_sel:BYTE_0
	v_and_b32_e32 v145, 0x1ffff0, v145
	v_lshlrev_b32_e32 v143, 5, v143
	v_sub_u32_e32 v132, v132, v146
	s_addc_u32 s11, s7, 0
	s_lshl_b32 s3, s3, 4
	v_bfe_i32 v142, v142, 0, 16
	v_add_u32_e32 v145, v147, v145
	v_and_b32_e32 v143, 32, v143
	v_ashrrev_i16_sdwa v132, v178, sext(v132) dst_sel:DWORD dst_unused:UNUSED_PAD src0_sel:DWORD src1_sel:BYTE_0
	v_lshl_or_b32 v133, v144, 10, v133
	s_and_b32 s3, s3, 0xfffffc00
	v_bfe_i32 v132, v132, 0, 16
	v_add_lshl_u32 v142, v133, v142, 1
	v_lshl_or_b32 v133, v145, 10, v143
	s_mov_b64 s[12:13], 0x40000
	s_add_i32 s3, s3, 0
	v_add_lshl_u32 v143, v133, v132, 1
	v_lshl_add_u64 v[132:133], v[130:131], 0, s[12:13]
	v_readfirstlane_b32 s13, v131
	v_readfirstlane_b32 s12, v130
	s_add_i32 s5, s3, 0x10000
	s_mov_b32 m0, s5
	s_nop 2
	global_load_lds_dwordx4 v142, s[12:13]
	s_add_i32 s5, s3, 0x12000
	s_mov_b32 m0, s5
	s_nop 0
	global_load_lds_dwordx4 v143, s[12:13]
	s_mov_b32 m0, s3
	s_nop 0
	global_load_lds_dwordx4 v142, s[6:7]
	s_add_i32 s5, s3, 0x2000
	s_mov_b32 m0, s5
	s_nop 0
	global_load_lds_dwordx4 v143, s[6:7]
	v_readfirstlane_b32 s13, v133
	v_readfirstlane_b32 s12, v132
	s_add_i32 s5, s3, 0x14000
	s_mov_b32 m0, s5
	s_nop 2
	global_load_lds_dwordx4 v142, s[12:13]
	s_add_i32 s5, s3, 0x16000
	s_mov_b32 m0, s5
	s_nop 0
	global_load_lds_dwordx4 v143, s[12:13]
	s_add_i32 s5, s3, 0x4000
	s_mov_b32 m0, s5
	s_nop 0
	global_load_lds_dwordx4 v142, s[10:11]
	s_add_i32 s5, s3, 0x6000
	s_mov_b32 m0, s5
	s_nop 0
	global_load_lds_dwordx4 v143, s[10:11]
	s_mov_b64 s[10:11], 0x80
	v_lshl_add_u64 v[132:133], v[130:131], 0, s[10:11]
	s_add_i32 s5, s3, 0x18000
	v_readfirstlane_b32 s11, v133
	v_readfirstlane_b32 s10, v132
	s_mov_b32 m0, s5
	s_nop 3
	global_load_lds_dwordx4 v142, s[10:11]
	s_add_i32 s5, s3, 0x1a000
	s_mov_b32 m0, s5
	s_nop 0
	global_load_lds_dwordx4 v143, s[10:11]
	s_add_u32 s6, s6, 0x80
	s_addc_u32 s7, s7, 0
	s_add_i32 s5, s3, 0x8000
	s_mov_b32 m0, s5
	s_nop 0
	global_load_lds_dwordx4 v142, s[6:7]
	s_add_i32 s5, s3, 0xa000
	s_mov_b32 m0, s5
	s_nop 0
	global_load_lds_dwordx4 v143, s[6:7]
	s_mov_b64 s[6:7], 0x40080
	v_lshl_add_u64 v[130:131], v[130:131], 0, s[6:7]
	s_add_i32 s5, s3, 0x1c000
	v_readfirstlane_b32 s7, v131
	v_readfirstlane_b32 s6, v130
	s_mov_b32 m0, s5
	s_nop 3
	global_load_lds_dwordx4 v142, s[6:7]
	s_add_i32 s3, s3, 0x1e000
	s_mov_b32 m0, s3
	s_nop 0
	global_load_lds_dwordx4 v143, s[6:7]
	s_branch .LBB0_853

; __device__ __forceinline__ int srccol(int perm, int n) {
;   if (perm == 1) {
;     int blk = n >> 5, t = (n >> 4) & 1, i = n & 15;
;     int j = blk * 16 + i;
;     return t ? DFF + j : j;
; __device__ __forceinline__ void conv_family(const float* __restrict__ W, u16* __restrict__ Wt, int cnt, int K, int N, int perm,
;                             float* tile, const int tid, const float* __restrict__ kscale = nullptr) {
;     ...
;   for (int t = blockIdx.x; t < total; t += gridDim.x) {
;     int mi = t / per, r = t % per, kt = r / tn, ntile = r % tn;
;     const float* Ws = W + (size_t)mi * K * N;
;     u16* Wd = Wt + (size_t)mi * K * N;
;     int k0 = kt * 64, n0 = ntile * 256;
;     {
;       int n = tid & 255;
;       int sc = srccol(perm, n0 + n);
;       const float* wp = Ws + (size_t)(k0 + (tid >> 8)) * N + sc;
;       float v[32];
; #pragma unroll
;       for (int i = 0; i < 32; ++i) v[i] = wp[(size_t)(2 * i) * N];
.LBB0_908:
	s_mul_hi_i32 s1, s0, 0x2e8ba2e9
	s_lshr_b32 s2, s1, 31
	s_ashr_i32 s1, s1, 6
	s_add_i32 s1, s1, s2
	s_mul_i32 s6, s1, 0xfffffea0
	s_mul_hi_i32 s3, s1, 0x580000
	s_mul_i32 s2, s1, 0x580000
	s_add_i32 s1, s0, s6
	s_mul_i32 s8, s1, 0xba3
	s_lshr_b32 s9, s8, 31
	s_lshr_b32 s8, s8, 16
	s_add_i32 s8, s8, s9
	s_sext_i32_i16 s9, s8
	s_mul_i32 s8, s8, 22
	s_lshl_b64 s[6:7], s[2:3], 2
	s_sub_i32 s1, s1, s8
	s_add_u32 s6, s18, s6
	s_addc_u32 s7, s19, s7
	s_lshl_b64 s[2:3], s[2:3], 1
	s_sext_i32_i16 s1, s1
	s_add_u32 s8, s66, s2
	s_addc_u32 s10, s67, s3
	s_lshl_b32 s1, s1, 8
	v_or_b32_e32 v11, s1, v3
	v_lshrrev_b32_e32 v13, 5, v3
	v_and_b32_e32 v20, 3, v13
	v_lshrrev_b32_e32 v13, 2, v13
	v_lshl_add_u32 v13, v5, 1, v13
	v_lshl_add_u32 v20, v20, 5, v13
	v_lshrrev_b32_e32 v13, 1, v11
	v_and_b32_e32 v13, 0xffffff80, v13
	v_add_u32_e32 v20, v20, v13
	s_lshl_b32 s2, s9, 6
	v_add_u32_e32 v21, 0xb00, v20
	v_mov_b64_e32 v[8:9], s[6:7]
	v_add_u32_e32 v12, s2, v4
	v_add_u32_e32 v10, s1, v7
	s_movk_i32 s1, 0x5800
	v_cndmask_b32_e64 v20, v21, v20, s[4:5]
	v_mad_i64_i32 v[16:17], s[6:7], v12, s1, v[8:9]
	v_ashrrev_i32_e32 v21, 31, v20
	v_lshl_add_u64 v[48:49], v[20:21], 2, v[16:17]
	v_add_co_u32_e32 v50, vcc, s12, v48
	s_mov_b32 s1, 0x37000
	s_nop 0
	v_addc_co_u32_e32 v51, vcc, 0, v49, vcc
	v_add_co_u32_e32 v52, vcc, s11, v48
	s_ashr_i32 s3, s2, 31
	s_nop 0
	v_addc_co_u32_e32 v53, vcc, 0, v49, vcc
	v_add_co_u32_e32 v54, vcc, s13, v48
	s_lshl_b64 s[2:3], s[2:3], 1
	s_nop 0
	v_addc_co_u32_e32 v55, vcc, 0, v49, vcc
	v_add_co_u32_e32 v56, vcc, s39, v48
	v_add_u32_e32 v8, 64, v10
	s_nop 0
	v_addc_co_u32_e32 v57, vcc, 0, v49, vcc
	v_add_co_u32_e32 v58, vcc, s1, v48
	s_mov_b32 s1, 0x4d000
	s_nop 0
	v_addc_co_u32_e32 v59, vcc, 0, v49, vcc
	v_add_co_u32_e32 v60, vcc, s14, v48
	s_add_u32 s2, s8, s2
	s_nop 0
	v_addc_co_u32_e32 v61, vcc, 0, v49, vcc
	v_add_co_u32_e32 v62, vcc, s1, v48
	s_mov_b32 s1, 0x58000
	s_nop 0
	v_addc_co_u32_e32 v63, vcc, 0, v49, vcc
	v_add_co_u32_e32 v64, vcc, s1, v48
	s_mov_b32 s1, 0x6e000
	s_nop 0
	v_addc_co_u32_e32 v65, vcc, 0, v49, vcc
	v_add_co_u32_e32 v66, vcc, s35, v48
	v_ashrrev_i32_e32 v11, 31, v10
	s_nop 0
	v_addc_co_u32_e32 v67, vcc, 0, v49, vcc
	v_add_co_u32_e32 v68, vcc, s1, v48
	s_mov_b32 s1, 0x79000
	s_nop 0
	v_addc_co_u32_e32 v69, vcc, 0, v49, vcc
	v_add_co_u32_e32 v70, vcc, s1, v48
	s_mov_b32 s1, 0x8f000
	s_nop 0
	v_addc_co_u32_e32 v71, vcc, 0, v49, vcc
	v_add_co_u32_e32 v78, vcc, s15, v48
	v_ashrrev_i32_e32 v9, 31, v8
	s_nop 0
	v_addc_co_u32_e32 v79, vcc, 0, v49, vcc
	v_add_co_u32_e32 v80, vcc, s1, v48
	s_mov_b32 s1, 0x9a000
	s_nop 0
	v_addc_co_u32_e32 v81, vcc, 0, v49, vcc
	v_add_co_u32_e32 v82, vcc, s1, v48
	s_mov_b32 s1, 0xa5000
	s_nop 0
	v_addc_co_u32_e32 v83, vcc, 0, v49, vcc
	v_add_co_u32_e32 v84, vcc, s1, v48
	s_mov_b32 s1, 0xb0000
	s_nop 0
	v_addc_co_u32_e32 v85, vcc, 0, v49, vcc
	v_add_co_u32_e32 v86, vcc, s1, v48
	s_mov_b32 s1, 0xbb000
	s_nop 0
	v_addc_co_u32_e32 v87, vcc, 0, v49, vcc
	v_add_co_u32_e32 v34, vcc, s1, v48
	s_mov_b32 s1, 0xc6000
	s_nop 0
	v_addc_co_u32_e32 v35, vcc, 0, v49, vcc
	v_add_co_u32_e32 v36, vcc, s1, v48
	s_mov_b32 s1, 0xd1000
	s_nop 0
	v_addc_co_u32_e32 v37, vcc, 0, v49, vcc
	v_add_co_u32_e32 v38, vcc, s1, v48
	s_mov_b32 s1, 0xdc000
	s_nop 0
	v_addc_co_u32_e32 v39, vcc, 0, v49, vcc
	v_add_co_u32_e32 v40, vcc, s1, v48
	s_mov_b32 s1, 0xe7000
	s_nop 0
	v_addc_co_u32_e32 v41, vcc, 0, v49, vcc
	v_add_co_u32_e32 v42, vcc, s1, v48
	s_mov_b32 s1, 0xf2000
	s_nop 0
	v_addc_co_u32_e32 v43, vcc, 0, v49, vcc
	v_add_co_u32_e32 v44, vcc, s1, v48
	s_mov_b32 s1, 0xfd000
	s_nop 0
	v_addc_co_u32_e32 v45, vcc, 0, v49, vcc
	s_addc_u32 s3, s10, s3
	v_add_co_u32_e32 v16, vcc, s1, v48
	v_add_u32_e32 v12, 0x80, v10
	v_add_u32_e32 v14, 0xc0, v10
	v_lshlrev_b64 v[10:11], 11, v[10:11]
	v_lshlrev_b64 v[18:19], 11, v[8:9]
	v_lshl_add_u64 v[22:23], s[2:3], 0, v[0:1]
	v_addc_co_u32_e32 v17, vcc, 0, v49, vcc
	v_lshl_add_u64 v[8:9], v[22:23], 0, v[10:11]
	v_lshl_add_u64 v[10:11], v[22:23], 0, v[18:19]
	v_add_co_u32_e32 v18, vcc, s16, v48
	s_mov_b32 s1, 0x113000
	s_nop 0
	v_addc_co_u32_e32 v19, vcc, 0, v49, vcc
	v_ashrrev_i32_e32 v13, 31, v12
	v_ashrrev_i32_e32 v15, 31, v14
	v_add_co_u32_e32 v20, vcc, s1, v48
	v_lshlrev_b64 v[12:13], 11, v[12:13]
	v_lshlrev_b64 v[14:15], 11, v[14:15]
	v_addc_co_u32_e32 v21, vcc, 0, v49, vcc
	s_mov_b32 s1, 0x11e000
	v_lshl_add_u64 v[12:13], v[22:23], 0, v[12:13]
	v_lshl_add_u64 v[14:15], v[22:23], 0, v[14:15]
	v_add_co_u32_e32 v22, vcc, s1, v48
	s_mov_b32 s1, 0x129000
	s_nop 0
	v_addc_co_u32_e32 v23, vcc, 0, v49, vcc
	v_add_co_u32_e32 v24, vcc, s1, v48
	s_mov_b32 s1, 0x134000
	s_nop 0
	v_addc_co_u32_e32 v25, vcc, 0, v49, vcc
	v_add_co_u32_e32 v26, vcc, s1, v48
	s_mov_b32 s1, 0x13f000
	s_nop 0
	v_addc_co_u32_e32 v27, vcc, 0, v49, vcc
	v_add_co_u32_e32 v28, vcc, s1, v48
	s_mov_b32 s1, 0x14a000
	s_waitcnt lgkmcnt(0)
; __device__ __forceinline__ unsigned pack2(float a, float b) { return (unsigned)f2bf(a) | ((unsigned)f2bf(b) << 16); }
; __device__ __forceinline__ void conv_family(const float* __restrict__ W, u16* __restrict__ Wt, int cnt, int K, int N, int perm,
;                             float* tile, const int tid, const float* __restrict__ kscale = nullptr) {
;     ...
;       int n = tid & 255;
;       int sc = srccol(perm, n0 + n);
;       const float* wp = Ws + (size_t)(k0 + (tid >> 8)) * N + sc;
;       float v[32];
; #pragma unroll
;       for (int i = 0; i < 32; ++i) v[i] = wp[(size_t)(2 * i) * N];
;       if (kscale) {
;         const float* ks = kscale + (size_t)mi * K + k0 + (tid >> 8);
; #pragma unroll
;         for (int i = 0; i < 32; ++i) v[i] *= ks[2 * i];
;       }
; #pragma unroll
;       for (int i = 0; i < 32; ++i) tile[(2 * i + (tid >> 8)) * 257 + n] = v[i];
;     }
;     __syncthreads();
; #pragma unroll
;     for (int i = 0; i < 4; ++i) {
;       int n = i * 64 + (tid >> 3), ks = (tid & 7) * 8;
;       uint4 pk;
;       pk.x = pack2(tile[(ks + 0) * 257 + n], tile[(ks + 1) * 257 + n]);
	v_addc_co_u32_e32 v29, vcc, 0, v49, vcc
	v_add_co_u32_e32 v30, vcc, s1, v48
	s_mov_b32 s1, 0x155000
	s_nop 0
	v_addc_co_u32_e32 v31, vcc, 0, v49, vcc
	v_add_co_u32_e32 v32, vcc, s1, v48
	s_add_i32 s0, s0, s44
	s_nop 0
	v_addc_co_u32_e32 v33, vcc, 0, v49, vcc
	global_load_dword v48, v[48:49], off
	s_nop 0
	global_load_dword v49, v[50:51], off
	s_nop 0
	global_load_dword v50, v[52:53], off
	global_load_dword v51, v[54:55], off
	s_nop 0
	global_load_dword v52, v[56:57], off
	global_load_dword v53, v[58:59], off
	global_load_dword v54, v[60:61], off
	global_load_dword v55, v[62:63], off
	s_nop 0
	global_load_dword v56, v[64:65], off
	global_load_dword v57, v[66:67], off
	global_load_dword v58, v[68:69], off
	global_load_dword v59, v[70:71], off
	global_load_dword v60, v[78:79], off
	global_load_dword v61, v[80:81], off
	global_load_dword v62, v[82:83], off
	global_load_dword v63, v[84:85], off
	global_load_dword v64, v[86:87], off
	global_load_dword v66, v[34:35], off
	global_load_dword v67, v[36:37], off
	global_load_dword v68, v[38:39], off
	v_add_u32_e32 v65, 4, v46
	global_load_dword v40, v[40:41], off
	v_add_u32_e32 v34, 8, v46
	global_load_dword v41, v[42:43], off
	v_add_u32_e32 v35, 12, v46
	global_load_dword v42, v[44:45], off
	s_nop 0
	global_load_dword v16, v[16:17], off
	s_nop 0
	global_load_dword v17, v[18:19], off
	s_nop 0
	global_load_dword v18, v[20:21], off
	global_load_dword v19, v[22:23], off
	s_nop 0
	global_load_dword v20, v[24:25], off
	global_load_dword v21, v[26:27], off
	global_load_dword v22, v[28:29], off
	global_load_dword v23, v[30:31], off
	s_nop 0
	global_load_dword v24, v[32:33], off
	v_add_u32_e32 v36, 16, v46
	v_add_u32_e32 v37, 20, v46
	v_add_u32_e32 v38, 24, v46
	v_add_u32_e32 v39, 28, v46
	s_waitcnt vmcnt(31)
	ds_write_b32 v47, v48
	s_waitcnt vmcnt(30)
	ds_write_b32 v47, v49 offset:2056
	s_waitcnt vmcnt(29)
	ds_write_b32 v47, v50 offset:4112
	s_waitcnt vmcnt(28)
	ds_write_b32 v47, v51 offset:6168
	s_waitcnt vmcnt(27)
	ds_write_b32 v47, v52 offset:8224
	s_waitcnt vmcnt(26)
	ds_write_b32 v47, v53 offset:10280
	s_waitcnt vmcnt(25)
	ds_write_b32 v47, v54 offset:12336
	s_waitcnt vmcnt(24)
	ds_write_b32 v47, v55 offset:14392
	s_waitcnt vmcnt(23)
	ds_write_b32 v47, v56 offset:16448
	s_waitcnt vmcnt(22)
	ds_write_b32 v47, v57 offset:18504
	s_waitcnt vmcnt(21)
	ds_write_b32 v47, v58 offset:20560
	s_waitcnt vmcnt(20)
	ds_write_b32 v47, v59 offset:22616
	s_waitcnt vmcnt(19)
	ds_write_b32 v47, v60 offset:24672
	s_waitcnt vmcnt(18)
	ds_write_b32 v47, v61 offset:26728
	s_waitcnt vmcnt(17)
	ds_write_b32 v47, v62 offset:28784
	s_waitcnt vmcnt(16)
	ds_write_b32 v47, v63 offset:30840
	s_waitcnt vmcnt(15)
	ds_write_b32 v47, v64 offset:32896
	s_waitcnt vmcnt(14)
	ds_write_b32 v47, v66 offset:34952
	s_waitcnt vmcnt(13)
	ds_write_b32 v47, v67 offset:37008
	s_waitcnt vmcnt(12)
	ds_write_b32 v47, v68 offset:39064
	s_waitcnt vmcnt(11)
	ds_write_b32 v47, v40 offset:41120
	s_waitcnt vmcnt(10)
	ds_write_b32 v47, v41 offset:43176
	s_waitcnt vmcnt(9)
	ds_write_b32 v47, v42 offset:45232
	s_waitcnt vmcnt(8)
	ds_write_b32 v47, v16 offset:47288
	s_waitcnt vmcnt(7)
	ds_write_b32 v47, v17 offset:49344
	s_waitcnt vmcnt(6)
	ds_write_b32 v47, v18 offset:51400
	s_waitcnt vmcnt(5)
	ds_write_b32 v47, v19 offset:53456
	s_waitcnt vmcnt(4)
	ds_write_b32 v47, v20 offset:55512
	s_waitcnt vmcnt(3)
	ds_write_b32 v47, v21 offset:57568
	s_waitcnt vmcnt(2)
	ds_write_b32 v47, v22 offset:59624
	s_waitcnt vmcnt(1)
	ds_write_b32 v47, v23 offset:61680
	s_waitcnt vmcnt(0)
	ds_write_b32 v47, v24 offset:63736
	s_waitcnt lgkmcnt(0)
	s_barrier
	ds_read2st64_b32 v[16:17], v46 offset1:1
	ds_read2st64_b32 v[18:19], v46 offset0:2 offset1:3
	ds_read2st64_b32 v[20:21], v65 offset0:4 offset1:5
	ds_read2st64_b32 v[22:23], v65 offset0:6 offset1:7
	ds_read2st64_b32 v[24:25], v34 offset0:8 offset1:9
	ds_read2st64_b32 v[26:27], v34 offset0:10 offset1:11
	ds_read2st64_b32 v[28:29], v35 offset0:12 offset1:13
	ds_read2st64_b32 v[30:31], v35 offset0:14 offset1:15
	ds_read2st64_b32 v[32:33], v36 offset0:16 offset1:17
	ds_read2st64_b32 v[34:35], v36 offset0:18 offset1:19
	ds_read2st64_b32 v[40:41], v37 offset0:20 offset1:21
	ds_read2st64_b32 v[36:37], v37 offset0:22 offset1:23
	ds_read2st64_b32 v[42:43], v38 offset0:24 offset1:25
	ds_read2st64_b32 v[44:45], v38 offset0:26 offset1:27
	ds_read2st64_b32 v[48:49], v39 offset0:28 offset1:29
	ds_read2st64_b32 v[38:39], v39 offset0:30 offset1:31
	s_waitcnt lgkmcnt(11)
	v_and_b32_sdwa v50, v24, v178 dst_sel:DWORD dst_unused:UNUSED_PAD src0_sel:WORD_1 src1_sel:DWORD
	v_and_b32_sdwa v51, v16, v178 dst_sel:DWORD dst_unused:UNUSED_PAD src0_sel:WORD_1 src1_sel:DWORD
	s_waitcnt lgkmcnt(9)
	v_and_b32_sdwa v52, v28, v178 dst_sel:DWORD dst_unused:UNUSED_PAD src0_sel:WORD_1 src1_sel:DWORD
	v_and_b32_sdwa v53, v20, v178 dst_sel:DWORD dst_unused:UNUSED_PAD src0_sel:WORD_1 src1_sel:DWORD
	s_waitcnt lgkmcnt(3)
	v_and_b32_sdwa v54, v42, v178 dst_sel:DWORD dst_unused:UNUSED_PAD src0_sel:WORD_1 src1_sel:DWORD
	v_and_b32_sdwa v55, v32, v178 dst_sel:DWORD dst_unused:UNUSED_PAD src0_sel:WORD_1 src1_sel:DWORD
	s_waitcnt lgkmcnt(1)
; __device__ __forceinline__ unsigned pack2(float a, float b) { return (unsigned)f2bf(a) | ((unsigned)f2bf(b) << 16); }
; __device__ __forceinline__ void conv_family(const float* __restrict__ W, u16* __restrict__ Wt, int cnt, int K, int N, int perm,
;                             float* tile, const int tid, const float* __restrict__ kscale = nullptr) {
;     ...
;       pk.x = pack2(tile[(ks + 0) * 257 + n], tile[(ks + 1) * 257 + n]);
;       pk.y = pack2(tile[(ks + 2) * 257 + n], tile[(ks + 3) * 257 + n]);
;       pk.z = pack2(tile[(ks + 4) * 257 + n], tile[(ks + 5) * 257 + n]);
;       pk.w = pack2(tile[(ks + 6) * 257 + n], tile[(ks + 7) * 257 + n]);
;       *(uint4*)(Wd + (size_t)(n0 + n) * K + k0 + ks) = pk;
;     }
;     __syncthreads();
;   }
	v_and_b32_sdwa v56, v48, v178 dst_sel:DWORD dst_unused:UNUSED_PAD src0_sel:WORD_1 src1_sel:DWORD
	v_and_b32_sdwa v57, v40, v178 dst_sel:DWORD dst_unused:UNUSED_PAD src0_sel:WORD_1 src1_sel:DWORD
	v_and_b32_sdwa v58, v25, v178 dst_sel:DWORD dst_unused:UNUSED_PAD src0_sel:WORD_1 src1_sel:DWORD
	v_and_b32_sdwa v59, v17, v178 dst_sel:DWORD dst_unused:UNUSED_PAD src0_sel:WORD_1 src1_sel:DWORD
	v_and_b32_sdwa v60, v29, v178 dst_sel:DWORD dst_unused:UNUSED_PAD src0_sel:WORD_1 src1_sel:DWORD
	v_and_b32_sdwa v61, v21, v178 dst_sel:DWORD dst_unused:UNUSED_PAD src0_sel:WORD_1 src1_sel:DWORD
	v_and_b32_sdwa v62, v43, v178 dst_sel:DWORD dst_unused:UNUSED_PAD src0_sel:WORD_1 src1_sel:DWORD
	v_and_b32_sdwa v63, v33, v178 dst_sel:DWORD dst_unused:UNUSED_PAD src0_sel:WORD_1 src1_sel:DWORD
	v_and_b32_sdwa v65, v41, v178 dst_sel:DWORD dst_unused:UNUSED_PAD src0_sel:WORD_1 src1_sel:DWORD
	v_and_b32_sdwa v64, v49, v178 dst_sel:DWORD dst_unused:UNUSED_PAD src0_sel:WORD_1 src1_sel:DWORD
	v_add3_u32 v16, v16, v51, s81
	v_add3_u32 v51, v17, v59, s81
	v_and_b32_sdwa v17, v26, v178 dst_sel:DWORD dst_unused:UNUSED_PAD src0_sel:WORD_1 src1_sel:DWORD
	v_and_b32_sdwa v59, v18, v178 dst_sel:DWORD dst_unused:UNUSED_PAD src0_sel:WORD_1 src1_sel:DWORD
	v_add3_u32 v24, v24, v50, s81
	v_add3_u32 v25, v25, v58, s81
	v_and_b32_sdwa v50, v30, v178 dst_sel:DWORD dst_unused:UNUSED_PAD src0_sel:WORD_1 src1_sel:DWORD
	v_and_b32_sdwa v58, v22, v178 dst_sel:DWORD dst_unused:UNUSED_PAD src0_sel:WORD_1 src1_sel:DWORD
	v_add3_u32 v28, v28, v52, s81
	v_add3_u32 v29, v29, v60, s81
	v_and_b32_sdwa v52, v44, v178 dst_sel:DWORD dst_unused:UNUSED_PAD src0_sel:WORD_1 src1_sel:DWORD
	v_and_b32_sdwa v60, v34, v178 dst_sel:DWORD dst_unused:UNUSED_PAD src0_sel:WORD_1 src1_sel:DWORD
	v_add3_u32 v20, v20, v53, s81
	v_add3_u32 v21, v21, v61, s81
	s_waitcnt lgkmcnt(0)
	v_and_b32_sdwa v53, v38, v178 dst_sel:DWORD dst_unused:UNUSED_PAD src0_sel:WORD_1 src1_sel:DWORD
	v_and_b32_sdwa v61, v36, v178 dst_sel:DWORD dst_unused:UNUSED_PAD src0_sel:WORD_1 src1_sel:DWORD
	v_add3_u32 v32, v32, v55, s81
	v_add3_u32 v33, v33, v63, s81
	v_and_b32_sdwa v55, v27, v178 dst_sel:DWORD dst_unused:UNUSED_PAD src0_sel:WORD_1 src1_sel:DWORD
	v_and_b32_sdwa v63, v19, v178 dst_sel:DWORD dst_unused:UNUSED_PAD src0_sel:WORD_1 src1_sel:DWORD
	v_add3_u32 v42, v42, v54, s81
	v_add3_u32 v43, v43, v62, s81
	v_and_b32_sdwa v54, v31, v178 dst_sel:DWORD dst_unused:UNUSED_PAD src0_sel:WORD_1 src1_sel:DWORD
	v_and_b32_sdwa v62, v23, v178 dst_sel:DWORD dst_unused:UNUSED_PAD src0_sel:WORD_1 src1_sel:DWORD
	v_add3_u32 v48, v48, v56, s81
	v_add3_u32 v40, v40, v57, s81
	v_add3_u32 v41, v41, v65, s81
	v_and_b32_sdwa v57, v39, v178 dst_sel:DWORD dst_unused:UNUSED_PAD src0_sel:WORD_1 src1_sel:DWORD
	v_and_b32_sdwa v65, v37, v178 dst_sel:DWORD dst_unused:UNUSED_PAD src0_sel:WORD_1 src1_sel:DWORD
	v_add3_u32 v49, v49, v64, s81
	v_and_b32_sdwa v56, v45, v178 dst_sel:DWORD dst_unused:UNUSED_PAD src0_sel:WORD_1 src1_sel:DWORD
	v_and_b32_sdwa v64, v35, v178 dst_sel:DWORD dst_unused:UNUSED_PAD src0_sel:WORD_1 src1_sel:DWORD
	v_add3_u32 v59, v18, v59, s81
	v_add3_u32 v26, v26, v17, s81
	v_add3_u32 v17, v30, v50, s81
	v_add3_u32 v18, v22, v58, s81
	v_add3_u32 v30, v34, v60, s81
	v_add3_u32 v34, v44, v52, s81
	v_add3_u32 v22, v38, v53, s81
	v_add3_u32 v36, v36, v61, s81
	v_add3_u32 v38, v19, v63, s81
	v_add3_u32 v44, v27, v55, s81
	v_add3_u32 v19, v31, v54, s81
	v_add3_u32 v23, v23, v62, s81
	v_add3_u32 v27, v39, v57, s81
	v_add3_u32 v37, v37, v65, s81
	v_and_b32_e32 v28, 0xffff0000, v28
	v_and_b32_e32 v20, 0xffff0000, v20
	v_and_b32_e32 v39, 0xffff0000, v48
	v_and_b32_e32 v40, 0xffff0000, v40
	s_cmpk_lt_i32 s0, 0xb00
	v_add3_u32 v35, v35, v64, s81
	v_add3_u32 v31, v45, v56, s81
	v_and_b32_e32 v29, 0xffff0000, v29
	v_and_b32_e32 v45, 0xffff0000, v21
	v_and_b32_e32 v48, 0xffff0000, v49
	v_and_b32_e32 v41, 0xffff0000, v41
	v_and_b32_e32 v49, 0xffff0000, v17
	v_and_b32_e32 v50, 0xffff0000, v18
	v_and_b32_e32 v52, 0xffff0000, v22
	v_and_b32_e32 v36, 0xffff0000, v36
	v_and_b32_e32 v53, 0xffff0000, v19
	v_and_b32_e32 v54, 0xffff0000, v23
	v_and_b32_e32 v55, 0xffff0000, v27
	v_and_b32_e32 v37, 0xffff0000, v37
	v_or_b32_sdwa v17, v28, v24 dst_sel:DWORD dst_unused:UNUSED_PAD src0_sel:DWORD src1_sel:WORD_1
	v_or_b32_sdwa v16, v20, v16 dst_sel:DWORD dst_unused:UNUSED_PAD src0_sel:DWORD src1_sel:WORD_1
	v_or_b32_sdwa v19, v39, v42 dst_sel:DWORD dst_unused:UNUSED_PAD src0_sel:DWORD src1_sel:WORD_1
	v_or_b32_sdwa v18, v40, v32 dst_sel:DWORD dst_unused:UNUSED_PAD src0_sel:DWORD src1_sel:WORD_1
	v_or_b32_sdwa v21, v29, v25 dst_sel:DWORD dst_unused:UNUSED_PAD src0_sel:DWORD src1_sel:WORD_1
	v_or_b32_sdwa v20, v45, v51 dst_sel:DWORD dst_unused:UNUSED_PAD src0_sel:DWORD src1_sel:WORD_1
	v_or_b32_sdwa v23, v48, v43 dst_sel:DWORD dst_unused:UNUSED_PAD src0_sel:DWORD src1_sel:WORD_1
	v_or_b32_sdwa v22, v41, v33 dst_sel:DWORD dst_unused:UNUSED_PAD src0_sel:DWORD src1_sel:WORD_1
	v_or_b32_sdwa v25, v49, v26 dst_sel:DWORD dst_unused:UNUSED_PAD src0_sel:DWORD src1_sel:WORD_1
	v_or_b32_sdwa v24, v50, v59 dst_sel:DWORD dst_unused:UNUSED_PAD src0_sel:DWORD src1_sel:WORD_1
	v_or_b32_sdwa v27, v52, v34 dst_sel:DWORD dst_unused:UNUSED_PAD src0_sel:DWORD src1_sel:WORD_1
	v_or_b32_sdwa v26, v36, v30 dst_sel:DWORD dst_unused:UNUSED_PAD src0_sel:DWORD src1_sel:WORD_1
	v_or_b32_sdwa v29, v53, v44 dst_sel:DWORD dst_unused:UNUSED_PAD src0_sel:DWORD src1_sel:WORD_1
	v_or_b32_sdwa v28, v54, v38 dst_sel:DWORD dst_unused:UNUSED_PAD src0_sel:DWORD src1_sel:WORD_1
	v_or_b32_sdwa v31, v55, v31 dst_sel:DWORD dst_unused:UNUSED_PAD src0_sel:DWORD src1_sel:WORD_1
	v_or_b32_sdwa v30, v37, v35 dst_sel:DWORD dst_unused:UNUSED_PAD src0_sel:DWORD src1_sel:WORD_1
	global_store_dwordx4 v[8:9], v[16:19], off
	global_store_dwordx4 v[10:11], v[20:23], off
	global_store_dwordx4 v[12:13], v[24:27], off
	global_store_dwordx4 v[14:15], v[28:31], off
	s_barrier
	s_cbranch_scc1 .LBB0_908
